# fft: 12 hand-scheduled radix-16 loops with hoisted twiddle tables; hyena kernel-build and fourier load ladders de-serialised (16 loads up front)
# speedup vs baseline: 1.0063x; 1.0063x over previous
; #define GAS __attribute__((address_space(1)))
; #define LAS __attribute__((address_space(3)))
; __device__ __forceinline__ f32x2 cmul(f32x2 a, f32x2 b) { return (f32x2){a.x * b.x - a.y * b.y, a.x * b.y + a.y * b.x}; }
; #define LT() ({ int lt_ = tid; asm volatile("" : "+v"(lt_)); lt_; })
; __device__ __forceinline__ void tw4(const LAS f32x2* TH, const LAS f32x2* TL, int n0, f32x2 (&w)[4]) {
;     const f32x2 th = TH[n0 >> 7]; const LAS f32x4* tl = (const LAS f32x4*)(TL + (n0 & 127)); const f32x4 a = tl[0], b = tl[1];
;     w[0] = cmul(th, (f32x2){a.x, a.y}); w[1] = cmul(th, (f32x2){a.z, a.w}); w[2] = cmul(th, (f32x2){b.x, b.y}); w[3] = cmul(th, (f32x2){b.z, b.w});
; }
; __device__ __forceinline__ void hyena_latent(Frame& F, int l, int ch, LAS f32x2* X, const LAS f32x2* TH, const LAS f32x2* TL, GAS f32x2* KS, const LAS float* CT  , bool wr = true) {
;     ...
;             for (int i = 0; i < 8; ++i) { const int g = LT() + NTHR * i, n0 = 4 * g; const f32x4 f = *(const GAS f32x4*)(hf + n0), bk = *(const GAS f32x4*)(hbr + n0);
;                 LAS f32x4* XP = (LAS f32x4*)(X + phys(n0));
;                 if (par == 0) { XP[0] = (f32x4){f.x + bk.x, 0.f, f.y + bk.y, 0.f}; XP[1] = (f32x4){f.z + bk.z, 0.f, f.w + bk.w, 0.f}; }
;                 else { f32x2 w[4]; tw4(TH, TL, n0, w); const f32x4 d = f - bk;
;                     XP[0] = (f32x4){w[0].x * d.x, w[0].y * d.x, w[1].x * d.y, w[1].y * d.y}; XP[1] = (f32x4){w[2].x * d.z, w[2].y * d.z, w[3].x * d.w, w[3].y * d.w}; } }
.LBB0_663:
	v_lshlrev_b32_e32 v60, 4, v140
	global_load_dwordx4 v[64:67], v60, s[28:29]
	global_load_dwordx4 v[68:71], v60, s[30:31]
	v_add_u32_e32 v62, 0x2000, v60
	global_load_dwordx4 v[72:75], v62, s[28:29]
	global_load_dwordx4 v[76:79], v62, s[30:31]
	v_add_u32_e32 v63, 0x4000, v60
	global_load_dwordx4 v[80:83], v63, s[28:29]
	global_load_dwordx4 v[84:87], v63, s[30:31]
	v_add_u32_e32 v61, 0x6000, v60
	global_load_dwordx4 v[88:91], v61, s[28:29]
	global_load_dwordx4 v[92:95], v61, s[30:31]
	v_add_u32_e32 v62, 0x8000, v60
	global_load_dwordx4 v[96:99], v62, s[28:29]
	global_load_dwordx4 v[100:103], v62, s[30:31]
	v_add_u32_e32 v63, 0xa000, v60
	global_load_dwordx4 v[104:107], v63, s[28:29]
	global_load_dwordx4 v[108:111], v63, s[30:31]
	v_add_u32_e32 v61, 0xc000, v60
	global_load_dwordx4 v[112:115], v61, s[28:29]
	global_load_dwordx4 v[116:119], v61, s[30:31]
	v_add_u32_e32 v62, 0xe000, v60
	global_load_dwordx4 v[120:123], v62, s[28:29]
	global_load_dwordx4 v[124:127], v62, s[30:31]
	v_mov_b32_e32 v0, v140
	s_xor_b64 s[14:15], s[34:35], -1
	v_lshlrev_b32_e32 v16, 2, v0
	v_ashrrev_i32_e32 v17, 31, v16
	v_lshlrev_b64 v[0:1], 2, v[16:17]
	v_lshl_add_u64 v[2:3], s[28:29], 0, v[0:1]
	v_lshl_add_u64 v[4:5], s[30:31], 0, v[0:1]
	s_waitcnt vmcnt(14)
	v_mov_b32_e32 v0, v64
	v_mov_b32_e32 v1, v65
	v_mov_b32_e32 v2, v66
	v_mov_b32_e32 v3, v67
	v_mov_b32_e32 v4, v68
	v_mov_b32_e32 v5, v69
	v_mov_b32_e32 v6, v70
	v_mov_b32_e32 v7, v71
	s_mov_b64 s[12:13], -1
	s_and_b64 vcc, exec, s[14:15]
	s_cbranch_vccz .LBB0_665
	v_ashrrev_i32_e32 v8, 7, v16
	v_and_b32_e32 v9, 0x7c, v16
	v_lshl_add_u32 v8, v8, 3, 0
	v_lshl_add_u32 v9, v9, 3, 0
	v_add_u32_e32 v8, 0x26000, v8
	v_add_u32_e32 v12, 0x26400, v9
	ds_read_b64 v[18:19], v8
	ds_read_b128 v[8:11], v12
	ds_read_b128 v[12:15], v12 offset:16
	s_waitcnt vmcnt(14)
	v_sub_f32_e32 v26, v0, v4
	v_sub_f32_e32 v24, v2, v6
	s_mov_b64 s[12:13], 0
	s_waitcnt lgkmcnt(1)
	v_mul_f32_e32 v20, v19, v11
	v_mul_f32_e32 v22, v18, v11
	v_pk_fma_f32 v[20:21], v[18:19], v[10:11], v[20:21] op_sel_hi:[1,1,0] neg_lo:[0,0,1] neg_hi:[0,0,1]
	v_pk_fma_f32 v[10:11], v[18:19], v[10:11], v[22:23] op_sel:[0,1,0] op_sel_hi:[1,0,0]
	v_pk_mul_f32 v[28:29], v[18:19], v[8:9] op_sel:[1,0]
	s_waitcnt lgkmcnt(0)
	v_mul_f32_e32 v10, v19, v15
	v_pk_fma_f32 v[22:23], v[18:19], v[14:15], v[10:11] op_sel_hi:[1,1,0] neg_lo:[0,0,1] neg_hi:[0,0,1]
	v_mul_f32_e32 v10, v18, v15
	v_pk_fma_f32 v[14:15], v[18:19], v[14:15], v[10:11] op_sel:[0,1,0] op_sel_hi:[1,0,0]
	v_sub_f32_e32 v10, v1, v5
	v_pk_fma_f32 v[30:31], v[18:19], v[8:9], v[28:29] op_sel:[0,0,1] op_sel_hi:[1,1,0] neg_lo:[0,0,1] neg_hi:[0,0,1]
	v_pk_fma_f32 v[8:9], v[18:19], v[8:9], v[28:29] op_sel:[0,0,1] op_sel_hi:[0,1,0]
	v_mov_b32_e32 v21, v11
	v_mov_b32_e32 v31, v9
	v_pk_mul_f32 v[10:11], v[10:11], v[20:21] op_sel_hi:[0,1]
	v_pk_mul_f32 v[20:21], v[18:19], v[12:13] op_sel:[1,0]
	v_pk_mul_f32 v[8:9], v[26:27], v[30:31] op_sel_hi:[0,1]
	v_pk_fma_f32 v[26:27], v[18:19], v[12:13], v[20:21] op_sel:[0,0,1] op_sel_hi:[1,1,0] neg_lo:[0,0,1] neg_hi:[0,0,1]
	v_pk_fma_f32 v[12:13], v[18:19], v[12:13], v[20:21] op_sel:[0,0,1] op_sel_hi:[0,1,0]
	v_sub_f32_e32 v14, v3, v7
	v_mov_b32_e32 v27, v13
	v_mov_b32_e32 v23, v15
	v_pk_mul_f32 v[12:13], v[24:25], v[26:27] op_sel_hi:[0,1]
	v_pk_mul_f32 v[14:15], v[14:15], v[22:23] op_sel_hi:[0,1]
.LBB0_665:
	s_andn2_b64 vcc, exec, s[12:13]
	s_cbranch_vccnz .LBB0_667
	s_waitcnt vmcnt(14)
	v_pk_add_f32 v[2:3], v[2:3], v[6:7]
	v_pk_add_f32 v[0:1], v[0:1], v[4:5]
	v_mov_b32_e32 v9, 0
	v_mov_b32_e32 v8, v0
	v_mov_b32_e32 v10, v1
	v_mov_b32_e32 v11, v9
	v_mov_b32_e32 v12, v2
	v_mov_b32_e32 v13, v9
	v_mov_b32_e32 v14, v3
	v_mov_b32_e32 v15, v9
.LBB0_667:
	s_waitcnt vmcnt(14)
	v_ashrrev_i32_e32 v0, 4, v16
	v_lshlrev_b32_e32 v0, 3, v0
	v_and_b32_e32 v0, 0xffffffe0, v0
	v_lshlrev_b32_e32 v1, 3, v16
	v_add3_u32 v0, 0, v0, v1
	ds_write_b128 v0, v[8:11]
	ds_write_b128 v0, v[12:15] offset:16
	v_mov_b32_e32 v0, v140
	v_cndmask_b32_e64 v8, 0, 1, s[14:15]
	v_lshlrev_b32_e32 v18, 2, v0
	v_add_u32_e32 v16, 0x800, v18
	v_ashrrev_i32_e32 v17, 31, v16
	v_lshlrev_b64 v[0:1], 2, v[16:17]
	v_lshl_add_u64 v[2:3], s[28:29], 0, v[0:1]
	v_lshl_add_u64 v[4:5], s[30:31], 0, v[0:1]
	s_waitcnt vmcnt(12)
	v_mov_b32_e32 v0, v72
	v_mov_b32_e32 v1, v73
	v_mov_b32_e32 v2, v74
	v_mov_b32_e32 v3, v75
	v_mov_b32_e32 v4, v76
	v_mov_b32_e32 v5, v77
	v_mov_b32_e32 v6, v78
	v_mov_b32_e32 v7, v79
	v_cmp_ne_u32_e64 s[12:13], 1, v8
	s_andn2_b64 vcc, exec, s[14:15]
	s_mov_b64 s[36:37], -1
	s_cbranch_vccnz .LBB0_669
	v_ashrrev_i32_e32 v8, 7, v16
	v_and_b32_e32 v9, 0x7c, v18
	v_lshl_add_u32 v8, v8, 3, 0
	v_lshl_add_u32 v9, v9, 3, 0
	v_add_u32_e32 v8, 0x26000, v8
	v_add_u32_e32 v12, 0x26400, v9
	ds_read_b64 v[20:21], v8
	ds_read_b128 v[8:11], v12
	ds_read_b128 v[12:15], v12 offset:16
	s_waitcnt vmcnt(12)
	v_sub_f32_e32 v28, v0, v4
	v_sub_f32_e32 v26, v2, v6
	s_mov_b64 s[36:37], 0
	s_waitcnt lgkmcnt(1)
	v_mul_f32_e32 v22, v21, v11
	v_mul_f32_e32 v24, v20, v11
	v_pk_fma_f32 v[22:23], v[20:21], v[10:11], v[22:23] op_sel_hi:[1,1,0] neg_lo:[0,0,1] neg_hi:[0,0,1]
	v_pk_fma_f32 v[10:11], v[20:21], v[10:11], v[24:25] op_sel:[0,1,0] op_sel_hi:[1,0,0]
	v_pk_mul_f32 v[30:31], v[20:21], v[8:9] op_sel:[1,0]
	s_waitcnt lgkmcnt(0)
	v_mul_f32_e32 v10, v21, v15
	v_pk_fma_f32 v[24:25], v[20:21], v[14:15], v[10:11] op_sel_hi:[1,1,0] neg_lo:[0,0,1] neg_hi:[0,0,1]
	v_mul_f32_e32 v10, v20, v15
	v_pk_fma_f32 v[14:15], v[20:21], v[14:15], v[10:11] op_sel:[0,1,0] op_sel_hi:[1,0,0]
	v_sub_f32_e32 v10, v1, v5
	v_pk_fma_f32 v[32:33], v[20:21], v[8:9], v[30:31] op_sel:[0,0,1] op_sel_hi:[1,1,0] neg_lo:[0,0,1] neg_hi:[0,0,1]
	v_pk_fma_f32 v[8:9], v[20:21], v[8:9], v[30:31] op_sel:[0,0,1] op_sel_hi:[0,1,0]
	v_mov_b32_e32 v23, v11
	v_mov_b32_e32 v33, v9
	v_pk_mul_f32 v[10:11], v[10:11], v[22:23] op_sel_hi:[0,1]
	v_pk_mul_f32 v[22:23], v[20:21], v[12:13] op_sel:[1,0]
	v_pk_mul_f32 v[8:9], v[28:29], v[32:33] op_sel_hi:[0,1]
	v_pk_fma_f32 v[28:29], v[20:21], v[12:13], v[22:23] op_sel:[0,0,1] op_sel_hi:[1,1,0] neg_lo:[0,0,1] neg_hi:[0,0,1]
	v_pk_fma_f32 v[12:13], v[20:21], v[12:13], v[22:23] op_sel:[0,0,1] op_sel_hi:[0,1,0]
	v_sub_f32_e32 v14, v3, v7
	v_mov_b32_e32 v29, v13
	v_mov_b32_e32 v25, v15
	v_pk_mul_f32 v[12:13], v[26:27], v[28:29] op_sel_hi:[0,1]
	v_pk_mul_f32 v[14:15], v[14:15], v[24:25] op_sel_hi:[0,1]
; #define GAS __attribute__((address_space(1)))
; #define LAS __attribute__((address_space(3)))
; __device__ __forceinline__ f32x2 cmul(f32x2 a, f32x2 b) { return (f32x2){a.x * b.x - a.y * b.y, a.x * b.y + a.y * b.x}; }
; #define LT() ({ int lt_ = tid; asm volatile("" : "+v"(lt_)); lt_; })
; __device__ __forceinline__ void tw4(const LAS f32x2* TH, const LAS f32x2* TL, int n0, f32x2 (&w)[4]) {
;     const f32x2 th = TH[n0 >> 7]; const LAS f32x4* tl = (const LAS f32x4*)(TL + (n0 & 127)); const f32x4 a = tl[0], b = tl[1];
;     w[0] = cmul(th, (f32x2){a.x, a.y}); w[1] = cmul(th, (f32x2){a.z, a.w}); w[2] = cmul(th, (f32x2){b.x, b.y}); w[3] = cmul(th, (f32x2){b.z, b.w});
; }
; __device__ __forceinline__ void hyena_latent(Frame& F, int l, int ch, LAS f32x2* X, const LAS f32x2* TH, const LAS f32x2* TL, GAS f32x2* KS, const LAS float* CT  , bool wr = true) {
;     ...
;             for (int i = 0; i < 8; ++i) { const int g = LT() + NTHR * i, n0 = 4 * g; const f32x4 f = *(const GAS f32x4*)(hf + n0), bk = *(const GAS f32x4*)(hbr + n0);
;                 LAS f32x4* XP = (LAS f32x4*)(X + phys(n0));
;                 if (par == 0) { XP[0] = (f32x4){f.x + bk.x, 0.f, f.y + bk.y, 0.f}; XP[1] = (f32x4){f.z + bk.z, 0.f, f.w + bk.w, 0.f}; }
;                 else { f32x2 w[4]; tw4(TH, TL, n0, w); const f32x4 d = f - bk;
;                     XP[0] = (f32x4){w[0].x * d.x, w[0].y * d.x, w[1].x * d.y, w[1].y * d.y}; XP[1] = (f32x4){w[2].x * d.z, w[2].y * d.z, w[3].x * d.w, w[3].y * d.w}; } }
.LBB0_669:
	s_andn2_b64 vcc, exec, s[36:37]
	s_cbranch_vccnz .LBB0_671
	s_waitcnt vmcnt(12)
	v_pk_add_f32 v[2:3], v[2:3], v[6:7]
	v_pk_add_f32 v[0:1], v[0:1], v[4:5]
	v_mov_b32_e32 v9, 0
	v_mov_b32_e32 v8, v0
	v_mov_b32_e32 v10, v1
	v_mov_b32_e32 v11, v9
	v_mov_b32_e32 v12, v2
	v_mov_b32_e32 v13, v9
	v_mov_b32_e32 v14, v3
	v_mov_b32_e32 v15, v9
.LBB0_671:
	s_waitcnt vmcnt(13)
	v_ashrrev_i32_e32 v0, 4, v16
	v_lshlrev_b32_e32 v0, 3, v0
	v_and_b32_e32 v0, 0xffffffe0, v0
	v_lshlrev_b32_e32 v1, 3, v18
	v_add3_u32 v0, 0, v0, v1
	ds_write_b128 v0, v[8:11] offset:16384
	ds_write_b128 v0, v[12:15] offset:16400
	v_mov_b32_e32 v0, v140
	s_and_b64 vcc, exec, s[12:13]
	v_lshlrev_b32_e32 v18, 2, v0
	v_add_u32_e32 v16, 0x1000, v18
	v_ashrrev_i32_e32 v17, 31, v16
	v_lshlrev_b64 v[0:1], 2, v[16:17]
	v_lshl_add_u64 v[2:3], s[28:29], 0, v[0:1]
	s_waitcnt vmcnt(12)
	v_lshl_add_u64 v[4:5], s[30:31], 0, v[0:1]
	s_waitcnt vmcnt(10)
	v_mov_b32_e32 v0, v80
	v_mov_b32_e32 v1, v81
	v_mov_b32_e32 v2, v82
	v_mov_b32_e32 v3, v83
	v_mov_b32_e32 v4, v84
	v_mov_b32_e32 v5, v85
	v_mov_b32_e32 v6, v86
	v_mov_b32_e32 v7, v87
	s_mov_b64 s[36:37], -1
	s_cbranch_vccnz .LBB0_673
	v_ashrrev_i32_e32 v8, 7, v16
	v_and_b32_e32 v9, 0x7c, v18
	v_lshl_add_u32 v8, v8, 3, 0
	v_lshl_add_u32 v9, v9, 3, 0
	v_add_u32_e32 v8, 0x26000, v8
	v_add_u32_e32 v12, 0x26400, v9
	ds_read_b64 v[20:21], v8
	ds_read_b128 v[8:11], v12
	ds_read_b128 v[12:15], v12 offset:16
	s_waitcnt vmcnt(10)
	v_sub_f32_e32 v28, v0, v4
	v_sub_f32_e32 v26, v2, v6
	s_mov_b64 s[36:37], 0
	s_waitcnt lgkmcnt(1)
	v_mul_f32_e32 v22, v21, v11
	v_mul_f32_e32 v24, v20, v11
	v_pk_fma_f32 v[22:23], v[20:21], v[10:11], v[22:23] op_sel_hi:[1,1,0] neg_lo:[0,0,1] neg_hi:[0,0,1]
	v_pk_fma_f32 v[10:11], v[20:21], v[10:11], v[24:25] op_sel:[0,1,0] op_sel_hi:[1,0,0]
	v_pk_mul_f32 v[30:31], v[20:21], v[8:9] op_sel:[1,0]
	s_waitcnt lgkmcnt(0)
	v_mul_f32_e32 v10, v21, v15
	v_pk_fma_f32 v[24:25], v[20:21], v[14:15], v[10:11] op_sel_hi:[1,1,0] neg_lo:[0,0,1] neg_hi:[0,0,1]
	v_mul_f32_e32 v10, v20, v15
	v_pk_fma_f32 v[14:15], v[20:21], v[14:15], v[10:11] op_sel:[0,1,0] op_sel_hi:[1,0,0]
	v_sub_f32_e32 v10, v1, v5
	v_pk_fma_f32 v[32:33], v[20:21], v[8:9], v[30:31] op_sel:[0,0,1] op_sel_hi:[1,1,0] neg_lo:[0,0,1] neg_hi:[0,0,1]
	v_pk_fma_f32 v[8:9], v[20:21], v[8:9], v[30:31] op_sel:[0,0,1] op_sel_hi:[0,1,0]
	v_mov_b32_e32 v23, v11
	v_mov_b32_e32 v33, v9
	v_pk_mul_f32 v[10:11], v[10:11], v[22:23] op_sel_hi:[0,1]
	v_pk_mul_f32 v[22:23], v[20:21], v[12:13] op_sel:[1,0]
	v_pk_mul_f32 v[8:9], v[28:29], v[32:33] op_sel_hi:[0,1]
	v_pk_fma_f32 v[28:29], v[20:21], v[12:13], v[22:23] op_sel:[0,0,1] op_sel_hi:[1,1,0] neg_lo:[0,0,1] neg_hi:[0,0,1]
	v_pk_fma_f32 v[12:13], v[20:21], v[12:13], v[22:23] op_sel:[0,0,1] op_sel_hi:[0,1,0]
	v_sub_f32_e32 v14, v3, v7
	v_mov_b32_e32 v29, v13
	v_mov_b32_e32 v25, v15
	v_pk_mul_f32 v[12:13], v[26:27], v[28:29] op_sel_hi:[0,1]
	v_pk_mul_f32 v[14:15], v[14:15], v[24:25] op_sel_hi:[0,1]
.LBB0_673:
	s_andn2_b64 vcc, exec, s[36:37]
	s_cbranch_vccnz .LBB0_675
	s_waitcnt vmcnt(10)
	v_pk_add_f32 v[2:3], v[2:3], v[6:7]
	v_pk_add_f32 v[0:1], v[0:1], v[4:5]
	v_mov_b32_e32 v9, 0
	v_mov_b32_e32 v8, v0
	v_mov_b32_e32 v10, v1
	v_mov_b32_e32 v11, v9
	v_mov_b32_e32 v12, v2
	v_mov_b32_e32 v13, v9
	v_mov_b32_e32 v14, v3
	v_mov_b32_e32 v15, v9
.LBB0_675:
	s_waitcnt vmcnt(11)
	v_ashrrev_i32_e32 v0, 4, v16
	v_lshlrev_b32_e32 v0, 3, v0
	v_and_b32_e32 v0, 0xffffffe0, v0
	v_lshlrev_b32_e32 v1, 3, v18
	v_add3_u32 v0, 0, v0, v1
	ds_write_b128 v0, v[8:11] offset:32768
	ds_write_b128 v0, v[12:15] offset:32784
	v_mov_b32_e32 v0, v140
	s_and_b64 vcc, exec, s[12:13]
	v_lshlrev_b32_e32 v18, 2, v0
	v_add_u32_e32 v16, 0x1800, v18
	v_ashrrev_i32_e32 v17, 31, v16
	v_lshlrev_b64 v[0:1], 2, v[16:17]
	v_lshl_add_u64 v[2:3], s[28:29], 0, v[0:1]
	s_waitcnt vmcnt(10)
	v_lshl_add_u64 v[4:5], s[30:31], 0, v[0:1]
	s_waitcnt vmcnt(8)
	v_mov_b32_e32 v0, v88
	v_mov_b32_e32 v1, v89
	v_mov_b32_e32 v2, v90
	v_mov_b32_e32 v3, v91
	v_mov_b32_e32 v4, v92
	v_mov_b32_e32 v5, v93
	v_mov_b32_e32 v6, v94
	v_mov_b32_e32 v7, v95
	s_mov_b64 s[36:37], -1
	s_cbranch_vccnz .LBB0_677
	v_ashrrev_i32_e32 v8, 7, v16
	v_and_b32_e32 v9, 0x7c, v18
	v_lshl_add_u32 v8, v8, 3, 0
	v_lshl_add_u32 v9, v9, 3, 0
	v_add_u32_e32 v8, 0x26000, v8
	v_add_u32_e32 v12, 0x26400, v9
	ds_read_b64 v[20:21], v8
	ds_read_b128 v[8:11], v12
	ds_read_b128 v[12:15], v12 offset:16
	s_waitcnt vmcnt(8)
	v_sub_f32_e32 v28, v0, v4
	v_sub_f32_e32 v26, v2, v6
	s_mov_b64 s[36:37], 0
	s_waitcnt lgkmcnt(1)
	v_mul_f32_e32 v22, v21, v11
	v_mul_f32_e32 v24, v20, v11
	v_pk_fma_f32 v[22:23], v[20:21], v[10:11], v[22:23] op_sel_hi:[1,1,0] neg_lo:[0,0,1] neg_hi:[0,0,1]
	v_pk_fma_f32 v[10:11], v[20:21], v[10:11], v[24:25] op_sel:[0,1,0] op_sel_hi:[1,0,0]
	v_pk_mul_f32 v[30:31], v[20:21], v[8:9] op_sel:[1,0]
	s_waitcnt lgkmcnt(0)
	v_mul_f32_e32 v10, v21, v15
	v_pk_fma_f32 v[24:25], v[20:21], v[14:15], v[10:11] op_sel_hi:[1,1,0] neg_lo:[0,0,1] neg_hi:[0,0,1]
	v_mul_f32_e32 v10, v20, v15
	v_pk_fma_f32 v[14:15], v[20:21], v[14:15], v[10:11] op_sel:[0,1,0] op_sel_hi:[1,0,0]
	v_sub_f32_e32 v10, v1, v5
	v_pk_fma_f32 v[32:33], v[20:21], v[8:9], v[30:31] op_sel:[0,0,1] op_sel_hi:[1,1,0] neg_lo:[0,0,1] neg_hi:[0,0,1]
	v_pk_fma_f32 v[8:9], v[20:21], v[8:9], v[30:31] op_sel:[0,0,1] op_sel_hi:[0,1,0]
	v_mov_b32_e32 v23, v11
	v_mov_b32_e32 v33, v9
	v_pk_mul_f32 v[10:11], v[10:11], v[22:23] op_sel_hi:[0,1]
	v_pk_mul_f32 v[22:23], v[20:21], v[12:13] op_sel:[1,0]
	v_pk_mul_f32 v[8:9], v[28:29], v[32:33] op_sel_hi:[0,1]
	v_pk_fma_f32 v[28:29], v[20:21], v[12:13], v[22:23] op_sel:[0,0,1] op_sel_hi:[1,1,0] neg_lo:[0,0,1] neg_hi:[0,0,1]
	v_pk_fma_f32 v[12:13], v[20:21], v[12:13], v[22:23] op_sel:[0,0,1] op_sel_hi:[0,1,0]
	v_sub_f32_e32 v14, v3, v7
	v_mov_b32_e32 v29, v13
	v_mov_b32_e32 v25, v15
	v_pk_mul_f32 v[12:13], v[26:27], v[28:29] op_sel_hi:[0,1]
	v_pk_mul_f32 v[14:15], v[14:15], v[24:25] op_sel_hi:[0,1]
; #define GAS __attribute__((address_space(1)))
; #define LAS __attribute__((address_space(3)))
; __device__ __forceinline__ f32x2 cmul(f32x2 a, f32x2 b) { return (f32x2){a.x * b.x - a.y * b.y, a.x * b.y + a.y * b.x}; }
; #define LT() ({ int lt_ = tid; asm volatile("" : "+v"(lt_)); lt_; })
; __device__ __forceinline__ void tw4(const LAS f32x2* TH, const LAS f32x2* TL, int n0, f32x2 (&w)[4]) {
;     const f32x2 th = TH[n0 >> 7]; const LAS f32x4* tl = (const LAS f32x4*)(TL + (n0 & 127)); const f32x4 a = tl[0], b = tl[1];
;     w[0] = cmul(th, (f32x2){a.x, a.y}); w[1] = cmul(th, (f32x2){a.z, a.w}); w[2] = cmul(th, (f32x2){b.x, b.y}); w[3] = cmul(th, (f32x2){b.z, b.w});
; }
; __device__ __forceinline__ void hyena_latent(Frame& F, int l, int ch, LAS f32x2* X, const LAS f32x2* TH, const LAS f32x2* TL, GAS f32x2* KS, const LAS float* CT  , bool wr = true) {
;     ...
;             for (int i = 0; i < 8; ++i) { const int g = LT() + NTHR * i, n0 = 4 * g; const f32x4 f = *(const GAS f32x4*)(hf + n0), bk = *(const GAS f32x4*)(hbr + n0);
;                 LAS f32x4* XP = (LAS f32x4*)(X + phys(n0));
;                 if (par == 0) { XP[0] = (f32x4){f.x + bk.x, 0.f, f.y + bk.y, 0.f}; XP[1] = (f32x4){f.z + bk.z, 0.f, f.w + bk.w, 0.f}; }
;                 else { f32x2 w[4]; tw4(TH, TL, n0, w); const f32x4 d = f - bk;
;                     XP[0] = (f32x4){w[0].x * d.x, w[0].y * d.x, w[1].x * d.y, w[1].y * d.y}; XP[1] = (f32x4){w[2].x * d.z, w[2].y * d.z, w[3].x * d.w, w[3].y * d.w}; } }
.LBB0_677:
	s_andn2_b64 vcc, exec, s[36:37]
	s_cbranch_vccnz .LBB0_679
	s_waitcnt vmcnt(8)
	v_pk_add_f32 v[2:3], v[2:3], v[6:7]
	v_pk_add_f32 v[0:1], v[0:1], v[4:5]
	v_mov_b32_e32 v9, 0
	v_mov_b32_e32 v8, v0
	v_mov_b32_e32 v10, v1
	v_mov_b32_e32 v11, v9
	v_mov_b32_e32 v12, v2
	v_mov_b32_e32 v13, v9
	v_mov_b32_e32 v14, v3
	v_mov_b32_e32 v15, v9
.LBB0_679:
	s_waitcnt vmcnt(9)
	v_ashrrev_i32_e32 v0, 4, v16
	v_lshlrev_b32_e32 v0, 3, v0
	v_and_b32_e32 v0, 0xffffffe0, v0
	v_lshlrev_b32_e32 v1, 3, v18
	v_add3_u32 v0, 0, v0, v1
	ds_write_b128 v0, v[8:11] offset:49152
	ds_write_b128 v0, v[12:15] offset:49168
	v_mov_b32_e32 v0, v140
	s_and_b64 vcc, exec, s[12:13]
	v_lshlrev_b32_e32 v8, 2, v0
	v_add_u32_e32 v16, 0x2000, v8
	v_ashrrev_i32_e32 v17, 31, v16
	v_lshlrev_b64 v[0:1], 2, v[16:17]
	v_lshl_add_u64 v[2:3], s[28:29], 0, v[0:1]
	s_waitcnt vmcnt(8)
	v_lshl_add_u64 v[4:5], s[30:31], 0, v[0:1]
	s_waitcnt vmcnt(6)
	v_mov_b32_e32 v0, v96
	v_mov_b32_e32 v1, v97
	v_mov_b32_e32 v2, v98
	v_mov_b32_e32 v3, v99
	v_mov_b32_e32 v4, v100
	v_mov_b32_e32 v5, v101
	v_mov_b32_e32 v6, v102
	v_mov_b32_e32 v7, v103
	s_mov_b64 s[36:37], -1
	s_cbranch_vccnz .LBB0_681
	v_ashrrev_i32_e32 v9, 7, v16
	v_and_b32_e32 v8, 0x7c, v8
	v_lshl_add_u32 v9, v9, 3, 0
	v_lshl_add_u32 v8, v8, 3, 0
	v_add_u32_e32 v9, 0x26000, v9
	v_add_u32_e32 v12, 0x26400, v8
	ds_read_b64 v[18:19], v9
	ds_read_b128 v[8:11], v12
	ds_read_b128 v[12:15], v12 offset:16
	s_waitcnt vmcnt(6)
	v_sub_f32_e32 v26, v0, v4
	v_sub_f32_e32 v24, v2, v6
	s_mov_b64 s[36:37], 0
	s_waitcnt lgkmcnt(1)
	v_mul_f32_e32 v20, v19, v11
	v_mul_f32_e32 v22, v18, v11
	v_pk_fma_f32 v[20:21], v[18:19], v[10:11], v[20:21] op_sel_hi:[1,1,0] neg_lo:[0,0,1] neg_hi:[0,0,1]
	v_pk_fma_f32 v[10:11], v[18:19], v[10:11], v[22:23] op_sel:[0,1,0] op_sel_hi:[1,0,0]
	v_pk_mul_f32 v[28:29], v[18:19], v[8:9] op_sel:[1,0]
	s_waitcnt lgkmcnt(0)
	v_mul_f32_e32 v10, v19, v15
	v_pk_fma_f32 v[22:23], v[18:19], v[14:15], v[10:11] op_sel_hi:[1,1,0] neg_lo:[0,0,1] neg_hi:[0,0,1]
	v_mul_f32_e32 v10, v18, v15
	v_pk_fma_f32 v[14:15], v[18:19], v[14:15], v[10:11] op_sel:[0,1,0] op_sel_hi:[1,0,0]
	v_sub_f32_e32 v10, v1, v5
	v_pk_fma_f32 v[30:31], v[18:19], v[8:9], v[28:29] op_sel:[0,0,1] op_sel_hi:[1,1,0] neg_lo:[0,0,1] neg_hi:[0,0,1]
	v_pk_fma_f32 v[8:9], v[18:19], v[8:9], v[28:29] op_sel:[0,0,1] op_sel_hi:[0,1,0]
	v_mov_b32_e32 v21, v11
	v_mov_b32_e32 v31, v9
	v_pk_mul_f32 v[10:11], v[10:11], v[20:21] op_sel_hi:[0,1]
	v_pk_mul_f32 v[20:21], v[18:19], v[12:13] op_sel:[1,0]
	v_pk_mul_f32 v[8:9], v[26:27], v[30:31] op_sel_hi:[0,1]
	v_pk_fma_f32 v[26:27], v[18:19], v[12:13], v[20:21] op_sel:[0,0,1] op_sel_hi:[1,1,0] neg_lo:[0,0,1] neg_hi:[0,0,1]
	v_pk_fma_f32 v[12:13], v[18:19], v[12:13], v[20:21] op_sel:[0,0,1] op_sel_hi:[0,1,0]
	v_sub_f32_e32 v14, v3, v7
	v_mov_b32_e32 v27, v13
	v_mov_b32_e32 v23, v15
	v_pk_mul_f32 v[12:13], v[24:25], v[26:27] op_sel_hi:[0,1]
	v_pk_mul_f32 v[14:15], v[14:15], v[22:23] op_sel_hi:[0,1]
.LBB0_681:
	s_andn2_b64 vcc, exec, s[36:37]
	s_cbranch_vccnz .LBB0_683
	s_waitcnt vmcnt(6)
	v_pk_add_f32 v[2:3], v[2:3], v[6:7]
	v_pk_add_f32 v[0:1], v[0:1], v[4:5]
	v_mov_b32_e32 v9, 0
	v_mov_b32_e32 v8, v0
	v_mov_b32_e32 v10, v1
	v_mov_b32_e32 v11, v9
	v_mov_b32_e32 v12, v2
	v_mov_b32_e32 v13, v9
	v_mov_b32_e32 v14, v3
	v_mov_b32_e32 v15, v9
.LBB0_683:
	s_waitcnt vmcnt(7)
	v_ashrrev_i32_e32 v0, 4, v16
	v_lshlrev_b32_e32 v0, 3, v0
	v_and_b32_e32 v0, 0xffffffe0, v0
	v_lshlrev_b32_e32 v1, 3, v16
	v_add3_u32 v0, 0, v0, v1
	ds_write_b128 v0, v[8:11]
	ds_write_b128 v0, v[12:15] offset:16
	v_mov_b32_e32 v0, v140
	s_and_b64 vcc, exec, s[12:13]
	v_lshlrev_b32_e32 v8, 2, v0
	v_add_u32_e32 v16, 0x2800, v8
	v_ashrrev_i32_e32 v17, 31, v16
	v_lshlrev_b64 v[0:1], 2, v[16:17]
	v_lshl_add_u64 v[2:3], s[28:29], 0, v[0:1]
	s_waitcnt vmcnt(6)
	v_lshl_add_u64 v[4:5], s[30:31], 0, v[0:1]
	s_waitcnt vmcnt(4)
	v_mov_b32_e32 v0, v104
	v_mov_b32_e32 v1, v105
	v_mov_b32_e32 v2, v106
	v_mov_b32_e32 v3, v107
	v_mov_b32_e32 v4, v108
	v_mov_b32_e32 v5, v109
	v_mov_b32_e32 v6, v110
	v_mov_b32_e32 v7, v111
	s_mov_b64 s[36:37], -1
	s_cbranch_vccnz .LBB0_685
	v_ashrrev_i32_e32 v9, 7, v16
	v_and_b32_e32 v8, 0x7c, v8
	v_lshl_add_u32 v9, v9, 3, 0
	v_lshl_add_u32 v8, v8, 3, 0
	v_add_u32_e32 v9, 0x26000, v9
	v_add_u32_e32 v12, 0x26400, v8
	ds_read_b64 v[18:19], v9
	ds_read_b128 v[8:11], v12
	ds_read_b128 v[12:15], v12 offset:16
	s_waitcnt vmcnt(4)
	v_sub_f32_e32 v26, v0, v4
	v_sub_f32_e32 v24, v2, v6
	s_mov_b64 s[36:37], 0
	s_waitcnt lgkmcnt(1)
	v_mul_f32_e32 v20, v19, v11
	v_mul_f32_e32 v22, v18, v11
	v_pk_fma_f32 v[20:21], v[18:19], v[10:11], v[20:21] op_sel_hi:[1,1,0] neg_lo:[0,0,1] neg_hi:[0,0,1]
	v_pk_fma_f32 v[10:11], v[18:19], v[10:11], v[22:23] op_sel:[0,1,0] op_sel_hi:[1,0,0]
	v_pk_mul_f32 v[28:29], v[18:19], v[8:9] op_sel:[1,0]
	s_waitcnt lgkmcnt(0)
	v_mul_f32_e32 v10, v19, v15
	v_pk_fma_f32 v[22:23], v[18:19], v[14:15], v[10:11] op_sel_hi:[1,1,0] neg_lo:[0,0,1] neg_hi:[0,0,1]
	v_mul_f32_e32 v10, v18, v15
	v_pk_fma_f32 v[14:15], v[18:19], v[14:15], v[10:11] op_sel:[0,1,0] op_sel_hi:[1,0,0]
	v_sub_f32_e32 v10, v1, v5
	v_pk_fma_f32 v[30:31], v[18:19], v[8:9], v[28:29] op_sel:[0,0,1] op_sel_hi:[1,1,0] neg_lo:[0,0,1] neg_hi:[0,0,1]
	v_pk_fma_f32 v[8:9], v[18:19], v[8:9], v[28:29] op_sel:[0,0,1] op_sel_hi:[0,1,0]
	v_mov_b32_e32 v21, v11
	v_mov_b32_e32 v31, v9
	v_pk_mul_f32 v[10:11], v[10:11], v[20:21] op_sel_hi:[0,1]
	v_pk_mul_f32 v[20:21], v[18:19], v[12:13] op_sel:[1,0]
	v_pk_mul_f32 v[8:9], v[26:27], v[30:31] op_sel_hi:[0,1]
	v_pk_fma_f32 v[26:27], v[18:19], v[12:13], v[20:21] op_sel:[0,0,1] op_sel_hi:[1,1,0] neg_lo:[0,0,1] neg_hi:[0,0,1]
	v_pk_fma_f32 v[12:13], v[18:19], v[12:13], v[20:21] op_sel:[0,0,1] op_sel_hi:[0,1,0]
	v_sub_f32_e32 v14, v3, v7
	v_mov_b32_e32 v27, v13
	v_mov_b32_e32 v23, v15
	v_pk_mul_f32 v[12:13], v[24:25], v[26:27] op_sel_hi:[0,1]
	v_pk_mul_f32 v[14:15], v[14:15], v[22:23] op_sel_hi:[0,1]
; #define GAS __attribute__((address_space(1)))
; #define LAS __attribute__((address_space(3)))
; __device__ __forceinline__ f32x2 cmul(f32x2 a, f32x2 b) { return (f32x2){a.x * b.x - a.y * b.y, a.x * b.y + a.y * b.x}; }
; #define LT() ({ int lt_ = tid; asm volatile("" : "+v"(lt_)); lt_; })
; __device__ __forceinline__ void tw4(const LAS f32x2* TH, const LAS f32x2* TL, int n0, f32x2 (&w)[4]) {
;     const f32x2 th = TH[n0 >> 7]; const LAS f32x4* tl = (const LAS f32x4*)(TL + (n0 & 127)); const f32x4 a = tl[0], b = tl[1];
;     w[0] = cmul(th, (f32x2){a.x, a.y}); w[1] = cmul(th, (f32x2){a.z, a.w}); w[2] = cmul(th, (f32x2){b.x, b.y}); w[3] = cmul(th, (f32x2){b.z, b.w});
; }
; __device__ __forceinline__ void hyena_latent(Frame& F, int l, int ch, LAS f32x2* X, const LAS f32x2* TH, const LAS f32x2* TL, GAS f32x2* KS, const LAS float* CT  , bool wr = true) {
;     ...
;             for (int i = 0; i < 8; ++i) { const int g = LT() + NTHR * i, n0 = 4 * g; const f32x4 f = *(const GAS f32x4*)(hf + n0), bk = *(const GAS f32x4*)(hbr + n0);
;                 LAS f32x4* XP = (LAS f32x4*)(X + phys(n0));
;                 if (par == 0) { XP[0] = (f32x4){f.x + bk.x, 0.f, f.y + bk.y, 0.f}; XP[1] = (f32x4){f.z + bk.z, 0.f, f.w + bk.w, 0.f}; }
;                 else { f32x2 w[4]; tw4(TH, TL, n0, w); const f32x4 d = f - bk;
;                     XP[0] = (f32x4){w[0].x * d.x, w[0].y * d.x, w[1].x * d.y, w[1].y * d.y}; XP[1] = (f32x4){w[2].x * d.z, w[2].y * d.z, w[3].x * d.w, w[3].y * d.w}; } }
.LBB0_685:
	s_andn2_b64 vcc, exec, s[36:37]
	s_cbranch_vccnz .LBB0_687
	s_waitcnt vmcnt(4)
	v_pk_add_f32 v[2:3], v[2:3], v[6:7]
	v_pk_add_f32 v[0:1], v[0:1], v[4:5]
	v_mov_b32_e32 v9, 0
	v_mov_b32_e32 v8, v0
	v_mov_b32_e32 v10, v1
	v_mov_b32_e32 v11, v9
	v_mov_b32_e32 v12, v2
	v_mov_b32_e32 v13, v9
	v_mov_b32_e32 v14, v3
	v_mov_b32_e32 v15, v9
.LBB0_687:
	s_waitcnt vmcnt(5)
	v_ashrrev_i32_e32 v0, 4, v16
	v_lshlrev_b32_e32 v0, 3, v0
	v_and_b32_e32 v0, 0xffffffe0, v0
	v_lshlrev_b32_e32 v1, 3, v16
	v_add3_u32 v0, 0, v0, v1
	ds_write_b128 v0, v[8:11]
	ds_write_b128 v0, v[12:15] offset:16
	v_mov_b32_e32 v0, v140
	s_and_b64 vcc, exec, s[12:13]
	v_lshlrev_b32_e32 v8, 2, v0
	v_add_u32_e32 v16, 0x3000, v8
	v_ashrrev_i32_e32 v17, 31, v16
	v_lshlrev_b64 v[0:1], 2, v[16:17]
	v_lshl_add_u64 v[2:3], s[28:29], 0, v[0:1]
	s_waitcnt vmcnt(4)
	v_lshl_add_u64 v[4:5], s[30:31], 0, v[0:1]
	s_waitcnt vmcnt(2)
	v_mov_b32_e32 v0, v112
	v_mov_b32_e32 v1, v113
	v_mov_b32_e32 v2, v114
	v_mov_b32_e32 v3, v115
	v_mov_b32_e32 v4, v116
	v_mov_b32_e32 v5, v117
	v_mov_b32_e32 v6, v118
	v_mov_b32_e32 v7, v119
	s_mov_b64 s[36:37], -1
	s_cbranch_vccnz .LBB0_689
	v_ashrrev_i32_e32 v9, 7, v16
	v_and_b32_e32 v8, 0x7c, v8
	v_lshl_add_u32 v9, v9, 3, 0
	v_lshl_add_u32 v8, v8, 3, 0
	v_add_u32_e32 v9, 0x26000, v9
	v_add_u32_e32 v12, 0x26400, v8
	ds_read_b64 v[18:19], v9
	ds_read_b128 v[8:11], v12
	ds_read_b128 v[12:15], v12 offset:16
	s_waitcnt vmcnt(2)
	v_sub_f32_e32 v26, v0, v4
	v_sub_f32_e32 v24, v2, v6
	s_mov_b64 s[36:37], 0
	s_waitcnt lgkmcnt(1)
	v_mul_f32_e32 v20, v19, v11
	v_mul_f32_e32 v22, v18, v11
	v_pk_fma_f32 v[20:21], v[18:19], v[10:11], v[20:21] op_sel_hi:[1,1,0] neg_lo:[0,0,1] neg_hi:[0,0,1]
	v_pk_fma_f32 v[10:11], v[18:19], v[10:11], v[22:23] op_sel:[0,1,0] op_sel_hi:[1,0,0]
	v_pk_mul_f32 v[28:29], v[18:19], v[8:9] op_sel:[1,0]
	s_waitcnt lgkmcnt(0)
	v_mul_f32_e32 v10, v19, v15
	v_pk_fma_f32 v[22:23], v[18:19], v[14:15], v[10:11] op_sel_hi:[1,1,0] neg_lo:[0,0,1] neg_hi:[0,0,1]
	v_mul_f32_e32 v10, v18, v15
	v_pk_fma_f32 v[14:15], v[18:19], v[14:15], v[10:11] op_sel:[0,1,0] op_sel_hi:[1,0,0]
	v_sub_f32_e32 v10, v1, v5
	v_pk_fma_f32 v[30:31], v[18:19], v[8:9], v[28:29] op_sel:[0,0,1] op_sel_hi:[1,1,0] neg_lo:[0,0,1] neg_hi:[0,0,1]
	v_pk_fma_f32 v[8:9], v[18:19], v[8:9], v[28:29] op_sel:[0,0,1] op_sel_hi:[0,1,0]
	v_mov_b32_e32 v21, v11
	v_mov_b32_e32 v31, v9
	v_pk_mul_f32 v[10:11], v[10:11], v[20:21] op_sel_hi:[0,1]
	v_pk_mul_f32 v[20:21], v[18:19], v[12:13] op_sel:[1,0]
	v_pk_mul_f32 v[8:9], v[26:27], v[30:31] op_sel_hi:[0,1]
	v_pk_fma_f32 v[26:27], v[18:19], v[12:13], v[20:21] op_sel:[0,0,1] op_sel_hi:[1,1,0] neg_lo:[0,0,1] neg_hi:[0,0,1]
	v_pk_fma_f32 v[12:13], v[18:19], v[12:13], v[20:21] op_sel:[0,0,1] op_sel_hi:[0,1,0]
	v_sub_f32_e32 v14, v3, v7
	v_mov_b32_e32 v27, v13
	v_mov_b32_e32 v23, v15
	v_pk_mul_f32 v[12:13], v[24:25], v[26:27] op_sel_hi:[0,1]
	v_pk_mul_f32 v[14:15], v[14:15], v[22:23] op_sel_hi:[0,1]
.LBB0_689:
	s_andn2_b64 vcc, exec, s[36:37]
	s_cbranch_vccnz .LBB0_691
	s_waitcnt vmcnt(2)
	v_pk_add_f32 v[2:3], v[2:3], v[6:7]
	v_pk_add_f32 v[0:1], v[0:1], v[4:5]
	v_mov_b32_e32 v9, 0
	v_mov_b32_e32 v8, v0
	v_mov_b32_e32 v10, v1
	v_mov_b32_e32 v11, v9
	v_mov_b32_e32 v12, v2
	v_mov_b32_e32 v13, v9
	v_mov_b32_e32 v14, v3
	v_mov_b32_e32 v15, v9
.LBB0_691:
	s_waitcnt vmcnt(3)
	v_ashrrev_i32_e32 v0, 4, v16
	v_lshlrev_b32_e32 v0, 3, v0
	v_and_b32_e32 v0, 0xffffffe0, v0
	v_lshlrev_b32_e32 v1, 3, v16
	v_add3_u32 v0, 0, v0, v1
	ds_write_b128 v0, v[8:11]
	ds_write_b128 v0, v[12:15] offset:16
	v_mov_b32_e32 v0, v140
	s_and_b64 vcc, exec, s[12:13]
	v_lshlrev_b32_e32 v8, 2, v0
	v_add_u32_e32 v16, 0x3800, v8
	v_ashrrev_i32_e32 v17, 31, v16
	v_lshlrev_b64 v[0:1], 2, v[16:17]
	v_lshl_add_u64 v[2:3], s[28:29], 0, v[0:1]
	s_waitcnt vmcnt(2)
	v_lshl_add_u64 v[4:5], s[30:31], 0, v[0:1]
	s_waitcnt vmcnt(0)
	v_mov_b32_e32 v0, v120
	v_mov_b32_e32 v1, v121
	v_mov_b32_e32 v2, v122
	v_mov_b32_e32 v3, v123
	v_mov_b32_e32 v4, v124
	v_mov_b32_e32 v5, v125
	v_mov_b32_e32 v6, v126
	v_mov_b32_e32 v7, v127
	s_mov_b64 s[36:37], -1
	s_cbranch_vccnz .LBB0_693
	v_ashrrev_i32_e32 v9, 7, v16
	v_and_b32_e32 v8, 0x7c, v8
	v_lshl_add_u32 v9, v9, 3, 0
	v_lshl_add_u32 v8, v8, 3, 0
	v_add_u32_e32 v9, 0x26000, v9
	v_add_u32_e32 v12, 0x26400, v8
	ds_read_b64 v[18:19], v9
	ds_read_b128 v[8:11], v12
	ds_read_b128 v[12:15], v12 offset:16
	s_waitcnt vmcnt(0)
	v_sub_f32_e32 v26, v0, v4
	v_sub_f32_e32 v24, v2, v6
	s_mov_b64 s[36:37], 0
	s_waitcnt lgkmcnt(1)
	v_mul_f32_e32 v20, v19, v11
	v_mul_f32_e32 v22, v18, v11
	v_pk_fma_f32 v[20:21], v[18:19], v[10:11], v[20:21] op_sel_hi:[1,1,0] neg_lo:[0,0,1] neg_hi:[0,0,1]
	v_pk_fma_f32 v[10:11], v[18:19], v[10:11], v[22:23] op_sel:[0,1,0] op_sel_hi:[1,0,0]
	v_pk_mul_f32 v[28:29], v[18:19], v[8:9] op_sel:[1,0]
	s_waitcnt lgkmcnt(0)
	v_mul_f32_e32 v10, v19, v15
	v_pk_fma_f32 v[22:23], v[18:19], v[14:15], v[10:11] op_sel_hi:[1,1,0] neg_lo:[0,0,1] neg_hi:[0,0,1]
	v_mul_f32_e32 v10, v18, v15
	v_pk_fma_f32 v[14:15], v[18:19], v[14:15], v[10:11] op_sel:[0,1,0] op_sel_hi:[1,0,0]
	v_sub_f32_e32 v10, v1, v5
	v_pk_fma_f32 v[30:31], v[18:19], v[8:9], v[28:29] op_sel:[0,0,1] op_sel_hi:[1,1,0] neg_lo:[0,0,1] neg_hi:[0,0,1]
	v_pk_fma_f32 v[8:9], v[18:19], v[8:9], v[28:29] op_sel:[0,0,1] op_sel_hi:[0,1,0]
	v_mov_b32_e32 v21, v11
	v_mov_b32_e32 v31, v9
	v_pk_mul_f32 v[10:11], v[10:11], v[20:21] op_sel_hi:[0,1]
	v_pk_mul_f32 v[20:21], v[18:19], v[12:13] op_sel:[1,0]
	v_pk_mul_f32 v[8:9], v[26:27], v[30:31] op_sel_hi:[0,1]
	v_pk_fma_f32 v[26:27], v[18:19], v[12:13], v[20:21] op_sel:[0,0,1] op_sel_hi:[1,1,0] neg_lo:[0,0,1] neg_hi:[0,0,1]
	v_pk_fma_f32 v[12:13], v[18:19], v[12:13], v[20:21] op_sel:[0,0,1] op_sel_hi:[0,1,0]
	v_sub_f32_e32 v14, v3, v7
	v_mov_b32_e32 v27, v13
	v_mov_b32_e32 v23, v15
	v_pk_mul_f32 v[12:13], v[24:25], v[26:27] op_sel_hi:[0,1]
	v_pk_mul_f32 v[14:15], v[14:15], v[22:23] op_sel_hi:[0,1]

; #define LAS __attribute__((address_space(3)))
; __device__ __forceinline__ f32x2 cmul(f32x2 a, f32x2 b) { return (f32x2){a.x * b.x - a.y * b.y, a.x * b.y + a.y * b.x}; }
; __device__ __forceinline__ f32x2 tw32k(const LAS f32x2* TH, const LAS f32x2* TL, int n) { return cmul(TH[n >> 7], TL[n & 127]); }
; template <bool INV> __device__ __forceinline__ void dft16(f32x2 (&x)[16]) {
; #pragma unroll
;     for (int b = 0; b < 4; ++b) r4<INV>(x[b], x[4 + b], x[8 + b], x[12 + b]);
;     const float sg = INV ? -1.f : 1.f;
;     const f32x2 W1 = {0.92387953251f, -0.38268343236f * sg}, W2 = {0.70710678118f, -0.70710678118f * sg}, W3 = {0.38268343236f, -0.92387953251f * sg},
;                 W4 = {0.f, -1.f * sg}, W6 = {-0.70710678118f, -0.70710678118f * sg}, W9 = {-0.92387953251f, 0.38268343236f * sg};
;     x[5] = cmul(x[5], W1); x[9] = cmul(x[9], W2); x[13] = cmul(x[13], W3);
;     x[6] = cmul(x[6], W2); x[10] = cmul(x[10], W4); x[14] = cmul(x[14], W6);
;     x[7] = cmul(x[7], W3); x[11] = cmul(x[11], W6); x[15] = cmul(x[15], W9);
; #pragma unroll
;     for (int c = 0; c < 4; ++c) r4<INV>(x[4 * c], x[4 * c + 1], x[4 * c + 2], x[4 * c + 3]);
; }
; template <bool INV> __device__ __forceinline__ void bfly16(f32x2 (&x)[16], const LAS f32x2* TH, const LAS f32x2* TL, int tw) {
;     f32x2 W = tw32k(TH, TL, tw); if (INV) W.y = -W.y;
;     if (INV) { f32x2 p = W;
; #pragma unroll
;         for (int q = 1; q < 16; ++q) { x[q] = cmul(x[q], p); if (q < 15) p = cmul(p, W); } }
;     dft16<INV>(x);
;     if (!INV) { f32x2 p = W;
; #pragma unroll
;         for (int r = 1; r < 16; ++r) { x[4 * (r & 3) + (r >> 2)] = cmul(x[4 * (r & 3) + (r >> 2)], p); if (r < 15) p = cmul(p, W); } }
; }
; template <bool INV> __device__ __forceinline__ void pass16(LAS f32x2* X, const LAS f32x2* TH, const LAS f32x2* TL, int base, int stride, int tw) {
;     f32x2 x[16];
; #pragma unroll
;     for (int q = 0; q < 16; ++q) x[q] = X[base + q * stride];
;     bfly16<INV>(x, TH, TL, tw);
; #pragma unroll
;     for (int c = 0; c < 4; ++c)
; #pragma unroll
;         for (int d = 0; d < 4; ++d) X[base + (c + 4 * d) * stride] = x[4 * c + d];
; }
.LBB0_696:
	v_add_u32_e32 v44, s0, v140
	v_lshrrev_b32_e32 v252, 6, v44
	v_and_b32_e32 v251, 63, v44
	v_lshlrev_b32_e32 v253, 5, v252
	v_lshlrev_b32_e32 v250, 3, v252
	v_lshlrev_b32_e32 v251, 4, v251
	v_lshl_add_u32 v253, v44, 3, v253
	v_add_u32_e32 v250, 0x26000, v250
	v_add_u32_e32 v251, 0x26400, v251
	ds_read_b64 v[0:1], v250
	ds_read_b64 v[2:3], v251
	ds_read2st64_b64 v[4:7], v253 offset0:0 offset1:17
	ds_read2st64_b64 v[8:11], v253 offset0:136 offset1:153
	ds_read2st64_b64 v[12:15], v253 offset0:34 offset1:51
	ds_read2st64_b64 v[16:19], v253 offset0:170 offset1:187
	ds_read2st64_b64 v[20:23], v253 offset0:68 offset1:85
	ds_read2st64_b64 v[24:27], v253 offset0:204 offset1:221
	ds_read2st64_b64 v[28:31], v253 offset0:102 offset1:119
	ds_read2st64_b64 v[32:35], v253 offset0:238 offset1:255
	s_cmp_eq_u32 s0, 0
	s_movk_i32 s0, 0x200
	s_mov_b64 s[36:37], 0
	s_waitcnt lgkmcnt(8)
	v_pk_mul_f32 v[36:37], v[0:1], v[2:3] op_sel:[0,1] op_sel_hi:[1,1]
	s_nop 0
	v_pk_fma_f32 v[2:3], v[0:1], v[2:3], v[36:37] op_sel:[0,0,1] op_sel_hi:[1,0,0] neg_lo:[0,0,1]
	s_nop 0
	v_pk_mul_f32 v[36:37], v[2:3], v[2:3] op_sel:[0,1] op_sel_hi:[1,1]
	s_nop 0
	v_pk_fma_f32 v[36:37], v[2:3], v[2:3], v[36:37] op_sel:[0,0,1] op_sel_hi:[1,0,0] neg_lo:[0,0,1]
	s_nop 0
	v_pk_mul_f32 v[0:1], v[36:37], v[2:3] op_sel:[0,1] op_sel_hi:[1,1]
	v_pk_mul_f32 v[38:39], v[36:37], v[36:37] op_sel:[0,1] op_sel_hi:[1,1]
	v_pk_fma_f32 v[0:1], v[36:37], v[2:3], v[0:1] op_sel:[0,0,1] op_sel_hi:[1,0,0] neg_lo:[0,0,1]
	v_pk_fma_f32 v[38:39], v[36:37], v[36:37], v[38:39] op_sel:[0,0,1] op_sel_hi:[1,0,0] neg_lo:[0,0,1]
	s_nop 0
	v_pk_mul_f32 v[40:41], v[38:39], v[2:3] op_sel:[0,1] op_sel_hi:[1,1]
	v_pk_mul_f32 v[42:43], v[38:39], v[36:37] op_sel:[0,1] op_sel_hi:[1,1]
	v_pk_mul_f32 v[46:47], v[38:39], v[0:1] op_sel:[0,1] op_sel_hi:[1,1]
	v_pk_fma_f32 v[40:41], v[38:39], v[2:3], v[40:41] op_sel:[0,0,1] op_sel_hi:[1,0,0] neg_lo:[0,0,1]
	v_pk_fma_f32 v[42:43], v[38:39], v[36:37], v[42:43] op_sel:[0,0,1] op_sel_hi:[1,0,0] neg_lo:[0,0,1]
	v_pk_fma_f32 v[46:47], v[38:39], v[0:1], v[46:47] op_sel:[0,0,1] op_sel_hi:[1,0,0] neg_lo:[0,0,1]
	v_pk_mul_f32 v[48:49], v[38:39], v[38:39] op_sel:[0,1] op_sel_hi:[1,1]
	s_nop 0
	v_pk_fma_f32 v[48:49], v[38:39], v[38:39], v[48:49] op_sel:[0,0,1] op_sel_hi:[1,0,0] neg_lo:[0,0,1]
	s_nop 0
	v_pk_mul_f32 v[50:51], v[48:49], v[2:3] op_sel:[0,1] op_sel_hi:[1,1]
	v_pk_mul_f32 v[52:53], v[48:49], v[36:37] op_sel:[0,1] op_sel_hi:[1,1]
	v_pk_mul_f32 v[54:55], v[48:49], v[0:1] op_sel:[0,1] op_sel_hi:[1,1]
	v_pk_fma_f32 v[50:51], v[48:49], v[2:3], v[50:51] op_sel:[0,0,1] op_sel_hi:[1,0,0] neg_lo:[0,0,1]
	v_pk_fma_f32 v[52:53], v[48:49], v[36:37], v[52:53] op_sel:[0,0,1] op_sel_hi:[1,0,0] neg_lo:[0,0,1]
	v_pk_fma_f32 v[54:55], v[48:49], v[0:1], v[54:55] op_sel:[0,0,1] op_sel_hi:[1,0,0] neg_lo:[0,0,1]
	v_pk_mul_f32 v[56:57], v[48:49], v[38:39] op_sel:[0,1] op_sel_hi:[1,1]
	v_pk_mul_f32 v[58:59], v[48:49], v[40:41] op_sel:[0,1] op_sel_hi:[1,1]
	v_pk_mul_f32 v[188:189], v[48:49], v[42:43] op_sel:[0,1] op_sel_hi:[1,1]
	v_pk_fma_f32 v[56:57], v[48:49], v[38:39], v[56:57] op_sel:[0,0,1] op_sel_hi:[1,0,0] neg_lo:[0,0,1]
	v_pk_fma_f32 v[58:59], v[48:49], v[40:41], v[58:59] op_sel:[0,0,1] op_sel_hi:[1,0,0] neg_lo:[0,0,1]
	v_pk_fma_f32 v[188:189], v[48:49], v[42:43], v[188:189] op_sel:[0,0,1] op_sel_hi:[1,0,0] neg_lo:[0,0,1]
	v_pk_mul_f32 v[190:191], v[48:49], v[46:47] op_sel:[0,1] op_sel_hi:[1,1]
	s_nop 0
	v_pk_fma_f32 v[190:191], v[48:49], v[46:47], v[190:191] op_sel:[0,0,1] op_sel_hi:[1,0,0] neg_lo:[0,0,1]
	s_waitcnt lgkmcnt(6)
	v_pk_add_f32 v[192:193], v[4:5], v[8:9]
	v_pk_add_f32 v[194:195], v[6:7], v[10:11]
	s_waitcnt lgkmcnt(4)
	v_pk_add_f32 v[196:197], v[12:13], v[16:17]
	v_pk_add_f32 v[198:199], v[14:15], v[18:19]
	v_pk_add_f32 v[4:5], v[4:5], v[8:9] neg_lo:[0,1] neg_hi:[0,1]
	v_pk_add_f32 v[10:11], v[6:7], v[10:11] neg_lo:[0,1] neg_hi:[0,1]
	v_pk_add_f32 v[16:17], v[12:13], v[16:17] neg_lo:[0,1] neg_hi:[0,1]
	v_pk_add_f32 v[18:19], v[14:15], v[18:19] neg_lo:[0,1] neg_hi:[0,1]
	s_waitcnt lgkmcnt(2)
	v_pk_add_f32 v[14:15], v[20:21], v[24:25]
	v_pk_add_f32 v[12:13], v[22:23], v[26:27]
	s_waitcnt lgkmcnt(0)
	v_pk_add_f32 v[6:7], v[28:29], v[32:33]
	v_pk_add_f32 v[8:9], v[30:31], v[34:35]
	v_pk_add_f32 v[24:25], v[20:21], v[24:25] neg_lo:[0,1] neg_hi:[0,1]
	v_pk_add_f32 v[22:23], v[22:23], v[26:27] neg_lo:[0,1] neg_hi:[0,1]
	v_pk_add_f32 v[32:33], v[28:29], v[32:33] neg_lo:[0,1] neg_hi:[0,1]
	v_pk_add_f32 v[34:35], v[30:31], v[34:35] neg_lo:[0,1] neg_hi:[0,1]
	v_pk_add_f32 v[30:31], v[192:193], v[14:15]
	v_pk_add_f32 v[28:29], v[194:195], v[12:13]
	v_pk_add_f32 v[26:27], v[196:197], v[6:7]
	v_pk_add_f32 v[20:21], v[198:199], v[8:9]
	v_pk_add_f32 v[192:193], v[192:193], v[14:15] neg_lo:[0,1] neg_hi:[0,1]
	v_pk_add_f32 v[194:195], v[194:195], v[12:13] neg_lo:[0,1] neg_hi:[0,1]
	v_pk_add_f32 v[6:7], v[196:197], v[6:7] neg_lo:[0,1] neg_hi:[0,1]
	v_pk_add_f32 v[8:9], v[198:199], v[8:9] neg_lo:[0,1] neg_hi:[0,1]
	v_pk_add_f32 v[198:199], v[4:5], v[24:25] op_sel:[0,1] op_sel_hi:[1,0] neg_hi:[0,1]
	v_pk_add_f32 v[196:197], v[10:11], v[22:23] op_sel:[0,1] op_sel_hi:[1,0] neg_hi:[0,1]
	v_pk_add_f32 v[12:13], v[16:17], v[32:33] op_sel:[0,1] op_sel_hi:[1,0] neg_hi:[0,1]
	v_pk_add_f32 v[14:15], v[18:19], v[34:35] op_sel:[0,1] op_sel_hi:[1,0] neg_hi:[0,1]
	v_pk_add_f32 v[24:25], v[4:5], v[24:25] op_sel:[0,1] op_sel_hi:[1,0] neg_lo:[0,1]
	v_pk_add_f32 v[22:23], v[10:11], v[22:23] op_sel:[0,1] op_sel_hi:[1,0] neg_lo:[0,1]
	v_pk_add_f32 v[32:33], v[16:17], v[32:33] op_sel:[0,1] op_sel_hi:[1,0] neg_lo:[0,1]
	v_pk_add_f32 v[34:35], v[18:19], v[34:35] op_sel:[0,1] op_sel_hi:[1,0] neg_lo:[0,1]
; #define LAS __attribute__((address_space(3)))
; __device__ __forceinline__ f32x2 cmul(f32x2 a, f32x2 b) { return (f32x2){a.x * b.x - a.y * b.y, a.x * b.y + a.y * b.x}; }
; __device__ __forceinline__ f32x2 tw32k(const LAS f32x2* TH, const LAS f32x2* TL, int n) { return cmul(TH[n >> 7], TL[n & 127]); }
; template <bool INV> __device__ __forceinline__ void dft16(f32x2 (&x)[16]) {
; #pragma unroll
;     for (int b = 0; b < 4; ++b) r4<INV>(x[b], x[4 + b], x[8 + b], x[12 + b]);
;     const float sg = INV ? -1.f : 1.f;
;     const f32x2 W1 = {0.92387953251f, -0.38268343236f * sg}, W2 = {0.70710678118f, -0.70710678118f * sg}, W3 = {0.38268343236f, -0.92387953251f * sg},
;                 W4 = {0.f, -1.f * sg}, W6 = {-0.70710678118f, -0.70710678118f * sg}, W9 = {-0.92387953251f, 0.38268343236f * sg};
;     x[5] = cmul(x[5], W1); x[9] = cmul(x[9], W2); x[13] = cmul(x[13], W3);
;     x[6] = cmul(x[6], W2); x[10] = cmul(x[10], W4); x[14] = cmul(x[14], W6);
;     x[7] = cmul(x[7], W3); x[11] = cmul(x[11], W6); x[15] = cmul(x[15], W9);
; #pragma unroll
;     for (int c = 0; c < 4; ++c) r4<INV>(x[4 * c], x[4 * c + 1], x[4 * c + 2], x[4 * c + 3]);
; }
; template <bool INV> __device__ __forceinline__ void bfly16(f32x2 (&x)[16], const LAS f32x2* TH, const LAS f32x2* TL, int tw) {
;     f32x2 W = tw32k(TH, TL, tw); if (INV) W.y = -W.y;
;     if (INV) { f32x2 p = W;
; #pragma unroll
;         for (int q = 1; q < 16; ++q) { x[q] = cmul(x[q], p); if (q < 15) p = cmul(p, W); } }
;     dft16<INV>(x);
;     if (!INV) { f32x2 p = W;
; #pragma unroll
;         for (int r = 1; r < 16; ++r) { x[4 * (r & 3) + (r >> 2)] = cmul(x[4 * (r & 3) + (r >> 2)], p); if (r < 15) p = cmul(p, W); } }
; }
; template <bool INV> __device__ __forceinline__ void pass16(LAS f32x2* X, const LAS f32x2* TH, const LAS f32x2* TL, int base, int stride, int tw) {
;     f32x2 x[16];
; #pragma unroll
;     for (int q = 0; q < 16; ++q) x[q] = X[base + q * stride];
;     bfly16<INV>(x, TH, TL, tw);
; #pragma unroll
;     for (int c = 0; c < 4; ++c)
; #pragma unroll
;         for (int d = 0; d < 4; ++d) X[base + (c + 4 * d) * stride] = x[4 * c + d];
; }
	v_pk_mul_f32 v[18:19], v[196:197], s[70:71] op_sel_hi:[1,0]
	v_pk_mul_f32 v[16:17], v[194:195], s[72:73] op_sel_hi:[1,0]
	v_pk_mul_f32 v[10:11], v[22:23], s[64:65] op_sel_hi:[1,0]
	v_pk_mul_f32 v[4:5], v[12:13], s[72:73] op_sel_hi:[1,0]
	v_pk_mul_f32 v[200:201], v[32:33], s[72:73] op_sel_hi:[1,0]
	v_pk_mul_f32 v[202:203], v[14:15], s[64:65] op_sel_hi:[1,0]
	v_pk_mul_f32 v[204:205], v[8:9], s[72:73] op_sel_hi:[1,0]
	v_pk_mul_f32 v[206:207], v[34:35], s[82:83] op_sel_hi:[1,0]
	v_pk_fma_f32 v[196:197], v[196:197], s[44:45], v[18:19] op_sel:[0,0,1] op_sel_hi:[1,0,0] neg_lo:[0,0,1]
	v_pk_fma_f32 v[16:17], v[194:195], s[76:77], v[16:17] op_sel:[0,0,1] op_sel_hi:[1,0,0] neg_lo:[0,0,1]
	v_pk_fma_f32 v[10:11], v[22:23], s[82:83], v[10:11] op_sel:[0,0,1] op_sel_hi:[1,0,0] neg_lo:[0,0,1]
	v_pk_fma_f32 v[12:13], v[12:13], s[76:77], v[4:5] op_sel:[0,0,1] op_sel_hi:[1,0,0] neg_lo:[0,0,1]
	v_pk_fma_f32 v[200:201], v[32:33], s[72:73], v[200:201] op_sel:[0,0,1] op_sel_hi:[1,0,0] neg_lo:[0,0,1]
	v_pk_fma_f32 v[14:15], v[14:15], s[82:83], v[202:203] op_sel:[0,0,1] op_sel_hi:[1,0,0] neg_lo:[0,0,1]
	v_pk_fma_f32 v[204:205], v[8:9], s[72:73], v[204:205] op_sel:[0,0,1] op_sel_hi:[1,0,0] neg_lo:[0,0,1]
	v_pk_fma_f32 v[34:35], v[34:35], s[64:65], v[206:207] op_sel:[0,0,1] op_sel_hi:[1,0,0] neg_lo:[0,0,1]
	v_pk_add_f32 v[206:207], v[30:31], v[26:27]
	v_pk_add_f32 v[8:9], v[198:199], v[12:13]
	v_pk_add_f32 v[202:203], v[192:193], v[6:7] op_sel:[0,1] op_sel_hi:[1,0] neg_hi:[0,1]
	v_pk_add_f32 v[32:33], v[24:25], v[200:201]
	v_pk_add_f32 v[30:31], v[30:31], v[26:27] neg_lo:[0,1] neg_hi:[0,1]
	v_pk_add_f32 v[198:199], v[198:199], v[12:13] neg_lo:[0,1] neg_hi:[0,1]
	v_pk_add_f32 v[192:193], v[192:193], v[6:7] op_sel:[0,1] op_sel_hi:[1,0] neg_lo:[0,1]
	v_pk_add_f32 v[24:25], v[24:25], v[200:201] neg_lo:[0,1] neg_hi:[0,1]
	v_pk_add_f32 v[200:201], v[28:29], v[20:21]
	v_pk_add_f32 v[6:7], v[196:197], v[14:15]
	v_pk_add_f32 v[12:13], v[16:17], v[204:205]
	v_pk_add_f32 v[26:27], v[10:11], v[34:35]
	v_pk_add_f32 v[20:21], v[28:29], v[20:21] neg_lo:[0,1] neg_hi:[0,1]
	v_pk_add_f32 v[196:197], v[196:197], v[14:15] neg_lo:[0,1] neg_hi:[0,1]
	v_pk_add_f32 v[204:205], v[16:17], v[204:205] neg_lo:[0,1] neg_hi:[0,1]
	v_pk_add_f32 v[10:11], v[10:11], v[34:35] neg_lo:[0,1] neg_hi:[0,1]
	v_pk_add_f32 v[34:35], v[206:207], v[200:201]
	v_pk_add_f32 v[16:17], v[8:9], v[6:7]
	v_pk_add_f32 v[14:15], v[202:203], v[12:13]
	v_pk_add_f32 v[28:29], v[32:33], v[26:27]
	v_pk_add_f32 v[206:207], v[206:207], v[200:201] neg_lo:[0,1] neg_hi:[0,1]
	v_pk_add_f32 v[8:9], v[8:9], v[6:7] neg_lo:[0,1] neg_hi:[0,1]
	v_pk_add_f32 v[202:203], v[202:203], v[12:13] neg_lo:[0,1] neg_hi:[0,1]
	v_pk_add_f32 v[32:33], v[32:33], v[26:27] neg_lo:[0,1] neg_hi:[0,1]
	v_pk_add_f32 v[26:27], v[30:31], v[20:21] op_sel:[0,1] op_sel_hi:[1,0] neg_hi:[0,1]
	v_pk_add_f32 v[12:13], v[198:199], v[196:197] op_sel:[0,1] op_sel_hi:[1,0] neg_hi:[0,1]
	v_pk_add_f32 v[6:7], v[192:193], v[204:205] op_sel:[0,1] op_sel_hi:[1,0] neg_hi:[0,1]
	v_pk_add_f32 v[200:201], v[24:25], v[10:11] op_sel:[0,1] op_sel_hi:[1,0] neg_hi:[0,1]
	v_pk_add_f32 v[30:31], v[30:31], v[20:21] op_sel:[0,1] op_sel_hi:[1,0] neg_lo:[0,1]
	v_pk_add_f32 v[198:199], v[198:199], v[196:197] op_sel:[0,1] op_sel_hi:[1,0] neg_lo:[0,1]
	v_pk_add_f32 v[192:193], v[192:193], v[204:205] op_sel:[0,1] op_sel_hi:[1,0] neg_lo:[0,1]
	v_pk_add_f32 v[10:11], v[24:25], v[10:11] op_sel:[0,1] op_sel_hi:[1,0] neg_lo:[0,1]
	v_pk_mul_f32 v[24:25], v[16:17], v[2:3] op_sel:[0,1] op_sel_hi:[1,1]
	v_pk_mul_f32 v[204:205], v[14:15], v[36:37] op_sel:[0,1] op_sel_hi:[1,1]
	v_pk_fma_f32 v[16:17], v[16:17], v[2:3], v[24:25] op_sel:[0,0,1] op_sel_hi:[1,0,0] neg_lo:[0,0,1]
	v_pk_mul_f32 v[24:25], v[28:29], v[0:1] op_sel:[0,1] op_sel_hi:[1,1]
	v_pk_fma_f32 v[14:15], v[14:15], v[36:37], v[204:205] op_sel:[0,0,1] op_sel_hi:[1,0,0] neg_lo:[0,0,1]
	v_pk_mul_f32 v[36:37], v[26:27], v[38:39] op_sel:[0,1] op_sel_hi:[1,1]
	v_pk_fma_f32 v[0:1], v[28:29], v[0:1], v[24:25] op_sel:[0,0,1] op_sel_hi:[1,0,0] neg_lo:[0,0,1]
	v_pk_mul_f32 v[28:29], v[12:13], v[40:41] op_sel:[0,1] op_sel_hi:[1,1]
	v_pk_fma_f32 v[36:37], v[26:27], v[38:39], v[36:37] op_sel:[0,0,1] op_sel_hi:[1,0,0] neg_lo:[0,0,1]
	v_pk_mul_f32 v[38:39], v[6:7], v[42:43] op_sel:[0,1] op_sel_hi:[1,1]
	v_pk_fma_f32 v[40:41], v[12:13], v[40:41], v[28:29] op_sel:[0,0,1] op_sel_hi:[1,0,0] neg_lo:[0,0,1]
	v_pk_mul_f32 v[28:29], v[200:201], v[46:47] op_sel:[0,1] op_sel_hi:[1,1]
	v_pk_fma_f32 v[42:43], v[6:7], v[42:43], v[38:39] op_sel:[0,0,1] op_sel_hi:[1,0,0] neg_lo:[0,0,1]
	v_pk_mul_f32 v[38:39], v[206:207], v[48:49] op_sel:[0,1] op_sel_hi:[1,1]
	v_pk_fma_f32 v[200:201], v[200:201], v[46:47], v[28:29] op_sel:[0,0,1] op_sel_hi:[1,0,0] neg_lo:[0,0,1]
	v_pk_mul_f32 v[46:47], v[8:9], v[50:51] op_sel:[0,1] op_sel_hi:[1,1]
	v_pk_fma_f32 v[48:49], v[206:207], v[48:49], v[38:39] op_sel:[0,0,1] op_sel_hi:[1,0,0] neg_lo:[0,0,1]
	v_pk_mul_f32 v[206:207], v[202:203], v[52:53] op_sel:[0,1] op_sel_hi:[1,1]
	v_pk_fma_f32 v[50:51], v[8:9], v[50:51], v[46:47] op_sel:[0,0,1] op_sel_hi:[1,0,0] neg_lo:[0,0,1]
	v_pk_mul_f32 v[46:47], v[32:33], v[54:55] op_sel:[0,1] op_sel_hi:[1,1]
	v_pk_fma_f32 v[52:53], v[202:203], v[52:53], v[206:207] op_sel:[0,0,1] op_sel_hi:[1,0,0] neg_lo:[0,0,1]
	v_pk_mul_f32 v[202:203], v[30:31], v[56:57] op_sel:[0,1] op_sel_hi:[1,1]
	v_pk_fma_f32 v[46:47], v[32:33], v[54:55], v[46:47] op_sel:[0,0,1] op_sel_hi:[1,0,0] neg_lo:[0,0,1]
	v_pk_mul_f32 v[54:55], v[198:199], v[58:59] op_sel:[0,1] op_sel_hi:[1,1]
	v_pk_fma_f32 v[56:57], v[30:31], v[56:57], v[202:203] op_sel:[0,0,1] op_sel_hi:[1,0,0] neg_lo:[0,0,1]
	v_pk_mul_f32 v[202:203], v[192:193], v[188:189] op_sel:[0,1] op_sel_hi:[1,1]
	v_pk_fma_f32 v[54:55], v[198:199], v[58:59], v[54:55] op_sel:[0,0,1] op_sel_hi:[1,0,0] neg_lo:[0,0,1]
	v_pk_mul_f32 v[58:59], v[10:11], v[190:191] op_sel:[0,1] op_sel_hi:[1,1]
	v_pk_fma_f32 v[188:189], v[192:193], v[188:189], v[202:203] op_sel:[0,0,1] op_sel_hi:[1,0,0] neg_lo:[0,0,1]
	v_pk_fma_f32 v[58:59], v[10:11], v[190:191], v[58:59] op_sel:[0,0,1] op_sel_hi:[1,0,0] neg_lo:[0,0,1]
	ds_write2st64_b64 v253, v[34:35], v[16:17] offset0:0 offset1:17
	ds_write2st64_b64 v253, v[14:15], v[0:1] offset0:34 offset1:51
	ds_write2st64_b64 v253, v[36:37], v[40:41] offset0:68 offset1:85
	ds_write2st64_b64 v253, v[42:43], v[200:201] offset0:102 offset1:119
	ds_write2st64_b64 v253, v[48:49], v[50:51] offset0:136 offset1:153
	ds_write2st64_b64 v253, v[52:53], v[46:47] offset0:170 offset1:187
	ds_write2st64_b64 v253, v[56:57], v[54:55] offset0:204 offset1:221
	ds_write2st64_b64 v253, v[188:189], v[58:59] offset0:238 offset1:255
	s_cbranch_scc1 .LBB0_696
; #define LAS __attribute__((address_space(3)))
; __device__ __forceinline__ f32x2 cmul(f32x2 a, f32x2 b) { return (f32x2){a.x * b.x - a.y * b.y, a.x * b.y + a.y * b.x}; }
; template <bool INV> __device__ __forceinline__ void dft16(f32x2 (&x)[16]) {
; #pragma unroll
;     for (int b = 0; b < 4; ++b) r4<INV>(x[b], x[4 + b], x[8 + b], x[12 + b]);
;     const float sg = INV ? -1.f : 1.f;
;     const f32x2 W1 = {0.92387953251f, -0.38268343236f * sg}, W2 = {0.70710678118f, -0.70710678118f * sg}, W3 = {0.38268343236f, -0.92387953251f * sg},
;                 W4 = {0.f, -1.f * sg}, W6 = {-0.70710678118f, -0.70710678118f * sg}, W9 = {-0.92387953251f, 0.38268343236f * sg};
;     x[5] = cmul(x[5], W1); x[9] = cmul(x[9], W2); x[13] = cmul(x[13], W3);
;     x[6] = cmul(x[6], W2); x[10] = cmul(x[10], W4); x[14] = cmul(x[14], W6);
;     x[7] = cmul(x[7], W3); x[11] = cmul(x[11], W6); x[15] = cmul(x[15], W9);
; #pragma unroll
;     for (int c = 0; c < 4; ++c) r4<INV>(x[4 * c], x[4 * c + 1], x[4 * c + 2], x[4 * c + 3]);
; }
; template <bool INV> __device__ __forceinline__ void bfly16_tab(f32x2 (&x)[16], const LAS f32x2* T, int tstride, int j) {
;     if (INV) {
; #pragma unroll
;         for (int q = 1; q < 16; ++q) { f32x2 p = T[q * tstride + j]; p.y = -p.y; x[q] = cmul(x[q], p); } }
;     dft16<INV>(x);
;     if (!INV) {
; #pragma unroll
;         for (int r = 1; r < 16; ++r) { const f32x2 p = T[r * tstride + j]; x[4 * (r & 3) + (r >> 2)] = cmul(x[4 * (r & 3) + (r >> 2)], p); } }
; }
; template <bool INV> __device__ __forceinline__ void pass16_s64(LAS f32x2* X, const LAS f32x2* TH, int base, int j) {
;     f32x2 x[16];
; #pragma unroll
;     for (int q = 0; q < 16; ++q) x[q] = X[base + q * 68];
;     bfly16_tab<INV>(x, TH - 2048, 64, j);
; #pragma unroll
;     for (int c = 0; c < 4; ++c)
; #pragma unroll
;         for (int d = 0; d < 4; ++d) X[base + (c + 4 * d) * 68] = x[4 * c + d];
; }
	s_waitcnt lgkmcnt(0)
	s_barrier
	s_mov_b32 s0, 0
	s_mov_b64 s[36:37], -1
	ds_read2st64_b64 v[232:235], v139 offset0:1 offset1:2
	ds_read2st64_b64 v[208:211], v139 offset0:3 offset1:4
	ds_read2st64_b64 v[204:207], v139 offset0:5 offset1:6
	ds_read2st64_b64 v[200:203], v139 offset0:7 offset1:8
	ds_read2st64_b64 v[196:199], v139 offset0:9 offset1:10
	ds_read2st64_b64 v[192:195], v139 offset0:11 offset1:12
	ds_read2st64_b64 v[188:191], v139 offset0:13 offset1:14
	ds_read_b64 v[222:223], v139 offset:7680
.LBB0_698:
	v_add_u32_e32 v252, s0, v140
	v_lshrrev_b32_e32 v253, 6, v252
	v_mad_u32_u24 v250, v253, s77, v142
	v_add_u32_e32 v251, 0x800, v250
	v_add_u32_e32 v248, 0x1000, v250
	v_add_u32_e32 v249, 0x1800, v250
	ds_read2_b64 v[0:3], v250 offset0:0 offset1:68
	ds_read2_b64 v[4:7], v248 offset0:32 offset1:100
	ds_read2_b64 v[8:11], v250 offset0:136 offset1:204
	ds_read2_b64 v[12:15], v248 offset0:168 offset1:236
	ds_read2_b64 v[16:19], v251 offset0:16 offset1:84
	ds_read2_b64 v[20:23], v249 offset0:48 offset1:116
	ds_read2_b64 v[24:27], v251 offset0:152 offset1:220
	ds_read2_b64 v[28:31], v249 offset0:184 offset1:252
	s_cmp_eq_u32 s0, 0
	s_movk_i32 s0, 0x200
	s_mov_b64 s[36:37], 0
	s_waitcnt lgkmcnt(6)
	v_pk_add_f32 v[32:33], v[0:1], v[4:5]
	v_pk_add_f32 v[34:35], v[2:3], v[6:7]
	s_waitcnt lgkmcnt(4)
	v_pk_add_f32 v[36:37], v[8:9], v[12:13]
	v_pk_add_f32 v[38:39], v[10:11], v[14:15]
	v_pk_add_f32 v[0:1], v[0:1], v[4:5] neg_lo:[0,1] neg_hi:[0,1]
	v_pk_add_f32 v[2:3], v[2:3], v[6:7] neg_lo:[0,1] neg_hi:[0,1]
	v_pk_add_f32 v[12:13], v[8:9], v[12:13] neg_lo:[0,1] neg_hi:[0,1]
	v_pk_add_f32 v[14:15], v[10:11], v[14:15] neg_lo:[0,1] neg_hi:[0,1]
	s_waitcnt lgkmcnt(2)
	v_pk_add_f32 v[10:11], v[16:17], v[20:21]
	v_pk_add_f32 v[8:9], v[18:19], v[22:23]
	s_waitcnt lgkmcnt(0)
	v_pk_add_f32 v[6:7], v[24:25], v[28:29]
	v_pk_add_f32 v[4:5], v[26:27], v[30:31]
	v_pk_add_f32 v[20:21], v[16:17], v[20:21] neg_lo:[0,1] neg_hi:[0,1]
	v_pk_add_f32 v[18:19], v[18:19], v[22:23] neg_lo:[0,1] neg_hi:[0,1]
	v_pk_add_f32 v[24:25], v[24:25], v[28:29] neg_lo:[0,1] neg_hi:[0,1]
	v_pk_add_f32 v[30:31], v[26:27], v[30:31] neg_lo:[0,1] neg_hi:[0,1]
	v_pk_add_f32 v[26:27], v[32:33], v[10:11]
	v_pk_add_f32 v[28:29], v[34:35], v[8:9]
	v_pk_add_f32 v[22:23], v[36:37], v[6:7]
	v_pk_add_f32 v[16:17], v[38:39], v[4:5]
	v_pk_add_f32 v[10:11], v[32:33], v[10:11] neg_lo:[0,1] neg_hi:[0,1]
	v_pk_add_f32 v[8:9], v[34:35], v[8:9] neg_lo:[0,1] neg_hi:[0,1]
	v_pk_add_f32 v[36:37], v[36:37], v[6:7] neg_lo:[0,1] neg_hi:[0,1]
	v_pk_add_f32 v[38:39], v[38:39], v[4:5] neg_lo:[0,1] neg_hi:[0,1]
	v_pk_add_f32 v[4:5], v[0:1], v[20:21] op_sel:[0,1] op_sel_hi:[1,0] neg_hi:[0,1]
	v_pk_add_f32 v[6:7], v[2:3], v[18:19] op_sel:[0,1] op_sel_hi:[1,0] neg_hi:[0,1]
	v_pk_add_f32 v[34:35], v[12:13], v[24:25] op_sel:[0,1] op_sel_hi:[1,0] neg_hi:[0,1]
	v_pk_add_f32 v[32:33], v[14:15], v[30:31] op_sel:[0,1] op_sel_hi:[1,0] neg_hi:[0,1]
	v_pk_add_f32 v[20:21], v[0:1], v[20:21] op_sel:[0,1] op_sel_hi:[1,0] neg_lo:[0,1]
	v_pk_add_f32 v[18:19], v[2:3], v[18:19] op_sel:[0,1] op_sel_hi:[1,0] neg_lo:[0,1]
	v_pk_add_f32 v[12:13], v[12:13], v[24:25] op_sel:[0,1] op_sel_hi:[1,0] neg_lo:[0,1]
	v_pk_add_f32 v[14:15], v[14:15], v[30:31] op_sel:[0,1] op_sel_hi:[1,0] neg_lo:[0,1]
	v_pk_mul_f32 v[30:31], v[6:7], s[70:71] op_sel_hi:[1,0]
	v_pk_mul_f32 v[24:25], v[8:9], s[72:73] op_sel_hi:[1,0]
	v_pk_mul_f32 v[2:3], v[18:19], s[64:65] op_sel_hi:[1,0]
	v_pk_mul_f32 v[0:1], v[34:35], s[72:73] op_sel_hi:[1,0]
	v_pk_mul_f32 v[40:41], v[12:13], s[72:73] op_sel_hi:[1,0]
	v_pk_mul_f32 v[42:43], v[32:33], s[64:65] op_sel_hi:[1,0]
	v_pk_mul_f32 v[44:45], v[38:39], s[72:73] op_sel_hi:[1,0]
	v_pk_mul_f32 v[218:219], v[14:15], s[82:83] op_sel_hi:[1,0]
	v_pk_fma_f32 v[30:31], v[6:7], s[44:45], v[30:31] op_sel:[0,0,1] op_sel_hi:[1,0,0] neg_lo:[0,0,1]
	v_pk_fma_f32 v[8:9], v[8:9], s[76:77], v[24:25] op_sel:[0,0,1] op_sel_hi:[1,0,0] neg_lo:[0,0,1]
	v_pk_fma_f32 v[2:3], v[18:19], s[82:83], v[2:3] op_sel:[0,0,1] op_sel_hi:[1,0,0] neg_lo:[0,0,1]
	v_pk_fma_f32 v[0:1], v[34:35], s[76:77], v[0:1] op_sel:[0,0,1] op_sel_hi:[1,0,0] neg_lo:[0,0,1]
	v_pk_fma_f32 v[40:41], v[12:13], s[72:73], v[40:41] op_sel:[0,0,1] op_sel_hi:[1,0,0] neg_lo:[0,0,1]
	v_pk_fma_f32 v[32:33], v[32:33], s[82:83], v[42:43] op_sel:[0,0,1] op_sel_hi:[1,0,0] neg_lo:[0,0,1]
	v_pk_fma_f32 v[44:45], v[38:39], s[72:73], v[44:45] op_sel:[0,0,1] op_sel_hi:[1,0,0] neg_lo:[0,0,1]
	v_pk_fma_f32 v[218:219], v[14:15], s[64:65], v[218:219] op_sel:[0,0,1] op_sel_hi:[1,0,0] neg_lo:[0,0,1]
	v_pk_add_f32 v[14:15], v[26:27], v[22:23]
	v_pk_add_f32 v[38:39], v[4:5], v[0:1]
	v_pk_add_f32 v[42:43], v[10:11], v[36:37] op_sel:[0,1] op_sel_hi:[1,0] neg_hi:[0,1]
	v_pk_add_f32 v[12:13], v[20:21], v[40:41]
	v_pk_add_f32 v[22:23], v[26:27], v[22:23] neg_lo:[0,1] neg_hi:[0,1]
	v_pk_add_f32 v[4:5], v[4:5], v[0:1] neg_lo:[0,1] neg_hi:[0,1]
	v_pk_add_f32 v[36:37], v[10:11], v[36:37] op_sel:[0,1] op_sel_hi:[1,0] neg_lo:[0,1]
	v_pk_add_f32 v[20:21], v[20:21], v[40:41] neg_lo:[0,1] neg_hi:[0,1]
	v_pk_add_f32 v[40:41], v[28:29], v[16:17]
	v_pk_add_f32 v[10:11], v[30:31], v[32:33]
	v_pk_add_f32 v[0:1], v[8:9], v[44:45]
	v_pk_add_f32 v[26:27], v[2:3], v[218:219]
	v_pk_add_f32 v[16:17], v[28:29], v[16:17] neg_lo:[0,1] neg_hi:[0,1]
	v_pk_add_f32 v[30:31], v[30:31], v[32:33] neg_lo:[0,1] neg_hi:[0,1]
	v_pk_add_f32 v[44:45], v[8:9], v[44:45] neg_lo:[0,1] neg_hi:[0,1]
	v_pk_add_f32 v[2:3], v[2:3], v[218:219] neg_lo:[0,1] neg_hi:[0,1]
	v_pk_add_f32 v[218:219], v[14:15], v[40:41]
	v_pk_add_f32 v[8:9], v[38:39], v[10:11]
	v_pk_add_f32 v[32:33], v[42:43], v[0:1]
	v_pk_add_f32 v[28:29], v[12:13], v[26:27]
; #define LAS __attribute__((address_space(3)))
; __device__ __forceinline__ f32x2 cmul(f32x2 a, f32x2 b) { return (f32x2){a.x * b.x - a.y * b.y, a.x * b.y + a.y * b.x}; }
; template <bool INV> __device__ __forceinline__ void bfly16_tab(f32x2 (&x)[16], const LAS f32x2* T, int tstride, int j) {
;     if (INV) {
; #pragma unroll
;         for (int q = 1; q < 16; ++q) { f32x2 p = T[q * tstride + j]; p.y = -p.y; x[q] = cmul(x[q], p); } }
;     dft16<INV>(x);
;     if (!INV) {
; #pragma unroll
;         for (int r = 1; r < 16; ++r) { const f32x2 p = T[r * tstride + j]; x[4 * (r & 3) + (r >> 2)] = cmul(x[4 * (r & 3) + (r >> 2)], p); } }
; }
; template <bool INV> __device__ __forceinline__ void pass16_s64(LAS f32x2* X, const LAS f32x2* TH, int base, int j) {
;     f32x2 x[16];
; #pragma unroll
;     for (int q = 0; q < 16; ++q) x[q] = X[base + q * 68];
;     bfly16_tab<INV>(x, TH - 2048, 64, j);
; #pragma unroll
;     for (int c = 0; c < 4; ++c)
; #pragma unroll
;         for (int d = 0; d < 4; ++d) X[base + (c + 4 * d) * 68] = x[4 * c + d];
; }
; template <bool INV> __device__ __forceinline__ void pass16_s4(LAS f32x2* X, const LAS f32x2* TH, const LAS f32x2* TL, int tid) {
; #pragma unroll 1
;     for (int s = 0; s < 2; ++s) {
;         const int b = tid + NTHR * s, blk = b >> 2, jj = b & 3;
;         LAS f32x2* P = X + blk * 68 + jj;
;         f32x2 x[16];
; #pragma unroll
;         for (int q = 0; q < 16; ++q) x[q] = P[4 * q];
;         bfly16_tab<INV>(x, TH - 1024, 4, jj);
; #pragma unroll
;         for (int c = 0; c < 4; ++c)
; #pragma unroll
;             for (int d = 0; d < 4; ++d) P[4 * (c + 4 * d)] = x[4 * c + d];
;     }
; }
	v_pk_add_f32 v[14:15], v[14:15], v[40:41] neg_lo:[0,1] neg_hi:[0,1]
	v_pk_add_f32 v[10:11], v[38:39], v[10:11] neg_lo:[0,1] neg_hi:[0,1]
	v_pk_add_f32 v[0:1], v[42:43], v[0:1] neg_lo:[0,1] neg_hi:[0,1]
	v_pk_add_f32 v[26:27], v[12:13], v[26:27] neg_lo:[0,1] neg_hi:[0,1]
	v_pk_add_f32 v[12:13], v[22:23], v[16:17] op_sel:[0,1] op_sel_hi:[1,0] neg_hi:[0,1]
	v_pk_add_f32 v[42:43], v[4:5], v[30:31] op_sel:[0,1] op_sel_hi:[1,0] neg_hi:[0,1]
	v_pk_add_f32 v[38:39], v[36:37], v[44:45] op_sel:[0,1] op_sel_hi:[1,0] neg_hi:[0,1]
	v_pk_add_f32 v[40:41], v[20:21], v[2:3] op_sel:[0,1] op_sel_hi:[1,0] neg_hi:[0,1]
	v_pk_add_f32 v[22:23], v[22:23], v[16:17] op_sel:[0,1] op_sel_hi:[1,0] neg_lo:[0,1]
	v_pk_add_f32 v[30:31], v[4:5], v[30:31] op_sel:[0,1] op_sel_hi:[1,0] neg_lo:[0,1]
	v_pk_add_f32 v[44:45], v[36:37], v[44:45] op_sel:[0,1] op_sel_hi:[1,0] neg_lo:[0,1]
	v_pk_add_f32 v[2:3], v[20:21], v[2:3] op_sel:[0,1] op_sel_hi:[1,0] neg_lo:[0,1]
	v_pk_mul_f32 v[20:21], v[8:9], v[232:233] op_sel:[0,1] op_sel_hi:[1,1]
	v_pk_mul_f32 v[36:37], v[32:33], v[234:235] op_sel:[0,1] op_sel_hi:[1,1]
	v_pk_fma_f32 v[20:21], v[8:9], v[232:233], v[20:21] op_sel:[0,0,1] op_sel_hi:[1,0,0] neg_lo:[0,0,1]
	v_pk_mul_f32 v[8:9], v[28:29], v[208:209] op_sel:[0,1] op_sel_hi:[1,1]
	v_pk_fma_f32 v[36:37], v[32:33], v[234:235], v[36:37] op_sel:[0,0,1] op_sel_hi:[1,0,0] neg_lo:[0,0,1]
	v_pk_mul_f32 v[32:33], v[12:13], v[210:211] op_sel:[0,1] op_sel_hi:[1,1]
	v_pk_fma_f32 v[8:9], v[28:29], v[208:209], v[8:9] op_sel:[0,0,1] op_sel_hi:[1,0,0] neg_lo:[0,0,1]
	v_pk_mul_f32 v[28:29], v[42:43], v[204:205] op_sel:[0,1] op_sel_hi:[1,1]
	v_pk_fma_f32 v[32:33], v[12:13], v[210:211], v[32:33] op_sel:[0,0,1] op_sel_hi:[1,0,0] neg_lo:[0,0,1]
	v_pk_mul_f32 v[12:13], v[38:39], v[206:207] op_sel:[0,1] op_sel_hi:[1,1]
	v_pk_fma_f32 v[42:43], v[42:43], v[204:205], v[28:29] op_sel:[0,0,1] op_sel_hi:[1,0,0] neg_lo:[0,0,1]
	v_pk_mul_f32 v[28:29], v[40:41], v[200:201] op_sel:[0,1] op_sel_hi:[1,1]
	v_pk_fma_f32 v[38:39], v[38:39], v[206:207], v[12:13] op_sel:[0,0,1] op_sel_hi:[1,0,0] neg_lo:[0,0,1]
	v_pk_mul_f32 v[12:13], v[14:15], v[202:203] op_sel:[0,1] op_sel_hi:[1,1]
	v_pk_fma_f32 v[40:41], v[40:41], v[200:201], v[28:29] op_sel:[0,0,1] op_sel_hi:[1,0,0] neg_lo:[0,0,1]
	v_pk_mul_f32 v[28:29], v[10:11], v[196:197] op_sel:[0,1] op_sel_hi:[1,1]
	v_pk_fma_f32 v[14:15], v[14:15], v[202:203], v[12:13] op_sel:[0,0,1] op_sel_hi:[1,0,0] neg_lo:[0,0,1]
	v_pk_mul_f32 v[12:13], v[0:1], v[198:199] op_sel:[0,1] op_sel_hi:[1,1]
	v_pk_fma_f32 v[28:29], v[10:11], v[196:197], v[28:29] op_sel:[0,0,1] op_sel_hi:[1,0,0] neg_lo:[0,0,1]
	v_pk_mul_f32 v[10:11], v[26:27], v[192:193] op_sel:[0,1] op_sel_hi:[1,1]
	v_pk_fma_f32 v[12:13], v[0:1], v[198:199], v[12:13] op_sel:[0,0,1] op_sel_hi:[1,0,0] neg_lo:[0,0,1]
	v_pk_mul_f32 v[0:1], v[22:23], v[194:195] op_sel:[0,1] op_sel_hi:[1,1]
	v_pk_fma_f32 v[10:11], v[26:27], v[192:193], v[10:11] op_sel:[0,0,1] op_sel_hi:[1,0,0] neg_lo:[0,0,1]
	v_pk_mul_f32 v[26:27], v[30:31], v[188:189] op_sel:[0,1] op_sel_hi:[1,1]
	v_pk_fma_f32 v[22:23], v[22:23], v[194:195], v[0:1] op_sel:[0,0,1] op_sel_hi:[1,0,0] neg_lo:[0,0,1]
	v_pk_mul_f32 v[0:1], v[44:45], v[190:191] op_sel:[0,1] op_sel_hi:[1,1]
	v_pk_fma_f32 v[30:31], v[30:31], v[188:189], v[26:27] op_sel:[0,0,1] op_sel_hi:[1,0,0] neg_lo:[0,0,1]
	v_pk_mul_f32 v[26:27], v[2:3], v[222:223] op_sel:[0,1] op_sel_hi:[1,1]
	v_pk_fma_f32 v[0:1], v[44:45], v[190:191], v[0:1] op_sel:[0,0,1] op_sel_hi:[1,0,0] neg_lo:[0,0,1]
	v_pk_fma_f32 v[2:3], v[2:3], v[222:223], v[26:27] op_sel:[0,0,1] op_sel_hi:[1,0,0] neg_lo:[0,0,1]
	ds_write2_b64 v250, v[218:219], v[20:21] offset0:0 offset1:68
	ds_write2_b64 v250, v[36:37], v[8:9] offset0:136 offset1:204
	ds_write2_b64 v251, v[32:33], v[42:43] offset0:16 offset1:84
	ds_write2_b64 v251, v[38:39], v[40:41] offset0:152 offset1:220
	ds_write2_b64 v248, v[14:15], v[28:29] offset0:32 offset1:100
	ds_write2_b64 v248, v[12:13], v[10:11] offset0:168 offset1:236
	ds_write2_b64 v249, v[22:23], v[30:31] offset0:48 offset1:116
	ds_write2_b64 v249, v[0:1], v[2:3] offset0:184 offset1:252
	s_cbranch_scc1 .LBB0_698
	s_waitcnt lgkmcnt(0)
	s_barrier
	s_mov_b32 s0, 0
	s_mov_b64 s[36:37], -1
	ds_read2_b64 v[232:235], v141 offset0:4 offset1:8
	ds_read2_b64 v[208:211], v141 offset0:12 offset1:16
	ds_read2_b64 v[204:207], v141 offset0:20 offset1:24
	ds_read2_b64 v[200:203], v141 offset0:28 offset1:32
	ds_read2_b64 v[196:199], v141 offset0:36 offset1:40
	ds_read2_b64 v[192:195], v141 offset0:44 offset1:48
	ds_read2_b64 v[188:191], v141 offset0:52 offset1:56
	ds_read_b64 v[248:249], v141 offset:480
; #define LAS __attribute__((address_space(3)))
; __device__ __forceinline__ f32x2 cmul(f32x2 a, f32x2 b) { return (f32x2){a.x * b.x - a.y * b.y, a.x * b.y + a.y * b.x}; }
; template <bool INV> __device__ __forceinline__ void bfly16_tab(f32x2 (&x)[16], const LAS f32x2* T, int tstride, int j) {
;     if (INV) {
; #pragma unroll
;         for (int q = 1; q < 16; ++q) { f32x2 p = T[q * tstride + j]; p.y = -p.y; x[q] = cmul(x[q], p); } }
;     dft16<INV>(x);
;     if (!INV) {
; #pragma unroll
;         for (int r = 1; r < 16; ++r) { const f32x2 p = T[r * tstride + j]; x[4 * (r & 3) + (r >> 2)] = cmul(x[4 * (r & 3) + (r >> 2)], p); } }
; }
; template <bool INV> __device__ __forceinline__ void pass16_s4(LAS f32x2* X, const LAS f32x2* TH, const LAS f32x2* TL, int tid) {
; #pragma unroll 1
;     for (int s = 0; s < 2; ++s) {
;         const int b = tid + NTHR * s, blk = b >> 2, jj = b & 3;
;         LAS f32x2* P = X + blk * 68 + jj;
;         f32x2 x[16];
; #pragma unroll
;         for (int q = 0; q < 16; ++q) x[q] = P[4 * q];
;         bfly16_tab<INV>(x, TH - 1024, 4, jj);
; #pragma unroll
;         for (int c = 0; c < 4; ++c)
; #pragma unroll
;             for (int d = 0; d < 4; ++d) P[4 * (c + 4 * d)] = x[4 * c + d];
;     }
; }
.LBB0_700:
	v_add_u32_e32 v252, s0, v140
	v_lshrrev_b32_e32 v253, 2, v252
	v_mad_u32_u24 v250, v253, s43, v144
	ds_read2_b64 v[0:3], v250 offset0:0 offset1:4
	ds_read2_b64 v[4:7], v250 offset0:32 offset1:36
	ds_read2_b64 v[8:11], v250 offset0:8 offset1:12
	ds_read2_b64 v[12:15], v250 offset0:40 offset1:44
	ds_read2_b64 v[16:19], v250 offset0:16 offset1:20
	ds_read2_b64 v[20:23], v250 offset0:48 offset1:52
	ds_read2_b64 v[24:27], v250 offset0:24 offset1:28
	ds_read2_b64 v[28:31], v250 offset0:56 offset1:60
	s_cmp_eq_u32 s0, 0
	s_movk_i32 s0, 0x200
	s_mov_b64 s[36:37], 0
	s_waitcnt lgkmcnt(6)
	v_pk_add_f32 v[32:33], v[0:1], v[4:5]
	v_pk_add_f32 v[34:35], v[2:3], v[6:7]
	s_waitcnt lgkmcnt(4)
	v_pk_add_f32 v[36:37], v[8:9], v[12:13]
	v_pk_add_f32 v[38:39], v[10:11], v[14:15]
	v_pk_add_f32 v[0:1], v[0:1], v[4:5] neg_lo:[0,1] neg_hi:[0,1]
	v_pk_add_f32 v[2:3], v[2:3], v[6:7] neg_lo:[0,1] neg_hi:[0,1]
	v_pk_add_f32 v[12:13], v[8:9], v[12:13] neg_lo:[0,1] neg_hi:[0,1]
	v_pk_add_f32 v[14:15], v[10:11], v[14:15] neg_lo:[0,1] neg_hi:[0,1]
	s_waitcnt lgkmcnt(2)
	v_pk_add_f32 v[10:11], v[16:17], v[20:21]
	v_pk_add_f32 v[8:9], v[18:19], v[22:23]
	s_waitcnt lgkmcnt(0)
	v_pk_add_f32 v[6:7], v[24:25], v[28:29]
	v_pk_add_f32 v[4:5], v[26:27], v[30:31]
	v_pk_add_f32 v[20:21], v[16:17], v[20:21] neg_lo:[0,1] neg_hi:[0,1]
	v_pk_add_f32 v[18:19], v[18:19], v[22:23] neg_lo:[0,1] neg_hi:[0,1]
	v_pk_add_f32 v[24:25], v[24:25], v[28:29] neg_lo:[0,1] neg_hi:[0,1]
	v_pk_add_f32 v[30:31], v[26:27], v[30:31] neg_lo:[0,1] neg_hi:[0,1]
	v_pk_add_f32 v[26:27], v[32:33], v[10:11]
	v_pk_add_f32 v[28:29], v[34:35], v[8:9]
	v_pk_add_f32 v[22:23], v[36:37], v[6:7]
	v_pk_add_f32 v[16:17], v[38:39], v[4:5]
	v_pk_add_f32 v[32:33], v[32:33], v[10:11] neg_lo:[0,1] neg_hi:[0,1]
	v_pk_add_f32 v[34:35], v[34:35], v[8:9] neg_lo:[0,1] neg_hi:[0,1]
	v_pk_add_f32 v[36:37], v[36:37], v[6:7] neg_lo:[0,1] neg_hi:[0,1]
	v_pk_add_f32 v[38:39], v[38:39], v[4:5] neg_lo:[0,1] neg_hi:[0,1]
	v_pk_add_f32 v[4:5], v[0:1], v[20:21] op_sel:[0,1] op_sel_hi:[1,0] neg_hi:[0,1]
	v_pk_add_f32 v[6:7], v[2:3], v[18:19] op_sel:[0,1] op_sel_hi:[1,0] neg_hi:[0,1]
	v_pk_add_f32 v[8:9], v[12:13], v[24:25] op_sel:[0,1] op_sel_hi:[1,0] neg_hi:[0,1]
	v_pk_add_f32 v[10:11], v[14:15], v[30:31] op_sel:[0,1] op_sel_hi:[1,0] neg_hi:[0,1]
	v_pk_add_f32 v[20:21], v[0:1], v[20:21] op_sel:[0,1] op_sel_hi:[1,0] neg_lo:[0,1]
	v_pk_add_f32 v[18:19], v[2:3], v[18:19] op_sel:[0,1] op_sel_hi:[1,0] neg_lo:[0,1]
	v_pk_add_f32 v[24:25], v[12:13], v[24:25] op_sel:[0,1] op_sel_hi:[1,0] neg_lo:[0,1]
	v_pk_add_f32 v[30:31], v[14:15], v[30:31] op_sel:[0,1] op_sel_hi:[1,0] neg_lo:[0,1]
	v_pk_mul_f32 v[14:15], v[6:7], s[70:71] op_sel_hi:[1,0]
	v_pk_mul_f32 v[12:13], v[34:35], s[72:73] op_sel_hi:[1,0]
	v_pk_mul_f32 v[2:3], v[18:19], s[64:65] op_sel_hi:[1,0]
	v_pk_mul_f32 v[0:1], v[8:9], s[72:73] op_sel_hi:[1,0]
	v_pk_mul_f32 v[40:41], v[24:25], s[72:73] op_sel_hi:[1,0]
	v_pk_mul_f32 v[42:43], v[10:11], s[64:65] op_sel_hi:[1,0]
	v_pk_mul_f32 v[218:219], v[38:39], s[72:73] op_sel_hi:[1,0]
	v_pk_mul_f32 v[222:223], v[30:31], s[82:83] op_sel_hi:[1,0]
	v_pk_fma_f32 v[14:15], v[6:7], s[44:45], v[14:15] op_sel:[0,0,1] op_sel_hi:[1,0,0] neg_lo:[0,0,1]
	v_pk_fma_f32 v[34:35], v[34:35], s[76:77], v[12:13] op_sel:[0,0,1] op_sel_hi:[1,0,0] neg_lo:[0,0,1]
	v_pk_fma_f32 v[18:19], v[18:19], s[82:83], v[2:3] op_sel:[0,0,1] op_sel_hi:[1,0,0] neg_lo:[0,0,1]
	v_pk_fma_f32 v[0:1], v[8:9], s[76:77], v[0:1] op_sel:[0,0,1] op_sel_hi:[1,0,0] neg_lo:[0,0,1]
	v_pk_fma_f32 v[24:25], v[24:25], s[72:73], v[40:41] op_sel:[0,0,1] op_sel_hi:[1,0,0] neg_lo:[0,0,1]
	v_pk_fma_f32 v[10:11], v[10:11], s[82:83], v[42:43] op_sel:[0,0,1] op_sel_hi:[1,0,0] neg_lo:[0,0,1]
	v_pk_fma_f32 v[218:219], v[38:39], s[72:73], v[218:219] op_sel:[0,0,1] op_sel_hi:[1,0,0] neg_lo:[0,0,1]
	v_pk_fma_f32 v[30:31], v[30:31], s[64:65], v[222:223] op_sel:[0,0,1] op_sel_hi:[1,0,0] neg_lo:[0,0,1]
	v_pk_add_f32 v[222:223], v[26:27], v[22:23]
	v_pk_add_f32 v[38:39], v[4:5], v[0:1]
	v_pk_add_f32 v[42:43], v[32:33], v[36:37] op_sel:[0,1] op_sel_hi:[1,0] neg_hi:[0,1]
	v_pk_add_f32 v[40:41], v[20:21], v[24:25]
	v_pk_add_f32 v[26:27], v[26:27], v[22:23] neg_lo:[0,1] neg_hi:[0,1]
	v_pk_add_f32 v[0:1], v[4:5], v[0:1] neg_lo:[0,1] neg_hi:[0,1]
	v_pk_add_f32 v[32:33], v[32:33], v[36:37] op_sel:[0,1] op_sel_hi:[1,0] neg_lo:[0,1]
	v_pk_add_f32 v[20:21], v[20:21], v[24:25] neg_lo:[0,1] neg_hi:[0,1]
	v_pk_add_f32 v[24:25], v[28:29], v[16:17]
	v_pk_add_f32 v[36:37], v[14:15], v[10:11]
	v_pk_add_f32 v[4:5], v[34:35], v[218:219]
	v_pk_add_f32 v[22:23], v[18:19], v[30:31]
	v_pk_add_f32 v[28:29], v[28:29], v[16:17] neg_lo:[0,1] neg_hi:[0,1]
	v_pk_add_f32 v[10:11], v[14:15], v[10:11] neg_lo:[0,1] neg_hi:[0,1]
	v_pk_add_f32 v[34:35], v[34:35], v[218:219] neg_lo:[0,1] neg_hi:[0,1]
	v_pk_add_f32 v[18:19], v[18:19], v[30:31] neg_lo:[0,1] neg_hi:[0,1]
	v_pk_add_f32 v[30:31], v[222:223], v[24:25]
	v_pk_add_f32 v[218:219], v[38:39], v[36:37]
	v_pk_add_f32 v[14:15], v[42:43], v[4:5]
	v_pk_add_f32 v[16:17], v[40:41], v[22:23]
	v_pk_add_f32 v[222:223], v[222:223], v[24:25] neg_lo:[0,1] neg_hi:[0,1]
	v_pk_add_f32 v[36:37], v[38:39], v[36:37] neg_lo:[0,1] neg_hi:[0,1]
	v_pk_add_f32 v[4:5], v[42:43], v[4:5] neg_lo:[0,1] neg_hi:[0,1]
	v_pk_add_f32 v[40:41], v[40:41], v[22:23] neg_lo:[0,1] neg_hi:[0,1]
	v_pk_add_f32 v[22:23], v[26:27], v[28:29] op_sel:[0,1] op_sel_hi:[1,0] neg_hi:[0,1]
	v_pk_add_f32 v[42:43], v[0:1], v[10:11] op_sel:[0,1] op_sel_hi:[1,0] neg_hi:[0,1]
	v_pk_add_f32 v[38:39], v[32:33], v[34:35] op_sel:[0,1] op_sel_hi:[1,0] neg_hi:[0,1]
	v_pk_add_f32 v[24:25], v[20:21], v[18:19] op_sel:[0,1] op_sel_hi:[1,0] neg_hi:[0,1]
; #define LAS __attribute__((address_space(3)))
; __device__ __forceinline__ float lane_read(float v, int src_lane) { return __builtin_bit_cast(float, __builtin_amdgcn_ds_bpermute(src_lane << 2, __builtin_bit_cast(int, v))); }
; #define LDS_BARRIER() do { asm volatile("s_waitcnt lgkmcnt(0)" ::: "memory"); __builtin_amdgcn_s_barrier(); asm volatile("" ::: "memory"); } while (0)
; #define LT() ({ int lt_ = tid; asm volatile("" : "+v"(lt_)); lt_; })
; template <bool INV> __device__ __forceinline__ void pass16_s4(LAS f32x2* X, const LAS f32x2* TH, const LAS f32x2* TL, int tid) {
; #pragma unroll 1
;     for (int s = 0; s < 2; ++s) {
;         const int b = tid + NTHR * s, blk = b >> 2, jj = b & 3;
;         LAS f32x2* P = X + blk * 68 + jj;
;         f32x2 x[16];
; #pragma unroll
;         for (int q = 0; q < 16; ++q) x[q] = P[4 * q];
;         bfly16_tab<INV>(x, TH - 1024, 4, jj);
; #pragma unroll
;         for (int c = 0; c < 4; ++c)
; #pragma unroll
;             for (int d = 0; d < 4; ++d) P[4 * (c + 4 * d)] = x[4 * c + d];
;     }
; }
; __device__ __forceinline__ void hyena_latent(Frame& F, int l, int ch, LAS f32x2* X, const LAS f32x2* TH, const LAS f32x2* TL, GAS f32x2* KS, const LAS float* CT  , bool wr = true) {
;     ...
; #pragma unroll
;             for (int i = 0; i < 8; ++i) { const int b = LT() + NTHR * i; const LAS f32x4* P = (const LAS f32x4*)(X + 4 * b + ((b >> 4) << 2)); const f32x4 u = P[0], v = P[1];
;                 f32x2 x0 = {u.x, u.y}, x1 = {u.z, u.w}, x2 = {v.x, v.y}, x3 = {v.z, v.w}; r4<false>(x0, x1, x2, x3);
;                 kreg[2 * i] = (f32x4){x0.x, x0.y, x1.x, x1.y}; kreg[2 * i + 1] = (f32x4){x2.x, x2.y, x3.x, x3.y}; }
;             LDS_BARRIER();
;             HP_END(31) }
;             { HP_BEGIN(32)
; #pragma unroll
;             for (int i = 0; i < 8; ++i) { const int g = LT() + NTHR * i, n0 = 4 * g;
;                 f32x4 z0 = pc0[i], z1 = pc1[i];
;                 if (o == 0) { const f32x4 c = pc0[i], d = pc1[i]; const int ln = F.lane;
;                     float l0 = lane_read(c.w, ln - 1), r0 = lane_read(c.x, ln + 1), l1 = lane_read(d.w, ln - 1), r1 = lane_read(d.x, ln + 1);
;                     if (ln == 0) { l0 = n0 > 0 ? hv[n0 - 1] : 0.f; l1 = n0 > 0 ? hv[SEQ + n0 - 1] : 0.f; }
;                     if (ln == 63) { r0 = n0 + 4 < SEQ ? hv[n0 + 4] : 0.f; r1 = n0 + 4 < SEQ ? hv[SEQ + n0 + 4] : 0.f; }
	v_pk_add_f32 v[28:29], v[26:27], v[28:29] op_sel:[0,1] op_sel_hi:[1,0] neg_lo:[0,1]
	v_pk_add_f32 v[0:1], v[0:1], v[10:11] op_sel:[0,1] op_sel_hi:[1,0] neg_lo:[0,1]
	v_pk_add_f32 v[34:35], v[32:33], v[34:35] op_sel:[0,1] op_sel_hi:[1,0] neg_lo:[0,1]
	v_pk_add_f32 v[18:19], v[20:21], v[18:19] op_sel:[0,1] op_sel_hi:[1,0] neg_lo:[0,1]
	v_pk_mul_f32 v[20:21], v[218:219], v[232:233] op_sel:[0,1] op_sel_hi:[1,1]
	v_pk_mul_f32 v[32:33], v[14:15], v[234:235] op_sel:[0,1] op_sel_hi:[1,1]
	v_pk_fma_f32 v[218:219], v[218:219], v[232:233], v[20:21] op_sel:[0,0,1] op_sel_hi:[1,0,0] neg_lo:[0,0,1]
	v_pk_mul_f32 v[20:21], v[16:17], v[208:209] op_sel:[0,1] op_sel_hi:[1,1]
	v_pk_fma_f32 v[32:33], v[14:15], v[234:235], v[32:33] op_sel:[0,0,1] op_sel_hi:[1,0,0] neg_lo:[0,0,1]
	v_pk_mul_f32 v[14:15], v[22:23], v[210:211] op_sel:[0,1] op_sel_hi:[1,1]
	v_pk_fma_f32 v[20:21], v[16:17], v[208:209], v[20:21] op_sel:[0,0,1] op_sel_hi:[1,0,0] neg_lo:[0,0,1]
	v_pk_mul_f32 v[16:17], v[42:43], v[204:205] op_sel:[0,1] op_sel_hi:[1,1]
	v_pk_fma_f32 v[14:15], v[22:23], v[210:211], v[14:15] op_sel:[0,0,1] op_sel_hi:[1,0,0] neg_lo:[0,0,1]
	v_pk_mul_f32 v[22:23], v[38:39], v[206:207] op_sel:[0,1] op_sel_hi:[1,1]
	v_pk_fma_f32 v[42:43], v[42:43], v[204:205], v[16:17] op_sel:[0,0,1] op_sel_hi:[1,0,0] neg_lo:[0,0,1]
	v_pk_mul_f32 v[16:17], v[24:25], v[200:201] op_sel:[0,1] op_sel_hi:[1,1]
	v_pk_fma_f32 v[22:23], v[38:39], v[206:207], v[22:23] op_sel:[0,0,1] op_sel_hi:[1,0,0] neg_lo:[0,0,1]
	v_pk_mul_f32 v[38:39], v[222:223], v[202:203] op_sel:[0,1] op_sel_hi:[1,1]
	v_pk_fma_f32 v[16:17], v[24:25], v[200:201], v[16:17] op_sel:[0,0,1] op_sel_hi:[1,0,0] neg_lo:[0,0,1]
	v_pk_mul_f32 v[24:25], v[36:37], v[196:197] op_sel:[0,1] op_sel_hi:[1,1]
	v_pk_fma_f32 v[38:39], v[222:223], v[202:203], v[38:39] op_sel:[0,0,1] op_sel_hi:[1,0,0] neg_lo:[0,0,1]
	v_pk_mul_f32 v[222:223], v[4:5], v[198:199] op_sel:[0,1] op_sel_hi:[1,1]
	v_pk_fma_f32 v[24:25], v[36:37], v[196:197], v[24:25] op_sel:[0,0,1] op_sel_hi:[1,0,0] neg_lo:[0,0,1]
	v_pk_mul_f32 v[36:37], v[40:41], v[192:193] op_sel:[0,1] op_sel_hi:[1,1]
	v_pk_fma_f32 v[4:5], v[4:5], v[198:199], v[222:223] op_sel:[0,0,1] op_sel_hi:[1,0,0] neg_lo:[0,0,1]
	v_pk_mul_f32 v[222:223], v[28:29], v[194:195] op_sel:[0,1] op_sel_hi:[1,1]
	v_pk_fma_f32 v[40:41], v[40:41], v[192:193], v[36:37] op_sel:[0,0,1] op_sel_hi:[1,0,0] neg_lo:[0,0,1]
	v_pk_mul_f32 v[36:37], v[0:1], v[188:189] op_sel:[0,1] op_sel_hi:[1,1]
	v_pk_fma_f32 v[28:29], v[28:29], v[194:195], v[222:223] op_sel:[0,0,1] op_sel_hi:[1,0,0] neg_lo:[0,0,1]
	v_pk_mul_f32 v[222:223], v[34:35], v[190:191] op_sel:[0,1] op_sel_hi:[1,1]
	v_pk_fma_f32 v[0:1], v[0:1], v[188:189], v[36:37] op_sel:[0,0,1] op_sel_hi:[1,0,0] neg_lo:[0,0,1]
	v_pk_mul_f32 v[36:37], v[18:19], v[248:249] op_sel:[0,1] op_sel_hi:[1,1]
	v_pk_fma_f32 v[34:35], v[34:35], v[190:191], v[222:223] op_sel:[0,0,1] op_sel_hi:[1,0,0] neg_lo:[0,0,1]
	v_pk_fma_f32 v[18:19], v[18:19], v[248:249], v[36:37] op_sel:[0,0,1] op_sel_hi:[1,0,0] neg_lo:[0,0,1]
	ds_write2_b64 v250, v[30:31], v[218:219] offset0:0 offset1:4
	ds_write2_b64 v250, v[32:33], v[20:21] offset0:8 offset1:12
	ds_write2_b64 v250, v[14:15], v[42:43] offset0:16 offset1:20
	ds_write2_b64 v250, v[22:23], v[16:17] offset0:24 offset1:28
	ds_write2_b64 v250, v[38:39], v[24:25] offset0:32 offset1:36
	ds_write2_b64 v250, v[4:5], v[40:41] offset0:40 offset1:44
	ds_write2_b64 v250, v[28:29], v[0:1] offset0:48 offset1:52
	ds_write2_b64 v250, v[34:35], v[18:19] offset0:56 offset1:60
	s_cbranch_scc1 .LBB0_700
	v_mov_b32_e32 v0, v140
	s_waitcnt lgkmcnt(0)
	s_barrier
	v_mov_b32_e32 v128, v140
	v_lshlrev_b32_e32 v1, 5, v0
	v_lshlrev_b32_e32 v0, 1, v0
	v_and_b32_e32 v0, 0xffffffe0, v0
	v_add3_u32 v0, 0, v1, v0
	ds_read_b128 v[56:59], v0
	ds_read_b128 v[60:63], v0 offset:16
	v_mov_b32_e32 v0, v140
	s_and_b64 vcc, s[26:27], exec
	v_add_u32_e32 v0, 0x200, v0
	v_lshlrev_b32_e32 v1, 5, v0
	v_lshlrev_b32_e32 v0, 1, v0
	v_and_b32_e32 v0, 0xffffffe0, v0
	v_add3_u32 v0, 0, v1, v0
	ds_read_b128 v[48:51], v0
	ds_read_b128 v[52:55], v0 offset:16
	v_mov_b32_e32 v0, v140
	s_nop 0
	v_add_u32_e32 v0, 0x400, v0
	v_lshlrev_b32_e32 v1, 5, v0
	v_lshlrev_b32_e32 v0, 1, v0
	v_and_b32_e32 v0, 0xffffffe0, v0
	v_add3_u32 v0, 0, v1, v0
	ds_read_b128 v[40:43], v0
	ds_read_b128 v[44:47], v0 offset:16
	v_mov_b32_e32 v0, v140
	s_nop 0
	v_add_u32_e32 v0, 0x600, v0
	v_lshlrev_b32_e32 v1, 5, v0
	v_lshlrev_b32_e32 v0, 1, v0
	v_and_b32_e32 v0, 0xffffffe0, v0
	v_add3_u32 v0, 0, v1, v0
	ds_read_b128 v[32:35], v0
	ds_read_b128 v[36:39], v0 offset:16
	v_mov_b32_e32 v0, v140
	s_nop 0
	v_add_u32_e32 v0, 0x800, v0
	v_lshlrev_b32_e32 v1, 5, v0
	v_lshlrev_b32_e32 v0, 1, v0
	v_and_b32_e32 v0, 0xffffffe0, v0
	v_add3_u32 v0, 0, v1, v0
	ds_read_b128 v[24:27], v0
	ds_read_b128 v[28:31], v0 offset:16
	v_mov_b32_e32 v0, v140
	s_nop 0
	v_add_u32_e32 v0, 0xa00, v0
	v_lshlrev_b32_e32 v1, 5, v0
	v_lshlrev_b32_e32 v0, 1, v0
	v_and_b32_e32 v0, 0xffffffe0, v0
	v_add3_u32 v0, 0, v1, v0
	ds_read_b128 v[12:15], v0
	ds_read_b128 v[20:23], v0 offset:16
	v_mov_b32_e32 v0, v140
	s_nop 0
	v_add_u32_e32 v0, 0xc00, v0
	v_lshlrev_b32_e32 v1, 5, v0
	v_lshlrev_b32_e32 v0, 1, v0
	v_and_b32_e32 v0, 0xffffffe0, v0
	v_add3_u32 v0, 0, v1, v0
	ds_read_b128 v[4:7], v0
	ds_read_b128 v[16:19], v0 offset:16
	v_mov_b32_e32 v0, v140
	s_nop 0
	v_add_u32_e32 v0, 0xe00, v0
	v_lshlrev_b32_e32 v1, 5, v0
	v_lshlrev_b32_e32 v0, 1, v0
	v_and_b32_e32 v0, 0xffffffe0, v0
	v_add3_u32 v8, 0, v1, v0
	ds_read_b128 v[0:3], v8
	ds_read_b128 v[8:11], v8 offset:16
	s_waitcnt lgkmcnt(0)
	s_barrier
	s_nop 0
	v_lshlrev_b32_e32 v176, 2, v128
	s_cbranch_vccz .LBB0_715
	s_waitcnt vmcnt(15)
	ds_bpermute_b32 v134, v143, v127
	ds_bpermute_b32 v133, v145, v124
	s_waitcnt vmcnt(14)
	ds_bpermute_b32 v130, v143, v123
	ds_bpermute_b32 v129, v145, v120
	s_and_saveexec_b64 s[36:37], s[8:9]
	s_cbranch_execz .LBB0_708
	v_cmp_lt_i32_e32 vcc, 0, v176
	s_waitcnt lgkmcnt(1)
	v_mov_b32_e32 v130, 0
	v_mov_b32_e32 v134, 0
	s_and_saveexec_b64 s[38:39], vcc
	s_cbranch_execz .LBB0_705
	v_lshl_add_u64 v[134:135], v[176:177], 2, s[20:21]
	global_load_dword v134, v[134:135], off offset:-4

; #define LAS __attribute__((address_space(3)))
; __device__ __forceinline__ f32x2 cmul(f32x2 a, f32x2 b) { return (f32x2){a.x * b.x - a.y * b.y, a.x * b.y + a.y * b.x}; }
; __device__ __forceinline__ f32x2 tw32k(const LAS f32x2* TH, const LAS f32x2* TL, int n) { return cmul(TH[n >> 7], TL[n & 127]); }
; template <bool INV> __device__ __forceinline__ void dft16(f32x2 (&x)[16]) {
; #pragma unroll
;     for (int b = 0; b < 4; ++b) r4<INV>(x[b], x[4 + b], x[8 + b], x[12 + b]);
;     const float sg = INV ? -1.f : 1.f;
;     const f32x2 W1 = {0.92387953251f, -0.38268343236f * sg}, W2 = {0.70710678118f, -0.70710678118f * sg}, W3 = {0.38268343236f, -0.92387953251f * sg},
;                 W4 = {0.f, -1.f * sg}, W6 = {-0.70710678118f, -0.70710678118f * sg}, W9 = {-0.92387953251f, 0.38268343236f * sg};
;     x[5] = cmul(x[5], W1); x[9] = cmul(x[9], W2); x[13] = cmul(x[13], W3);
;     x[6] = cmul(x[6], W2); x[10] = cmul(x[10], W4); x[14] = cmul(x[14], W6);
;     x[7] = cmul(x[7], W3); x[11] = cmul(x[11], W6); x[15] = cmul(x[15], W9);
; #pragma unroll
;     for (int c = 0; c < 4; ++c) r4<INV>(x[4 * c], x[4 * c + 1], x[4 * c + 2], x[4 * c + 3]);
; }
; template <bool INV> __device__ __forceinline__ void bfly16(f32x2 (&x)[16], const LAS f32x2* TH, const LAS f32x2* TL, int tw) {
;     f32x2 W = tw32k(TH, TL, tw); if (INV) W.y = -W.y;
;     if (INV) { f32x2 p = W;
; #pragma unroll
;         for (int q = 1; q < 16; ++q) { x[q] = cmul(x[q], p); if (q < 15) p = cmul(p, W); } }
;     dft16<INV>(x);
;     if (!INV) { f32x2 p = W;
; #pragma unroll
;         for (int r = 1; r < 16; ++r) { x[4 * (r & 3) + (r >> 2)] = cmul(x[4 * (r & 3) + (r >> 2)], p); if (r < 15) p = cmul(p, W); } }
; }
; template <bool INV> __device__ __forceinline__ void pass16(LAS f32x2* X, const LAS f32x2* TH, const LAS f32x2* TL, int base, int stride, int tw) {
;     f32x2 x[16];
; #pragma unroll
;     for (int q = 0; q < 16; ++q) x[q] = X[base + q * stride];
;     bfly16<INV>(x, TH, TL, tw);
; #pragma unroll
;     for (int c = 0; c < 4; ++c)
; #pragma unroll
;         for (int d = 0; d < 4; ++d) X[base + (c + 4 * d) * stride] = x[4 * c + d];
; }
.LBB0_846:
	v_add_u32_e32 v108, s0, v140
	v_lshrrev_b32_e32 v252, 6, v108
	v_and_b32_e32 v251, 63, v108
	v_lshlrev_b32_e32 v253, 5, v252
	v_lshlrev_b32_e32 v250, 3, v252
	v_lshlrev_b32_e32 v251, 4, v251
	v_lshl_add_u32 v253, v108, 3, v253
	v_add_u32_e32 v250, 0x26000, v250
	v_add_u32_e32 v251, 0x26400, v251
	ds_read_b64 v[64:65], v250
	ds_read_b64 v[66:67], v251
	ds_read2st64_b64 v[68:71], v253 offset0:0 offset1:17
	ds_read2st64_b64 v[72:75], v253 offset0:136 offset1:153
	ds_read2st64_b64 v[76:79], v253 offset0:34 offset1:51
	ds_read2st64_b64 v[80:83], v253 offset0:170 offset1:187
	ds_read2st64_b64 v[84:87], v253 offset0:68 offset1:85
	ds_read2st64_b64 v[88:91], v253 offset0:204 offset1:221
	ds_read2st64_b64 v[92:95], v253 offset0:102 offset1:119
	ds_read2st64_b64 v[96:99], v253 offset0:238 offset1:255
	s_cmp_eq_u32 s0, 0
	s_movk_i32 s0, 0x200
	s_mov_b64 s[12:13], 0
	s_waitcnt lgkmcnt(8)
	v_pk_mul_f32 v[100:101], v[64:65], v[66:67] op_sel:[0,1] op_sel_hi:[1,1]
	s_nop 0
	v_pk_fma_f32 v[66:67], v[64:65], v[66:67], v[100:101] op_sel:[0,0,1] op_sel_hi:[1,0,0] neg_lo:[0,0,1]
	s_nop 0
	v_pk_mul_f32 v[100:101], v[66:67], v[66:67] op_sel:[0,1] op_sel_hi:[1,1]
	s_nop 0
	v_pk_fma_f32 v[100:101], v[66:67], v[66:67], v[100:101] op_sel:[0,0,1] op_sel_hi:[1,0,0] neg_lo:[0,0,1]
	s_nop 0
	v_pk_mul_f32 v[64:65], v[100:101], v[66:67] op_sel:[0,1] op_sel_hi:[1,1]
	v_pk_mul_f32 v[102:103], v[100:101], v[100:101] op_sel:[0,1] op_sel_hi:[1,1]
	v_pk_fma_f32 v[64:65], v[100:101], v[66:67], v[64:65] op_sel:[0,0,1] op_sel_hi:[1,0,0] neg_lo:[0,0,1]
	v_pk_fma_f32 v[102:103], v[100:101], v[100:101], v[102:103] op_sel:[0,0,1] op_sel_hi:[1,0,0] neg_lo:[0,0,1]
	s_nop 0
	v_pk_mul_f32 v[104:105], v[102:103], v[66:67] op_sel:[0,1] op_sel_hi:[1,1]
	v_pk_mul_f32 v[106:107], v[102:103], v[100:101] op_sel:[0,1] op_sel_hi:[1,1]
	v_pk_mul_f32 v[110:111], v[102:103], v[64:65] op_sel:[0,1] op_sel_hi:[1,1]
	v_pk_fma_f32 v[104:105], v[102:103], v[66:67], v[104:105] op_sel:[0,0,1] op_sel_hi:[1,0,0] neg_lo:[0,0,1]
	v_pk_fma_f32 v[106:107], v[102:103], v[100:101], v[106:107] op_sel:[0,0,1] op_sel_hi:[1,0,0] neg_lo:[0,0,1]
	v_pk_fma_f32 v[110:111], v[102:103], v[64:65], v[110:111] op_sel:[0,0,1] op_sel_hi:[1,0,0] neg_lo:[0,0,1]
	v_pk_mul_f32 v[112:113], v[102:103], v[102:103] op_sel:[0,1] op_sel_hi:[1,1]
	s_nop 0
	v_pk_fma_f32 v[112:113], v[102:103], v[102:103], v[112:113] op_sel:[0,0,1] op_sel_hi:[1,0,0] neg_lo:[0,0,1]
	s_nop 0
	v_pk_mul_f32 v[114:115], v[112:113], v[66:67] op_sel:[0,1] op_sel_hi:[1,1]
	v_pk_mul_f32 v[116:117], v[112:113], v[100:101] op_sel:[0,1] op_sel_hi:[1,1]
	v_pk_mul_f32 v[118:119], v[112:113], v[64:65] op_sel:[0,1] op_sel_hi:[1,1]
	v_pk_fma_f32 v[114:115], v[112:113], v[66:67], v[114:115] op_sel:[0,0,1] op_sel_hi:[1,0,0] neg_lo:[0,0,1]
	v_pk_fma_f32 v[116:117], v[112:113], v[100:101], v[116:117] op_sel:[0,0,1] op_sel_hi:[1,0,0] neg_lo:[0,0,1]
	v_pk_fma_f32 v[118:119], v[112:113], v[64:65], v[118:119] op_sel:[0,0,1] op_sel_hi:[1,0,0] neg_lo:[0,0,1]
	v_pk_mul_f32 v[120:121], v[112:113], v[102:103] op_sel:[0,1] op_sel_hi:[1,1]
	v_pk_mul_f32 v[122:123], v[112:113], v[104:105] op_sel:[0,1] op_sel_hi:[1,1]
	v_pk_mul_f32 v[188:189], v[112:113], v[106:107] op_sel:[0,1] op_sel_hi:[1,1]
	v_pk_fma_f32 v[120:121], v[112:113], v[102:103], v[120:121] op_sel:[0,0,1] op_sel_hi:[1,0,0] neg_lo:[0,0,1]
	v_pk_fma_f32 v[122:123], v[112:113], v[104:105], v[122:123] op_sel:[0,0,1] op_sel_hi:[1,0,0] neg_lo:[0,0,1]
	v_pk_fma_f32 v[188:189], v[112:113], v[106:107], v[188:189] op_sel:[0,0,1] op_sel_hi:[1,0,0] neg_lo:[0,0,1]
	v_pk_mul_f32 v[190:191], v[112:113], v[110:111] op_sel:[0,1] op_sel_hi:[1,1]
	s_nop 0
	v_pk_fma_f32 v[190:191], v[112:113], v[110:111], v[190:191] op_sel:[0,0,1] op_sel_hi:[1,0,0] neg_lo:[0,0,1]
	s_waitcnt lgkmcnt(6)
	v_pk_add_f32 v[192:193], v[68:69], v[72:73]
	v_pk_add_f32 v[194:195], v[70:71], v[74:75]
	s_waitcnt lgkmcnt(4)
	v_pk_add_f32 v[196:197], v[76:77], v[80:81]
	v_pk_add_f32 v[198:199], v[78:79], v[82:83]
	v_pk_add_f32 v[72:73], v[68:69], v[72:73] neg_lo:[0,1] neg_hi:[0,1]
	v_pk_add_f32 v[74:75], v[70:71], v[74:75] neg_lo:[0,1] neg_hi:[0,1]
	v_pk_add_f32 v[80:81], v[76:77], v[80:81] neg_lo:[0,1] neg_hi:[0,1]
	v_pk_add_f32 v[78:79], v[78:79], v[82:83] neg_lo:[0,1] neg_hi:[0,1]
	s_waitcnt lgkmcnt(2)
	v_pk_add_f32 v[82:83], v[84:85], v[88:89]
	v_pk_add_f32 v[76:77], v[86:87], v[90:91]
	s_waitcnt lgkmcnt(0)
; #define LAS __attribute__((address_space(3)))
; __device__ __forceinline__ f32x2 cmul(f32x2 a, f32x2 b) { return (f32x2){a.x * b.x - a.y * b.y, a.x * b.y + a.y * b.x}; }
; __device__ __forceinline__ f32x2 tw32k(const LAS f32x2* TH, const LAS f32x2* TL, int n) { return cmul(TH[n >> 7], TL[n & 127]); }
; template <bool INV> __device__ __forceinline__ void dft16(f32x2 (&x)[16]) {
; #pragma unroll
;     for (int b = 0; b < 4; ++b) r4<INV>(x[b], x[4 + b], x[8 + b], x[12 + b]);
;     const float sg = INV ? -1.f : 1.f;
;     const f32x2 W1 = {0.92387953251f, -0.38268343236f * sg}, W2 = {0.70710678118f, -0.70710678118f * sg}, W3 = {0.38268343236f, -0.92387953251f * sg},
;                 W4 = {0.f, -1.f * sg}, W6 = {-0.70710678118f, -0.70710678118f * sg}, W9 = {-0.92387953251f, 0.38268343236f * sg};
;     x[5] = cmul(x[5], W1); x[9] = cmul(x[9], W2); x[13] = cmul(x[13], W3);
;     x[6] = cmul(x[6], W2); x[10] = cmul(x[10], W4); x[14] = cmul(x[14], W6);
;     x[7] = cmul(x[7], W3); x[11] = cmul(x[11], W6); x[15] = cmul(x[15], W9);
; #pragma unroll
;     for (int c = 0; c < 4; ++c) r4<INV>(x[4 * c], x[4 * c + 1], x[4 * c + 2], x[4 * c + 3]);
; }
; template <bool INV> __device__ __forceinline__ void bfly16(f32x2 (&x)[16], const LAS f32x2* TH, const LAS f32x2* TL, int tw) {
;     f32x2 W = tw32k(TH, TL, tw); if (INV) W.y = -W.y;
;     if (INV) { f32x2 p = W;
; #pragma unroll
;         for (int q = 1; q < 16; ++q) { x[q] = cmul(x[q], p); if (q < 15) p = cmul(p, W); } }
;     dft16<INV>(x);
;     if (!INV) { f32x2 p = W;
; #pragma unroll
;         for (int r = 1; r < 16; ++r) { x[4 * (r & 3) + (r >> 2)] = cmul(x[4 * (r & 3) + (r >> 2)], p); if (r < 15) p = cmul(p, W); } }
; }
; template <bool INV> __device__ __forceinline__ void pass16(LAS f32x2* X, const LAS f32x2* TH, const LAS f32x2* TL, int base, int stride, int tw) {
;     f32x2 x[16];
; #pragma unroll
;     for (int q = 0; q < 16; ++q) x[q] = X[base + q * stride];
;     bfly16<INV>(x, TH, TL, tw);
; #pragma unroll
;     for (int c = 0; c < 4; ++c)
; #pragma unroll
;         for (int d = 0; d < 4; ++d) X[base + (c + 4 * d) * stride] = x[4 * c + d];
; }
	v_pk_add_f32 v[70:71], v[92:93], v[96:97]
	v_pk_add_f32 v[68:69], v[94:95], v[98:99]
	v_pk_add_f32 v[84:85], v[84:85], v[88:89] neg_lo:[0,1] neg_hi:[0,1]
	v_pk_add_f32 v[86:87], v[86:87], v[90:91] neg_lo:[0,1] neg_hi:[0,1]
	v_pk_add_f32 v[96:97], v[92:93], v[96:97] neg_lo:[0,1] neg_hi:[0,1]
	v_pk_add_f32 v[94:95], v[94:95], v[98:99] neg_lo:[0,1] neg_hi:[0,1]
	v_pk_add_f32 v[98:99], v[192:193], v[82:83]
	v_pk_add_f32 v[92:93], v[194:195], v[76:77]
	v_pk_add_f32 v[90:91], v[196:197], v[70:71]
	v_pk_add_f32 v[88:89], v[198:199], v[68:69]
	v_pk_add_f32 v[82:83], v[192:193], v[82:83] neg_lo:[0,1] neg_hi:[0,1]
	v_pk_add_f32 v[76:77], v[194:195], v[76:77] neg_lo:[0,1] neg_hi:[0,1]
	v_pk_add_f32 v[196:197], v[196:197], v[70:71] neg_lo:[0,1] neg_hi:[0,1]
	v_pk_add_f32 v[198:199], v[198:199], v[68:69] neg_lo:[0,1] neg_hi:[0,1]
	v_pk_add_f32 v[68:69], v[72:73], v[84:85] op_sel:[0,1] op_sel_hi:[1,0] neg_hi:[0,1]
	v_pk_add_f32 v[70:71], v[74:75], v[86:87] op_sel:[0,1] op_sel_hi:[1,0] neg_hi:[0,1]
	v_pk_add_f32 v[194:195], v[80:81], v[96:97] op_sel:[0,1] op_sel_hi:[1,0] neg_hi:[0,1]
	v_pk_add_f32 v[192:193], v[78:79], v[94:95] op_sel:[0,1] op_sel_hi:[1,0] neg_hi:[0,1]
	v_pk_add_f32 v[84:85], v[72:73], v[84:85] op_sel:[0,1] op_sel_hi:[1,0] neg_lo:[0,1]
	v_pk_add_f32 v[74:75], v[74:75], v[86:87] op_sel:[0,1] op_sel_hi:[1,0] neg_lo:[0,1]
	v_pk_add_f32 v[80:81], v[80:81], v[96:97] op_sel:[0,1] op_sel_hi:[1,0] neg_lo:[0,1]
	v_pk_add_f32 v[78:79], v[78:79], v[94:95] op_sel:[0,1] op_sel_hi:[1,0] neg_lo:[0,1]
	v_pk_mul_f32 v[94:95], v[70:71], s[70:71] op_sel_hi:[1,0]
	v_pk_mul_f32 v[96:97], v[76:77], s[72:73] op_sel_hi:[1,0]
	v_pk_mul_f32 v[86:87], v[74:75], s[64:65] op_sel_hi:[1,0]
	v_pk_mul_f32 v[72:73], v[194:195], s[72:73] op_sel_hi:[1,0]
	v_pk_mul_f32 v[200:201], v[80:81], s[72:73] op_sel_hi:[1,0]
	v_pk_mul_f32 v[202:203], v[192:193], s[64:65] op_sel_hi:[1,0]
	v_pk_mul_f32 v[204:205], v[198:199], s[72:73] op_sel_hi:[1,0]
	v_pk_mul_f32 v[206:207], v[78:79], s[82:83] op_sel_hi:[1,0]
	v_pk_fma_f32 v[70:71], v[70:71], s[44:45], v[94:95] op_sel:[0,0,1] op_sel_hi:[1,0,0] neg_lo:[0,0,1]
	v_pk_fma_f32 v[76:77], v[76:77], s[76:77], v[96:97] op_sel:[0,0,1] op_sel_hi:[1,0,0] neg_lo:[0,0,1]
	v_pk_fma_f32 v[86:87], v[74:75], s[82:83], v[86:87] op_sel:[0,0,1] op_sel_hi:[1,0,0] neg_lo:[0,0,1]
	v_pk_fma_f32 v[194:195], v[194:195], s[76:77], v[72:73] op_sel:[0,0,1] op_sel_hi:[1,0,0] neg_lo:[0,0,1]
	v_pk_fma_f32 v[80:81], v[80:81], s[72:73], v[200:201] op_sel:[0,0,1] op_sel_hi:[1,0,0] neg_lo:[0,0,1]
	v_pk_fma_f32 v[202:203], v[192:193], s[82:83], v[202:203] op_sel:[0,0,1] op_sel_hi:[1,0,0] neg_lo:[0,0,1]
	v_pk_fma_f32 v[204:205], v[198:199], s[72:73], v[204:205] op_sel:[0,0,1] op_sel_hi:[1,0,0] neg_lo:[0,0,1]
	v_pk_fma_f32 v[206:207], v[78:79], s[64:65], v[206:207] op_sel:[0,0,1] op_sel_hi:[1,0,0] neg_lo:[0,0,1]
	v_pk_add_f32 v[78:79], v[98:99], v[90:91]
	v_pk_add_f32 v[198:199], v[68:69], v[194:195]
	v_pk_add_f32 v[192:193], v[82:83], v[196:197] op_sel:[0,1] op_sel_hi:[1,0] neg_hi:[0,1]
	v_pk_add_f32 v[200:201], v[84:85], v[80:81]
	v_pk_add_f32 v[98:99], v[98:99], v[90:91] neg_lo:[0,1] neg_hi:[0,1]
	v_pk_add_f32 v[68:69], v[68:69], v[194:195] neg_lo:[0,1] neg_hi:[0,1]
	v_pk_add_f32 v[196:197], v[82:83], v[196:197] op_sel:[0,1] op_sel_hi:[1,0] neg_lo:[0,1]
	v_pk_add_f32 v[84:85], v[84:85], v[80:81] neg_lo:[0,1] neg_hi:[0,1]
	v_pk_add_f32 v[80:81], v[92:93], v[88:89]
	v_pk_add_f32 v[82:83], v[70:71], v[202:203]
	v_pk_add_f32 v[194:195], v[76:77], v[204:205]
	v_pk_add_f32 v[90:91], v[86:87], v[206:207]
	v_pk_add_f32 v[88:89], v[92:93], v[88:89] neg_lo:[0,1] neg_hi:[0,1]
	v_pk_add_f32 v[70:71], v[70:71], v[202:203] neg_lo:[0,1] neg_hi:[0,1]
	v_pk_add_f32 v[76:77], v[76:77], v[204:205] neg_lo:[0,1] neg_hi:[0,1]
	v_pk_add_f32 v[86:87], v[86:87], v[206:207] neg_lo:[0,1] neg_hi:[0,1]
	v_pk_add_f32 v[206:207], v[78:79], v[80:81]
	v_pk_add_f32 v[204:205], v[198:199], v[82:83]
	v_pk_add_f32 v[202:203], v[192:193], v[194:195]
	v_pk_add_f32 v[92:93], v[200:201], v[90:91]
	v_pk_add_f32 v[78:79], v[78:79], v[80:81] neg_lo:[0,1] neg_hi:[0,1]
	v_pk_add_f32 v[198:199], v[198:199], v[82:83] neg_lo:[0,1] neg_hi:[0,1]
	v_pk_add_f32 v[192:193], v[192:193], v[194:195] neg_lo:[0,1] neg_hi:[0,1]
	v_pk_add_f32 v[90:91], v[200:201], v[90:91] neg_lo:[0,1] neg_hi:[0,1]
	v_pk_add_f32 v[200:201], v[98:99], v[88:89] op_sel:[0,1] op_sel_hi:[1,0] neg_hi:[0,1]
	v_pk_add_f32 v[194:195], v[68:69], v[70:71] op_sel:[0,1] op_sel_hi:[1,0] neg_hi:[0,1]
	v_pk_add_f32 v[82:83], v[196:197], v[76:77] op_sel:[0,1] op_sel_hi:[1,0] neg_hi:[0,1]
	v_pk_add_f32 v[80:81], v[84:85], v[86:87] op_sel:[0,1] op_sel_hi:[1,0] neg_hi:[0,1]
	v_pk_add_f32 v[98:99], v[98:99], v[88:89] op_sel:[0,1] op_sel_hi:[1,0] neg_lo:[0,1]
	v_pk_add_f32 v[68:69], v[68:69], v[70:71] op_sel:[0,1] op_sel_hi:[1,0] neg_lo:[0,1]
	v_pk_add_f32 v[196:197], v[196:197], v[76:77] op_sel:[0,1] op_sel_hi:[1,0] neg_lo:[0,1]
	v_pk_add_f32 v[84:85], v[84:85], v[86:87] op_sel:[0,1] op_sel_hi:[1,0] neg_lo:[0,1]
	v_pk_mul_f32 v[86:87], v[204:205], v[66:67] op_sel:[0,1] op_sel_hi:[1,1]
	v_pk_mul_f32 v[76:77], v[202:203], v[100:101] op_sel:[0,1] op_sel_hi:[1,1]
	v_pk_fma_f32 v[66:67], v[204:205], v[66:67], v[86:87] op_sel:[0,0,1] op_sel_hi:[1,0,0] neg_lo:[0,0,1]
	v_pk_mul_f32 v[86:87], v[92:93], v[64:65] op_sel:[0,1] op_sel_hi:[1,1]
	v_pk_fma_f32 v[100:101], v[202:203], v[100:101], v[76:77] op_sel:[0,0,1] op_sel_hi:[1,0,0] neg_lo:[0,0,1]
	v_pk_mul_f32 v[202:203], v[200:201], v[102:103] op_sel:[0,1] op_sel_hi:[1,1]
	v_pk_fma_f32 v[92:93], v[92:93], v[64:65], v[86:87] op_sel:[0,0,1] op_sel_hi:[1,0,0] neg_lo:[0,0,1]
	v_pk_mul_f32 v[86:87], v[194:195], v[104:105] op_sel:[0,1] op_sel_hi:[1,1]
; #define LAS __attribute__((address_space(3)))
; __device__ __forceinline__ f32x2 cmul(f32x2 a, f32x2 b) { return (f32x2){a.x * b.x - a.y * b.y, a.x * b.y + a.y * b.x}; }
; template <bool INV> __device__ __forceinline__ void bfly16_tab(f32x2 (&x)[16], const LAS f32x2* T, int tstride, int j) {
;     if (INV) {
; #pragma unroll
;         for (int q = 1; q < 16; ++q) { f32x2 p = T[q * tstride + j]; p.y = -p.y; x[q] = cmul(x[q], p); } }
;     dft16<INV>(x);
;     if (!INV) {
; #pragma unroll
;         for (int r = 1; r < 16; ++r) { const f32x2 p = T[r * tstride + j]; x[4 * (r & 3) + (r >> 2)] = cmul(x[4 * (r & 3) + (r >> 2)], p); } }
; }
; template <bool INV> __device__ __forceinline__ void pass16_s64(LAS f32x2* X, const LAS f32x2* TH, int base, int j) {
;     f32x2 x[16];
; #pragma unroll
;     for (int q = 0; q < 16; ++q) x[q] = X[base + q * 68];
;     bfly16_tab<INV>(x, TH - 2048, 64, j);
; #pragma unroll
;     for (int c = 0; c < 4; ++c)
; #pragma unroll
;         for (int d = 0; d < 4; ++d) X[base + (c + 4 * d) * 68] = x[4 * c + d];
; }
; template <bool INV> __device__ __forceinline__ void pass16(LAS f32x2* X, const LAS f32x2* TH, const LAS f32x2* TL, int base, int stride, int tw) {
;     f32x2 x[16];
; #pragma unroll
;     for (int q = 0; q < 16; ++q) x[q] = X[base + q * stride];
;     bfly16<INV>(x, TH, TL, tw);
; #pragma unroll
;     for (int c = 0; c < 4; ++c)
; #pragma unroll
;         for (int d = 0; d < 4; ++d) X[base + (c + 4 * d) * stride] = x[4 * c + d];
; }
	v_pk_fma_f32 v[202:203], v[200:201], v[102:103], v[202:203] op_sel:[0,0,1] op_sel_hi:[1,0,0] neg_lo:[0,0,1]
	v_pk_mul_f32 v[102:103], v[82:83], v[106:107] op_sel:[0,1] op_sel_hi:[1,1]
	v_pk_fma_f32 v[194:195], v[194:195], v[104:105], v[86:87] op_sel:[0,0,1] op_sel_hi:[1,0,0] neg_lo:[0,0,1]
	v_pk_mul_f32 v[86:87], v[80:81], v[110:111] op_sel:[0,1] op_sel_hi:[1,1]
	v_pk_fma_f32 v[106:107], v[82:83], v[106:107], v[102:103] op_sel:[0,0,1] op_sel_hi:[1,0,0] neg_lo:[0,0,1]
	v_pk_mul_f32 v[102:103], v[78:79], v[112:113] op_sel:[0,1] op_sel_hi:[1,1]
	v_pk_fma_f32 v[110:111], v[80:81], v[110:111], v[86:87] op_sel:[0,0,1] op_sel_hi:[1,0,0] neg_lo:[0,0,1]
	v_pk_mul_f32 v[80:81], v[198:199], v[114:115] op_sel:[0,1] op_sel_hi:[1,1]
	v_pk_fma_f32 v[112:113], v[78:79], v[112:113], v[102:103] op_sel:[0,0,1] op_sel_hi:[1,0,0] neg_lo:[0,0,1]
	v_pk_mul_f32 v[78:79], v[192:193], v[116:117] op_sel:[0,1] op_sel_hi:[1,1]
	v_pk_fma_f32 v[114:115], v[198:199], v[114:115], v[80:81] op_sel:[0,0,1] op_sel_hi:[1,0,0] neg_lo:[0,0,1]
	v_pk_mul_f32 v[198:199], v[90:91], v[118:119] op_sel:[0,1] op_sel_hi:[1,1]
	v_pk_fma_f32 v[116:117], v[192:193], v[116:117], v[78:79] op_sel:[0,0,1] op_sel_hi:[1,0,0] neg_lo:[0,0,1]
	v_pk_mul_f32 v[192:193], v[98:99], v[120:121] op_sel:[0,1] op_sel_hi:[1,1]
	v_pk_fma_f32 v[198:199], v[90:91], v[118:119], v[198:199] op_sel:[0,0,1] op_sel_hi:[1,0,0] neg_lo:[0,0,1]
	v_pk_mul_f32 v[90:91], v[68:69], v[122:123] op_sel:[0,1] op_sel_hi:[1,1]
	v_pk_fma_f32 v[120:121], v[98:99], v[120:121], v[192:193] op_sel:[0,0,1] op_sel_hi:[1,0,0] neg_lo:[0,0,1]
	v_pk_mul_f32 v[98:99], v[196:197], v[188:189] op_sel:[0,1] op_sel_hi:[1,1]
	v_pk_fma_f32 v[68:69], v[68:69], v[122:123], v[90:91] op_sel:[0,0,1] op_sel_hi:[1,0,0] neg_lo:[0,0,1]
	v_pk_mul_f32 v[90:91], v[84:85], v[190:191] op_sel:[0,1] op_sel_hi:[1,1]
	v_pk_fma_f32 v[188:189], v[196:197], v[188:189], v[98:99] op_sel:[0,0,1] op_sel_hi:[1,0,0] neg_lo:[0,0,1]
	v_pk_fma_f32 v[84:85], v[84:85], v[190:191], v[90:91] op_sel:[0,0,1] op_sel_hi:[1,0,0] neg_lo:[0,0,1]
	ds_write2st64_b64 v253, v[206:207], v[66:67] offset0:0 offset1:17
	ds_write2st64_b64 v253, v[100:101], v[92:93] offset0:34 offset1:51
	ds_write2st64_b64 v253, v[202:203], v[194:195] offset0:68 offset1:85
	ds_write2st64_b64 v253, v[106:107], v[110:111] offset0:102 offset1:119
	ds_write2st64_b64 v253, v[112:113], v[114:115] offset0:136 offset1:153
	ds_write2st64_b64 v253, v[116:117], v[198:199] offset0:170 offset1:187
	ds_write2st64_b64 v253, v[120:121], v[68:69] offset0:204 offset1:221
	ds_write2st64_b64 v253, v[188:189], v[84:85] offset0:238 offset1:255
	s_cbranch_scc1 .LBB0_846
	s_waitcnt lgkmcnt(0)
	s_barrier
	s_mov_b32 s0, 0
	s_mov_b64 s[12:13], -1
	ds_read2st64_b64 v[232:235], v139 offset0:1 offset1:2
	ds_read2st64_b64 v[208:211], v139 offset0:3 offset1:4
	ds_read2st64_b64 v[204:207], v139 offset0:5 offset1:6
	ds_read2st64_b64 v[200:203], v139 offset0:7 offset1:8
	ds_read2st64_b64 v[196:199], v139 offset0:9 offset1:10
	ds_read2st64_b64 v[192:195], v139 offset0:11 offset1:12
	ds_read2st64_b64 v[188:191], v139 offset0:13 offset1:14
	ds_read_b64 v[222:223], v139 offset:7680
.LBB0_848:
	v_add_u32_e32 v252, s0, v140
	v_lshrrev_b32_e32 v253, 6, v252
	v_mad_u32_u24 v250, v253, s77, v142
	v_add_u32_e32 v251, 0x800, v250
	v_add_u32_e32 v248, 0x1000, v250
	v_add_u32_e32 v249, 0x1800, v250
	ds_read2_b64 v[64:67], v250 offset0:0 offset1:68
	ds_read2_b64 v[68:71], v248 offset0:32 offset1:100
	ds_read2_b64 v[72:75], v250 offset0:136 offset1:204
	ds_read2_b64 v[76:79], v248 offset0:168 offset1:236
	ds_read2_b64 v[80:83], v251 offset0:16 offset1:84
	ds_read2_b64 v[84:87], v249 offset0:48 offset1:116
	ds_read2_b64 v[88:91], v251 offset0:152 offset1:220
	ds_read2_b64 v[92:95], v249 offset0:184 offset1:252
	s_cmp_eq_u32 s0, 0
	s_movk_i32 s0, 0x200
	s_mov_b64 s[12:13], 0
	s_waitcnt lgkmcnt(6)
	v_pk_add_f32 v[96:97], v[64:65], v[68:69]
	v_pk_add_f32 v[98:99], v[66:67], v[70:71]
	s_waitcnt lgkmcnt(4)
	v_pk_add_f32 v[100:101], v[72:73], v[76:77]
	v_pk_add_f32 v[102:103], v[74:75], v[78:79]
	v_pk_add_f32 v[68:69], v[64:65], v[68:69] neg_lo:[0,1] neg_hi:[0,1]
	v_pk_add_f32 v[66:67], v[66:67], v[70:71] neg_lo:[0,1] neg_hi:[0,1]
	v_pk_add_f32 v[72:73], v[72:73], v[76:77] neg_lo:[0,1] neg_hi:[0,1]
	v_pk_add_f32 v[78:79], v[74:75], v[78:79] neg_lo:[0,1] neg_hi:[0,1]
	s_waitcnt lgkmcnt(2)
	v_pk_add_f32 v[74:75], v[80:81], v[84:85]
	v_pk_add_f32 v[76:77], v[82:83], v[86:87]
	s_waitcnt lgkmcnt(0)
; #define LAS __attribute__((address_space(3)))
; __device__ __forceinline__ f32x2 cmul(f32x2 a, f32x2 b) { return (f32x2){a.x * b.x - a.y * b.y, a.x * b.y + a.y * b.x}; }
; template <bool INV> __device__ __forceinline__ void dft16(f32x2 (&x)[16]) {
; #pragma unroll
;     for (int b = 0; b < 4; ++b) r4<INV>(x[b], x[4 + b], x[8 + b], x[12 + b]);
;     const float sg = INV ? -1.f : 1.f;
;     const f32x2 W1 = {0.92387953251f, -0.38268343236f * sg}, W2 = {0.70710678118f, -0.70710678118f * sg}, W3 = {0.38268343236f, -0.92387953251f * sg},
;                 W4 = {0.f, -1.f * sg}, W6 = {-0.70710678118f, -0.70710678118f * sg}, W9 = {-0.92387953251f, 0.38268343236f * sg};
;     x[5] = cmul(x[5], W1); x[9] = cmul(x[9], W2); x[13] = cmul(x[13], W3);
;     x[6] = cmul(x[6], W2); x[10] = cmul(x[10], W4); x[14] = cmul(x[14], W6);
;     x[7] = cmul(x[7], W3); x[11] = cmul(x[11], W6); x[15] = cmul(x[15], W9);
; #pragma unroll
;     for (int c = 0; c < 4; ++c) r4<INV>(x[4 * c], x[4 * c + 1], x[4 * c + 2], x[4 * c + 3]);
; }
; template <bool INV> __device__ __forceinline__ void bfly16_tab(f32x2 (&x)[16], const LAS f32x2* T, int tstride, int j) {
;     if (INV) {
; #pragma unroll
;         for (int q = 1; q < 16; ++q) { f32x2 p = T[q * tstride + j]; p.y = -p.y; x[q] = cmul(x[q], p); } }
;     dft16<INV>(x);
;     if (!INV) {
; #pragma unroll
;         for (int r = 1; r < 16; ++r) { const f32x2 p = T[r * tstride + j]; x[4 * (r & 3) + (r >> 2)] = cmul(x[4 * (r & 3) + (r >> 2)], p); } }
; }
; template <bool INV> __device__ __forceinline__ void pass16_s64(LAS f32x2* X, const LAS f32x2* TH, int base, int j) {
;     f32x2 x[16];
; #pragma unroll
;     for (int q = 0; q < 16; ++q) x[q] = X[base + q * 68];
;     bfly16_tab<INV>(x, TH - 2048, 64, j);
; #pragma unroll
;     for (int c = 0; c < 4; ++c)
; #pragma unroll
;         for (int d = 0; d < 4; ++d) X[base + (c + 4 * d) * 68] = x[4 * c + d];
; }
	v_pk_add_f32 v[70:71], v[88:89], v[92:93]
	v_pk_add_f32 v[64:65], v[90:91], v[94:95]
	v_pk_add_f32 v[84:85], v[80:81], v[84:85] neg_lo:[0,1] neg_hi:[0,1]
	v_pk_add_f32 v[86:87], v[82:83], v[86:87] neg_lo:[0,1] neg_hi:[0,1]
	v_pk_add_f32 v[92:93], v[88:89], v[92:93] neg_lo:[0,1] neg_hi:[0,1]
	v_pk_add_f32 v[94:95], v[90:91], v[94:95] neg_lo:[0,1] neg_hi:[0,1]
	v_pk_add_f32 v[90:91], v[96:97], v[74:75]
	v_pk_add_f32 v[88:89], v[98:99], v[76:77]
	v_pk_add_f32 v[82:83], v[100:101], v[70:71]
	v_pk_add_f32 v[80:81], v[102:103], v[64:65]
	v_pk_add_f32 v[96:97], v[96:97], v[74:75] neg_lo:[0,1] neg_hi:[0,1]
	v_pk_add_f32 v[76:77], v[98:99], v[76:77] neg_lo:[0,1] neg_hi:[0,1]
	v_pk_add_f32 v[100:101], v[100:101], v[70:71] neg_lo:[0,1] neg_hi:[0,1]
	v_pk_add_f32 v[102:103], v[102:103], v[64:65] neg_lo:[0,1] neg_hi:[0,1]
	v_pk_add_f32 v[64:65], v[68:69], v[84:85] op_sel:[0,1] op_sel_hi:[1,0] neg_hi:[0,1]
	v_pk_add_f32 v[70:71], v[66:67], v[86:87] op_sel:[0,1] op_sel_hi:[1,0] neg_hi:[0,1]
	v_pk_add_f32 v[98:99], v[72:73], v[92:93] op_sel:[0,1] op_sel_hi:[1,0] neg_hi:[0,1]
	v_pk_add_f32 v[74:75], v[78:79], v[94:95] op_sel:[0,1] op_sel_hi:[1,0] neg_hi:[0,1]
	v_pk_add_f32 v[84:85], v[68:69], v[84:85] op_sel:[0,1] op_sel_hi:[1,0] neg_lo:[0,1]
	v_pk_add_f32 v[66:67], v[66:67], v[86:87] op_sel:[0,1] op_sel_hi:[1,0] neg_lo:[0,1]
	v_pk_add_f32 v[92:93], v[72:73], v[92:93] op_sel:[0,1] op_sel_hi:[1,0] neg_lo:[0,1]
	v_pk_add_f32 v[94:95], v[78:79], v[94:95] op_sel:[0,1] op_sel_hi:[1,0] neg_lo:[0,1]
	v_pk_mul_f32 v[78:79], v[70:71], s[70:71] op_sel_hi:[1,0]
	v_pk_mul_f32 v[72:73], v[76:77], s[72:73] op_sel_hi:[1,0]
	v_pk_mul_f32 v[86:87], v[66:67], s[64:65] op_sel_hi:[1,0]
	v_pk_mul_f32 v[68:69], v[98:99], s[72:73] op_sel_hi:[1,0]
	v_pk_mul_f32 v[104:105], v[92:93], s[72:73] op_sel_hi:[1,0]
	v_pk_mul_f32 v[106:107], v[74:75], s[64:65] op_sel_hi:[1,0]
	v_pk_mul_f32 v[108:109], v[102:103], s[72:73] op_sel_hi:[1,0]
	v_pk_mul_f32 v[218:219], v[94:95], s[82:83] op_sel_hi:[1,0]
	v_pk_fma_f32 v[70:71], v[70:71], s[44:45], v[78:79] op_sel:[0,0,1] op_sel_hi:[1,0,0] neg_lo:[0,0,1]
	v_pk_fma_f32 v[76:77], v[76:77], s[76:77], v[72:73] op_sel:[0,0,1] op_sel_hi:[1,0,0] neg_lo:[0,0,1]
	v_pk_fma_f32 v[66:67], v[66:67], s[82:83], v[86:87] op_sel:[0,0,1] op_sel_hi:[1,0,0] neg_lo:[0,0,1]
	v_pk_fma_f32 v[98:99], v[98:99], s[76:77], v[68:69] op_sel:[0,0,1] op_sel_hi:[1,0,0] neg_lo:[0,0,1]
	v_pk_fma_f32 v[104:105], v[92:93], s[72:73], v[104:105] op_sel:[0,0,1] op_sel_hi:[1,0,0] neg_lo:[0,0,1]
	v_pk_fma_f32 v[106:107], v[74:75], s[82:83], v[106:107] op_sel:[0,0,1] op_sel_hi:[1,0,0] neg_lo:[0,0,1]
	v_pk_fma_f32 v[108:109], v[102:103], s[72:73], v[108:109] op_sel:[0,0,1] op_sel_hi:[1,0,0] neg_lo:[0,0,1]
	v_pk_fma_f32 v[94:95], v[94:95], s[64:65], v[218:219] op_sel:[0,0,1] op_sel_hi:[1,0,0] neg_lo:[0,0,1]
	v_pk_add_f32 v[218:219], v[90:91], v[82:83]
	v_pk_add_f32 v[102:103], v[64:65], v[98:99]
	v_pk_add_f32 v[74:75], v[96:97], v[100:101] op_sel:[0,1] op_sel_hi:[1,0] neg_hi:[0,1]
	v_pk_add_f32 v[92:93], v[84:85], v[104:105]
	v_pk_add_f32 v[90:91], v[90:91], v[82:83] neg_lo:[0,1] neg_hi:[0,1]
	v_pk_add_f32 v[98:99], v[64:65], v[98:99] neg_lo:[0,1] neg_hi:[0,1]
	v_pk_add_f32 v[100:101], v[96:97], v[100:101] op_sel:[0,1] op_sel_hi:[1,0] neg_lo:[0,1]
	v_pk_add_f32 v[104:105], v[84:85], v[104:105] neg_lo:[0,1] neg_hi:[0,1]
	v_pk_add_f32 v[84:85], v[88:89], v[80:81]
	v_pk_add_f32 v[96:97], v[70:71], v[106:107]
	v_pk_add_f32 v[64:65], v[76:77], v[108:109]
	v_pk_add_f32 v[82:83], v[66:67], v[94:95]
	v_pk_add_f32 v[88:89], v[88:89], v[80:81] neg_lo:[0,1] neg_hi:[0,1]
	v_pk_add_f32 v[106:107], v[70:71], v[106:107] neg_lo:[0,1] neg_hi:[0,1]
	v_pk_add_f32 v[76:77], v[76:77], v[108:109] neg_lo:[0,1] neg_hi:[0,1]
	v_pk_add_f32 v[94:95], v[66:67], v[94:95] neg_lo:[0,1] neg_hi:[0,1]
	v_pk_add_f32 v[66:67], v[218:219], v[84:85]
	v_pk_add_f32 v[108:109], v[102:103], v[96:97]
	v_pk_add_f32 v[70:71], v[74:75], v[64:65]
	v_pk_add_f32 v[80:81], v[92:93], v[82:83]
	v_pk_add_f32 v[218:219], v[218:219], v[84:85] neg_lo:[0,1] neg_hi:[0,1]
	v_pk_add_f32 v[102:103], v[102:103], v[96:97] neg_lo:[0,1] neg_hi:[0,1]
	v_pk_add_f32 v[74:75], v[74:75], v[64:65] neg_lo:[0,1] neg_hi:[0,1]
	v_pk_add_f32 v[92:93], v[92:93], v[82:83] neg_lo:[0,1] neg_hi:[0,1]
	v_pk_add_f32 v[82:83], v[90:91], v[88:89] op_sel:[0,1] op_sel_hi:[1,0] neg_hi:[0,1]
	v_pk_add_f32 v[64:65], v[98:99], v[106:107] op_sel:[0,1] op_sel_hi:[1,0] neg_hi:[0,1]
	v_pk_add_f32 v[96:97], v[100:101], v[76:77] op_sel:[0,1] op_sel_hi:[1,0] neg_hi:[0,1]
	v_pk_add_f32 v[84:85], v[104:105], v[94:95] op_sel:[0,1] op_sel_hi:[1,0] neg_hi:[0,1]
	v_pk_add_f32 v[88:89], v[90:91], v[88:89] op_sel:[0,1] op_sel_hi:[1,0] neg_lo:[0,1]
	v_pk_add_f32 v[106:107], v[98:99], v[106:107] op_sel:[0,1] op_sel_hi:[1,0] neg_lo:[0,1]
	v_pk_add_f32 v[76:77], v[100:101], v[76:77] op_sel:[0,1] op_sel_hi:[1,0] neg_lo:[0,1]
	v_pk_add_f32 v[94:95], v[104:105], v[94:95] op_sel:[0,1] op_sel_hi:[1,0] neg_lo:[0,1]
	v_pk_mul_f32 v[104:105], v[108:109], v[232:233] op_sel:[0,1] op_sel_hi:[1,1]
	v_pk_mul_f32 v[100:101], v[70:71], v[234:235] op_sel:[0,1] op_sel_hi:[1,1]
	v_pk_fma_f32 v[104:105], v[108:109], v[232:233], v[104:105] op_sel:[0,0,1] op_sel_hi:[1,0,0] neg_lo:[0,0,1]
	v_pk_mul_f32 v[108:109], v[80:81], v[208:209] op_sel:[0,1] op_sel_hi:[1,1]
	v_pk_fma_f32 v[70:71], v[70:71], v[234:235], v[100:101] op_sel:[0,0,1] op_sel_hi:[1,0,0] neg_lo:[0,0,1]
	v_pk_mul_f32 v[100:101], v[82:83], v[210:211] op_sel:[0,1] op_sel_hi:[1,1]
	v_pk_fma_f32 v[108:109], v[80:81], v[208:209], v[108:109] op_sel:[0,0,1] op_sel_hi:[1,0,0] neg_lo:[0,0,1]
	v_pk_mul_f32 v[80:81], v[64:65], v[204:205] op_sel:[0,1] op_sel_hi:[1,1]
; #define LAS __attribute__((address_space(3)))
; __device__ __forceinline__ f32x2 cmul(f32x2 a, f32x2 b) { return (f32x2){a.x * b.x - a.y * b.y, a.x * b.y + a.y * b.x}; }
; template <bool INV> __device__ __forceinline__ void bfly16_tab(f32x2 (&x)[16], const LAS f32x2* T, int tstride, int j) {
;     if (INV) {
; #pragma unroll
;         for (int q = 1; q < 16; ++q) { f32x2 p = T[q * tstride + j]; p.y = -p.y; x[q] = cmul(x[q], p); } }
;     dft16<INV>(x);
;     if (!INV) {
; #pragma unroll
;         for (int r = 1; r < 16; ++r) { const f32x2 p = T[r * tstride + j]; x[4 * (r & 3) + (r >> 2)] = cmul(x[4 * (r & 3) + (r >> 2)], p); } }
; }
; template <bool INV> __device__ __forceinline__ void pass16_s64(LAS f32x2* X, const LAS f32x2* TH, int base, int j) {
;     f32x2 x[16];
; #pragma unroll
;     for (int q = 0; q < 16; ++q) x[q] = X[base + q * 68];
;     bfly16_tab<INV>(x, TH - 2048, 64, j);
; #pragma unroll
;     for (int c = 0; c < 4; ++c)
; #pragma unroll
;         for (int d = 0; d < 4; ++d) X[base + (c + 4 * d) * 68] = x[4 * c + d];
; }
; template <bool INV> __device__ __forceinline__ void pass16(LAS f32x2* X, const LAS f32x2* TH, const LAS f32x2* TL, int base, int stride, int tw) {
;     f32x2 x[16];
; #pragma unroll
;     for (int q = 0; q < 16; ++q) x[q] = X[base + q * stride];
;     bfly16<INV>(x, TH, TL, tw);
; #pragma unroll
;     for (int c = 0; c < 4; ++c)
; #pragma unroll
;         for (int d = 0; d < 4; ++d) X[base + (c + 4 * d) * stride] = x[4 * c + d];
; }
; template <bool INV> __device__ __forceinline__ void pass16_s4(LAS f32x2* X, const LAS f32x2* TH, const LAS f32x2* TL, int tid) {
; #pragma unroll 1
;     for (int s = 0; s < 2; ++s) {
;         const int b = tid + NTHR * s, blk = b >> 2, jj = b & 3;
;         LAS f32x2* P = X + blk * 68 + jj;
;         f32x2 x[16];
; #pragma unroll
;         for (int q = 0; q < 16; ++q) x[q] = P[4 * q];
;         bfly16_tab<INV>(x, TH - 1024, 4, jj);
; #pragma unroll
;         for (int c = 0; c < 4; ++c)
; #pragma unroll
;             for (int d = 0; d < 4; ++d) P[4 * (c + 4 * d)] = x[4 * c + d];
;     }
; }
	v_pk_fma_f32 v[100:101], v[82:83], v[210:211], v[100:101] op_sel:[0,0,1] op_sel_hi:[1,0,0] neg_lo:[0,0,1]
	v_pk_mul_f32 v[82:83], v[96:97], v[206:207] op_sel:[0,1] op_sel_hi:[1,1]
	v_pk_fma_f32 v[80:81], v[64:65], v[204:205], v[80:81] op_sel:[0,0,1] op_sel_hi:[1,0,0] neg_lo:[0,0,1]
	v_pk_mul_f32 v[64:65], v[84:85], v[200:201] op_sel:[0,1] op_sel_hi:[1,1]
	v_pk_fma_f32 v[82:83], v[96:97], v[206:207], v[82:83] op_sel:[0,0,1] op_sel_hi:[1,0,0] neg_lo:[0,0,1]
	v_pk_mul_f32 v[96:97], v[218:219], v[202:203] op_sel:[0,1] op_sel_hi:[1,1]
	v_pk_fma_f32 v[64:65], v[84:85], v[200:201], v[64:65] op_sel:[0,0,1] op_sel_hi:[1,0,0] neg_lo:[0,0,1]
	v_pk_mul_f32 v[84:85], v[102:103], v[196:197] op_sel:[0,1] op_sel_hi:[1,1]
	v_pk_fma_f32 v[96:97], v[218:219], v[202:203], v[96:97] op_sel:[0,0,1] op_sel_hi:[1,0,0] neg_lo:[0,0,1]
	v_pk_mul_f32 v[218:219], v[74:75], v[198:199] op_sel:[0,1] op_sel_hi:[1,1]
	v_pk_fma_f32 v[102:103], v[102:103], v[196:197], v[84:85] op_sel:[0,0,1] op_sel_hi:[1,0,0] neg_lo:[0,0,1]
	v_pk_mul_f32 v[84:85], v[92:93], v[192:193] op_sel:[0,1] op_sel_hi:[1,1]
	v_pk_fma_f32 v[218:219], v[74:75], v[198:199], v[218:219] op_sel:[0,0,1] op_sel_hi:[1,0,0] neg_lo:[0,0,1]
	v_pk_mul_f32 v[74:75], v[88:89], v[194:195] op_sel:[0,1] op_sel_hi:[1,1]
	v_pk_fma_f32 v[92:93], v[92:93], v[192:193], v[84:85] op_sel:[0,0,1] op_sel_hi:[1,0,0] neg_lo:[0,0,1]
	v_pk_mul_f32 v[84:85], v[106:107], v[188:189] op_sel:[0,1] op_sel_hi:[1,1]
	v_pk_fma_f32 v[88:89], v[88:89], v[194:195], v[74:75] op_sel:[0,0,1] op_sel_hi:[1,0,0] neg_lo:[0,0,1]
	v_pk_mul_f32 v[74:75], v[76:77], v[190:191] op_sel:[0,1] op_sel_hi:[1,1]
	v_pk_fma_f32 v[106:107], v[106:107], v[188:189], v[84:85] op_sel:[0,0,1] op_sel_hi:[1,0,0] neg_lo:[0,0,1]
	v_pk_mul_f32 v[84:85], v[94:95], v[222:223] op_sel:[0,1] op_sel_hi:[1,1]
	v_pk_fma_f32 v[76:77], v[76:77], v[190:191], v[74:75] op_sel:[0,0,1] op_sel_hi:[1,0,0] neg_lo:[0,0,1]
	v_pk_fma_f32 v[94:95], v[94:95], v[222:223], v[84:85] op_sel:[0,0,1] op_sel_hi:[1,0,0] neg_lo:[0,0,1]
	ds_write2_b64 v250, v[66:67], v[104:105] offset0:0 offset1:68
	ds_write2_b64 v250, v[70:71], v[108:109] offset0:136 offset1:204
	ds_write2_b64 v251, v[100:101], v[80:81] offset0:16 offset1:84
	ds_write2_b64 v251, v[82:83], v[64:65] offset0:152 offset1:220
	ds_write2_b64 v248, v[96:97], v[102:103] offset0:32 offset1:100
	ds_write2_b64 v248, v[218:219], v[92:93] offset0:168 offset1:236
	ds_write2_b64 v249, v[88:89], v[106:107] offset0:48 offset1:116
	ds_write2_b64 v249, v[76:77], v[94:95] offset0:184 offset1:252
	s_cbranch_scc1 .LBB0_848
	s_waitcnt lgkmcnt(0)
	s_barrier
	s_mov_b32 s0, 0
	s_mov_b64 s[12:13], -1
	ds_read2_b64 v[232:235], v141 offset0:4 offset1:8
	ds_read2_b64 v[208:211], v141 offset0:12 offset1:16
	ds_read2_b64 v[204:207], v141 offset0:20 offset1:24
	ds_read2_b64 v[200:203], v141 offset0:28 offset1:32
	ds_read2_b64 v[196:199], v141 offset0:36 offset1:40
	ds_read2_b64 v[192:195], v141 offset0:44 offset1:48
	ds_read2_b64 v[188:191], v141 offset0:52 offset1:56
	ds_read_b64 v[248:249], v141 offset:480
.LBB0_850:
	v_add_u32_e32 v252, s0, v140
	v_lshrrev_b32_e32 v253, 2, v252
	v_mad_u32_u24 v250, v253, s43, v144
	ds_read2_b64 v[64:67], v250 offset0:0 offset1:4
	ds_read2_b64 v[68:71], v250 offset0:32 offset1:36
	ds_read2_b64 v[72:75], v250 offset0:8 offset1:12
	ds_read2_b64 v[76:79], v250 offset0:40 offset1:44
	ds_read2_b64 v[80:83], v250 offset0:16 offset1:20
	ds_read2_b64 v[84:87], v250 offset0:48 offset1:52
	ds_read2_b64 v[88:91], v250 offset0:24 offset1:28
	ds_read2_b64 v[92:95], v250 offset0:56 offset1:60
	s_cmp_eq_u32 s0, 0
	s_movk_i32 s0, 0x200
	s_mov_b64 s[12:13], 0
	s_waitcnt lgkmcnt(6)
	v_pk_add_f32 v[96:97], v[64:65], v[68:69]
	v_pk_add_f32 v[98:99], v[66:67], v[70:71]
	s_waitcnt lgkmcnt(4)
	v_pk_add_f32 v[100:101], v[72:73], v[76:77]
	v_pk_add_f32 v[102:103], v[74:75], v[78:79]
	v_pk_add_f32 v[64:65], v[64:65], v[68:69] neg_lo:[0,1] neg_hi:[0,1]
	v_pk_add_f32 v[66:67], v[66:67], v[70:71] neg_lo:[0,1] neg_hi:[0,1]
	v_pk_add_f32 v[72:73], v[72:73], v[76:77] neg_lo:[0,1] neg_hi:[0,1]
	v_pk_add_f32 v[74:75], v[74:75], v[78:79] neg_lo:[0,1] neg_hi:[0,1]
	s_waitcnt lgkmcnt(2)
	v_pk_add_f32 v[78:79], v[80:81], v[84:85]
	v_pk_add_f32 v[76:77], v[82:83], v[86:87]
	s_waitcnt lgkmcnt(0)
; #define LAS __attribute__((address_space(3)))
; __device__ __forceinline__ f32x2 cmul(f32x2 a, f32x2 b) { return (f32x2){a.x * b.x - a.y * b.y, a.x * b.y + a.y * b.x}; }
; template <bool INV> __device__ __forceinline__ void bfly16_tab(f32x2 (&x)[16], const LAS f32x2* T, int tstride, int j) {
;     if (INV) {
; #pragma unroll
;         for (int q = 1; q < 16; ++q) { f32x2 p = T[q * tstride + j]; p.y = -p.y; x[q] = cmul(x[q], p); } }
;     dft16<INV>(x);
;     if (!INV) {
; #pragma unroll
;         for (int r = 1; r < 16; ++r) { const f32x2 p = T[r * tstride + j]; x[4 * (r & 3) + (r >> 2)] = cmul(x[4 * (r & 3) + (r >> 2)], p); } }
; }
; template <bool INV> __device__ __forceinline__ void pass16_s4(LAS f32x2* X, const LAS f32x2* TH, const LAS f32x2* TL, int tid) {
; #pragma unroll 1
;     for (int s = 0; s < 2; ++s) {
;         const int b = tid + NTHR * s, blk = b >> 2, jj = b & 3;
;         LAS f32x2* P = X + blk * 68 + jj;
;         f32x2 x[16];
; #pragma unroll
;         for (int q = 0; q < 16; ++q) x[q] = P[4 * q];
;         bfly16_tab<INV>(x, TH - 1024, 4, jj);
; #pragma unroll
;         for (int c = 0; c < 4; ++c)
; #pragma unroll
;             for (int d = 0; d < 4; ++d) P[4 * (c + 4 * d)] = x[4 * c + d];
;     }
; }
	v_pk_add_f32 v[70:71], v[88:89], v[92:93]
	v_pk_add_f32 v[68:69], v[90:91], v[94:95]
	v_pk_add_f32 v[84:85], v[80:81], v[84:85] neg_lo:[0,1] neg_hi:[0,1]
	v_pk_add_f32 v[86:87], v[82:83], v[86:87] neg_lo:[0,1] neg_hi:[0,1]
	v_pk_add_f32 v[92:93], v[88:89], v[92:93] neg_lo:[0,1] neg_hi:[0,1]
	v_pk_add_f32 v[90:91], v[90:91], v[94:95] neg_lo:[0,1] neg_hi:[0,1]
	v_pk_add_f32 v[94:95], v[96:97], v[78:79]
	v_pk_add_f32 v[88:89], v[98:99], v[76:77]
	v_pk_add_f32 v[82:83], v[100:101], v[70:71]
	v_pk_add_f32 v[80:81], v[102:103], v[68:69]
	v_pk_add_f32 v[96:97], v[96:97], v[78:79] neg_lo:[0,1] neg_hi:[0,1]
	v_pk_add_f32 v[98:99], v[98:99], v[76:77] neg_lo:[0,1] neg_hi:[0,1]
	v_pk_add_f32 v[70:71], v[100:101], v[70:71] neg_lo:[0,1] neg_hi:[0,1]
	v_pk_add_f32 v[68:69], v[102:103], v[68:69] neg_lo:[0,1] neg_hi:[0,1]
	v_pk_add_f32 v[102:103], v[64:65], v[84:85] op_sel:[0,1] op_sel_hi:[1,0] neg_hi:[0,1]
	v_pk_add_f32 v[100:101], v[66:67], v[86:87] op_sel:[0,1] op_sel_hi:[1,0] neg_hi:[0,1]
	v_pk_add_f32 v[76:77], v[72:73], v[92:93] op_sel:[0,1] op_sel_hi:[1,0] neg_hi:[0,1]
	v_pk_add_f32 v[78:79], v[74:75], v[90:91] op_sel:[0,1] op_sel_hi:[1,0] neg_hi:[0,1]
	v_pk_add_f32 v[64:65], v[64:65], v[84:85] op_sel:[0,1] op_sel_hi:[1,0] neg_lo:[0,1]
	v_pk_add_f32 v[66:67], v[66:67], v[86:87] op_sel:[0,1] op_sel_hi:[1,0] neg_lo:[0,1]
	v_pk_add_f32 v[92:93], v[72:73], v[92:93] op_sel:[0,1] op_sel_hi:[1,0] neg_lo:[0,1]
	v_pk_add_f32 v[74:75], v[74:75], v[90:91] op_sel:[0,1] op_sel_hi:[1,0] neg_lo:[0,1]
	v_pk_mul_f32 v[90:91], v[100:101], s[70:71] op_sel_hi:[1,0]
	v_pk_mul_f32 v[72:73], v[98:99], s[72:73] op_sel_hi:[1,0]
	v_pk_mul_f32 v[86:87], v[66:67], s[64:65] op_sel_hi:[1,0]
	v_pk_mul_f32 v[84:85], v[76:77], s[72:73] op_sel_hi:[1,0]
	v_pk_mul_f32 v[104:105], v[92:93], s[72:73] op_sel_hi:[1,0]
	v_pk_mul_f32 v[106:107], v[78:79], s[64:65] op_sel_hi:[1,0]
	v_pk_mul_f32 v[218:219], v[68:69], s[72:73] op_sel_hi:[1,0]
	v_pk_mul_f32 v[222:223], v[74:75], s[82:83] op_sel_hi:[1,0]
	v_pk_fma_f32 v[90:91], v[100:101], s[44:45], v[90:91] op_sel:[0,0,1] op_sel_hi:[1,0,0] neg_lo:[0,0,1]
	v_pk_fma_f32 v[98:99], v[98:99], s[76:77], v[72:73] op_sel:[0,0,1] op_sel_hi:[1,0,0] neg_lo:[0,0,1]
	v_pk_fma_f32 v[66:67], v[66:67], s[82:83], v[86:87] op_sel:[0,0,1] op_sel_hi:[1,0,0] neg_lo:[0,0,1]
	v_pk_fma_f32 v[84:85], v[76:77], s[76:77], v[84:85] op_sel:[0,0,1] op_sel_hi:[1,0,0] neg_lo:[0,0,1]
	v_pk_fma_f32 v[104:105], v[92:93], s[72:73], v[104:105] op_sel:[0,0,1] op_sel_hi:[1,0,0] neg_lo:[0,0,1]
	v_pk_fma_f32 v[106:107], v[78:79], s[82:83], v[106:107] op_sel:[0,0,1] op_sel_hi:[1,0,0] neg_lo:[0,0,1]
	v_pk_fma_f32 v[68:69], v[68:69], s[72:73], v[218:219] op_sel:[0,0,1] op_sel_hi:[1,0,0] neg_lo:[0,0,1]
	v_pk_fma_f32 v[222:223], v[74:75], s[64:65], v[222:223] op_sel:[0,0,1] op_sel_hi:[1,0,0] neg_lo:[0,0,1]
	v_pk_add_f32 v[74:75], v[94:95], v[82:83]
	v_pk_add_f32 v[218:219], v[102:103], v[84:85]
	v_pk_add_f32 v[78:79], v[96:97], v[70:71] op_sel:[0,1] op_sel_hi:[1,0] neg_hi:[0,1]
	v_pk_add_f32 v[92:93], v[64:65], v[104:105]
	v_pk_add_f32 v[94:95], v[94:95], v[82:83] neg_lo:[0,1] neg_hi:[0,1]
	v_pk_add_f32 v[102:103], v[102:103], v[84:85] neg_lo:[0,1] neg_hi:[0,1]
	v_pk_add_f32 v[70:71], v[96:97], v[70:71] op_sel:[0,1] op_sel_hi:[1,0] neg_lo:[0,1]
	v_pk_add_f32 v[64:65], v[64:65], v[104:105] neg_lo:[0,1] neg_hi:[0,1]
	v_pk_add_f32 v[104:105], v[88:89], v[80:81]
	v_pk_add_f32 v[96:97], v[90:91], v[106:107]
	v_pk_add_f32 v[84:85], v[98:99], v[68:69]
	v_pk_add_f32 v[82:83], v[66:67], v[222:223]
	v_pk_add_f32 v[80:81], v[88:89], v[80:81] neg_lo:[0,1] neg_hi:[0,1]
	v_pk_add_f32 v[90:91], v[90:91], v[106:107] neg_lo:[0,1] neg_hi:[0,1]
	v_pk_add_f32 v[68:69], v[98:99], v[68:69] neg_lo:[0,1] neg_hi:[0,1]
	v_pk_add_f32 v[66:67], v[66:67], v[222:223] neg_lo:[0,1] neg_hi:[0,1]
	v_pk_add_f32 v[222:223], v[74:75], v[104:105]
	v_pk_add_f32 v[98:99], v[218:219], v[96:97]
	v_pk_add_f32 v[106:107], v[78:79], v[84:85]
	v_pk_add_f32 v[88:89], v[92:93], v[82:83]
	v_pk_add_f32 v[104:105], v[74:75], v[104:105] neg_lo:[0,1] neg_hi:[0,1]
	v_pk_add_f32 v[96:97], v[218:219], v[96:97] neg_lo:[0,1] neg_hi:[0,1]
	v_pk_add_f32 v[84:85], v[78:79], v[84:85] neg_lo:[0,1] neg_hi:[0,1]
	v_pk_add_f32 v[92:93], v[92:93], v[82:83] neg_lo:[0,1] neg_hi:[0,1]
	v_pk_add_f32 v[82:83], v[94:95], v[80:81] op_sel:[0,1] op_sel_hi:[1,0] neg_hi:[0,1]
	v_pk_add_f32 v[78:79], v[102:103], v[90:91] op_sel:[0,1] op_sel_hi:[1,0] neg_hi:[0,1]
	v_pk_add_f32 v[218:219], v[70:71], v[68:69] op_sel:[0,1] op_sel_hi:[1,0] neg_hi:[0,1]
	v_pk_add_f32 v[74:75], v[64:65], v[66:67] op_sel:[0,1] op_sel_hi:[1,0] neg_hi:[0,1]
	v_pk_add_f32 v[94:95], v[94:95], v[80:81] op_sel:[0,1] op_sel_hi:[1,0] neg_lo:[0,1]
	v_pk_add_f32 v[102:103], v[102:103], v[90:91] op_sel:[0,1] op_sel_hi:[1,0] neg_lo:[0,1]
	v_pk_add_f32 v[70:71], v[70:71], v[68:69] op_sel:[0,1] op_sel_hi:[1,0] neg_lo:[0,1]
	v_pk_add_f32 v[64:65], v[64:65], v[66:67] op_sel:[0,1] op_sel_hi:[1,0] neg_lo:[0,1]
	v_pk_mul_f32 v[66:67], v[98:99], v[232:233] op_sel:[0,1] op_sel_hi:[1,1]
	v_pk_mul_f32 v[68:69], v[106:107], v[234:235] op_sel:[0,1] op_sel_hi:[1,1]
	v_pk_fma_f32 v[66:67], v[98:99], v[232:233], v[66:67] op_sel:[0,0,1] op_sel_hi:[1,0,0] neg_lo:[0,0,1]
	v_pk_mul_f32 v[98:99], v[88:89], v[208:209] op_sel:[0,1] op_sel_hi:[1,1]
	v_pk_fma_f32 v[68:69], v[106:107], v[234:235], v[68:69] op_sel:[0,0,1] op_sel_hi:[1,0,0] neg_lo:[0,0,1]
	v_pk_mul_f32 v[106:107], v[82:83], v[210:211] op_sel:[0,1] op_sel_hi:[1,1]
	v_pk_fma_f32 v[88:89], v[88:89], v[208:209], v[98:99] op_sel:[0,0,1] op_sel_hi:[1,0,0] neg_lo:[0,0,1]
	v_pk_mul_f32 v[98:99], v[78:79], v[204:205] op_sel:[0,1] op_sel_hi:[1,1]
; template <bool INV> __device__ __forceinline__ void bfly16_tab(f32x2 (&x)[16], const LAS f32x2* T, int tstride, int j) {
;     if (INV) {
; #pragma unroll
;         for (int q = 1; q < 16; ++q) { f32x2 p = T[q * tstride + j]; p.y = -p.y; x[q] = cmul(x[q], p); } }
;     dft16<INV>(x);
;     if (!INV) {
; #pragma unroll
;         for (int r = 1; r < 16; ++r) { const f32x2 p = T[r * tstride + j]; x[4 * (r & 3) + (r >> 2)] = cmul(x[4 * (r & 3) + (r >> 2)], p); } }
; }
; template <bool INV> __device__ __forceinline__ void pass16_s64(LAS f32x2* X, const LAS f32x2* TH, int base, int j) {
;     f32x2 x[16];
; #pragma unroll
;     for (int q = 0; q < 16; ++q) x[q] = X[base + q * 68];
;     bfly16_tab<INV>(x, TH - 2048, 64, j);
; #pragma unroll
;     for (int c = 0; c < 4; ++c)
; #pragma unroll
;         for (int d = 0; d < 4; ++d) X[base + (c + 4 * d) * 68] = x[4 * c + d];
; }
; template <bool INV> __device__ __forceinline__ void pass16(LAS f32x2* X, const LAS f32x2* TH, const LAS f32x2* TL, int base, int stride, int tw) {
;     f32x2 x[16];
; #pragma unroll
;     for (int q = 0; q < 16; ++q) x[q] = X[base + q * stride];
;     bfly16<INV>(x, TH, TL, tw);
; #pragma unroll
;     for (int c = 0; c < 4; ++c)
; #pragma unroll
;         for (int d = 0; d < 4; ++d) X[base + (c + 4 * d) * stride] = x[4 * c + d];
; }
; template <bool INV> __device__ __forceinline__ void pass16_s4(LAS f32x2* X, const LAS f32x2* TH, const LAS f32x2* TL, int tid) {
; #pragma unroll 1
;     for (int s = 0; s < 2; ++s) {
;         const int b = tid + NTHR * s, blk = b >> 2, jj = b & 3;
;         LAS f32x2* P = X + blk * 68 + jj;
;         f32x2 x[16];
; #pragma unroll
;         for (int q = 0; q < 16; ++q) x[q] = P[4 * q];
;         bfly16_tab<INV>(x, TH - 1024, 4, jj);
; #pragma unroll
;         for (int c = 0; c < 4; ++c)
; #pragma unroll
;             for (int d = 0; d < 4; ++d) P[4 * (c + 4 * d)] = x[4 * c + d];
; __device__ __forceinline__ void hyena_latent(Frame& F, int l, int ch, LAS f32x2* X, const LAS f32x2* TH, const LAS f32x2* TL, GAS f32x2* KS, const LAS float* CT  , bool wr = true) {
;     ...
;             for (int i = 0; i < 8; ++i) { const int b = LT() + NTHR * i; const LAS f32x4* P = (const LAS f32x4*)(X + 4 * b + ((b >> 4) << 2)); const f32x4 u = P[0], v = P[1];
;                 f32x2 x0 = {u.x, u.y}, x1 = {u.z, u.w}, x2 = {v.x, v.y}, x3 = {v.z, v.w}; r4<false>(x0, x1, x2, x3);
	v_pk_fma_f32 v[82:83], v[82:83], v[210:211], v[106:107] op_sel:[0,0,1] op_sel_hi:[1,0,0] neg_lo:[0,0,1]
	v_pk_mul_f32 v[106:107], v[218:219], v[206:207] op_sel:[0,1] op_sel_hi:[1,1]
	v_pk_fma_f32 v[98:99], v[78:79], v[204:205], v[98:99] op_sel:[0,0,1] op_sel_hi:[1,0,0] neg_lo:[0,0,1]
	v_pk_mul_f32 v[78:79], v[74:75], v[200:201] op_sel:[0,1] op_sel_hi:[1,1]
	v_pk_fma_f32 v[218:219], v[218:219], v[206:207], v[106:107] op_sel:[0,0,1] op_sel_hi:[1,0,0] neg_lo:[0,0,1]
	v_pk_mul_f32 v[106:107], v[104:105], v[202:203] op_sel:[0,1] op_sel_hi:[1,1]
	v_pk_fma_f32 v[78:79], v[74:75], v[200:201], v[78:79] op_sel:[0,0,1] op_sel_hi:[1,0,0] neg_lo:[0,0,1]
	v_pk_mul_f32 v[74:75], v[96:97], v[196:197] op_sel:[0,1] op_sel_hi:[1,1]
	v_pk_fma_f32 v[104:105], v[104:105], v[202:203], v[106:107] op_sel:[0,0,1] op_sel_hi:[1,0,0] neg_lo:[0,0,1]
	v_pk_mul_f32 v[106:107], v[84:85], v[198:199] op_sel:[0,1] op_sel_hi:[1,1]
	v_pk_fma_f32 v[96:97], v[96:97], v[196:197], v[74:75] op_sel:[0,0,1] op_sel_hi:[1,0,0] neg_lo:[0,0,1]
	v_pk_mul_f32 v[74:75], v[92:93], v[192:193] op_sel:[0,1] op_sel_hi:[1,1]
	v_pk_fma_f32 v[84:85], v[84:85], v[198:199], v[106:107] op_sel:[0,0,1] op_sel_hi:[1,0,0] neg_lo:[0,0,1]
	v_pk_mul_f32 v[106:107], v[94:95], v[194:195] op_sel:[0,1] op_sel_hi:[1,1]
	v_pk_fma_f32 v[74:75], v[92:93], v[192:193], v[74:75] op_sel:[0,0,1] op_sel_hi:[1,0,0] neg_lo:[0,0,1]
	v_pk_mul_f32 v[92:93], v[102:103], v[188:189] op_sel:[0,1] op_sel_hi:[1,1]
	v_pk_fma_f32 v[106:107], v[94:95], v[194:195], v[106:107] op_sel:[0,0,1] op_sel_hi:[1,0,0] neg_lo:[0,0,1]
	v_pk_mul_f32 v[94:95], v[70:71], v[190:191] op_sel:[0,1] op_sel_hi:[1,1]
	v_pk_fma_f32 v[92:93], v[102:103], v[188:189], v[92:93] op_sel:[0,0,1] op_sel_hi:[1,0,0] neg_lo:[0,0,1]
	v_pk_mul_f32 v[102:103], v[64:65], v[248:249] op_sel:[0,1] op_sel_hi:[1,1]
	v_pk_fma_f32 v[94:95], v[70:71], v[190:191], v[94:95] op_sel:[0,0,1] op_sel_hi:[1,0,0] neg_lo:[0,0,1]
	v_pk_fma_f32 v[64:65], v[64:65], v[248:249], v[102:103] op_sel:[0,0,1] op_sel_hi:[1,0,0] neg_lo:[0,0,1]
	ds_write2_b64 v250, v[222:223], v[66:67] offset0:0 offset1:4
	ds_write2_b64 v250, v[68:69], v[88:89] offset0:8 offset1:12
	ds_write2_b64 v250, v[82:83], v[98:99] offset0:16 offset1:20
	ds_write2_b64 v250, v[218:219], v[78:79] offset0:24 offset1:28
	ds_write2_b64 v250, v[104:105], v[96:97] offset0:32 offset1:36
	ds_write2_b64 v250, v[84:85], v[74:75] offset0:40 offset1:44
	ds_write2_b64 v250, v[106:107], v[92:93] offset0:48 offset1:52
	ds_write2_b64 v250, v[94:95], v[64:65] offset0:56 offset1:60
	s_cbranch_scc1 .LBB0_850
	v_pk_add_f32 v[68:69], v[56:57], v[60:61]
	v_pk_add_f32 v[56:57], v[56:57], v[60:61] neg_lo:[0,1] neg_hi:[0,1]
	v_pk_add_f32 v[60:61], v[58:59], v[62:63]
	v_pk_add_f32 v[58:59], v[58:59], v[62:63] neg_lo:[0,1] neg_hi:[0,1]
	v_pk_add_f32 v[66:67], v[68:69], v[60:61]
	v_xor_b32_e32 v71, 0x80000000, v58
	v_mov_b32_e32 v70, v59
	v_pk_add_f32 v[62:63], v[68:69], v[60:61] neg_lo:[0,1] neg_hi:[0,1]
	v_pk_add_f32 v[68:69], v[48:49], v[52:53]
	v_pk_add_f32 v[48:49], v[48:49], v[52:53] neg_lo:[0,1] neg_hi:[0,1]
	v_pk_add_f32 v[52:53], v[50:51], v[54:55]
	v_pk_add_f32 v[50:51], v[50:51], v[54:55] neg_lo:[0,1] neg_hi:[0,1]
	v_pk_add_f32 v[64:65], v[56:57], v[70:71]
	v_pk_add_f32 v[60:61], v[56:57], v[70:71] neg_lo:[0,1] neg_hi:[0,1]
	v_xor_b32_e32 v71, 0x80000000, v50
	v_mov_b32_e32 v70, v51
	v_pk_add_f32 v[58:59], v[68:69], v[52:53]
	v_pk_add_f32 v[54:55], v[68:69], v[52:53] neg_lo:[0,1] neg_hi:[0,1]
	v_pk_add_f32 v[68:69], v[40:41], v[44:45]
	v_pk_add_f32 v[40:41], v[40:41], v[44:45] neg_lo:[0,1] neg_hi:[0,1]
	v_pk_add_f32 v[44:45], v[42:43], v[46:47]
	v_pk_add_f32 v[42:43], v[42:43], v[46:47] neg_lo:[0,1] neg_hi:[0,1]
	v_pk_add_f32 v[56:57], v[48:49], v[70:71]
	v_pk_add_f32 v[52:53], v[48:49], v[70:71] neg_lo:[0,1] neg_hi:[0,1]
	v_xor_b32_e32 v71, 0x80000000, v42
	v_mov_b32_e32 v70, v43
	v_pk_add_f32 v[50:51], v[68:69], v[44:45]
	v_pk_add_f32 v[46:47], v[68:69], v[44:45] neg_lo:[0,1] neg_hi:[0,1]
	v_pk_add_f32 v[68:69], v[32:33], v[36:37]
	v_pk_add_f32 v[32:33], v[32:33], v[36:37] neg_lo:[0,1] neg_hi:[0,1]
	v_pk_add_f32 v[36:37], v[34:35], v[38:39]
	v_pk_add_f32 v[34:35], v[34:35], v[38:39] neg_lo:[0,1] neg_hi:[0,1]
	v_pk_add_f32 v[48:49], v[40:41], v[70:71]
	v_pk_add_f32 v[44:45], v[40:41], v[70:71] neg_lo:[0,1] neg_hi:[0,1]
	v_xor_b32_e32 v71, 0x80000000, v34
	v_mov_b32_e32 v70, v35
	v_pk_add_f32 v[42:43], v[68:69], v[36:37]
	v_pk_add_f32 v[38:39], v[68:69], v[36:37] neg_lo:[0,1] neg_hi:[0,1]
	v_pk_add_f32 v[68:69], v[24:25], v[28:29]
	v_pk_add_f32 v[24:25], v[24:25], v[28:29] neg_lo:[0,1] neg_hi:[0,1]
	v_pk_add_f32 v[28:29], v[26:27], v[30:31]
	v_pk_add_f32 v[26:27], v[26:27], v[30:31] neg_lo:[0,1] neg_hi:[0,1]
	v_pk_add_f32 v[40:41], v[32:33], v[70:71]
	v_pk_add_f32 v[36:37], v[32:33], v[70:71] neg_lo:[0,1] neg_hi:[0,1]
	v_xor_b32_e32 v71, 0x80000000, v26
	v_mov_b32_e32 v70, v27
	v_pk_add_f32 v[34:35], v[68:69], v[28:29]
	v_pk_add_f32 v[30:31], v[68:69], v[28:29] neg_lo:[0,1] neg_hi:[0,1]
	v_pk_add_f32 v[68:69], v[12:13], v[20:21]
	v_pk_add_f32 v[12:13], v[12:13], v[20:21] neg_lo:[0,1] neg_hi:[0,1]
	v_pk_add_f32 v[20:21], v[14:15], v[22:23]
	v_pk_add_f32 v[14:15], v[14:15], v[22:23] neg_lo:[0,1] neg_hi:[0,1]
	v_pk_add_f32 v[32:33], v[24:25], v[70:71]
	v_pk_add_f32 v[28:29], v[24:25], v[70:71] neg_lo:[0,1] neg_hi:[0,1]
	v_xor_b32_e32 v71, 0x80000000, v14
	v_mov_b32_e32 v70, v15
	v_pk_add_f32 v[14:15], v[6:7], v[18:19]
	v_pk_add_f32 v[6:7], v[6:7], v[18:19] neg_lo:[0,1] neg_hi:[0,1]
	v_pk_add_f32 v[26:27], v[68:69], v[20:21]
	v_pk_add_f32 v[24:25], v[12:13], v[70:71]
	v_pk_add_f32 v[22:23], v[68:69], v[20:21] neg_lo:[0,1] neg_hi:[0,1]
	v_pk_add_f32 v[20:21], v[12:13], v[70:71] neg_lo:[0,1] neg_hi:[0,1]
	v_pk_add_f32 v[12:13], v[4:5], v[16:17]
	v_pk_add_f32 v[4:5], v[4:5], v[16:17] neg_lo:[0,1] neg_hi:[0,1]
	v_xor_b32_e32 v69, 0x80000000, v6
	v_mov_b32_e32 v68, v7
	v_pk_add_f32 v[18:19], v[12:13], v[14:15]
	v_pk_add_f32 v[16:17], v[4:5], v[68:69]
	v_pk_add_f32 v[14:15], v[12:13], v[14:15] neg_lo:[0,1] neg_hi:[0,1]
	v_pk_add_f32 v[12:13], v[4:5], v[68:69] neg_lo:[0,1] neg_hi:[0,1]
	v_pk_add_f32 v[68:69], v[0:1], v[8:9]
	v_pk_add_f32 v[0:1], v[0:1], v[8:9] neg_lo:[0,1] neg_hi:[0,1]
	v_pk_add_f32 v[8:9], v[2:3], v[10:11]
	v_pk_add_f32 v[2:3], v[2:3], v[10:11] neg_lo:[0,1] neg_hi:[0,1]
	v_pk_add_f32 v[6:7], v[68:69], v[8:9]
	v_xor_b32_e32 v11, 0x80000000, v2
	v_mov_b32_e32 v10, v3
	v_pk_add_f32 v[2:3], v[68:69], v[8:9] neg_lo:[0,1] neg_hi:[0,1]
	v_mov_b32_e32 v8, v140
	s_waitcnt lgkmcnt(0)
	s_barrier
; #define LAS __attribute__((address_space(3)))
; __device__ __forceinline__ f32x2 cmul(f32x2 a, f32x2 b) { return (f32x2){a.x * b.x - a.y * b.y, a.x * b.y + a.y * b.x}; }
; #define LT() ({ int lt_ = tid; asm volatile("" : "+v"(lt_)); lt_; })
; __device__ __forceinline__ void hyena_latent(Frame& F, int l, int ch, LAS f32x2* X, const LAS f32x2* TH, const LAS f32x2* TL, GAS f32x2* KS, const LAS float* CT  , bool wr = true) {
;     ...
;             fft_fwd_head(X, TH, TL, tid);
; #pragma unroll
;             for (int i = 0; i < 8; ++i) { const int b = LT() + NTHR * i; LAS f32x4* P = (LAS f32x4*)(X + 4 * b + ((b >> 4) << 2)); const f32x4 u = P[0], v = P[1], k0 = kreg[2 * i], k1 = kreg[2 * i + 1];
;                 f32x2 x0 = {u.x, u.y}, x1 = {u.z, u.w}, x2 = {v.x, v.y}, x3 = {v.z, v.w}; r4<false>(x0, x1, x2, x3);
;                 x0 = cmul(x0, (f32x2){k0.x, k0.y}); x1 = cmul(x1, (f32x2){k0.z, k0.w}); x2 = cmul(x2, (f32x2){k1.x, k1.y}); x3 = cmul(x3, (f32x2){k1.z, k1.w});
;                 r4<true>(x0, x1, x2, x3);
;                 P[0] = (f32x4){x0.x, x0.y, x1.x, x1.y}; P[1] = (f32x4){x2.x, x2.y, x3.x, x3.y};
;                 if (i & 1) asm volatile("" ::: "memory"); }
	v_pk_add_f32 v[4:5], v[0:1], v[10:11]
	v_lshlrev_b32_e32 v9, 5, v8
	v_lshlrev_b32_e32 v8, 1, v8
	v_and_b32_e32 v8, 0xffffffe0, v8
	v_add3_u32 v76, 0, v9, v8
	v_pk_add_f32 v[0:1], v[0:1], v[10:11] neg_lo:[0,1] neg_hi:[0,1]
	ds_read_b128 v[8:11], v76
	ds_read_b128 v[68:71], v76 offset:16
	s_mov_b32 s0, 0
	s_mov_b64 s[12:13], -1
	s_waitcnt lgkmcnt(0)
	v_pk_add_f32 v[72:73], v[8:9], v[68:69]
	v_pk_add_f32 v[8:9], v[8:9], v[68:69] neg_lo:[0,1] neg_hi:[0,1]
	v_pk_add_f32 v[68:69], v[10:11], v[70:71]
	v_pk_add_f32 v[10:11], v[10:11], v[70:71] neg_lo:[0,1] neg_hi:[0,1]
	s_nop 0
	v_xor_b32_e32 v71, 0x80000000, v10
	v_mov_b32_e32 v70, v11
	v_pk_add_f32 v[10:11], v[72:73], v[68:69]
	v_pk_add_f32 v[74:75], v[8:9], v[70:71]
	v_pk_add_f32 v[8:9], v[8:9], v[70:71] neg_lo:[0,1] neg_hi:[0,1]
	v_pk_mul_f32 v[70:71], v[66:67], v[10:11] op_sel:[1,1] op_sel_hi:[0,1]
	v_pk_add_f32 v[68:69], v[72:73], v[68:69] neg_lo:[0,1] neg_hi:[0,1]
	v_pk_fma_f32 v[72:73], v[66:67], v[10:11], v[70:71] neg_lo:[0,0,1] neg_hi:[0,0,1]
	v_pk_fma_f32 v[10:11], v[66:67], v[10:11], v[70:71] op_sel_hi:[1,0,1]
	s_nop 0
	v_mov_b32_e32 v73, v11
	v_pk_mul_f32 v[10:11], v[64:65], v[74:75] op_sel:[1,1] op_sel_hi:[0,1]
	v_pk_fma_f32 v[66:67], v[64:65], v[74:75], v[10:11] neg_lo:[0,0,1] neg_hi:[0,0,1]
	v_pk_fma_f32 v[10:11], v[64:65], v[74:75], v[10:11] op_sel_hi:[1,0,1]
	s_nop 0
	v_mov_b32_e32 v67, v11
	v_pk_mul_f32 v[10:11], v[62:63], v[68:69] op_sel:[1,1] op_sel_hi:[0,1]
	v_pk_fma_f32 v[64:65], v[62:63], v[68:69], v[10:11] neg_lo:[0,0,1] neg_hi:[0,0,1]
	v_pk_fma_f32 v[10:11], v[62:63], v[68:69], v[10:11] op_sel_hi:[1,0,1]
	s_nop 0
	v_mov_b32_e32 v65, v11
	v_pk_mul_f32 v[10:11], v[60:61], v[8:9] op_sel:[1,1] op_sel_hi:[0,1]
	v_pk_fma_f32 v[62:63], v[60:61], v[8:9], v[10:11] neg_lo:[0,0,1] neg_hi:[0,0,1]
	v_pk_fma_f32 v[8:9], v[60:61], v[8:9], v[10:11] op_sel_hi:[1,0,1]
	v_pk_add_f32 v[60:61], v[72:73], v[64:65]
	v_mov_b32_e32 v63, v9
	v_pk_add_f32 v[8:9], v[66:67], v[62:63] neg_lo:[0,1] neg_hi:[0,1]
	v_pk_add_f32 v[64:65], v[72:73], v[64:65] neg_lo:[0,1] neg_hi:[0,1]
	v_pk_add_f32 v[68:69], v[66:67], v[62:63]
	v_xor_b32_e32 v62, 0x80000000, v9
	v_mov_b32_e32 v63, v8
	v_pk_add_f32 v[8:9], v[60:61], v[68:69]
	v_pk_add_f32 v[10:11], v[64:65], v[62:63]
	v_pk_add_f32 v[60:61], v[60:61], v[68:69] neg_lo:[0,1] neg_hi:[0,1]
	v_pk_add_f32 v[62:63], v[64:65], v[62:63] neg_lo:[0,1] neg_hi:[0,1]
	ds_write_b128 v76, v[8:11]
	ds_write_b128 v76, v[60:63] offset:16
	v_mov_b32_e32 v8, v140
	s_nop 0
	v_add_u32_e32 v8, 0x200, v8
	v_lshlrev_b32_e32 v9, 5, v8
	v_lshlrev_b32_e32 v8, 1, v8
	v_and_b32_e32 v8, 0xffffffe0, v8
	v_add3_u32 v68, 0, v9, v8
	ds_read_b128 v[8:11], v68
	ds_read_b128 v[60:63], v68 offset:16
	s_waitcnt lgkmcnt(0)
	v_pk_add_f32 v[64:65], v[8:9], v[60:61]
	v_pk_add_f32 v[8:9], v[8:9], v[60:61] neg_lo:[0,1] neg_hi:[0,1]
	v_pk_add_f32 v[60:61], v[10:11], v[62:63]
	v_pk_add_f32 v[10:11], v[10:11], v[62:63] neg_lo:[0,1] neg_hi:[0,1]
	s_nop 0
	v_xor_b32_e32 v63, 0x80000000, v10
	v_mov_b32_e32 v62, v11
	v_pk_add_f32 v[10:11], v[64:65], v[60:61]
	v_pk_add_f32 v[66:67], v[8:9], v[62:63]
	v_pk_add_f32 v[8:9], v[8:9], v[62:63] neg_lo:[0,1] neg_hi:[0,1]
	v_pk_mul_f32 v[62:63], v[58:59], v[10:11] op_sel:[1,1] op_sel_hi:[0,1]
	v_pk_add_f32 v[60:61], v[64:65], v[60:61] neg_lo:[0,1] neg_hi:[0,1]
	v_pk_fma_f32 v[64:65], v[58:59], v[10:11], v[62:63] neg_lo:[0,0,1] neg_hi:[0,0,1]
	v_pk_fma_f32 v[10:11], v[58:59], v[10:11], v[62:63] op_sel_hi:[1,0,1]
	s_nop 0
	v_mov_b32_e32 v65, v11
	v_pk_mul_f32 v[10:11], v[56:57], v[66:67] op_sel:[1,1] op_sel_hi:[0,1]
	v_pk_fma_f32 v[58:59], v[56:57], v[66:67], v[10:11] neg_lo:[0,0,1] neg_hi:[0,0,1]
	v_pk_fma_f32 v[10:11], v[56:57], v[66:67], v[10:11] op_sel_hi:[1,0,1]
	s_nop 0
	v_mov_b32_e32 v59, v11
	v_pk_mul_f32 v[10:11], v[54:55], v[60:61] op_sel:[1,1] op_sel_hi:[0,1]
	v_pk_fma_f32 v[56:57], v[54:55], v[60:61], v[10:11] neg_lo:[0,0,1] neg_hi:[0,0,1]
	v_pk_fma_f32 v[10:11], v[54:55], v[60:61], v[10:11] op_sel_hi:[1,0,1]
	s_nop 0
	v_mov_b32_e32 v57, v11
	v_pk_mul_f32 v[10:11], v[52:53], v[8:9] op_sel:[1,1] op_sel_hi:[0,1]
	v_pk_fma_f32 v[54:55], v[52:53], v[8:9], v[10:11] neg_lo:[0,0,1] neg_hi:[0,0,1]
	v_pk_fma_f32 v[8:9], v[52:53], v[8:9], v[10:11] op_sel_hi:[1,0,1]
	v_pk_add_f32 v[52:53], v[64:65], v[56:57]
	v_mov_b32_e32 v55, v9
	v_pk_add_f32 v[8:9], v[58:59], v[54:55] neg_lo:[0,1] neg_hi:[0,1]
	v_pk_add_f32 v[56:57], v[64:65], v[56:57] neg_lo:[0,1] neg_hi:[0,1]
	v_pk_add_f32 v[60:61], v[58:59], v[54:55]
	v_xor_b32_e32 v54, 0x80000000, v9
	v_mov_b32_e32 v55, v8
	v_pk_add_f32 v[8:9], v[52:53], v[60:61]
	v_pk_add_f32 v[10:11], v[56:57], v[54:55]
	v_pk_add_f32 v[52:53], v[52:53], v[60:61] neg_lo:[0,1] neg_hi:[0,1]
	v_pk_add_f32 v[54:55], v[56:57], v[54:55] neg_lo:[0,1] neg_hi:[0,1]
	ds_write_b128 v68, v[8:11]
	ds_write_b128 v68, v[52:55] offset:16
	v_mov_b32_e32 v8, v140
	s_nop 0
	v_add_u32_e32 v8, 0x400, v8
	v_lshlrev_b32_e32 v9, 5, v8
	v_lshlrev_b32_e32 v8, 1, v8
	v_and_b32_e32 v8, 0xffffffe0, v8
	v_add3_u32 v60, 0, v9, v8
	ds_read_b128 v[8:11], v60
	ds_read_b128 v[52:55], v60 offset:16
	s_waitcnt lgkmcnt(0)
; #define LAS __attribute__((address_space(3)))
; __device__ __forceinline__ f32x2 cmul(f32x2 a, f32x2 b) { return (f32x2){a.x * b.x - a.y * b.y, a.x * b.y + a.y * b.x}; }
; #define LT() ({ int lt_ = tid; asm volatile("" : "+v"(lt_)); lt_; })
; __device__ __forceinline__ void hyena_latent(Frame& F, int l, int ch, LAS f32x2* X, const LAS f32x2* TH, const LAS f32x2* TL, GAS f32x2* KS, const LAS float* CT  , bool wr = true) {
;     ...
;             fft_fwd_head(X, TH, TL, tid);
; #pragma unroll
;             for (int i = 0; i < 8; ++i) { const int b = LT() + NTHR * i; LAS f32x4* P = (LAS f32x4*)(X + 4 * b + ((b >> 4) << 2)); const f32x4 u = P[0], v = P[1], k0 = kreg[2 * i], k1 = kreg[2 * i + 1];
;                 f32x2 x0 = {u.x, u.y}, x1 = {u.z, u.w}, x2 = {v.x, v.y}, x3 = {v.z, v.w}; r4<false>(x0, x1, x2, x3);
;                 x0 = cmul(x0, (f32x2){k0.x, k0.y}); x1 = cmul(x1, (f32x2){k0.z, k0.w}); x2 = cmul(x2, (f32x2){k1.x, k1.y}); x3 = cmul(x3, (f32x2){k1.z, k1.w});
;                 r4<true>(x0, x1, x2, x3);
;                 P[0] = (f32x4){x0.x, x0.y, x1.x, x1.y}; P[1] = (f32x4){x2.x, x2.y, x3.x, x3.y};
;                 if (i & 1) asm volatile("" ::: "memory"); }
	v_pk_add_f32 v[56:57], v[8:9], v[52:53]
	v_pk_add_f32 v[8:9], v[8:9], v[52:53] neg_lo:[0,1] neg_hi:[0,1]
	v_pk_add_f32 v[52:53], v[10:11], v[54:55]
	v_pk_add_f32 v[10:11], v[10:11], v[54:55] neg_lo:[0,1] neg_hi:[0,1]
	s_nop 0
	v_xor_b32_e32 v55, 0x80000000, v10
	v_mov_b32_e32 v54, v11
	v_pk_add_f32 v[10:11], v[56:57], v[52:53]
	v_pk_add_f32 v[58:59], v[8:9], v[54:55]
	v_pk_add_f32 v[8:9], v[8:9], v[54:55] neg_lo:[0,1] neg_hi:[0,1]
	v_pk_mul_f32 v[54:55], v[50:51], v[10:11] op_sel:[1,1] op_sel_hi:[0,1]
	v_pk_add_f32 v[52:53], v[56:57], v[52:53] neg_lo:[0,1] neg_hi:[0,1]
	v_pk_fma_f32 v[56:57], v[50:51], v[10:11], v[54:55] neg_lo:[0,0,1] neg_hi:[0,0,1]
	v_pk_fma_f32 v[10:11], v[50:51], v[10:11], v[54:55] op_sel_hi:[1,0,1]
	s_nop 0
	v_mov_b32_e32 v57, v11
	v_pk_mul_f32 v[10:11], v[48:49], v[58:59] op_sel:[1,1] op_sel_hi:[0,1]
	v_pk_fma_f32 v[50:51], v[48:49], v[58:59], v[10:11] neg_lo:[0,0,1] neg_hi:[0,0,1]
	v_pk_fma_f32 v[10:11], v[48:49], v[58:59], v[10:11] op_sel_hi:[1,0,1]
	s_nop 0
	v_mov_b32_e32 v51, v11
	v_pk_mul_f32 v[10:11], v[46:47], v[52:53] op_sel:[1,1] op_sel_hi:[0,1]
	v_pk_fma_f32 v[48:49], v[46:47], v[52:53], v[10:11] neg_lo:[0,0,1] neg_hi:[0,0,1]
	v_pk_fma_f32 v[10:11], v[46:47], v[52:53], v[10:11] op_sel_hi:[1,0,1]
	s_nop 0
	v_mov_b32_e32 v49, v11
	v_pk_mul_f32 v[10:11], v[44:45], v[8:9] op_sel:[1,1] op_sel_hi:[0,1]
	v_pk_fma_f32 v[46:47], v[44:45], v[8:9], v[10:11] neg_lo:[0,0,1] neg_hi:[0,0,1]
	v_pk_fma_f32 v[8:9], v[44:45], v[8:9], v[10:11] op_sel_hi:[1,0,1]
	v_pk_add_f32 v[44:45], v[56:57], v[48:49]
	v_mov_b32_e32 v47, v9
	v_pk_add_f32 v[8:9], v[50:51], v[46:47] neg_lo:[0,1] neg_hi:[0,1]
	v_pk_add_f32 v[48:49], v[56:57], v[48:49] neg_lo:[0,1] neg_hi:[0,1]
	v_pk_add_f32 v[52:53], v[50:51], v[46:47]
	v_xor_b32_e32 v46, 0x80000000, v9
	v_mov_b32_e32 v47, v8
	v_pk_add_f32 v[8:9], v[44:45], v[52:53]
	v_pk_add_f32 v[10:11], v[48:49], v[46:47]
	v_pk_add_f32 v[44:45], v[44:45], v[52:53] neg_lo:[0,1] neg_hi:[0,1]
	v_pk_add_f32 v[46:47], v[48:49], v[46:47] neg_lo:[0,1] neg_hi:[0,1]
	ds_write_b128 v60, v[8:11]
	ds_write_b128 v60, v[44:47] offset:16
	v_mov_b32_e32 v8, v140
	s_nop 0
	v_add_u32_e32 v8, 0x600, v8
	v_lshlrev_b32_e32 v9, 5, v8
	v_lshlrev_b32_e32 v8, 1, v8
	v_and_b32_e32 v8, 0xffffffe0, v8
	v_add3_u32 v52, 0, v9, v8
	ds_read_b128 v[8:11], v52
	ds_read_b128 v[44:47], v52 offset:16
	s_waitcnt lgkmcnt(0)
	v_pk_add_f32 v[48:49], v[8:9], v[44:45]
	v_pk_add_f32 v[8:9], v[8:9], v[44:45] neg_lo:[0,1] neg_hi:[0,1]
	v_pk_add_f32 v[44:45], v[10:11], v[46:47]
	v_pk_add_f32 v[10:11], v[10:11], v[46:47] neg_lo:[0,1] neg_hi:[0,1]
	s_nop 0
	v_xor_b32_e32 v47, 0x80000000, v10
	v_mov_b32_e32 v46, v11
	v_pk_add_f32 v[10:11], v[48:49], v[44:45]
	v_pk_add_f32 v[50:51], v[8:9], v[46:47]
	v_pk_add_f32 v[8:9], v[8:9], v[46:47] neg_lo:[0,1] neg_hi:[0,1]
	v_pk_mul_f32 v[46:47], v[42:43], v[10:11] op_sel:[1,1] op_sel_hi:[0,1]
	v_pk_add_f32 v[44:45], v[48:49], v[44:45] neg_lo:[0,1] neg_hi:[0,1]
	v_pk_fma_f32 v[48:49], v[42:43], v[10:11], v[46:47] neg_lo:[0,0,1] neg_hi:[0,0,1]
	v_pk_fma_f32 v[10:11], v[42:43], v[10:11], v[46:47] op_sel_hi:[1,0,1]
	s_nop 0
	v_mov_b32_e32 v49, v11
	v_pk_mul_f32 v[10:11], v[40:41], v[50:51] op_sel:[1,1] op_sel_hi:[0,1]
	v_pk_fma_f32 v[42:43], v[40:41], v[50:51], v[10:11] neg_lo:[0,0,1] neg_hi:[0,0,1]
	v_pk_fma_f32 v[10:11], v[40:41], v[50:51], v[10:11] op_sel_hi:[1,0,1]
	s_nop 0
	v_mov_b32_e32 v43, v11
	v_pk_mul_f32 v[10:11], v[38:39], v[44:45] op_sel:[1,1] op_sel_hi:[0,1]
	v_pk_fma_f32 v[40:41], v[38:39], v[44:45], v[10:11] neg_lo:[0,0,1] neg_hi:[0,0,1]
	v_pk_fma_f32 v[10:11], v[38:39], v[44:45], v[10:11] op_sel_hi:[1,0,1]
	s_nop 0
	v_mov_b32_e32 v41, v11
	v_pk_mul_f32 v[10:11], v[36:37], v[8:9] op_sel:[1,1] op_sel_hi:[0,1]
	v_pk_fma_f32 v[38:39], v[36:37], v[8:9], v[10:11] neg_lo:[0,0,1] neg_hi:[0,0,1]
	v_pk_fma_f32 v[8:9], v[36:37], v[8:9], v[10:11] op_sel_hi:[1,0,1]
	v_pk_add_f32 v[36:37], v[48:49], v[40:41]
	v_mov_b32_e32 v39, v9
	v_pk_add_f32 v[8:9], v[42:43], v[38:39] neg_lo:[0,1] neg_hi:[0,1]
	v_pk_add_f32 v[40:41], v[48:49], v[40:41] neg_lo:[0,1] neg_hi:[0,1]
	v_pk_add_f32 v[44:45], v[42:43], v[38:39]
	v_xor_b32_e32 v38, 0x80000000, v9
	v_mov_b32_e32 v39, v8
	v_pk_add_f32 v[8:9], v[36:37], v[44:45]
	v_pk_add_f32 v[10:11], v[40:41], v[38:39]
	v_pk_add_f32 v[36:37], v[36:37], v[44:45] neg_lo:[0,1] neg_hi:[0,1]
	v_pk_add_f32 v[38:39], v[40:41], v[38:39] neg_lo:[0,1] neg_hi:[0,1]
	ds_write_b128 v52, v[8:11]
	ds_write_b128 v52, v[36:39] offset:16
	v_mov_b32_e32 v8, v140
	s_nop 0
	v_add_u32_e32 v8, 0x800, v8
	v_lshlrev_b32_e32 v9, 5, v8
	v_lshlrev_b32_e32 v8, 1, v8
	v_and_b32_e32 v8, 0xffffffe0, v8
	v_add3_u32 v44, 0, v9, v8
	ds_read_b128 v[8:11], v44
	ds_read_b128 v[36:39], v44 offset:16
	s_waitcnt lgkmcnt(0)
; #define LAS __attribute__((address_space(3)))
; __device__ __forceinline__ f32x2 cmul(f32x2 a, f32x2 b) { return (f32x2){a.x * b.x - a.y * b.y, a.x * b.y + a.y * b.x}; }
; #define LT() ({ int lt_ = tid; asm volatile("" : "+v"(lt_)); lt_; })
; __device__ __forceinline__ void hyena_latent(Frame& F, int l, int ch, LAS f32x2* X, const LAS f32x2* TH, const LAS f32x2* TL, GAS f32x2* KS, const LAS float* CT  , bool wr = true) {
;     ...
;             fft_fwd_head(X, TH, TL, tid);
; #pragma unroll
;             for (int i = 0; i < 8; ++i) { const int b = LT() + NTHR * i; LAS f32x4* P = (LAS f32x4*)(X + 4 * b + ((b >> 4) << 2)); const f32x4 u = P[0], v = P[1], k0 = kreg[2 * i], k1 = kreg[2 * i + 1];
;                 f32x2 x0 = {u.x, u.y}, x1 = {u.z, u.w}, x2 = {v.x, v.y}, x3 = {v.z, v.w}; r4<false>(x0, x1, x2, x3);
;                 x0 = cmul(x0, (f32x2){k0.x, k0.y}); x1 = cmul(x1, (f32x2){k0.z, k0.w}); x2 = cmul(x2, (f32x2){k1.x, k1.y}); x3 = cmul(x3, (f32x2){k1.z, k1.w});
;                 r4<true>(x0, x1, x2, x3);
;                 P[0] = (f32x4){x0.x, x0.y, x1.x, x1.y}; P[1] = (f32x4){x2.x, x2.y, x3.x, x3.y};
;                 if (i & 1) asm volatile("" ::: "memory"); }
	v_pk_add_f32 v[40:41], v[8:9], v[36:37]
	v_pk_add_f32 v[8:9], v[8:9], v[36:37] neg_lo:[0,1] neg_hi:[0,1]
	v_pk_add_f32 v[36:37], v[10:11], v[38:39]
	v_pk_add_f32 v[10:11], v[10:11], v[38:39] neg_lo:[0,1] neg_hi:[0,1]
	s_nop 0
	v_xor_b32_e32 v39, 0x80000000, v10
	v_mov_b32_e32 v38, v11
	v_pk_add_f32 v[10:11], v[40:41], v[36:37]
	v_pk_add_f32 v[42:43], v[8:9], v[38:39]
	v_pk_add_f32 v[8:9], v[8:9], v[38:39] neg_lo:[0,1] neg_hi:[0,1]
	v_pk_mul_f32 v[38:39], v[34:35], v[10:11] op_sel:[1,1] op_sel_hi:[0,1]
	v_pk_add_f32 v[36:37], v[40:41], v[36:37] neg_lo:[0,1] neg_hi:[0,1]
	v_pk_fma_f32 v[40:41], v[34:35], v[10:11], v[38:39] neg_lo:[0,0,1] neg_hi:[0,0,1]
	v_pk_fma_f32 v[10:11], v[34:35], v[10:11], v[38:39] op_sel_hi:[1,0,1]
	s_nop 0
	v_mov_b32_e32 v41, v11
	v_pk_mul_f32 v[10:11], v[32:33], v[42:43] op_sel:[1,1] op_sel_hi:[0,1]
	v_pk_fma_f32 v[34:35], v[32:33], v[42:43], v[10:11] neg_lo:[0,0,1] neg_hi:[0,0,1]
	v_pk_fma_f32 v[10:11], v[32:33], v[42:43], v[10:11] op_sel_hi:[1,0,1]
	s_nop 0
	v_mov_b32_e32 v35, v11
	v_pk_mul_f32 v[10:11], v[30:31], v[36:37] op_sel:[1,1] op_sel_hi:[0,1]
	v_pk_fma_f32 v[32:33], v[30:31], v[36:37], v[10:11] neg_lo:[0,0,1] neg_hi:[0,0,1]
	v_pk_fma_f32 v[10:11], v[30:31], v[36:37], v[10:11] op_sel_hi:[1,0,1]
	s_nop 0
	v_mov_b32_e32 v33, v11
	v_pk_mul_f32 v[10:11], v[28:29], v[8:9] op_sel:[1,1] op_sel_hi:[0,1]
	v_pk_fma_f32 v[30:31], v[28:29], v[8:9], v[10:11] neg_lo:[0,0,1] neg_hi:[0,0,1]
	v_pk_fma_f32 v[8:9], v[28:29], v[8:9], v[10:11] op_sel_hi:[1,0,1]
	v_pk_add_f32 v[28:29], v[40:41], v[32:33]
	v_mov_b32_e32 v31, v9
	v_pk_add_f32 v[8:9], v[34:35], v[30:31] neg_lo:[0,1] neg_hi:[0,1]
	v_pk_add_f32 v[32:33], v[40:41], v[32:33] neg_lo:[0,1] neg_hi:[0,1]
	v_pk_add_f32 v[36:37], v[34:35], v[30:31]
	v_xor_b32_e32 v30, 0x80000000, v9
	v_mov_b32_e32 v31, v8
	v_pk_add_f32 v[8:9], v[28:29], v[36:37]
	v_pk_add_f32 v[10:11], v[32:33], v[30:31]
	v_pk_add_f32 v[28:29], v[28:29], v[36:37] neg_lo:[0,1] neg_hi:[0,1]
	v_pk_add_f32 v[30:31], v[32:33], v[30:31] neg_lo:[0,1] neg_hi:[0,1]
	ds_write_b128 v44, v[8:11]
	ds_write_b128 v44, v[28:31] offset:16
	v_mov_b32_e32 v8, v140
	s_nop 0
	v_add_u32_e32 v8, 0xa00, v8
	v_lshlrev_b32_e32 v9, 5, v8
	v_lshlrev_b32_e32 v8, 1, v8
	v_and_b32_e32 v8, 0xffffffe0, v8
	v_add3_u32 v36, 0, v9, v8
	ds_read_b128 v[8:11], v36
	ds_read_b128 v[28:31], v36 offset:16
	s_waitcnt lgkmcnt(0)
	v_pk_add_f32 v[32:33], v[8:9], v[28:29]
	v_pk_add_f32 v[8:9], v[8:9], v[28:29] neg_lo:[0,1] neg_hi:[0,1]
	v_pk_add_f32 v[28:29], v[10:11], v[30:31]
	v_pk_add_f32 v[10:11], v[10:11], v[30:31] neg_lo:[0,1] neg_hi:[0,1]
	s_nop 0
	v_xor_b32_e32 v31, 0x80000000, v10
	v_mov_b32_e32 v30, v11
	v_pk_add_f32 v[10:11], v[32:33], v[28:29]
	v_pk_add_f32 v[34:35], v[8:9], v[30:31]
	v_pk_add_f32 v[8:9], v[8:9], v[30:31] neg_lo:[0,1] neg_hi:[0,1]
	v_pk_mul_f32 v[30:31], v[26:27], v[10:11] op_sel:[1,1] op_sel_hi:[0,1]
	v_pk_add_f32 v[28:29], v[32:33], v[28:29] neg_lo:[0,1] neg_hi:[0,1]
	v_pk_fma_f32 v[32:33], v[26:27], v[10:11], v[30:31] neg_lo:[0,0,1] neg_hi:[0,0,1]
	v_pk_fma_f32 v[10:11], v[26:27], v[10:11], v[30:31] op_sel_hi:[1,0,1]
	s_nop 0
	v_mov_b32_e32 v33, v11
	v_pk_mul_f32 v[10:11], v[24:25], v[34:35] op_sel:[1,1] op_sel_hi:[0,1]
	v_pk_fma_f32 v[26:27], v[24:25], v[34:35], v[10:11] neg_lo:[0,0,1] neg_hi:[0,0,1]
	v_pk_fma_f32 v[10:11], v[24:25], v[34:35], v[10:11] op_sel_hi:[1,0,1]
	s_nop 0
	v_mov_b32_e32 v27, v11
	v_pk_mul_f32 v[10:11], v[22:23], v[28:29] op_sel:[1,1] op_sel_hi:[0,1]
	v_pk_fma_f32 v[24:25], v[22:23], v[28:29], v[10:11] neg_lo:[0,0,1] neg_hi:[0,0,1]
	v_pk_fma_f32 v[10:11], v[22:23], v[28:29], v[10:11] op_sel_hi:[1,0,1]
	s_nop 0
	v_mov_b32_e32 v25, v11
	v_pk_mul_f32 v[10:11], v[20:21], v[8:9] op_sel:[1,1] op_sel_hi:[0,1]
	v_pk_fma_f32 v[22:23], v[20:21], v[8:9], v[10:11] neg_lo:[0,0,1] neg_hi:[0,0,1]
	v_pk_fma_f32 v[8:9], v[20:21], v[8:9], v[10:11] op_sel_hi:[1,0,1]
	v_pk_add_f32 v[20:21], v[32:33], v[24:25]
	v_mov_b32_e32 v23, v9
	v_pk_add_f32 v[8:9], v[26:27], v[22:23] neg_lo:[0,1] neg_hi:[0,1]
	v_pk_add_f32 v[24:25], v[32:33], v[24:25] neg_lo:[0,1] neg_hi:[0,1]
	v_pk_add_f32 v[28:29], v[26:27], v[22:23]
	v_xor_b32_e32 v22, 0x80000000, v9
	v_mov_b32_e32 v23, v8
	v_pk_add_f32 v[8:9], v[20:21], v[28:29]
	v_pk_add_f32 v[10:11], v[24:25], v[22:23]
	v_pk_add_f32 v[20:21], v[20:21], v[28:29] neg_lo:[0,1] neg_hi:[0,1]
	v_pk_add_f32 v[22:23], v[24:25], v[22:23] neg_lo:[0,1] neg_hi:[0,1]
	ds_write_b128 v36, v[8:11]
	ds_write_b128 v36, v[20:23] offset:16
	v_mov_b32_e32 v8, v140
	s_nop 0
	v_add_u32_e32 v8, 0xc00, v8
	v_lshlrev_b32_e32 v9, 5, v8
	v_lshlrev_b32_e32 v8, 1, v8
	v_and_b32_e32 v8, 0xffffffe0, v8
	v_add3_u32 v28, 0, v9, v8
	ds_read_b128 v[8:11], v28
	ds_read_b128 v[20:23], v28 offset:16
	s_waitcnt lgkmcnt(0)
; #define LAS __attribute__((address_space(3)))
; __device__ __forceinline__ f32x2 cmul(f32x2 a, f32x2 b) { return (f32x2){a.x * b.x - a.y * b.y, a.x * b.y + a.y * b.x}; }
; #define LT() ({ int lt_ = tid; asm volatile("" : "+v"(lt_)); lt_; })
; template <bool INV> __device__ __forceinline__ void bfly16_tab(f32x2 (&x)[16], const LAS f32x2* T, int tstride, int j) {
;     if (INV) {
; #pragma unroll
;         for (int q = 1; q < 16; ++q) { f32x2 p = T[q * tstride + j]; p.y = -p.y; x[q] = cmul(x[q], p); } }
; __device__ __forceinline__ void hyena_latent(Frame& F, int l, int ch, LAS f32x2* X, const LAS f32x2* TH, const LAS f32x2* TL, GAS f32x2* KS, const LAS float* CT  , bool wr = true) {
;     ...
;             for (int i = 0; i < 8; ++i) { const int b = LT() + NTHR * i; LAS f32x4* P = (LAS f32x4*)(X + 4 * b + ((b >> 4) << 2)); const f32x4 u = P[0], v = P[1], k0 = kreg[2 * i], k1 = kreg[2 * i + 1];
;                 f32x2 x0 = {u.x, u.y}, x1 = {u.z, u.w}, x2 = {v.x, v.y}, x3 = {v.z, v.w}; r4<false>(x0, x1, x2, x3);
;                 x0 = cmul(x0, (f32x2){k0.x, k0.y}); x1 = cmul(x1, (f32x2){k0.z, k0.w}); x2 = cmul(x2, (f32x2){k1.x, k1.y}); x3 = cmul(x3, (f32x2){k1.z, k1.w});
;                 r4<true>(x0, x1, x2, x3);
;                 P[0] = (f32x4){x0.x, x0.y, x1.x, x1.y}; P[1] = (f32x4){x2.x, x2.y, x3.x, x3.y};
;                 if (i & 1) asm volatile("" ::: "memory"); }
;             __syncthreads();
;             fft_inv_tail(X, TH, TL, tid);
	v_pk_add_f32 v[24:25], v[8:9], v[20:21]
	v_pk_add_f32 v[8:9], v[8:9], v[20:21] neg_lo:[0,1] neg_hi:[0,1]
	v_pk_add_f32 v[20:21], v[10:11], v[22:23]
	v_pk_add_f32 v[10:11], v[10:11], v[22:23] neg_lo:[0,1] neg_hi:[0,1]
	s_nop 0
	v_xor_b32_e32 v23, 0x80000000, v10
	v_mov_b32_e32 v22, v11
	v_pk_add_f32 v[10:11], v[24:25], v[20:21]
	v_pk_add_f32 v[26:27], v[8:9], v[22:23]
	v_pk_add_f32 v[8:9], v[8:9], v[22:23] neg_lo:[0,1] neg_hi:[0,1]
	v_pk_mul_f32 v[22:23], v[18:19], v[10:11] op_sel:[1,1] op_sel_hi:[0,1]
	v_pk_add_f32 v[20:21], v[24:25], v[20:21] neg_lo:[0,1] neg_hi:[0,1]
	v_pk_fma_f32 v[24:25], v[18:19], v[10:11], v[22:23] neg_lo:[0,0,1] neg_hi:[0,0,1]
	v_pk_fma_f32 v[10:11], v[18:19], v[10:11], v[22:23] op_sel_hi:[1,0,1]
	s_nop 0
	v_mov_b32_e32 v25, v11
	v_pk_mul_f32 v[10:11], v[16:17], v[26:27] op_sel:[1,1] op_sel_hi:[0,1]
	v_pk_fma_f32 v[18:19], v[16:17], v[26:27], v[10:11] neg_lo:[0,0,1] neg_hi:[0,0,1]
	v_pk_fma_f32 v[10:11], v[16:17], v[26:27], v[10:11] op_sel_hi:[1,0,1]
	s_nop 0
	v_mov_b32_e32 v19, v11
	v_pk_mul_f32 v[10:11], v[14:15], v[20:21] op_sel:[1,1] op_sel_hi:[0,1]
	v_pk_fma_f32 v[16:17], v[14:15], v[20:21], v[10:11] neg_lo:[0,0,1] neg_hi:[0,0,1]
	v_pk_fma_f32 v[10:11], v[14:15], v[20:21], v[10:11] op_sel_hi:[1,0,1]
	s_nop 0
	v_mov_b32_e32 v17, v11
	v_pk_mul_f32 v[10:11], v[12:13], v[8:9] op_sel:[1,1] op_sel_hi:[0,1]
	v_pk_fma_f32 v[14:15], v[12:13], v[8:9], v[10:11] neg_lo:[0,0,1] neg_hi:[0,0,1]
	v_pk_fma_f32 v[8:9], v[12:13], v[8:9], v[10:11] op_sel_hi:[1,0,1]
	v_pk_add_f32 v[12:13], v[24:25], v[16:17]
	v_mov_b32_e32 v15, v9
	v_pk_add_f32 v[8:9], v[18:19], v[14:15] neg_lo:[0,1] neg_hi:[0,1]
	v_pk_add_f32 v[16:17], v[24:25], v[16:17] neg_lo:[0,1] neg_hi:[0,1]
	v_pk_add_f32 v[20:21], v[18:19], v[14:15]
	v_xor_b32_e32 v14, 0x80000000, v9
	v_mov_b32_e32 v15, v8
	v_pk_add_f32 v[8:9], v[12:13], v[20:21]
	v_pk_add_f32 v[10:11], v[16:17], v[14:15]
	v_pk_add_f32 v[12:13], v[12:13], v[20:21] neg_lo:[0,1] neg_hi:[0,1]
	v_pk_add_f32 v[14:15], v[16:17], v[14:15] neg_lo:[0,1] neg_hi:[0,1]
	ds_write_b128 v28, v[8:11]
	ds_write_b128 v28, v[12:15] offset:16
	v_mov_b32_e32 v8, v140
	s_nop 0
	v_add_u32_e32 v8, 0xe00, v8
	v_lshlrev_b32_e32 v9, 5, v8
	v_lshlrev_b32_e32 v8, 1, v8
	v_and_b32_e32 v8, 0xffffffe0, v8
	v_add3_u32 v20, 0, v9, v8
	ds_read_b128 v[8:11], v20
	ds_read_b128 v[12:15], v20 offset:16
	s_waitcnt lgkmcnt(0)
	v_pk_add_f32 v[16:17], v[8:9], v[12:13]
	v_pk_add_f32 v[8:9], v[8:9], v[12:13] neg_lo:[0,1] neg_hi:[0,1]
	v_pk_add_f32 v[12:13], v[10:11], v[14:15]
	v_pk_add_f32 v[10:11], v[10:11], v[14:15] neg_lo:[0,1] neg_hi:[0,1]
	s_nop 0
	v_xor_b32_e32 v15, 0x80000000, v10
	v_mov_b32_e32 v14, v11
	v_pk_add_f32 v[10:11], v[16:17], v[12:13]
	v_pk_add_f32 v[18:19], v[8:9], v[14:15]
	v_pk_add_f32 v[8:9], v[8:9], v[14:15] neg_lo:[0,1] neg_hi:[0,1]
	v_pk_mul_f32 v[14:15], v[6:7], v[10:11] op_sel:[1,1] op_sel_hi:[0,1]
	v_pk_add_f32 v[12:13], v[16:17], v[12:13] neg_lo:[0,1] neg_hi:[0,1]
	v_pk_fma_f32 v[16:17], v[6:7], v[10:11], v[14:15] neg_lo:[0,0,1] neg_hi:[0,0,1]
	v_pk_fma_f32 v[6:7], v[6:7], v[10:11], v[14:15] op_sel_hi:[1,0,1]
	s_nop 0
	v_mov_b32_e32 v17, v7
	v_pk_mul_f32 v[6:7], v[4:5], v[18:19] op_sel:[1,1] op_sel_hi:[0,1]
	v_pk_fma_f32 v[10:11], v[4:5], v[18:19], v[6:7] neg_lo:[0,0,1] neg_hi:[0,0,1]
	v_pk_fma_f32 v[4:5], v[4:5], v[18:19], v[6:7] op_sel_hi:[1,0,1]
	s_nop 0
	v_mov_b32_e32 v11, v5
	v_pk_mul_f32 v[4:5], v[2:3], v[12:13] op_sel:[1,1] op_sel_hi:[0,1]
	v_pk_fma_f32 v[6:7], v[2:3], v[12:13], v[4:5] neg_lo:[0,0,1] neg_hi:[0,0,1]
	v_pk_fma_f32 v[2:3], v[2:3], v[12:13], v[4:5] op_sel_hi:[1,0,1]
	s_nop 0
	v_mov_b32_e32 v7, v3
	v_pk_mul_f32 v[2:3], v[0:1], v[8:9] op_sel:[1,1] op_sel_hi:[0,1]
	v_pk_fma_f32 v[4:5], v[0:1], v[8:9], v[2:3] neg_lo:[0,0,1] neg_hi:[0,0,1]
	v_pk_fma_f32 v[0:1], v[0:1], v[8:9], v[2:3] op_sel_hi:[1,0,1]
	v_pk_add_f32 v[8:9], v[16:17], v[6:7]
	v_mov_b32_e32 v5, v1
	v_pk_add_f32 v[0:1], v[10:11], v[4:5] neg_lo:[0,1] neg_hi:[0,1]
	v_pk_add_f32 v[6:7], v[16:17], v[6:7] neg_lo:[0,1] neg_hi:[0,1]
	v_pk_add_f32 v[12:13], v[10:11], v[4:5]
	v_xor_b32_e32 v10, 0x80000000, v1
	v_mov_b32_e32 v11, v0
	v_pk_add_f32 v[0:1], v[8:9], v[12:13]
	v_pk_add_f32 v[2:3], v[6:7], v[10:11]
	v_pk_add_f32 v[4:5], v[8:9], v[12:13] neg_lo:[0,1] neg_hi:[0,1]
	v_pk_add_f32 v[6:7], v[6:7], v[10:11] neg_lo:[0,1] neg_hi:[0,1]
	ds_write_b128 v20, v[0:3]
	ds_write_b128 v20, v[4:7] offset:16
	s_waitcnt lgkmcnt(0)
	s_barrier
	ds_read2_b64 v[232:235], v141 offset0:4 offset1:8
	ds_read2_b64 v[208:211], v141 offset0:12 offset1:16
	ds_read2_b64 v[204:207], v141 offset0:20 offset1:24
	ds_read2_b64 v[200:203], v141 offset0:28 offset1:32
	ds_read2_b64 v[196:199], v141 offset0:36 offset1:40
	ds_read2_b64 v[192:195], v141 offset0:44 offset1:48
	ds_read2_b64 v[188:191], v141 offset0:52 offset1:56
	ds_read_b64 v[248:249], v141 offset:480
; #define LAS __attribute__((address_space(3)))
; __device__ __forceinline__ f32x2 cmul(f32x2 a, f32x2 b) { return (f32x2){a.x * b.x - a.y * b.y, a.x * b.y + a.y * b.x}; }
; template <bool INV> __device__ __forceinline__ void bfly16_tab(f32x2 (&x)[16], const LAS f32x2* T, int tstride, int j) {
;     if (INV) {
; #pragma unroll
;         for (int q = 1; q < 16; ++q) { f32x2 p = T[q * tstride + j]; p.y = -p.y; x[q] = cmul(x[q], p); } }
;     dft16<INV>(x);
;     if (!INV) {
; #pragma unroll
;         for (int r = 1; r < 16; ++r) { const f32x2 p = T[r * tstride + j]; x[4 * (r & 3) + (r >> 2)] = cmul(x[4 * (r & 3) + (r >> 2)], p); } }
; }
; template <bool INV> __device__ __forceinline__ void pass16_s64(LAS f32x2* X, const LAS f32x2* TH, int base, int j) {
;     f32x2 x[16];
; #pragma unroll
;     for (int q = 0; q < 16; ++q) x[q] = X[base + q * 68];
;     bfly16_tab<INV>(x, TH - 2048, 64, j);
; #pragma unroll
;     for (int c = 0; c < 4; ++c)
; #pragma unroll
;         for (int d = 0; d < 4; ++d) X[base + (c + 4 * d) * 68] = x[4 * c + d];
; }
; template <bool INV> __device__ __forceinline__ void pass16(LAS f32x2* X, const LAS f32x2* TH, const LAS f32x2* TL, int base, int stride, int tw) {
;     f32x2 x[16];
; #pragma unroll
;     for (int q = 0; q < 16; ++q) x[q] = X[base + q * stride];
;     bfly16<INV>(x, TH, TL, tw);
; #pragma unroll
;     for (int c = 0; c < 4; ++c)
; #pragma unroll
;         for (int d = 0; d < 4; ++d) X[base + (c + 4 * d) * stride] = x[4 * c + d];
; }
; template <bool INV> __device__ __forceinline__ void pass16_s4(LAS f32x2* X, const LAS f32x2* TH, const LAS f32x2* TL, int tid) {
; #pragma unroll 1
;     for (int s = 0; s < 2; ++s) {
;         const int b = tid + NTHR * s, blk = b >> 2, jj = b & 3;
;         LAS f32x2* P = X + blk * 68 + jj;
;         f32x2 x[16];
; #pragma unroll
;         for (int q = 0; q < 16; ++q) x[q] = P[4 * q];
;         bfly16_tab<INV>(x, TH - 1024, 4, jj);
; #pragma unroll
;         for (int c = 0; c < 4; ++c)
; #pragma unroll
;             for (int d = 0; d < 4; ++d) P[4 * (c + 4 * d)] = x[4 * c + d];
;     }
; }
.LBB0_852:
	v_add_u32_e32 v252, s0, v140
	v_lshrrev_b32_e32 v253, 2, v252
	v_mad_u32_u24 v250, v253, s43, v144
	ds_read2_b64 v[0:3], v250 offset0:0 offset1:4
	ds_read2_b64 v[4:7], v250 offset0:8 offset1:12
	ds_read2_b64 v[8:11], v250 offset0:16 offset1:20
	ds_read2_b64 v[12:15], v250 offset0:24 offset1:28
	ds_read2_b64 v[16:19], v250 offset0:32 offset1:36
	ds_read2_b64 v[20:23], v250 offset0:40 offset1:44
	ds_read2_b64 v[24:27], v250 offset0:48 offset1:52
	ds_read2_b64 v[28:31], v250 offset0:56 offset1:60
	s_cmp_eq_u32 s0, 0
	s_movk_i32 s0, 0x200
	s_mov_b64 s[12:13], 0
	s_waitcnt lgkmcnt(7)
	v_pk_mul_f32 v[32:33], v[2:3], v[232:233] op_sel:[0,1] op_sel_hi:[1,1]
	s_waitcnt lgkmcnt(6)
	v_pk_mul_f32 v[34:35], v[4:5], v[234:235] op_sel:[0,1] op_sel_hi:[1,1]
	v_pk_fma_f32 v[2:3], v[2:3], v[232:233], v[32:33] op_sel:[0,0,1] op_sel_hi:[1,0,0] neg_hi:[0,0,1]
	v_pk_mul_f32 v[32:33], v[6:7], v[208:209] op_sel:[0,1] op_sel_hi:[1,1]
	v_pk_fma_f32 v[4:5], v[4:5], v[234:235], v[34:35] op_sel:[0,0,1] op_sel_hi:[1,0,0] neg_hi:[0,0,1]
	s_waitcnt lgkmcnt(5)
	v_pk_mul_f32 v[34:35], v[8:9], v[210:211] op_sel:[0,1] op_sel_hi:[1,1]
	v_pk_fma_f32 v[6:7], v[6:7], v[208:209], v[32:33] op_sel:[0,0,1] op_sel_hi:[1,0,0] neg_hi:[0,0,1]
	v_pk_mul_f32 v[32:33], v[10:11], v[204:205] op_sel:[0,1] op_sel_hi:[1,1]
	v_pk_fma_f32 v[34:35], v[8:9], v[210:211], v[34:35] op_sel:[0,0,1] op_sel_hi:[1,0,0] neg_hi:[0,0,1]
	s_waitcnt lgkmcnt(4)
	v_pk_mul_f32 v[8:9], v[12:13], v[206:207] op_sel:[0,1] op_sel_hi:[1,1]
	v_pk_fma_f32 v[32:33], v[10:11], v[204:205], v[32:33] op_sel:[0,0,1] op_sel_hi:[1,0,0] neg_hi:[0,0,1]
	v_pk_mul_f32 v[10:11], v[14:15], v[200:201] op_sel:[0,1] op_sel_hi:[1,1]
	v_pk_fma_f32 v[12:13], v[12:13], v[206:207], v[8:9] op_sel:[0,0,1] op_sel_hi:[1,0,0] neg_hi:[0,0,1]
	s_waitcnt lgkmcnt(3)
	v_pk_mul_f32 v[8:9], v[16:17], v[202:203] op_sel:[0,1] op_sel_hi:[1,1]
	v_pk_fma_f32 v[14:15], v[14:15], v[200:201], v[10:11] op_sel:[0,0,1] op_sel_hi:[1,0,0] neg_hi:[0,0,1]
	v_pk_mul_f32 v[10:11], v[18:19], v[196:197] op_sel:[0,1] op_sel_hi:[1,1]
	v_pk_fma_f32 v[8:9], v[16:17], v[202:203], v[8:9] op_sel:[0,0,1] op_sel_hi:[1,0,0] neg_hi:[0,0,1]
	s_waitcnt lgkmcnt(2)
	v_pk_mul_f32 v[16:17], v[20:21], v[198:199] op_sel:[0,1] op_sel_hi:[1,1]
	v_pk_fma_f32 v[18:19], v[18:19], v[196:197], v[10:11] op_sel:[0,0,1] op_sel_hi:[1,0,0] neg_hi:[0,0,1]
	v_pk_mul_f32 v[10:11], v[22:23], v[192:193] op_sel:[0,1] op_sel_hi:[1,1]
	v_pk_fma_f32 v[20:21], v[20:21], v[198:199], v[16:17] op_sel:[0,0,1] op_sel_hi:[1,0,0] neg_hi:[0,0,1]
	s_waitcnt lgkmcnt(1)
	v_pk_mul_f32 v[16:17], v[24:25], v[194:195] op_sel:[0,1] op_sel_hi:[1,1]
	v_pk_fma_f32 v[10:11], v[22:23], v[192:193], v[10:11] op_sel:[0,0,1] op_sel_hi:[1,0,0] neg_hi:[0,0,1]
	v_pk_mul_f32 v[22:23], v[26:27], v[188:189] op_sel:[0,1] op_sel_hi:[1,1]
	v_pk_fma_f32 v[16:17], v[24:25], v[194:195], v[16:17] op_sel:[0,0,1] op_sel_hi:[1,0,0] neg_hi:[0,0,1]
	s_waitcnt lgkmcnt(0)
	v_pk_mul_f32 v[24:25], v[28:29], v[190:191] op_sel:[0,1] op_sel_hi:[1,1]
	v_pk_fma_f32 v[26:27], v[26:27], v[188:189], v[22:23] op_sel:[0,0,1] op_sel_hi:[1,0,0] neg_hi:[0,0,1]
	v_pk_mul_f32 v[22:23], v[30:31], v[248:249] op_sel:[0,1] op_sel_hi:[1,1]
	v_pk_fma_f32 v[28:29], v[28:29], v[190:191], v[24:25] op_sel:[0,0,1] op_sel_hi:[1,0,0] neg_hi:[0,0,1]
	v_pk_fma_f32 v[30:31], v[30:31], v[248:249], v[22:23] op_sel:[0,0,1] op_sel_hi:[1,0,0] neg_hi:[0,0,1]
	v_pk_add_f32 v[22:23], v[0:1], v[8:9]
	v_pk_add_f32 v[24:25], v[2:3], v[18:19]
	v_pk_add_f32 v[36:37], v[4:5], v[20:21]
	v_pk_add_f32 v[38:39], v[6:7], v[10:11]
	v_pk_add_f32 v[8:9], v[0:1], v[8:9] neg_lo:[0,1] neg_hi:[0,1]
	v_pk_add_f32 v[2:3], v[2:3], v[18:19] neg_lo:[0,1] neg_hi:[0,1]
	v_pk_add_f32 v[20:21], v[4:5], v[20:21] neg_lo:[0,1] neg_hi:[0,1]
	v_pk_add_f32 v[10:11], v[6:7], v[10:11] neg_lo:[0,1] neg_hi:[0,1]
	v_pk_add_f32 v[6:7], v[34:35], v[16:17]
	v_pk_add_f32 v[4:5], v[32:33], v[26:27]
	v_pk_add_f32 v[18:19], v[12:13], v[28:29]
	v_pk_add_f32 v[0:1], v[14:15], v[30:31]
	v_pk_add_f32 v[16:17], v[34:35], v[16:17] neg_lo:[0,1] neg_hi:[0,1]
	v_pk_add_f32 v[26:27], v[32:33], v[26:27] neg_lo:[0,1] neg_hi:[0,1]
	v_pk_add_f32 v[12:13], v[12:13], v[28:29] neg_lo:[0,1] neg_hi:[0,1]
	v_pk_add_f32 v[14:15], v[14:15], v[30:31] neg_lo:[0,1] neg_hi:[0,1]
	v_pk_add_f32 v[30:31], v[22:23], v[6:7]
	v_pk_add_f32 v[28:29], v[24:25], v[4:5]
	v_pk_add_f32 v[32:33], v[36:37], v[18:19]
	v_pk_add_f32 v[34:35], v[38:39], v[0:1]
	v_pk_add_f32 v[22:23], v[22:23], v[6:7] neg_lo:[0,1] neg_hi:[0,1]
	v_pk_add_f32 v[4:5], v[24:25], v[4:5] neg_lo:[0,1] neg_hi:[0,1]
	v_pk_add_f32 v[18:19], v[36:37], v[18:19] neg_lo:[0,1] neg_hi:[0,1]
	v_pk_add_f32 v[38:39], v[38:39], v[0:1] neg_lo:[0,1] neg_hi:[0,1]
	v_pk_add_f32 v[0:1], v[8:9], v[16:17] op_sel:[0,1] op_sel_hi:[1,0] neg_lo:[0,1]
	v_pk_add_f32 v[36:37], v[2:3], v[26:27] op_sel:[0,1] op_sel_hi:[1,0] neg_lo:[0,1]
	v_pk_add_f32 v[24:25], v[20:21], v[12:13] op_sel:[0,1] op_sel_hi:[1,0] neg_lo:[0,1]
	v_pk_add_f32 v[6:7], v[10:11], v[14:15] op_sel:[0,1] op_sel_hi:[1,0] neg_lo:[0,1]
	v_pk_add_f32 v[8:9], v[8:9], v[16:17] op_sel:[0,1] op_sel_hi:[1,0] neg_hi:[0,1]
	v_pk_add_f32 v[2:3], v[2:3], v[26:27] op_sel:[0,1] op_sel_hi:[1,0] neg_hi:[0,1]
	v_pk_add_f32 v[20:21], v[20:21], v[12:13] op_sel:[0,1] op_sel_hi:[1,0] neg_hi:[0,1]
	v_pk_add_f32 v[14:15], v[10:11], v[14:15] op_sel:[0,1] op_sel_hi:[1,0] neg_hi:[0,1]
	v_pk_mul_f32 v[10:11], v[36:37], s[82:83] op_sel_hi:[1,0]
	v_pk_mul_f32 v[12:13], v[4:5], s[76:77] op_sel_hi:[1,0]
	v_pk_mul_f32 v[26:27], v[2:3], s[44:45] op_sel_hi:[1,0]
	v_pk_mul_f32 v[16:17], v[24:25], s[76:77] op_sel_hi:[1,0]
	v_pk_mul_f32 v[40:41], v[20:21], s[76:77] op_sel_hi:[1,0]
; #define LAS __attribute__((address_space(3)))
; __device__ __forceinline__ f32x2 cmul(f32x2 a, f32x2 b) { return (f32x2){a.x * b.x - a.y * b.y, a.x * b.y + a.y * b.x}; }
; template <bool INV> __device__ __forceinline__ void bfly16_tab(f32x2 (&x)[16], const LAS f32x2* T, int tstride, int j) {
;     if (INV) {
; #pragma unroll
;         for (int q = 1; q < 16; ++q) { f32x2 p = T[q * tstride + j]; p.y = -p.y; x[q] = cmul(x[q], p); } }
;     dft16<INV>(x);
;     if (!INV) {
; #pragma unroll
;         for (int r = 1; r < 16; ++r) { const f32x2 p = T[r * tstride + j]; x[4 * (r & 3) + (r >> 2)] = cmul(x[4 * (r & 3) + (r >> 2)], p); } }
; }
; template <bool INV> __device__ __forceinline__ void pass16_s64(LAS f32x2* X, const LAS f32x2* TH, int base, int j) {
;     f32x2 x[16];
; #pragma unroll
;     for (int q = 0; q < 16; ++q) x[q] = X[base + q * 68];
;     bfly16_tab<INV>(x, TH - 2048, 64, j);
; #pragma unroll
;     for (int c = 0; c < 4; ++c)
; #pragma unroll
;         for (int d = 0; d < 4; ++d) X[base + (c + 4 * d) * 68] = x[4 * c + d];
; __device__ __forceinline__ void fft_inv_tail(LAS f32x2* X, const LAS f32x2* TH, const LAS f32x2* TL, int tid) {
;     ...
; #pragma unroll 1
;     for (int i = 0; i < 2; ++i) { const int b = tid + NTHR * i, j = b & 63, blk = b >> 6; pass16_s64<true>(X, TH, blk * 1088 + j, j); }
	v_pk_mul_f32 v[42:43], v[6:7], s[44:45] op_sel_hi:[1,0]
	v_pk_mul_f32 v[44:45], v[38:39], s[76:77] op_sel_hi:[1,0]
	v_pk_mul_f32 v[218:219], v[14:15], s[70:71] op_sel_hi:[1,0]
	v_pk_fma_f32 v[10:11], v[36:37], s[44:45], v[10:11] op_sel:[0,0,1] op_sel_hi:[1,0,0] neg_lo:[0,0,1]
	v_pk_fma_f32 v[4:5], v[4:5], s[76:77], v[12:13] op_sel:[0,0,1] op_sel_hi:[1,0,0] neg_lo:[0,0,1]
	v_pk_fma_f32 v[26:27], v[2:3], s[82:83], v[26:27] op_sel:[0,0,1] op_sel_hi:[1,0,0] neg_lo:[0,0,1]
	v_pk_fma_f32 v[24:25], v[24:25], s[76:77], v[16:17] op_sel:[0,0,1] op_sel_hi:[1,0,0] neg_lo:[0,0,1]
	v_pk_fma_f32 v[20:21], v[20:21], s[72:73], v[40:41] op_sel:[0,0,1] op_sel_hi:[1,0,0] neg_lo:[0,0,1]
	v_pk_fma_f32 v[42:43], v[6:7], s[82:83], v[42:43] op_sel:[0,0,1] op_sel_hi:[1,0,0] neg_lo:[0,0,1]
	v_pk_fma_f32 v[38:39], v[38:39], s[72:73], v[44:45] op_sel:[0,0,1] op_sel_hi:[1,0,0] neg_lo:[0,0,1]
	v_pk_fma_f32 v[14:15], v[14:15], s[64:65], v[218:219] op_sel:[0,0,1] op_sel_hi:[1,0,0] neg_lo:[0,0,1]
	v_pk_add_f32 v[218:219], v[30:31], v[32:33]
	v_pk_add_f32 v[44:45], v[0:1], v[24:25]
	v_pk_add_f32 v[6:7], v[22:23], v[18:19] op_sel:[0,1] op_sel_hi:[1,0] neg_lo:[0,1]
	v_pk_add_f32 v[40:41], v[8:9], v[20:21]
	v_pk_add_f32 v[30:31], v[30:31], v[32:33] neg_lo:[0,1] neg_hi:[0,1]
	v_pk_add_f32 v[0:1], v[0:1], v[24:25] neg_lo:[0,1] neg_hi:[0,1]
	v_pk_add_f32 v[18:19], v[22:23], v[18:19] op_sel:[0,1] op_sel_hi:[1,0] neg_hi:[0,1]
	v_pk_add_f32 v[20:21], v[8:9], v[20:21] neg_lo:[0,1] neg_hi:[0,1]
	v_pk_add_f32 v[8:9], v[28:29], v[34:35]
	v_pk_add_f32 v[22:23], v[10:11], v[42:43]
	v_pk_add_f32 v[24:25], v[4:5], v[38:39]
	v_pk_add_f32 v[32:33], v[26:27], v[14:15]
	v_pk_add_f32 v[34:35], v[28:29], v[34:35] neg_lo:[0,1] neg_hi:[0,1]
	v_pk_add_f32 v[42:43], v[10:11], v[42:43] neg_lo:[0,1] neg_hi:[0,1]
	v_pk_add_f32 v[4:5], v[4:5], v[38:39] neg_lo:[0,1] neg_hi:[0,1]
	v_pk_add_f32 v[14:15], v[26:27], v[14:15] neg_lo:[0,1] neg_hi:[0,1]
	v_pk_add_f32 v[26:27], v[218:219], v[8:9]
	v_pk_add_f32 v[38:39], v[44:45], v[22:23]
	v_pk_add_f32 v[10:11], v[6:7], v[24:25]
	v_pk_add_f32 v[28:29], v[40:41], v[32:33]
	v_pk_add_f32 v[8:9], v[218:219], v[8:9] neg_lo:[0,1] neg_hi:[0,1]
	v_pk_add_f32 v[44:45], v[44:45], v[22:23] neg_lo:[0,1] neg_hi:[0,1]
	v_pk_add_f32 v[24:25], v[6:7], v[24:25] neg_lo:[0,1] neg_hi:[0,1]
	v_pk_add_f32 v[40:41], v[40:41], v[32:33] neg_lo:[0,1] neg_hi:[0,1]
	v_pk_add_f32 v[32:33], v[30:31], v[34:35] op_sel:[0,1] op_sel_hi:[1,0] neg_lo:[0,1]
	v_pk_add_f32 v[6:7], v[0:1], v[42:43] op_sel:[0,1] op_sel_hi:[1,0] neg_lo:[0,1]
	v_pk_add_f32 v[22:23], v[18:19], v[4:5] op_sel:[0,1] op_sel_hi:[1,0] neg_lo:[0,1]
	v_pk_add_f32 v[218:219], v[20:21], v[14:15] op_sel:[0,1] op_sel_hi:[1,0] neg_lo:[0,1]
	v_pk_add_f32 v[34:35], v[30:31], v[34:35] op_sel:[0,1] op_sel_hi:[1,0] neg_hi:[0,1]
	v_pk_add_f32 v[42:43], v[0:1], v[42:43] op_sel:[0,1] op_sel_hi:[1,0] neg_hi:[0,1]
	v_pk_add_f32 v[18:19], v[18:19], v[4:5] op_sel:[0,1] op_sel_hi:[1,0] neg_hi:[0,1]
	v_pk_add_f32 v[20:21], v[20:21], v[14:15] op_sel:[0,1] op_sel_hi:[1,0] neg_hi:[0,1]
	ds_write2_b64 v250, v[26:27], v[38:39] offset0:0 offset1:4
	ds_write2_b64 v250, v[10:11], v[28:29] offset0:8 offset1:12
	ds_write2_b64 v250, v[32:33], v[6:7] offset0:16 offset1:20
	ds_write2_b64 v250, v[22:23], v[218:219] offset0:24 offset1:28
	ds_write2_b64 v250, v[8:9], v[44:45] offset0:32 offset1:36
	ds_write2_b64 v250, v[24:25], v[40:41] offset0:40 offset1:44
	ds_write2_b64 v250, v[34:35], v[42:43] offset0:48 offset1:52
	ds_write2_b64 v250, v[18:19], v[20:21] offset0:56 offset1:60
	s_cbranch_scc1 .LBB0_852
	s_waitcnt lgkmcnt(0)
	s_barrier
	s_mov_b32 s0, 0
	s_mov_b64 s[12:13], -1
	ds_read2st64_b64 v[232:235], v139 offset0:1 offset1:2
	ds_read2st64_b64 v[208:211], v139 offset0:3 offset1:4
	ds_read2st64_b64 v[204:207], v139 offset0:5 offset1:6
	ds_read2st64_b64 v[200:203], v139 offset0:7 offset1:8
	ds_read2st64_b64 v[196:199], v139 offset0:9 offset1:10
	ds_read2st64_b64 v[192:195], v139 offset0:11 offset1:12
	ds_read2st64_b64 v[188:191], v139 offset0:13 offset1:14
	ds_read_b64 v[222:223], v139 offset:7680
.LBB0_854:
	v_add_u32_e32 v36, s0, v140
	v_lshrrev_b32_e32 v252, 6, v36
	v_mad_u32_u24 v253, v252, s77, v142
	v_add_u32_e32 v250, 0x800, v253
	v_add_u32_e32 v251, 0x1000, v253
	v_add_u32_e32 v248, 0x1800, v253
	ds_read2_b64 v[0:3], v253 offset0:0 offset1:68
	ds_read2_b64 v[4:7], v253 offset0:136 offset1:204
	ds_read2_b64 v[8:11], v250 offset0:16 offset1:84
	ds_read2_b64 v[12:15], v250 offset0:152 offset1:220
	ds_read2_b64 v[16:19], v251 offset0:32 offset1:100
	ds_read2_b64 v[20:23], v251 offset0:168 offset1:236
	ds_read2_b64 v[24:27], v248 offset0:48 offset1:116
	ds_read2_b64 v[28:31], v248 offset0:184 offset1:252
	s_cmp_eq_u32 s0, 0
	s_movk_i32 s0, 0x200
	s_mov_b64 s[12:13], 0
	s_waitcnt lgkmcnt(7)
	v_pk_mul_f32 v[32:33], v[2:3], v[232:233] op_sel:[0,1] op_sel_hi:[1,1]
	s_waitcnt lgkmcnt(6)
	v_pk_mul_f32 v[34:35], v[4:5], v[234:235] op_sel:[0,1] op_sel_hi:[1,1]
	v_pk_fma_f32 v[2:3], v[2:3], v[232:233], v[32:33] op_sel:[0,0,1] op_sel_hi:[1,0,0] neg_hi:[0,0,1]
	v_pk_mul_f32 v[32:33], v[6:7], v[208:209] op_sel:[0,1] op_sel_hi:[1,1]
	v_pk_fma_f32 v[34:35], v[4:5], v[234:235], v[34:35] op_sel:[0,0,1] op_sel_hi:[1,0,0] neg_hi:[0,0,1]
	s_waitcnt lgkmcnt(5)
	v_pk_mul_f32 v[4:5], v[8:9], v[210:211] op_sel:[0,1] op_sel_hi:[1,1]
	v_pk_fma_f32 v[6:7], v[6:7], v[208:209], v[32:33] op_sel:[0,0,1] op_sel_hi:[1,0,0] neg_hi:[0,0,1]
	v_pk_mul_f32 v[32:33], v[10:11], v[204:205] op_sel:[0,1] op_sel_hi:[1,1]
	v_pk_fma_f32 v[8:9], v[8:9], v[210:211], v[4:5] op_sel:[0,0,1] op_sel_hi:[1,0,0] neg_hi:[0,0,1]
	s_waitcnt lgkmcnt(4)
; #define LAS __attribute__((address_space(3)))
; template <bool INV> __device__ __forceinline__ void dft16(f32x2 (&x)[16]) {
; #pragma unroll
;     for (int b = 0; b < 4; ++b) r4<INV>(x[b], x[4 + b], x[8 + b], x[12 + b]);
;     const float sg = INV ? -1.f : 1.f;
;     const f32x2 W1 = {0.92387953251f, -0.38268343236f * sg}, W2 = {0.70710678118f, -0.70710678118f * sg}, W3 = {0.38268343236f, -0.92387953251f * sg},
;                 W4 = {0.f, -1.f * sg}, W6 = {-0.70710678118f, -0.70710678118f * sg}, W9 = {-0.92387953251f, 0.38268343236f * sg};
;     x[5] = cmul(x[5], W1); x[9] = cmul(x[9], W2); x[13] = cmul(x[13], W3);
;     x[6] = cmul(x[6], W2); x[10] = cmul(x[10], W4); x[14] = cmul(x[14], W6);
;     x[7] = cmul(x[7], W3); x[11] = cmul(x[11], W6); x[15] = cmul(x[15], W9);
; #pragma unroll
;     for (int c = 0; c < 4; ++c) r4<INV>(x[4 * c], x[4 * c + 1], x[4 * c + 2], x[4 * c + 3]);
; }
; template <bool INV> __device__ __forceinline__ void bfly16(f32x2 (&x)[16], const LAS f32x2* TH, const LAS f32x2* TL, int tw) {
;     f32x2 W = tw32k(TH, TL, tw); if (INV) W.y = -W.y;
;     if (INV) { f32x2 p = W;
; #pragma unroll
;         for (int q = 1; q < 16; ++q) { x[q] = cmul(x[q], p); if (q < 15) p = cmul(p, W); } }
;     dft16<INV>(x);
;     if (!INV) { f32x2 p = W;
; #pragma unroll
;         for (int r = 1; r < 16; ++r) { x[4 * (r & 3) + (r >> 2)] = cmul(x[4 * (r & 3) + (r >> 2)], p); if (r < 15) p = cmul(p, W); } }
; }
; template <bool INV> __device__ __forceinline__ void bfly16_tab(f32x2 (&x)[16], const LAS f32x2* T, int tstride, int j) {
;     if (INV) {
; #pragma unroll
;         for (int q = 1; q < 16; ++q) { f32x2 p = T[q * tstride + j]; p.y = -p.y; x[q] = cmul(x[q], p); } }
;     dft16<INV>(x);
;     if (!INV) {
; #pragma unroll
;         for (int r = 1; r < 16; ++r) { const f32x2 p = T[r * tstride + j]; x[4 * (r & 3) + (r >> 2)] = cmul(x[4 * (r & 3) + (r >> 2)], p); } }
; }
; template <bool INV> __device__ __forceinline__ void pass16_s64(LAS f32x2* X, const LAS f32x2* TH, int base, int j) {
;     f32x2 x[16];
; #pragma unroll
;     for (int q = 0; q < 16; ++q) x[q] = X[base + q * 68];
;     bfly16_tab<INV>(x, TH - 2048, 64, j);
; #pragma unroll
;     for (int c = 0; c < 4; ++c)
; #pragma unroll
;         for (int d = 0; d < 4; ++d) X[base + (c + 4 * d) * 68] = x[4 * c + d];
	v_pk_mul_f32 v[4:5], v[12:13], v[206:207] op_sel:[0,1] op_sel_hi:[1,1]
	v_pk_fma_f32 v[32:33], v[10:11], v[204:205], v[32:33] op_sel:[0,0,1] op_sel_hi:[1,0,0] neg_hi:[0,0,1]
	v_pk_mul_f32 v[10:11], v[14:15], v[200:201] op_sel:[0,1] op_sel_hi:[1,1]
	v_pk_fma_f32 v[4:5], v[12:13], v[206:207], v[4:5] op_sel:[0,0,1] op_sel_hi:[1,0,0] neg_hi:[0,0,1]
	s_waitcnt lgkmcnt(3)
	v_pk_mul_f32 v[12:13], v[16:17], v[202:203] op_sel:[0,1] op_sel_hi:[1,1]
	v_pk_fma_f32 v[14:15], v[14:15], v[200:201], v[10:11] op_sel:[0,0,1] op_sel_hi:[1,0,0] neg_hi:[0,0,1]
	v_pk_mul_f32 v[10:11], v[18:19], v[196:197] op_sel:[0,1] op_sel_hi:[1,1]
	v_pk_fma_f32 v[12:13], v[16:17], v[202:203], v[12:13] op_sel:[0,0,1] op_sel_hi:[1,0,0] neg_hi:[0,0,1]
	s_waitcnt lgkmcnt(2)
	v_pk_mul_f32 v[16:17], v[20:21], v[198:199] op_sel:[0,1] op_sel_hi:[1,1]
	v_pk_fma_f32 v[18:19], v[18:19], v[196:197], v[10:11] op_sel:[0,0,1] op_sel_hi:[1,0,0] neg_hi:[0,0,1]
	v_pk_mul_f32 v[10:11], v[22:23], v[192:193] op_sel:[0,1] op_sel_hi:[1,1]
	v_pk_fma_f32 v[16:17], v[20:21], v[198:199], v[16:17] op_sel:[0,0,1] op_sel_hi:[1,0,0] neg_hi:[0,0,1]
	s_waitcnt lgkmcnt(1)
	v_pk_mul_f32 v[20:21], v[24:25], v[194:195] op_sel:[0,1] op_sel_hi:[1,1]
	v_pk_fma_f32 v[22:23], v[22:23], v[192:193], v[10:11] op_sel:[0,0,1] op_sel_hi:[1,0,0] neg_hi:[0,0,1]
	v_pk_mul_f32 v[10:11], v[26:27], v[188:189] op_sel:[0,1] op_sel_hi:[1,1]
	v_pk_fma_f32 v[20:21], v[24:25], v[194:195], v[20:21] op_sel:[0,0,1] op_sel_hi:[1,0,0] neg_hi:[0,0,1]
	s_waitcnt lgkmcnt(0)
	v_pk_mul_f32 v[24:25], v[28:29], v[190:191] op_sel:[0,1] op_sel_hi:[1,1]
	v_pk_fma_f32 v[10:11], v[26:27], v[188:189], v[10:11] op_sel:[0,0,1] op_sel_hi:[1,0,0] neg_hi:[0,0,1]
	v_pk_mul_f32 v[26:27], v[30:31], v[222:223] op_sel:[0,1] op_sel_hi:[1,1]
	v_pk_fma_f32 v[28:29], v[28:29], v[190:191], v[24:25] op_sel:[0,0,1] op_sel_hi:[1,0,0] neg_hi:[0,0,1]
	v_pk_fma_f32 v[26:27], v[30:31], v[222:223], v[26:27] op_sel:[0,0,1] op_sel_hi:[1,0,0] neg_hi:[0,0,1]
	v_pk_add_f32 v[30:31], v[0:1], v[12:13]
	v_pk_add_f32 v[24:25], v[2:3], v[18:19]
	v_pk_add_f32 v[38:39], v[34:35], v[16:17]
	v_pk_add_f32 v[40:41], v[6:7], v[22:23]
	v_pk_add_f32 v[12:13], v[0:1], v[12:13] neg_lo:[0,1] neg_hi:[0,1]
	v_pk_add_f32 v[18:19], v[2:3], v[18:19] neg_lo:[0,1] neg_hi:[0,1]
	v_pk_add_f32 v[16:17], v[34:35], v[16:17] neg_lo:[0,1] neg_hi:[0,1]
	v_pk_add_f32 v[6:7], v[6:7], v[22:23] neg_lo:[0,1] neg_hi:[0,1]
	v_pk_add_f32 v[22:23], v[8:9], v[20:21]
	v_pk_add_f32 v[34:35], v[32:33], v[10:11]
	v_pk_add_f32 v[2:3], v[4:5], v[28:29]
	v_pk_add_f32 v[0:1], v[14:15], v[26:27]
	v_pk_add_f32 v[20:21], v[8:9], v[20:21] neg_lo:[0,1] neg_hi:[0,1]
	v_pk_add_f32 v[10:11], v[32:33], v[10:11] neg_lo:[0,1] neg_hi:[0,1]
	v_pk_add_f32 v[28:29], v[4:5], v[28:29] neg_lo:[0,1] neg_hi:[0,1]
	v_pk_add_f32 v[26:27], v[14:15], v[26:27] neg_lo:[0,1] neg_hi:[0,1]
	v_pk_add_f32 v[14:15], v[30:31], v[22:23]
	v_pk_add_f32 v[4:5], v[24:25], v[34:35]
	v_pk_add_f32 v[32:33], v[38:39], v[2:3]
	v_pk_add_f32 v[8:9], v[40:41], v[0:1]
	v_pk_add_f32 v[22:23], v[30:31], v[22:23] neg_lo:[0,1] neg_hi:[0,1]
	v_pk_add_f32 v[24:25], v[24:25], v[34:35] neg_lo:[0,1] neg_hi:[0,1]
	v_pk_add_f32 v[2:3], v[38:39], v[2:3] neg_lo:[0,1] neg_hi:[0,1]
	v_pk_add_f32 v[40:41], v[40:41], v[0:1] neg_lo:[0,1] neg_hi:[0,1]
	v_pk_add_f32 v[0:1], v[12:13], v[20:21] op_sel:[0,1] op_sel_hi:[1,0] neg_lo:[0,1]
	v_pk_add_f32 v[38:39], v[18:19], v[10:11] op_sel:[0,1] op_sel_hi:[1,0] neg_lo:[0,1]
	v_pk_add_f32 v[34:35], v[16:17], v[28:29] op_sel:[0,1] op_sel_hi:[1,0] neg_lo:[0,1]
	v_pk_add_f32 v[30:31], v[6:7], v[26:27] op_sel:[0,1] op_sel_hi:[1,0] neg_lo:[0,1]
	v_pk_add_f32 v[20:21], v[12:13], v[20:21] op_sel:[0,1] op_sel_hi:[1,0] neg_hi:[0,1]
	v_pk_add_f32 v[18:19], v[18:19], v[10:11] op_sel:[0,1] op_sel_hi:[1,0] neg_hi:[0,1]
	v_pk_add_f32 v[16:17], v[16:17], v[28:29] op_sel:[0,1] op_sel_hi:[1,0] neg_hi:[0,1]
	v_pk_add_f32 v[6:7], v[6:7], v[26:27] op_sel:[0,1] op_sel_hi:[1,0] neg_hi:[0,1]
	v_pk_mul_f32 v[26:27], v[38:39], s[82:83] op_sel_hi:[1,0]
	v_pk_mul_f32 v[28:29], v[24:25], s[76:77] op_sel_hi:[1,0]
	v_pk_mul_f32 v[10:11], v[18:19], s[44:45] op_sel_hi:[1,0]
	v_pk_mul_f32 v[12:13], v[34:35], s[76:77] op_sel_hi:[1,0]
	v_pk_mul_f32 v[42:43], v[16:17], s[76:77] op_sel_hi:[1,0]
	v_pk_mul_f32 v[44:45], v[30:31], s[44:45] op_sel_hi:[1,0]
	v_pk_mul_f32 v[46:47], v[40:41], s[76:77] op_sel_hi:[1,0]
	v_pk_mul_f32 v[48:49], v[6:7], s[70:71] op_sel_hi:[1,0]
	v_pk_fma_f32 v[26:27], v[38:39], s[44:45], v[26:27] op_sel:[0,0,1] op_sel_hi:[1,0,0] neg_lo:[0,0,1]
	v_pk_fma_f32 v[24:25], v[24:25], s[76:77], v[28:29] op_sel:[0,0,1] op_sel_hi:[1,0,0] neg_lo:[0,0,1]
	v_pk_fma_f32 v[10:11], v[18:19], s[82:83], v[10:11] op_sel:[0,0,1] op_sel_hi:[1,0,0] neg_lo:[0,0,1]
	v_pk_fma_f32 v[12:13], v[34:35], s[76:77], v[12:13] op_sel:[0,0,1] op_sel_hi:[1,0,0] neg_lo:[0,0,1]
	v_pk_fma_f32 v[42:43], v[16:17], s[72:73], v[42:43] op_sel:[0,0,1] op_sel_hi:[1,0,0] neg_lo:[0,0,1]
	v_pk_fma_f32 v[30:31], v[30:31], s[82:83], v[44:45] op_sel:[0,0,1] op_sel_hi:[1,0,0] neg_lo:[0,0,1]
	v_pk_fma_f32 v[40:41], v[40:41], s[72:73], v[46:47] op_sel:[0,0,1] op_sel_hi:[1,0,0] neg_lo:[0,0,1]
	v_pk_fma_f32 v[48:49], v[6:7], s[64:65], v[48:49] op_sel:[0,0,1] op_sel_hi:[1,0,0] neg_lo:[0,0,1]
	v_pk_add_f32 v[6:7], v[14:15], v[32:33]
	v_pk_add_f32 v[46:47], v[0:1], v[12:13]
	v_pk_add_f32 v[44:45], v[22:23], v[2:3] op_sel:[0,1] op_sel_hi:[1,0] neg_lo:[0,1]
	v_pk_add_f32 v[16:17], v[20:21], v[42:43]
	v_pk_add_f32 v[32:33], v[14:15], v[32:33] neg_lo:[0,1] neg_hi:[0,1]
	v_pk_add_f32 v[0:1], v[0:1], v[12:13] neg_lo:[0,1] neg_hi:[0,1]
	v_pk_add_f32 v[22:23], v[22:23], v[2:3] op_sel:[0,1] op_sel_hi:[1,0] neg_hi:[0,1]
; template <bool INV> __device__ __forceinline__ void bfly16(f32x2 (&x)[16], const LAS f32x2* TH, const LAS f32x2* TL, int tw) {
;     f32x2 W = tw32k(TH, TL, tw); if (INV) W.y = -W.y;
;     if (INV) { f32x2 p = W;
; #pragma unroll
;         for (int q = 1; q < 16; ++q) { x[q] = cmul(x[q], p); if (q < 15) p = cmul(p, W); } }
;     dft16<INV>(x);
;     if (!INV) { f32x2 p = W;
; #pragma unroll
;         for (int r = 1; r < 16; ++r) { x[4 * (r & 3) + (r >> 2)] = cmul(x[4 * (r & 3) + (r >> 2)], p); if (r < 15) p = cmul(p, W); } }
; }
; template <bool INV> __device__ __forceinline__ void bfly16_tab(f32x2 (&x)[16], const LAS f32x2* T, int tstride, int j) {
;     if (INV) {
; #pragma unroll
;         for (int q = 1; q < 16; ++q) { f32x2 p = T[q * tstride + j]; p.y = -p.y; x[q] = cmul(x[q], p); } }
;     dft16<INV>(x);
;     if (!INV) {
; #pragma unroll
;         for (int r = 1; r < 16; ++r) { const f32x2 p = T[r * tstride + j]; x[4 * (r & 3) + (r >> 2)] = cmul(x[4 * (r & 3) + (r >> 2)], p); } }
; }
; template <bool INV> __device__ __forceinline__ void pass16_s64(LAS f32x2* X, const LAS f32x2* TH, int base, int j) {
;     f32x2 x[16];
; #pragma unroll
;     for (int q = 0; q < 16; ++q) x[q] = X[base + q * 68];
;     bfly16_tab<INV>(x, TH - 2048, 64, j);
; #pragma unroll
;     for (int c = 0; c < 4; ++c)
; #pragma unroll
;         for (int d = 0; d < 4; ++d) X[base + (c + 4 * d) * 68] = x[4 * c + d];
; }
; template <bool INV> __device__ __forceinline__ void pass16(LAS f32x2* X, const LAS f32x2* TH, const LAS f32x2* TL, int base, int stride, int tw) {
;     f32x2 x[16];
; #pragma unroll
;     for (int q = 0; q < 16; ++q) x[q] = X[base + q * stride];
;     bfly16<INV>(x, TH, TL, tw);
; #pragma unroll
;     for (int c = 0; c < 4; ++c)
; #pragma unroll
;         for (int d = 0; d < 4; ++d) X[base + (c + 4 * d) * stride] = x[4 * c + d];
; }
; __device__ __forceinline__ void fft_inv_tail(LAS f32x2* X, const LAS f32x2* TH, const LAS f32x2* TL, int tid) {
;     pass16_s4<true>(X, TH, TL, tid);
;     LDS_BARRIER();
; #pragma unroll 1
;     for (int i = 0; i < 2; ++i) { const int b = tid + NTHR * i, j = b & 63, blk = b >> 6; pass16_s64<true>(X, TH, blk * 1088 + j, j); }
;     LDS_BARRIER();
; #pragma unroll 1
;     for (int i = 0; i < 2; ++i) { const int j = tid + NTHR * i; pass16<true>(X, TH, TL, j + ((j >> 6) << 2), 1088, 2 * j); }
;     LDS_BARRIER();
	v_pk_add_f32 v[20:21], v[20:21], v[42:43] neg_lo:[0,1] neg_hi:[0,1]
	v_pk_add_f32 v[42:43], v[4:5], v[8:9]
	v_pk_add_f32 v[2:3], v[26:27], v[30:31]
	v_pk_add_f32 v[12:13], v[24:25], v[40:41]
	v_pk_add_f32 v[14:15], v[10:11], v[48:49]
	v_pk_add_f32 v[4:5], v[4:5], v[8:9] neg_lo:[0,1] neg_hi:[0,1]
	v_pk_add_f32 v[26:27], v[26:27], v[30:31] neg_lo:[0,1] neg_hi:[0,1]
	v_pk_add_f32 v[40:41], v[24:25], v[40:41] neg_lo:[0,1] neg_hi:[0,1]
	v_pk_add_f32 v[10:11], v[10:11], v[48:49] neg_lo:[0,1] neg_hi:[0,1]
	v_pk_add_f32 v[48:49], v[6:7], v[42:43]
	v_pk_add_f32 v[24:25], v[46:47], v[2:3]
	v_pk_add_f32 v[30:31], v[44:45], v[12:13]
	v_pk_add_f32 v[8:9], v[16:17], v[14:15]
	v_pk_add_f32 v[42:43], v[6:7], v[42:43] neg_lo:[0,1] neg_hi:[0,1]
	v_pk_add_f32 v[46:47], v[46:47], v[2:3] neg_lo:[0,1] neg_hi:[0,1]
	v_pk_add_f32 v[12:13], v[44:45], v[12:13] neg_lo:[0,1] neg_hi:[0,1]
	v_pk_add_f32 v[16:17], v[16:17], v[14:15] neg_lo:[0,1] neg_hi:[0,1]
	v_pk_add_f32 v[14:15], v[32:33], v[4:5] op_sel:[0,1] op_sel_hi:[1,0] neg_lo:[0,1]
	v_pk_add_f32 v[44:45], v[0:1], v[26:27] op_sel:[0,1] op_sel_hi:[1,0] neg_lo:[0,1]
	v_pk_add_f32 v[2:3], v[22:23], v[40:41] op_sel:[0,1] op_sel_hi:[1,0] neg_lo:[0,1]
	v_pk_add_f32 v[6:7], v[20:21], v[10:11] op_sel:[0,1] op_sel_hi:[1,0] neg_lo:[0,1]
	v_pk_add_f32 v[32:33], v[32:33], v[4:5] op_sel:[0,1] op_sel_hi:[1,0] neg_hi:[0,1]
	v_pk_add_f32 v[0:1], v[0:1], v[26:27] op_sel:[0,1] op_sel_hi:[1,0] neg_hi:[0,1]
	v_pk_add_f32 v[22:23], v[22:23], v[40:41] op_sel:[0,1] op_sel_hi:[1,0] neg_hi:[0,1]
	v_pk_add_f32 v[20:21], v[20:21], v[10:11] op_sel:[0,1] op_sel_hi:[1,0] neg_hi:[0,1]
	ds_write2_b64 v253, v[48:49], v[24:25] offset0:0 offset1:68
	ds_write2_b64 v253, v[30:31], v[8:9] offset0:136 offset1:204
	ds_write2_b64 v250, v[14:15], v[44:45] offset0:16 offset1:84
	ds_write2_b64 v250, v[2:3], v[6:7] offset0:152 offset1:220
	ds_write2_b64 v251, v[42:43], v[46:47] offset0:32 offset1:100
	ds_write2_b64 v251, v[12:13], v[16:17] offset0:168 offset1:236
	ds_write2_b64 v248, v[32:33], v[0:1] offset0:48 offset1:116
	ds_write2_b64 v248, v[22:23], v[20:21] offset0:184 offset1:252
	s_cbranch_scc1 .LBB0_854
	s_waitcnt lgkmcnt(0)
	s_barrier
	s_mov_b32 s0, 0
	s_mov_b64 s[12:13], -1
.LBB0_856:
	v_add_u32_e32 v252, s0, v140
	v_lshrrev_b32_e32 v253, 6, v252
	v_and_b32_e32 v248, 63, v252
	v_lshlrev_b32_e32 v250, 5, v253
	v_lshlrev_b32_e32 v251, 3, v253
	v_lshlrev_b32_e32 v248, 4, v248
	v_lshl_add_u32 v250, v252, 3, v250
	v_add_u32_e32 v251, 0x26000, v251
	v_add_u32_e32 v248, 0x26400, v248
	ds_read_b64 v[0:1], v251
	ds_read_b64 v[2:3], v248
	ds_read2st64_b64 v[4:7], v250 offset0:0 offset1:17
	ds_read2st64_b64 v[8:11], v250 offset0:34 offset1:51
	ds_read2st64_b64 v[12:15], v250 offset0:68 offset1:85
	ds_read2st64_b64 v[16:19], v250 offset0:102 offset1:119
	ds_read2st64_b64 v[20:23], v250 offset0:136 offset1:153
	ds_read2st64_b64 v[24:27], v250 offset0:170 offset1:187
	ds_read2st64_b64 v[28:31], v250 offset0:204 offset1:221
	ds_read2st64_b64 v[32:35], v250 offset0:238 offset1:255
	s_cmp_eq_u32 s0, 0
	s_movk_i32 s0, 0x200
	s_mov_b64 s[12:13], 0
	s_waitcnt lgkmcnt(8)
	v_pk_mul_f32 v[36:37], v[0:1], v[2:3] op_sel:[0,1] op_sel_hi:[1,1]
	s_nop 0
	v_pk_fma_f32 v[36:37], v[0:1], v[2:3], v[36:37] op_sel:[0,0,1] op_sel_hi:[1,0,0] neg_lo:[0,0,1]
	s_nop 0
	v_pk_mul_f32 v[2:3], v[36:37], v[36:37] op_sel:[0,1] op_sel_hi:[1,1]
	s_nop 0
	v_pk_fma_f32 v[2:3], v[36:37], v[36:37], v[2:3] op_sel:[0,0,1] op_sel_hi:[1,0,0] neg_lo:[0,0,1]
	s_nop 0
	v_pk_mul_f32 v[0:1], v[2:3], v[36:37] op_sel:[0,1] op_sel_hi:[1,1]
	v_pk_mul_f32 v[38:39], v[2:3], v[2:3] op_sel:[0,1] op_sel_hi:[1,1]
	v_pk_fma_f32 v[0:1], v[2:3], v[36:37], v[0:1] op_sel:[0,0,1] op_sel_hi:[1,0,0] neg_lo:[0,0,1]
	v_pk_fma_f32 v[38:39], v[2:3], v[2:3], v[38:39] op_sel:[0,0,1] op_sel_hi:[1,0,0] neg_lo:[0,0,1]
	s_nop 0
	v_pk_mul_f32 v[40:41], v[38:39], v[36:37] op_sel:[0,1] op_sel_hi:[1,1]
	v_pk_mul_f32 v[42:43], v[38:39], v[2:3] op_sel:[0,1] op_sel_hi:[1,1]
	v_pk_mul_f32 v[44:45], v[38:39], v[0:1] op_sel:[0,1] op_sel_hi:[1,1]
	v_pk_fma_f32 v[40:41], v[38:39], v[36:37], v[40:41] op_sel:[0,0,1] op_sel_hi:[1,0,0] neg_lo:[0,0,1]
	v_pk_fma_f32 v[42:43], v[38:39], v[2:3], v[42:43] op_sel:[0,0,1] op_sel_hi:[1,0,0] neg_lo:[0,0,1]
	v_pk_fma_f32 v[44:45], v[38:39], v[0:1], v[44:45] op_sel:[0,0,1] op_sel_hi:[1,0,0] neg_lo:[0,0,1]
	v_pk_mul_f32 v[46:47], v[38:39], v[38:39] op_sel:[0,1] op_sel_hi:[1,1]
	s_nop 0
	v_pk_fma_f32 v[46:47], v[38:39], v[38:39], v[46:47] op_sel:[0,0,1] op_sel_hi:[1,0,0] neg_lo:[0,0,1]
	s_nop 0
	v_pk_mul_f32 v[48:49], v[46:47], v[36:37] op_sel:[0,1] op_sel_hi:[1,1]
	v_pk_mul_f32 v[50:51], v[46:47], v[2:3] op_sel:[0,1] op_sel_hi:[1,1]
	v_pk_mul_f32 v[52:53], v[46:47], v[0:1] op_sel:[0,1] op_sel_hi:[1,1]
	v_pk_fma_f32 v[48:49], v[46:47], v[36:37], v[48:49] op_sel:[0,0,1] op_sel_hi:[1,0,0] neg_lo:[0,0,1]
	v_pk_fma_f32 v[50:51], v[46:47], v[2:3], v[50:51] op_sel:[0,0,1] op_sel_hi:[1,0,0] neg_lo:[0,0,1]
	v_pk_fma_f32 v[52:53], v[46:47], v[0:1], v[52:53] op_sel:[0,0,1] op_sel_hi:[1,0,0] neg_lo:[0,0,1]
	v_pk_mul_f32 v[54:55], v[46:47], v[38:39] op_sel:[0,1] op_sel_hi:[1,1]
	v_pk_mul_f32 v[56:57], v[46:47], v[40:41] op_sel:[0,1] op_sel_hi:[1,1]
	v_pk_mul_f32 v[58:59], v[46:47], v[42:43] op_sel:[0,1] op_sel_hi:[1,1]
	v_pk_fma_f32 v[54:55], v[46:47], v[38:39], v[54:55] op_sel:[0,0,1] op_sel_hi:[1,0,0] neg_lo:[0,0,1]
	v_pk_fma_f32 v[56:57], v[46:47], v[40:41], v[56:57] op_sel:[0,0,1] op_sel_hi:[1,0,0] neg_lo:[0,0,1]
	v_pk_fma_f32 v[58:59], v[46:47], v[42:43], v[58:59] op_sel:[0,0,1] op_sel_hi:[1,0,0] neg_lo:[0,0,1]
	v_pk_mul_f32 v[188:189], v[46:47], v[44:45] op_sel:[0,1] op_sel_hi:[1,1]
	s_nop 0
	v_pk_fma_f32 v[188:189], v[46:47], v[44:45], v[188:189] op_sel:[0,0,1] op_sel_hi:[1,0,0] neg_lo:[0,0,1]
	s_waitcnt lgkmcnt(7)
; #define LAS __attribute__((address_space(3)))
; __device__ __forceinline__ f32x2 cmul(f32x2 a, f32x2 b) { return (f32x2){a.x * b.x - a.y * b.y, a.x * b.y + a.y * b.x}; }
; __device__ __forceinline__ f32x2 tw32k(const LAS f32x2* TH, const LAS f32x2* TL, int n) { return cmul(TH[n >> 7], TL[n & 127]); }
; template <bool INV> __device__ __forceinline__ void dft16(f32x2 (&x)[16]) {
; #pragma unroll
;     for (int b = 0; b < 4; ++b) r4<INV>(x[b], x[4 + b], x[8 + b], x[12 + b]);
;     const float sg = INV ? -1.f : 1.f;
;     const f32x2 W1 = {0.92387953251f, -0.38268343236f * sg}, W2 = {0.70710678118f, -0.70710678118f * sg}, W3 = {0.38268343236f, -0.92387953251f * sg},
;                 W4 = {0.f, -1.f * sg}, W6 = {-0.70710678118f, -0.70710678118f * sg}, W9 = {-0.92387953251f, 0.38268343236f * sg};
;     x[5] = cmul(x[5], W1); x[9] = cmul(x[9], W2); x[13] = cmul(x[13], W3);
;     x[6] = cmul(x[6], W2); x[10] = cmul(x[10], W4); x[14] = cmul(x[14], W6);
;     x[7] = cmul(x[7], W3); x[11] = cmul(x[11], W6); x[15] = cmul(x[15], W9);
; #pragma unroll
;     for (int c = 0; c < 4; ++c) r4<INV>(x[4 * c], x[4 * c + 1], x[4 * c + 2], x[4 * c + 3]);
; }
; template <bool INV> __device__ __forceinline__ void bfly16(f32x2 (&x)[16], const LAS f32x2* TH, const LAS f32x2* TL, int tw) {
;     f32x2 W = tw32k(TH, TL, tw); if (INV) W.y = -W.y;
;     if (INV) { f32x2 p = W;
; #pragma unroll
;         for (int q = 1; q < 16; ++q) { x[q] = cmul(x[q], p); if (q < 15) p = cmul(p, W); } }
;     dft16<INV>(x);
	v_pk_mul_f32 v[190:191], v[6:7], v[36:37] op_sel:[0,1] op_sel_hi:[1,1]
	s_waitcnt lgkmcnt(6)
	v_pk_mul_f32 v[192:193], v[8:9], v[2:3] op_sel:[0,1] op_sel_hi:[1,1]
	v_pk_fma_f32 v[6:7], v[6:7], v[36:37], v[190:191] op_sel:[0,0,1] op_sel_hi:[1,0,0] neg_hi:[0,0,1]
	v_pk_mul_f32 v[36:37], v[10:11], v[0:1] op_sel:[0,1] op_sel_hi:[1,1]
	v_pk_fma_f32 v[8:9], v[8:9], v[2:3], v[192:193] op_sel:[0,0,1] op_sel_hi:[1,0,0] neg_hi:[0,0,1]
	s_waitcnt lgkmcnt(5)
	v_pk_mul_f32 v[2:3], v[12:13], v[38:39] op_sel:[0,1] op_sel_hi:[1,1]
	v_pk_fma_f32 v[0:1], v[10:11], v[0:1], v[36:37] op_sel:[0,0,1] op_sel_hi:[1,0,0] neg_hi:[0,0,1]
	v_pk_mul_f32 v[36:37], v[14:15], v[40:41] op_sel:[0,1] op_sel_hi:[1,1]
	v_pk_fma_f32 v[2:3], v[12:13], v[38:39], v[2:3] op_sel:[0,0,1] op_sel_hi:[1,0,0] neg_hi:[0,0,1]
	s_waitcnt lgkmcnt(4)
	v_pk_mul_f32 v[38:39], v[16:17], v[42:43] op_sel:[0,1] op_sel_hi:[1,1]
	v_pk_fma_f32 v[40:41], v[14:15], v[40:41], v[36:37] op_sel:[0,0,1] op_sel_hi:[1,0,0] neg_hi:[0,0,1]
	v_pk_mul_f32 v[36:37], v[18:19], v[44:45] op_sel:[0,1] op_sel_hi:[1,1]
	v_pk_fma_f32 v[42:43], v[16:17], v[42:43], v[38:39] op_sel:[0,0,1] op_sel_hi:[1,0,0] neg_hi:[0,0,1]
	s_waitcnt lgkmcnt(3)
	v_pk_mul_f32 v[16:17], v[20:21], v[46:47] op_sel:[0,1] op_sel_hi:[1,1]
	v_pk_fma_f32 v[18:19], v[18:19], v[44:45], v[36:37] op_sel:[0,0,1] op_sel_hi:[1,0,0] neg_hi:[0,0,1]
	v_pk_mul_f32 v[36:37], v[22:23], v[48:49] op_sel:[0,1] op_sel_hi:[1,1]
	v_pk_fma_f32 v[16:17], v[20:21], v[46:47], v[16:17] op_sel:[0,0,1] op_sel_hi:[1,0,0] neg_hi:[0,0,1]
	s_waitcnt lgkmcnt(2)
	v_pk_mul_f32 v[20:21], v[24:25], v[50:51] op_sel:[0,1] op_sel_hi:[1,1]
	v_pk_fma_f32 v[36:37], v[22:23], v[48:49], v[36:37] op_sel:[0,0,1] op_sel_hi:[1,0,0] neg_hi:[0,0,1]
	v_pk_mul_f32 v[48:49], v[26:27], v[52:53] op_sel:[0,1] op_sel_hi:[1,1]
	v_pk_fma_f32 v[24:25], v[24:25], v[50:51], v[20:21] op_sel:[0,0,1] op_sel_hi:[1,0,0] neg_hi:[0,0,1]
	s_waitcnt lgkmcnt(1)
	v_pk_mul_f32 v[50:51], v[28:29], v[54:55] op_sel:[0,1] op_sel_hi:[1,1]
	v_pk_fma_f32 v[48:49], v[26:27], v[52:53], v[48:49] op_sel:[0,0,1] op_sel_hi:[1,0,0] neg_hi:[0,0,1]
	v_pk_mul_f32 v[52:53], v[30:31], v[56:57] op_sel:[0,1] op_sel_hi:[1,1]
	v_pk_fma_f32 v[28:29], v[28:29], v[54:55], v[50:51] op_sel:[0,0,1] op_sel_hi:[1,0,0] neg_hi:[0,0,1]
	s_waitcnt lgkmcnt(0)
	v_pk_mul_f32 v[50:51], v[32:33], v[58:59] op_sel:[0,1] op_sel_hi:[1,1]
	v_pk_fma_f32 v[52:53], v[30:31], v[56:57], v[52:53] op_sel:[0,0,1] op_sel_hi:[1,0,0] neg_hi:[0,0,1]
	v_pk_mul_f32 v[30:31], v[34:35], v[188:189] op_sel:[0,1] op_sel_hi:[1,1]
	v_pk_fma_f32 v[58:59], v[32:33], v[58:59], v[50:51] op_sel:[0,0,1] op_sel_hi:[1,0,0] neg_hi:[0,0,1]
	v_pk_fma_f32 v[30:31], v[34:35], v[188:189], v[30:31] op_sel:[0,0,1] op_sel_hi:[1,0,0] neg_hi:[0,0,1]
	v_pk_add_f32 v[34:35], v[4:5], v[16:17]
	v_pk_add_f32 v[188:189], v[6:7], v[36:37]
	v_pk_add_f32 v[32:33], v[8:9], v[24:25]
	v_pk_add_f32 v[50:51], v[0:1], v[48:49]
	v_pk_add_f32 v[16:17], v[4:5], v[16:17] neg_lo:[0,1] neg_hi:[0,1]
	v_pk_add_f32 v[6:7], v[6:7], v[36:37] neg_lo:[0,1] neg_hi:[0,1]
	v_pk_add_f32 v[24:25], v[8:9], v[24:25] neg_lo:[0,1] neg_hi:[0,1]
	v_pk_add_f32 v[0:1], v[0:1], v[48:49] neg_lo:[0,1] neg_hi:[0,1]
	v_pk_add_f32 v[48:49], v[2:3], v[28:29]
	v_pk_add_f32 v[8:9], v[40:41], v[52:53]
	v_pk_add_f32 v[36:37], v[42:43], v[58:59]
	v_pk_add_f32 v[4:5], v[18:19], v[30:31]
	v_pk_add_f32 v[28:29], v[2:3], v[28:29] neg_lo:[0,1] neg_hi:[0,1]
	v_pk_add_f32 v[40:41], v[40:41], v[52:53] neg_lo:[0,1] neg_hi:[0,1]
	v_pk_add_f32 v[58:59], v[42:43], v[58:59] neg_lo:[0,1] neg_hi:[0,1]
	v_pk_add_f32 v[18:19], v[18:19], v[30:31] neg_lo:[0,1] neg_hi:[0,1]
	v_pk_add_f32 v[30:31], v[34:35], v[48:49]
	v_pk_add_f32 v[42:43], v[188:189], v[8:9]
	v_pk_add_f32 v[52:53], v[32:33], v[36:37]
	v_pk_add_f32 v[2:3], v[50:51], v[4:5]
	v_pk_add_f32 v[48:49], v[34:35], v[48:49] neg_lo:[0,1] neg_hi:[0,1]
	v_pk_add_f32 v[188:189], v[188:189], v[8:9] neg_lo:[0,1] neg_hi:[0,1]
	v_pk_add_f32 v[36:37], v[32:33], v[36:37] neg_lo:[0,1] neg_hi:[0,1]
	v_pk_add_f32 v[50:51], v[50:51], v[4:5] neg_lo:[0,1] neg_hi:[0,1]
	v_pk_add_f32 v[4:5], v[16:17], v[28:29] op_sel:[0,1] op_sel_hi:[1,0] neg_lo:[0,1]
	v_pk_add_f32 v[32:33], v[6:7], v[40:41] op_sel:[0,1] op_sel_hi:[1,0] neg_lo:[0,1]
	v_pk_add_f32 v[8:9], v[24:25], v[58:59] op_sel:[0,1] op_sel_hi:[1,0] neg_lo:[0,1]
	v_pk_add_f32 v[34:35], v[0:1], v[18:19] op_sel:[0,1] op_sel_hi:[1,0] neg_lo:[0,1]
	v_pk_add_f32 v[16:17], v[16:17], v[28:29] op_sel:[0,1] op_sel_hi:[1,0] neg_hi:[0,1]
	v_pk_add_f32 v[40:41], v[6:7], v[40:41] op_sel:[0,1] op_sel_hi:[1,0] neg_hi:[0,1]
	v_pk_add_f32 v[24:25], v[24:25], v[58:59] op_sel:[0,1] op_sel_hi:[1,0] neg_hi:[0,1]
	v_pk_add_f32 v[18:19], v[0:1], v[18:19] op_sel:[0,1] op_sel_hi:[1,0] neg_hi:[0,1]
	v_pk_mul_f32 v[0:1], v[32:33], s[82:83] op_sel_hi:[1,0]
	v_pk_mul_f32 v[58:59], v[188:189], s[76:77] op_sel_hi:[1,0]
	v_pk_mul_f32 v[6:7], v[40:41], s[44:45] op_sel_hi:[1,0]
	v_pk_mul_f32 v[28:29], v[8:9], s[76:77] op_sel_hi:[1,0]
	v_pk_mul_f32 v[56:57], v[24:25], s[76:77] op_sel_hi:[1,0]
	v_pk_mul_f32 v[54:55], v[34:35], s[44:45] op_sel_hi:[1,0]
	v_pk_mul_f32 v[26:27], v[50:51], s[76:77] op_sel_hi:[1,0]
	v_pk_mul_f32 v[20:21], v[18:19], s[70:71] op_sel_hi:[1,0]
	v_pk_fma_f32 v[32:33], v[32:33], s[44:45], v[0:1] op_sel:[0,0,1] op_sel_hi:[1,0,0] neg_lo:[0,0,1]
	v_pk_fma_f32 v[188:189], v[188:189], s[76:77], v[58:59] op_sel:[0,0,1] op_sel_hi:[1,0,0] neg_lo:[0,0,1]
	v_pk_fma_f32 v[40:41], v[40:41], s[82:83], v[6:7] op_sel:[0,0,1] op_sel_hi:[1,0,0] neg_lo:[0,0,1]
	v_pk_fma_f32 v[8:9], v[8:9], s[76:77], v[28:29] op_sel:[0,0,1] op_sel_hi:[1,0,0] neg_lo:[0,0,1]
	v_pk_fma_f32 v[56:57], v[24:25], s[72:73], v[56:57] op_sel:[0,0,1] op_sel_hi:[1,0,0] neg_lo:[0,0,1]
; #define LAS __attribute__((address_space(3)))
; #define LT() ({ int lt_ = tid; asm volatile("" : "+v"(lt_)); lt_; })
; template <bool INV> __device__ __forceinline__ void pass16(LAS f32x2* X, const LAS f32x2* TH, const LAS f32x2* TL, int base, int stride, int tw) {
;     ...
; #pragma unroll
;     for (int c = 0; c < 4; ++c)
; #pragma unroll
;         for (int d = 0; d < 4; ++d) X[base + (c + 4 * d) * stride] = x[4 * c + d];
; }
; __device__ __forceinline__ void hyena_latent(Frame& F, int l, int ch, LAS f32x2* X, const LAS f32x2* TH, const LAS f32x2* TL, GAS f32x2* KS, const LAS float* CT  , bool wr = true) {
;     ...
;             if (par == 0) {
; #pragma unroll
;                 for (int i = 0; i < 8; ++i) { const int g = LT() + NTHR * i; const LAS f32x4* XP = (const LAS f32x4*)(X + phys(4 * g)); KE4[2 * g] = XP[0]; KE4[2 * g + 1] = XP[1]; }
;                 __syncthreads();
;             }
	v_pk_fma_f32 v[54:55], v[34:35], s[82:83], v[54:55] op_sel:[0,0,1] op_sel_hi:[1,0,0] neg_lo:[0,0,1]
	v_pk_fma_f32 v[26:27], v[50:51], s[72:73], v[26:27] op_sel:[0,0,1] op_sel_hi:[1,0,0] neg_lo:[0,0,1]
	v_pk_fma_f32 v[18:19], v[18:19], s[64:65], v[20:21] op_sel:[0,0,1] op_sel_hi:[1,0,0] neg_lo:[0,0,1]
	v_pk_add_f32 v[20:21], v[30:31], v[52:53]
	v_pk_add_f32 v[50:51], v[4:5], v[8:9]
	v_pk_add_f32 v[34:35], v[48:49], v[36:37] op_sel:[0,1] op_sel_hi:[1,0] neg_lo:[0,1]
	v_pk_add_f32 v[24:25], v[16:17], v[56:57]
	v_pk_add_f32 v[52:53], v[30:31], v[52:53] neg_lo:[0,1] neg_hi:[0,1]
	v_pk_add_f32 v[4:5], v[4:5], v[8:9] neg_lo:[0,1] neg_hi:[0,1]
	v_pk_add_f32 v[48:49], v[48:49], v[36:37] op_sel:[0,1] op_sel_hi:[1,0] neg_hi:[0,1]
	v_pk_add_f32 v[56:57], v[16:17], v[56:57] neg_lo:[0,1] neg_hi:[0,1]
	v_pk_add_f32 v[16:17], v[42:43], v[2:3]
	v_pk_add_f32 v[36:37], v[32:33], v[54:55]
	v_pk_add_f32 v[8:9], v[188:189], v[26:27]
	v_pk_add_f32 v[30:31], v[40:41], v[18:19]
	v_pk_add_f32 v[42:43], v[42:43], v[2:3] neg_lo:[0,1] neg_hi:[0,1]
	v_pk_add_f32 v[32:33], v[32:33], v[54:55] neg_lo:[0,1] neg_hi:[0,1]
	v_pk_add_f32 v[188:189], v[188:189], v[26:27] neg_lo:[0,1] neg_hi:[0,1]
	v_pk_add_f32 v[40:41], v[40:41], v[18:19] neg_lo:[0,1] neg_hi:[0,1]
	v_pk_add_f32 v[18:19], v[20:21], v[16:17]
	v_pk_add_f32 v[26:27], v[50:51], v[36:37]
	v_pk_add_f32 v[54:55], v[34:35], v[8:9]
	v_pk_add_f32 v[2:3], v[24:25], v[30:31]
	v_pk_add_f32 v[20:21], v[20:21], v[16:17] neg_lo:[0,1] neg_hi:[0,1]
	v_pk_add_f32 v[50:51], v[50:51], v[36:37] neg_lo:[0,1] neg_hi:[0,1]
	v_pk_add_f32 v[8:9], v[34:35], v[8:9] neg_lo:[0,1] neg_hi:[0,1]
	v_pk_add_f32 v[30:31], v[24:25], v[30:31] neg_lo:[0,1] neg_hi:[0,1]
	v_pk_add_f32 v[24:25], v[52:53], v[42:43] op_sel:[0,1] op_sel_hi:[1,0] neg_lo:[0,1]
	v_pk_add_f32 v[34:35], v[4:5], v[32:33] op_sel:[0,1] op_sel_hi:[1,0] neg_lo:[0,1]
	v_pk_add_f32 v[36:37], v[48:49], v[188:189] op_sel:[0,1] op_sel_hi:[1,0] neg_lo:[0,1]
	v_pk_add_f32 v[16:17], v[56:57], v[40:41] op_sel:[0,1] op_sel_hi:[1,0] neg_lo:[0,1]
	v_pk_add_f32 v[52:53], v[52:53], v[42:43] op_sel:[0,1] op_sel_hi:[1,0] neg_hi:[0,1]
	v_pk_add_f32 v[32:33], v[4:5], v[32:33] op_sel:[0,1] op_sel_hi:[1,0] neg_hi:[0,1]
	v_pk_add_f32 v[188:189], v[48:49], v[188:189] op_sel:[0,1] op_sel_hi:[1,0] neg_hi:[0,1]
	v_pk_add_f32 v[56:57], v[56:57], v[40:41] op_sel:[0,1] op_sel_hi:[1,0] neg_hi:[0,1]
	ds_write2st64_b64 v250, v[18:19], v[26:27] offset0:0 offset1:17
	ds_write2st64_b64 v250, v[54:55], v[2:3] offset0:34 offset1:51
	ds_write2st64_b64 v250, v[24:25], v[34:35] offset0:68 offset1:85
	ds_write2st64_b64 v250, v[36:37], v[16:17] offset0:102 offset1:119
	ds_write2st64_b64 v250, v[20:21], v[50:51] offset0:136 offset1:153
	ds_write2st64_b64 v250, v[8:9], v[30:31] offset0:170 offset1:187
	ds_write2st64_b64 v250, v[52:53], v[32:33] offset0:204 offset1:221
	ds_write2st64_b64 v250, v[188:189], v[56:57] offset0:238 offset1:255
	s_cbranch_scc1 .LBB0_856
	s_waitcnt lgkmcnt(0)
	s_barrier
	s_andn2_b64 vcc, exec, s[34:35]
	s_mov_b64 s[12:13], -1
	s_cbranch_vccnz .LBB0_662
	v_mov_b32_e32 v1, v140
	s_mov_b64 s[12:13], 0
	v_lshlrev_b32_e32 v0, 1, v1
	v_and_b32_e32 v2, 0xffffffe0, v0
	v_lshlrev_b32_e32 v1, 5, v1
	v_add3_u32 v4, 0, v2, v1
	v_ashrrev_i32_e32 v1, 31, v0
	v_lshl_add_u64 v[8:9], v[0:1], 4, s[18:19]
	ds_read_b128 v[0:3], v4
	ds_read_b128 v[4:7], v4 offset:16
	s_waitcnt lgkmcnt(1)
	global_store_dwordx4 v[8:9], v[0:3], off
	s_waitcnt lgkmcnt(0)
	global_store_dwordx4 v[8:9], v[4:7], off offset:16
	v_mov_b32_e32 v0, v140
	s_nop 0
	v_add_u32_e32 v1, 0x200, v0
	v_lshlrev_b32_e32 v0, 1, v1
	v_and_b32_e32 v2, 0xffffffe0, v0
	v_lshlrev_b32_e32 v1, 5, v1
	v_add3_u32 v4, 0, v2, v1
	v_ashrrev_i32_e32 v1, 31, v0
	v_lshl_add_u64 v[8:9], v[0:1], 4, s[18:19]
	ds_read_b128 v[0:3], v4
	ds_read_b128 v[4:7], v4 offset:16
	s_waitcnt lgkmcnt(1)
	global_store_dwordx4 v[8:9], v[0:3], off
	s_waitcnt lgkmcnt(0)
	global_store_dwordx4 v[8:9], v[4:7], off offset:16
	v_mov_b32_e32 v0, v140
	s_nop 0
	v_add_u32_e32 v1, 0x400, v0
	v_lshlrev_b32_e32 v0, 1, v1
	v_and_b32_e32 v2, 0xffffffe0, v0
	v_lshlrev_b32_e32 v1, 5, v1
	v_add3_u32 v4, 0, v2, v1
	v_ashrrev_i32_e32 v1, 31, v0
	v_lshl_add_u64 v[8:9], v[0:1], 4, s[18:19]
	ds_read_b128 v[0:3], v4
	ds_read_b128 v[4:7], v4 offset:16
	s_waitcnt lgkmcnt(1)
	global_store_dwordx4 v[8:9], v[0:3], off
	s_waitcnt lgkmcnt(0)
	global_store_dwordx4 v[8:9], v[4:7], off offset:16
	v_mov_b32_e32 v0, v140
	s_nop 0
	v_add_u32_e32 v1, 0x600, v0
	v_lshlrev_b32_e32 v0, 1, v1
	v_and_b32_e32 v2, 0xffffffe0, v0
	v_lshlrev_b32_e32 v1, 5, v1
	v_add3_u32 v4, 0, v2, v1
	v_ashrrev_i32_e32 v1, 31, v0
	v_lshl_add_u64 v[8:9], v[0:1], 4, s[18:19]
	ds_read_b128 v[0:3], v4
	ds_read_b128 v[4:7], v4 offset:16
	s_waitcnt lgkmcnt(1)
	global_store_dwordx4 v[8:9], v[0:3], off
	s_waitcnt lgkmcnt(0)
	global_store_dwordx4 v[8:9], v[4:7], off offset:16
	v_mov_b32_e32 v0, v140
	s_nop 0
	v_add_u32_e32 v1, 0x800, v0
	v_lshlrev_b32_e32 v0, 1, v1
	v_and_b32_e32 v2, 0xffffffe0, v0
	v_lshlrev_b32_e32 v1, 5, v1
	v_add3_u32 v4, 0, v2, v1
	v_ashrrev_i32_e32 v1, 31, v0
	v_lshl_add_u64 v[8:9], v[0:1], 4, s[18:19]
	ds_read_b128 v[0:3], v4
	ds_read_b128 v[4:7], v4 offset:16
	s_waitcnt lgkmcnt(1)
	global_store_dwordx4 v[8:9], v[0:3], off
	s_waitcnt lgkmcnt(0)
	global_store_dwordx4 v[8:9], v[4:7], off offset:16
	v_mov_b32_e32 v0, v140
	s_nop 0
	v_add_u32_e32 v1, 0xa00, v0
	v_lshlrev_b32_e32 v0, 1, v1
	v_and_b32_e32 v2, 0xffffffe0, v0
	v_lshlrev_b32_e32 v1, 5, v1
	v_add3_u32 v4, 0, v2, v1
	v_ashrrev_i32_e32 v1, 31, v0
	v_lshl_add_u64 v[8:9], v[0:1], 4, s[18:19]
	ds_read_b128 v[0:3], v4
	ds_read_b128 v[4:7], v4 offset:16
	s_waitcnt lgkmcnt(1)
	global_store_dwordx4 v[8:9], v[0:3], off
	s_waitcnt lgkmcnt(0)
	global_store_dwordx4 v[8:9], v[4:7], off offset:16
	v_mov_b32_e32 v0, v140
	s_nop 0
	v_add_u32_e32 v1, 0xc00, v0
	v_lshlrev_b32_e32 v0, 1, v1
	v_and_b32_e32 v2, 0xffffffe0, v0
	v_lshlrev_b32_e32 v1, 5, v1
	v_add3_u32 v4, 0, v2, v1
	v_ashrrev_i32_e32 v1, 31, v0
	v_lshl_add_u64 v[8:9], v[0:1], 4, s[18:19]
	ds_read_b128 v[0:3], v4
	ds_read_b128 v[4:7], v4 offset:16
	s_waitcnt lgkmcnt(1)
	global_store_dwordx4 v[8:9], v[0:3], off
	s_waitcnt lgkmcnt(0)
	global_store_dwordx4 v[8:9], v[4:7], off offset:16
	v_mov_b32_e32 v0, v140
	s_nop 0
	v_add_u32_e32 v1, 0xe00, v0
	v_lshlrev_b32_e32 v0, 1, v1
	v_and_b32_e32 v2, 0xffffffe0, v0
	v_lshlrev_b32_e32 v1, 5, v1
	v_add3_u32 v4, 0, v2, v1
	v_ashrrev_i32_e32 v1, 31, v0
	v_lshl_add_u64 v[8:9], v[0:1], 4, s[18:19]
	ds_read_b128 v[0:3], v4
	ds_read_b128 v[4:7], v4 offset:16
	s_waitcnt lgkmcnt(1)
	global_store_dwordx4 v[8:9], v[0:3], off
	s_waitcnt lgkmcnt(0)
	global_store_dwordx4 v[8:9], v[4:7], off offset:16
	s_barrier
	s_branch .LBB0_662

; #define GAS __attribute__((address_space(1)))
; #define LAS __attribute__((address_space(3)))
; #define LT() ({ int lt_ = tid; asm volatile("" : "+v"(lt_)); lt_; })
; __device__ __forceinline__ void fourier_latent(Frame& F, int b, int gq, int m, LAS f32x2* X, const LAS f32x2* TH, const LAS f32x2* TL, bool wr = true) {
;     ...
;     for (int i = 0; i < 8; ++i) { const int g = LT() + NTHR * i, n0 = 4 * g; const f32x4 a = *(const GAS f32x4*)(ra + n0), c = *(const GAS f32x4*)(rb + n0);
;         LAS f32x4* XP = (LAS f32x4*)(X + phys(n0)); XP[0] = (f32x4){a.x, c.x, a.y, c.y}; XP[1] = (f32x4){a.z, c.z, a.w, c.w}; }
.LBB0_943:
	s_lshl_b32 s0, s4, 1
	s_and_b32 s5, s4, 63
	s_and_b32 s0, s0, 0x180
	s_or_b32 s0, s0, s5
	s_mul_i32 s0, s0, 0x20800
	s_add_u32 s0, s50, s0
	s_addc_u32 s8, s62, 0
	s_lshl_b32 s2, s4, 6
	s_and_b32 s2, s2, 0xffffc000
	s_ashr_i32 s3, s2, 31
	s_lshl_b64 s[2:3], s[2:3], 2
	s_add_u32 s10, s0, s2
	v_mov_b32_e32 v8, v140
	s_addc_u32 s11, s8, s3
	s_add_u32 s12, s10, 0x820000
	v_lshlrev_b32_e32 v0, 2, v8
	v_ashrrev_i32_e32 v1, 31, v0
	s_addc_u32 s13, s11, 0
	v_lshlrev_b64 v[4:5], 2, v[0:1]
	v_lshl_add_u64 v[0:1], s[10:11], 0, v[4:5]
	v_lshl_add_u64 v[4:5], s[12:13], 0, v[4:5]
	v_lshlrev_b32_e32 v60, 4, v140
	global_load_dwordx4 v[64:67], v60, s[10:11]
	global_load_dwordx4 v[68:71], v60, s[12:13]
	v_add_u32_e32 v62, 0x2000, v60
	global_load_dwordx4 v[72:75], v62, s[10:11]
	global_load_dwordx4 v[76:79], v62, s[12:13]
	v_add_u32_e32 v63, 0x4000, v60
	global_load_dwordx4 v[80:83], v63, s[10:11]
	global_load_dwordx4 v[84:87], v63, s[12:13]
	v_add_u32_e32 v61, 0x6000, v60
	global_load_dwordx4 v[88:91], v61, s[10:11]
	global_load_dwordx4 v[92:95], v61, s[12:13]
	v_add_u32_e32 v62, 0x8000, v60
	global_load_dwordx4 v[96:99], v62, s[10:11]
	global_load_dwordx4 v[100:103], v62, s[12:13]
	v_add_u32_e32 v63, 0xa000, v60
	global_load_dwordx4 v[104:107], v63, s[10:11]
	global_load_dwordx4 v[108:111], v63, s[12:13]
	v_add_u32_e32 v61, 0xc000, v60
	global_load_dwordx4 v[112:115], v61, s[10:11]
	global_load_dwordx4 v[116:119], v61, s[12:13]
	v_add_u32_e32 v62, 0xe000, v60
	global_load_dwordx4 v[120:123], v62, s[10:11]
	global_load_dwordx4 v[124:127], v62, s[12:13]
	s_waitcnt vmcnt(14)
	v_mov_b32_e32 v0, v64
	v_mov_b32_e32 v1, v65
	v_mov_b32_e32 v2, v66
	v_mov_b32_e32 v3, v67
	v_bfe_i32 v9, v8, 2, 28
	v_mov_b32_e32 v4, v68
	v_mov_b32_e32 v5, v69
	v_mov_b32_e32 v6, v70
	v_mov_b32_e32 v7, v71
	v_lshlrev_b32_e32 v9, 3, v9
	v_lshlrev_b32_e32 v8, 5, v8
	v_and_b32_e32 v9, 0xffffffe0, v9
	v_mov_b32_e32 v12, v140
	v_add3_u32 v13, 0, v9, v8
	s_mov_b32 s0, 0
	s_mov_b64 s[8:9], -1
	s_waitcnt vmcnt(15)
	v_mov_b32_e32 v8, v0
	v_mov_b32_e32 v10, v1
	s_waitcnt vmcnt(14)
	v_mov_b32_e32 v9, v4
	v_mov_b32_e32 v11, v5
	v_mov_b32_e32 v4, v2
	v_mov_b32_e32 v5, v6
	v_mov_b32_e32 v6, v3
	ds_write_b128 v13, v[8:11]
	ds_write_b128 v13, v[4:7] offset:16
	v_mov_b32_e32 v13, v140
	v_lshl_add_u32 v8, v12, 2, v224
	v_ashrrev_i32_e32 v9, 31, v8
	v_lshlrev_b64 v[0:1], 2, v[8:9]
	v_lshl_add_u64 v[2:3], s[10:11], 0, v[0:1]
	v_lshl_add_u64 v[4:5], s[12:13], 0, v[0:1]
	s_waitcnt vmcnt(12)
	v_mov_b32_e32 v0, v72
	v_mov_b32_e32 v1, v73
	v_mov_b32_e32 v2, v74
	v_mov_b32_e32 v3, v75
	v_mov_b32_e32 v4, v76
	v_mov_b32_e32 v5, v77
	v_mov_b32_e32 v6, v78
	v_mov_b32_e32 v7, v79
	v_ashrrev_i32_e32 v8, 4, v8
	v_lshlrev_b32_e32 v8, 3, v8
	v_lshlrev_b32_e32 v9, 5, v12
	v_and_b32_e32 v8, 0xffffffe0, v8
	v_add3_u32 v12, 0, v8, v9
	s_waitcnt vmcnt(13)
	v_mov_b32_e32 v8, v0
	s_waitcnt vmcnt(12)
	v_mov_b32_e32 v9, v4
	v_mov_b32_e32 v10, v1
	v_mov_b32_e32 v11, v5
	v_mov_b32_e32 v4, v2
	v_mov_b32_e32 v5, v6
	v_mov_b32_e32 v6, v3
	ds_write_b128 v12, v[8:11] offset:16384
	ds_write_b128 v12, v[4:7] offset:16400
	v_mov_b32_e32 v12, v140
	v_lshl_add_u32 v8, v13, 2, v225
	v_ashrrev_i32_e32 v9, 31, v8
	v_lshlrev_b64 v[0:1], 2, v[8:9]
	v_lshl_add_u64 v[2:3], s[10:11], 0, v[0:1]
	v_lshl_add_u64 v[4:5], s[12:13], 0, v[0:1]
	s_waitcnt vmcnt(10)
	v_mov_b32_e32 v0, v80
	v_mov_b32_e32 v1, v81
	v_mov_b32_e32 v2, v82
	v_mov_b32_e32 v3, v83
	v_mov_b32_e32 v4, v84
	v_mov_b32_e32 v5, v85
	v_mov_b32_e32 v6, v86
	v_mov_b32_e32 v7, v87
	v_ashrrev_i32_e32 v8, 4, v8
	v_lshlrev_b32_e32 v8, 3, v8
	v_lshlrev_b32_e32 v9, 5, v13
	v_and_b32_e32 v8, 0xffffffe0, v8
	v_add3_u32 v13, 0, v8, v9
	s_waitcnt vmcnt(11)
	v_mov_b32_e32 v8, v0
	s_waitcnt vmcnt(10)
	v_mov_b32_e32 v9, v4
	v_mov_b32_e32 v10, v1
	v_mov_b32_e32 v11, v5
	v_mov_b32_e32 v4, v2
	v_mov_b32_e32 v5, v6
	v_mov_b32_e32 v6, v3
	ds_write_b128 v13, v[8:11] offset:32768
	ds_write_b128 v13, v[4:7] offset:32784
	v_mov_b32_e32 v13, v140
	v_lshl_add_u32 v8, v12, 2, v226
	v_ashrrev_i32_e32 v9, 31, v8
	v_lshlrev_b64 v[0:1], 2, v[8:9]
	v_lshl_add_u64 v[2:3], s[10:11], 0, v[0:1]
	v_lshl_add_u64 v[4:5], s[12:13], 0, v[0:1]
	s_waitcnt vmcnt(8)
	v_mov_b32_e32 v0, v88
	v_mov_b32_e32 v1, v89
	v_mov_b32_e32 v2, v90
	v_mov_b32_e32 v3, v91
	v_mov_b32_e32 v4, v92
	v_mov_b32_e32 v5, v93
	v_mov_b32_e32 v6, v94
	v_mov_b32_e32 v7, v95
	v_ashrrev_i32_e32 v8, 4, v8
	v_lshlrev_b32_e32 v8, 3, v8
	v_lshlrev_b32_e32 v9, 5, v12
	v_and_b32_e32 v8, 0xffffffe0, v8
	v_add3_u32 v12, 0, v8, v9
	s_waitcnt vmcnt(9)
	v_mov_b32_e32 v8, v0
	s_waitcnt vmcnt(8)
	v_mov_b32_e32 v9, v4
	v_mov_b32_e32 v10, v1
	v_mov_b32_e32 v11, v5
	v_mov_b32_e32 v4, v2
	v_mov_b32_e32 v5, v6
	v_mov_b32_e32 v6, v3
	ds_write_b128 v12, v[8:11] offset:49152
	ds_write_b128 v12, v[4:7] offset:49168
	v_mov_b32_e32 v12, v140
	v_lshl_add_u32 v8, v13, 2, v227
	v_ashrrev_i32_e32 v9, 31, v8
	v_lshlrev_b64 v[0:1], 2, v[8:9]
	v_lshl_add_u64 v[2:3], s[10:11], 0, v[0:1]
	v_lshl_add_u64 v[4:5], s[12:13], 0, v[0:1]
	s_waitcnt vmcnt(6)
	v_mov_b32_e32 v0, v96
	v_mov_b32_e32 v1, v97
	v_mov_b32_e32 v2, v98
	v_mov_b32_e32 v3, v99
	v_mov_b32_e32 v4, v100
	v_mov_b32_e32 v5, v101
	v_mov_b32_e32 v6, v102
	v_mov_b32_e32 v7, v103
	v_ashrrev_i32_e32 v9, 4, v8
	v_lshlrev_b32_e32 v9, 3, v9
	v_lshlrev_b32_e32 v8, 3, v8
	v_and_b32_e32 v9, 0xffffffe0, v9
	v_add3_u32 v13, 0, v9, v8
	s_waitcnt vmcnt(7)
	v_mov_b32_e32 v8, v0
	s_waitcnt vmcnt(6)
	v_mov_b32_e32 v9, v4
	v_mov_b32_e32 v10, v1
	v_mov_b32_e32 v11, v5
	v_mov_b32_e32 v4, v2
	v_mov_b32_e32 v5, v6
	v_mov_b32_e32 v6, v3
	ds_write_b128 v13, v[8:11]
	ds_write_b128 v13, v[4:7] offset:16
	s_nop 0
	v_lshl_add_u32 v8, v12, 2, v228
	v_ashrrev_i32_e32 v9, 31, v8
	v_lshlrev_b64 v[0:1], 2, v[8:9]
	v_lshl_add_u64 v[2:3], s[10:11], 0, v[0:1]
	v_lshl_add_u64 v[4:5], s[12:13], 0, v[0:1]
	s_waitcnt vmcnt(4)
; template <bool INV> __device__ __forceinline__ void bfly16(f32x2 (&x)[16], const LAS f32x2* TH, const LAS f32x2* TL, int tw) {
;     f32x2 W = tw32k(TH, TL, tw); if (INV) W.y = -W.y;
;     if (INV) { f32x2 p = W;
; #pragma unroll
;         for (int q = 1; q < 16; ++q) { x[q] = cmul(x[q], p); if (q < 15) p = cmul(p, W); } }
;     dft16<INV>(x);
;     if (!INV) { f32x2 p = W;
; #pragma unroll
;         for (int r = 1; r < 16; ++r) { x[4 * (r & 3) + (r >> 2)] = cmul(x[4 * (r & 3) + (r >> 2)], p); if (r < 15) p = cmul(p, W); } }
; }
; template <bool INV> __device__ __forceinline__ void bfly16_tab(f32x2 (&x)[16], const LAS f32x2* T, int tstride, int j) {
;     if (INV) {
; #pragma unroll
;         for (int q = 1; q < 16; ++q) { f32x2 p = T[q * tstride + j]; p.y = -p.y; x[q] = cmul(x[q], p); } }
;     dft16<INV>(x);
;     if (!INV) {
; #pragma unroll
;         for (int r = 1; r < 16; ++r) { const f32x2 p = T[r * tstride + j]; x[4 * (r & 3) + (r >> 2)] = cmul(x[4 * (r & 3) + (r >> 2)], p); } }
; }
; template <bool INV> __device__ __forceinline__ void pass16_s64(LAS f32x2* X, const LAS f32x2* TH, int base, int j) {
;     f32x2 x[16];
; #pragma unroll
;     for (int q = 0; q < 16; ++q) x[q] = X[base + q * 68];
;     bfly16_tab<INV>(x, TH - 2048, 64, j);
; #pragma unroll
;     for (int c = 0; c < 4; ++c)
; #pragma unroll
;         for (int d = 0; d < 4; ++d) X[base + (c + 4 * d) * 68] = x[4 * c + d];
; }
; template <bool INV> __device__ __forceinline__ void pass16(LAS f32x2* X, const LAS f32x2* TH, const LAS f32x2* TL, int base, int stride, int tw) {
;     f32x2 x[16];
; #pragma unroll
;     for (int q = 0; q < 16; ++q) x[q] = X[base + q * stride];
;     bfly16<INV>(x, TH, TL, tw);
; #pragma unroll
;     for (int c = 0; c < 4; ++c)
; #pragma unroll
;         for (int d = 0; d < 4; ++d) X[base + (c + 4 * d) * stride] = x[4 * c + d];
; }
; __device__ __forceinline__ void fourier_latent(Frame& F, int b, int gq, int m, LAS f32x2* X, const LAS f32x2* TH, const LAS f32x2* TL, bool wr = true) {
;     ...
;     for (int i = 0; i < 8; ++i) { const int g = LT() + NTHR * i, n0 = 4 * g; const f32x4 a = *(const GAS f32x4*)(ra + n0), c = *(const GAS f32x4*)(rb + n0);
;         LAS f32x4* XP = (LAS f32x4*)(X + phys(n0)); XP[0] = (f32x4){a.x, c.x, a.y, c.y}; XP[1] = (f32x4){a.z, c.z, a.w, c.w}; }
;     __syncthreads();
;     fft_fwd(X, TH, TL, tid);
	v_mov_b32_e32 v0, v104
	v_mov_b32_e32 v1, v105
	v_mov_b32_e32 v2, v106
	v_mov_b32_e32 v3, v107
	v_mov_b32_e32 v4, v108
	v_mov_b32_e32 v5, v109
	v_mov_b32_e32 v6, v110
	v_mov_b32_e32 v7, v111
	v_ashrrev_i32_e32 v9, 4, v8
	v_lshlrev_b32_e32 v9, 3, v9
	v_lshlrev_b32_e32 v8, 3, v8
	v_and_b32_e32 v9, 0xffffffe0, v9
	v_mov_b32_e32 v12, v140
	v_add3_u32 v13, 0, v9, v8
	s_waitcnt vmcnt(5)
	v_mov_b32_e32 v8, v0
	s_waitcnt vmcnt(4)
	v_mov_b32_e32 v9, v4
	v_mov_b32_e32 v10, v1
	v_mov_b32_e32 v11, v5
	v_mov_b32_e32 v4, v2
	v_mov_b32_e32 v5, v6
	v_mov_b32_e32 v6, v3
	ds_write_b128 v13, v[8:11]
	ds_write_b128 v13, v[4:7] offset:16
	s_nop 0
	v_lshl_add_u32 v8, v12, 2, v229
	v_ashrrev_i32_e32 v9, 31, v8
	v_lshlrev_b64 v[0:1], 2, v[8:9]
	v_lshl_add_u64 v[2:3], s[10:11], 0, v[0:1]
	v_lshl_add_u64 v[4:5], s[12:13], 0, v[0:1]
	s_waitcnt vmcnt(2)
	v_mov_b32_e32 v0, v112
	v_mov_b32_e32 v1, v113
	v_mov_b32_e32 v2, v114
	v_mov_b32_e32 v3, v115
	v_mov_b32_e32 v4, v116
	v_mov_b32_e32 v5, v117
	v_mov_b32_e32 v6, v118
	v_mov_b32_e32 v7, v119
	v_ashrrev_i32_e32 v9, 4, v8
	v_lshlrev_b32_e32 v9, 3, v9
	v_lshlrev_b32_e32 v8, 3, v8
	v_and_b32_e32 v9, 0xffffffe0, v9
	v_mov_b32_e32 v12, v140
	v_add3_u32 v13, 0, v9, v8
	s_waitcnt vmcnt(3)
	v_mov_b32_e32 v8, v0
	s_waitcnt vmcnt(2)
	v_mov_b32_e32 v9, v4
	v_mov_b32_e32 v10, v1
	v_mov_b32_e32 v11, v5
	v_mov_b32_e32 v4, v2
	v_mov_b32_e32 v5, v6
	v_mov_b32_e32 v6, v3
	ds_write_b128 v13, v[8:11]
	ds_write_b128 v13, v[4:7] offset:16
	s_nop 0
	v_lshl_add_u32 v8, v12, 2, v230
	v_ashrrev_i32_e32 v9, 31, v8
	v_lshlrev_b64 v[0:1], 2, v[8:9]
	v_lshl_add_u64 v[2:3], s[10:11], 0, v[0:1]
	v_lshl_add_u64 v[4:5], s[12:13], 0, v[0:1]
	s_waitcnt vmcnt(0)
	v_mov_b32_e32 v0, v120
	v_mov_b32_e32 v1, v121
	v_mov_b32_e32 v2, v122
	v_mov_b32_e32 v3, v123
	v_mov_b32_e32 v4, v124
	v_mov_b32_e32 v5, v125
	v_mov_b32_e32 v6, v126
	v_mov_b32_e32 v7, v127
	v_ashrrev_i32_e32 v9, 4, v8
	v_lshlrev_b32_e32 v9, 3, v9
	v_lshlrev_b32_e32 v8, 3, v8
	v_and_b32_e32 v9, 0xffffffe0, v9
	v_add3_u32 v12, 0, v9, v8
	s_waitcnt vmcnt(1)
	v_mov_b32_e32 v8, v0
	s_waitcnt vmcnt(0)
	v_mov_b32_e32 v9, v4
	v_mov_b32_e32 v10, v1
	v_mov_b32_e32 v11, v5
	v_mov_b32_e32 v4, v2
	v_mov_b32_e32 v5, v6
	v_mov_b32_e32 v6, v3
	ds_write_b128 v12, v[8:11]
	ds_write_b128 v12, v[4:7] offset:16
	s_waitcnt lgkmcnt(0)
	s_barrier
.LBB0_944:
	v_add_u32_e32 v37, s0, v140
	v_lshrrev_b32_e32 v138, 6, v37
	v_and_b32_e32 v234, 63, v37
	v_lshlrev_b32_e32 v176, 5, v138
	v_lshlrev_b32_e32 v218, 3, v138
	v_lshlrev_b32_e32 v234, 4, v234
	v_lshl_add_u32 v176, v37, 3, v176
	v_add_u32_e32 v218, 0x26000, v218
	v_add_u32_e32 v234, 0x26400, v234
	ds_read_b64 v[0:1], v218
	ds_read_b64 v[2:3], v234
	ds_read2st64_b64 v[4:7], v176 offset0:0 offset1:17
	ds_read2st64_b64 v[8:11], v176 offset0:136 offset1:153
	ds_read2st64_b64 v[12:15], v176 offset0:34 offset1:51
	ds_read2st64_b64 v[16:19], v176 offset0:170 offset1:187
	ds_read2st64_b64 v[20:23], v176 offset0:68 offset1:85
	ds_read2st64_b64 v[24:27], v176 offset0:204 offset1:221
	ds_read2st64_b64 v[28:31], v176 offset0:102 offset1:119
	ds_read2st64_b64 v[32:35], v176 offset0:238 offset1:255
	s_cmp_eq_u32 s0, 0
	s_movk_i32 s0, 0x200
	s_mov_b64 s[8:9], 0
	s_waitcnt lgkmcnt(8)
	v_pk_mul_f32 v[38:39], v[0:1], v[2:3] op_sel:[0,1] op_sel_hi:[1,1]
	s_nop 0
	v_pk_fma_f32 v[38:39], v[0:1], v[2:3], v[38:39] op_sel:[0,0,1] op_sel_hi:[1,0,0] neg_lo:[0,0,1]
	s_nop 0
	v_pk_mul_f32 v[2:3], v[38:39], v[38:39] op_sel:[0,1] op_sel_hi:[1,1]
	s_nop 0
	v_pk_fma_f32 v[2:3], v[38:39], v[38:39], v[2:3] op_sel:[0,0,1] op_sel_hi:[1,0,0] neg_lo:[0,0,1]
	s_nop 0
	v_pk_mul_f32 v[0:1], v[2:3], v[38:39] op_sel:[0,1] op_sel_hi:[1,1]
	v_pk_mul_f32 v[40:41], v[2:3], v[2:3] op_sel:[0,1] op_sel_hi:[1,1]
	v_pk_fma_f32 v[0:1], v[2:3], v[38:39], v[0:1] op_sel:[0,0,1] op_sel_hi:[1,0,0] neg_lo:[0,0,1]
	v_pk_fma_f32 v[40:41], v[2:3], v[2:3], v[40:41] op_sel:[0,0,1] op_sel_hi:[1,0,0] neg_lo:[0,0,1]
	s_nop 0
	v_pk_mul_f32 v[42:43], v[40:41], v[38:39] op_sel:[0,1] op_sel_hi:[1,1]
	v_pk_mul_f32 v[44:45], v[40:41], v[2:3] op_sel:[0,1] op_sel_hi:[1,1]
	v_pk_mul_f32 v[46:47], v[40:41], v[0:1] op_sel:[0,1] op_sel_hi:[1,1]
	v_pk_fma_f32 v[42:43], v[40:41], v[38:39], v[42:43] op_sel:[0,0,1] op_sel_hi:[1,0,0] neg_lo:[0,0,1]
	v_pk_fma_f32 v[44:45], v[40:41], v[2:3], v[44:45] op_sel:[0,0,1] op_sel_hi:[1,0,0] neg_lo:[0,0,1]
	v_pk_fma_f32 v[46:47], v[40:41], v[0:1], v[46:47] op_sel:[0,0,1] op_sel_hi:[1,0,0] neg_lo:[0,0,1]
	v_pk_mul_f32 v[48:49], v[40:41], v[40:41] op_sel:[0,1] op_sel_hi:[1,1]
	s_nop 0
	v_pk_fma_f32 v[48:49], v[40:41], v[40:41], v[48:49] op_sel:[0,0,1] op_sel_hi:[1,0,0] neg_lo:[0,0,1]
	s_nop 0
	v_pk_mul_f32 v[50:51], v[48:49], v[38:39] op_sel:[0,1] op_sel_hi:[1,1]
	v_pk_mul_f32 v[52:53], v[48:49], v[2:3] op_sel:[0,1] op_sel_hi:[1,1]
	v_pk_mul_f32 v[54:55], v[48:49], v[0:1] op_sel:[0,1] op_sel_hi:[1,1]
	v_pk_fma_f32 v[50:51], v[48:49], v[38:39], v[50:51] op_sel:[0,0,1] op_sel_hi:[1,0,0] neg_lo:[0,0,1]
	v_pk_fma_f32 v[52:53], v[48:49], v[2:3], v[52:53] op_sel:[0,0,1] op_sel_hi:[1,0,0] neg_lo:[0,0,1]
	v_pk_fma_f32 v[54:55], v[48:49], v[0:1], v[54:55] op_sel:[0,0,1] op_sel_hi:[1,0,0] neg_lo:[0,0,1]
	v_pk_mul_f32 v[56:57], v[48:49], v[40:41] op_sel:[0,1] op_sel_hi:[1,1]
	v_pk_mul_f32 v[58:59], v[48:49], v[42:43] op_sel:[0,1] op_sel_hi:[1,1]
	v_pk_mul_f32 v[60:61], v[48:49], v[44:45] op_sel:[0,1] op_sel_hi:[1,1]
	v_pk_fma_f32 v[56:57], v[48:49], v[40:41], v[56:57] op_sel:[0,0,1] op_sel_hi:[1,0,0] neg_lo:[0,0,1]
	v_pk_fma_f32 v[58:59], v[48:49], v[42:43], v[58:59] op_sel:[0,0,1] op_sel_hi:[1,0,0] neg_lo:[0,0,1]
	v_pk_fma_f32 v[60:61], v[48:49], v[44:45], v[60:61] op_sel:[0,0,1] op_sel_hi:[1,0,0] neg_lo:[0,0,1]
	v_pk_mul_f32 v[62:63], v[48:49], v[46:47] op_sel:[0,1] op_sel_hi:[1,1]
	s_nop 0
	v_pk_fma_f32 v[62:63], v[48:49], v[46:47], v[62:63] op_sel:[0,0,1] op_sel_hi:[1,0,0] neg_lo:[0,0,1]
	s_waitcnt lgkmcnt(6)
; #define LAS __attribute__((address_space(3)))
; __device__ __forceinline__ f32x2 cmul(f32x2 a, f32x2 b) { return (f32x2){a.x * b.x - a.y * b.y, a.x * b.y + a.y * b.x}; }
; __device__ __forceinline__ f32x2 tw32k(const LAS f32x2* TH, const LAS f32x2* TL, int n) { return cmul(TH[n >> 7], TL[n & 127]); }
; template <bool INV> __device__ __forceinline__ void dft16(f32x2 (&x)[16]) {
; #pragma unroll
;     for (int b = 0; b < 4; ++b) r4<INV>(x[b], x[4 + b], x[8 + b], x[12 + b]);
;     const float sg = INV ? -1.f : 1.f;
;     const f32x2 W1 = {0.92387953251f, -0.38268343236f * sg}, W2 = {0.70710678118f, -0.70710678118f * sg}, W3 = {0.38268343236f, -0.92387953251f * sg},
;                 W4 = {0.f, -1.f * sg}, W6 = {-0.70710678118f, -0.70710678118f * sg}, W9 = {-0.92387953251f, 0.38268343236f * sg};
;     x[5] = cmul(x[5], W1); x[9] = cmul(x[9], W2); x[13] = cmul(x[13], W3);
;     x[6] = cmul(x[6], W2); x[10] = cmul(x[10], W4); x[14] = cmul(x[14], W6);
;     x[7] = cmul(x[7], W3); x[11] = cmul(x[11], W6); x[15] = cmul(x[15], W9);
; #pragma unroll
;     for (int c = 0; c < 4; ++c) r4<INV>(x[4 * c], x[4 * c + 1], x[4 * c + 2], x[4 * c + 3]);
; }
; template <bool INV> __device__ __forceinline__ void bfly16(f32x2 (&x)[16], const LAS f32x2* TH, const LAS f32x2* TL, int tw) {
;     f32x2 W = tw32k(TH, TL, tw); if (INV) W.y = -W.y;
;     if (INV) { f32x2 p = W;
; #pragma unroll
;         for (int q = 1; q < 16; ++q) { x[q] = cmul(x[q], p); if (q < 15) p = cmul(p, W); } }
;     dft16<INV>(x);
;     if (!INV) { f32x2 p = W;
; #pragma unroll
;         for (int r = 1; r < 16; ++r) { x[4 * (r & 3) + (r >> 2)] = cmul(x[4 * (r & 3) + (r >> 2)], p); if (r < 15) p = cmul(p, W); } }
	v_pk_add_f32 v[64:65], v[4:5], v[8:9]
	v_pk_add_f32 v[66:67], v[6:7], v[10:11]
	s_waitcnt lgkmcnt(4)
	v_pk_add_f32 v[68:69], v[12:13], v[16:17]
	v_pk_add_f32 v[70:71], v[14:15], v[18:19]
	v_pk_add_f32 v[8:9], v[4:5], v[8:9] neg_lo:[0,1] neg_hi:[0,1]
	v_pk_add_f32 v[10:11], v[6:7], v[10:11] neg_lo:[0,1] neg_hi:[0,1]
	v_pk_add_f32 v[16:17], v[12:13], v[16:17] neg_lo:[0,1] neg_hi:[0,1]
	v_pk_add_f32 v[18:19], v[14:15], v[18:19] neg_lo:[0,1] neg_hi:[0,1]
	s_waitcnt lgkmcnt(2)
	v_pk_add_f32 v[14:15], v[20:21], v[24:25]
	v_pk_add_f32 v[12:13], v[22:23], v[26:27]
	s_waitcnt lgkmcnt(0)
	v_pk_add_f32 v[6:7], v[28:29], v[32:33]
	v_pk_add_f32 v[4:5], v[30:31], v[34:35]
	v_pk_add_f32 v[24:25], v[20:21], v[24:25] neg_lo:[0,1] neg_hi:[0,1]
	v_pk_add_f32 v[26:27], v[22:23], v[26:27] neg_lo:[0,1] neg_hi:[0,1]
	v_pk_add_f32 v[28:29], v[28:29], v[32:33] neg_lo:[0,1] neg_hi:[0,1]
	v_pk_add_f32 v[30:31], v[30:31], v[34:35] neg_lo:[0,1] neg_hi:[0,1]
	v_pk_add_f32 v[34:35], v[64:65], v[14:15]
	v_pk_add_f32 v[32:33], v[66:67], v[12:13]
	v_pk_add_f32 v[22:23], v[68:69], v[6:7]
	v_pk_add_f32 v[20:21], v[70:71], v[4:5]
	v_pk_add_f32 v[64:65], v[64:65], v[14:15] neg_lo:[0,1] neg_hi:[0,1]
	v_pk_add_f32 v[66:67], v[66:67], v[12:13] neg_lo:[0,1] neg_hi:[0,1]
	v_pk_add_f32 v[6:7], v[68:69], v[6:7] neg_lo:[0,1] neg_hi:[0,1]
	v_pk_add_f32 v[70:71], v[70:71], v[4:5] neg_lo:[0,1] neg_hi:[0,1]
	v_pk_add_f32 v[4:5], v[8:9], v[24:25] op_sel:[0,1] op_sel_hi:[1,0] neg_hi:[0,1]
	v_pk_add_f32 v[68:69], v[10:11], v[26:27] op_sel:[0,1] op_sel_hi:[1,0] neg_hi:[0,1]
	v_pk_add_f32 v[12:13], v[16:17], v[28:29] op_sel:[0,1] op_sel_hi:[1,0] neg_hi:[0,1]
	v_pk_add_f32 v[14:15], v[18:19], v[30:31] op_sel:[0,1] op_sel_hi:[1,0] neg_hi:[0,1]
	v_pk_add_f32 v[24:25], v[8:9], v[24:25] op_sel:[0,1] op_sel_hi:[1,0] neg_lo:[0,1]
	v_pk_add_f32 v[26:27], v[10:11], v[26:27] op_sel:[0,1] op_sel_hi:[1,0] neg_lo:[0,1]
	v_pk_add_f32 v[28:29], v[16:17], v[28:29] op_sel:[0,1] op_sel_hi:[1,0] neg_lo:[0,1]
	v_pk_add_f32 v[18:19], v[18:19], v[30:31] op_sel:[0,1] op_sel_hi:[1,0] neg_lo:[0,1]
	v_pk_mul_f32 v[30:31], v[68:69], s[70:71] op_sel_hi:[1,0]
	v_pk_mul_f32 v[16:17], v[66:67], s[72:73] op_sel_hi:[1,0]
	v_pk_mul_f32 v[10:11], v[26:27], s[64:65] op_sel_hi:[1,0]
	v_pk_mul_f32 v[8:9], v[12:13], s[72:73] op_sel_hi:[1,0]
	v_pk_mul_f32 v[72:73], v[28:29], s[72:73] op_sel_hi:[1,0]
	v_pk_mul_f32 v[74:75], v[14:15], s[64:65] op_sel_hi:[1,0]
	v_pk_mul_f32 v[76:77], v[70:71], s[72:73] op_sel_hi:[1,0]
	v_pk_mul_f32 v[78:79], v[18:19], s[82:83] op_sel_hi:[1,0]
	v_pk_fma_f32 v[68:69], v[68:69], s[44:45], v[30:31] op_sel:[0,0,1] op_sel_hi:[1,0,0] neg_lo:[0,0,1]
	v_pk_fma_f32 v[16:17], v[66:67], s[76:77], v[16:17] op_sel:[0,0,1] op_sel_hi:[1,0,0] neg_lo:[0,0,1]
	v_pk_fma_f32 v[10:11], v[26:27], s[82:83], v[10:11] op_sel:[0,0,1] op_sel_hi:[1,0,0] neg_lo:[0,0,1]
	v_pk_fma_f32 v[8:9], v[12:13], s[76:77], v[8:9] op_sel:[0,0,1] op_sel_hi:[1,0,0] neg_lo:[0,0,1]
	v_pk_fma_f32 v[72:73], v[28:29], s[72:73], v[72:73] op_sel:[0,0,1] op_sel_hi:[1,0,0] neg_lo:[0,0,1]
	v_pk_fma_f32 v[74:75], v[14:15], s[82:83], v[74:75] op_sel:[0,0,1] op_sel_hi:[1,0,0] neg_lo:[0,0,1]
	v_pk_fma_f32 v[76:77], v[70:71], s[72:73], v[76:77] op_sel:[0,0,1] op_sel_hi:[1,0,0] neg_lo:[0,0,1]
	v_pk_fma_f32 v[78:79], v[18:19], s[64:65], v[78:79] op_sel:[0,0,1] op_sel_hi:[1,0,0] neg_lo:[0,0,1]
	v_pk_add_f32 v[18:19], v[34:35], v[22:23]
	v_pk_add_f32 v[70:71], v[4:5], v[8:9]
	v_pk_add_f32 v[14:15], v[64:65], v[6:7] op_sel:[0,1] op_sel_hi:[1,0] neg_hi:[0,1]
	v_pk_add_f32 v[28:29], v[24:25], v[72:73]
	v_pk_add_f32 v[34:35], v[34:35], v[22:23] neg_lo:[0,1] neg_hi:[0,1]
	v_pk_add_f32 v[4:5], v[4:5], v[8:9] neg_lo:[0,1] neg_hi:[0,1]
	v_pk_add_f32 v[64:65], v[64:65], v[6:7] op_sel:[0,1] op_sel_hi:[1,0] neg_lo:[0,1]
	v_pk_add_f32 v[72:73], v[24:25], v[72:73] neg_lo:[0,1] neg_hi:[0,1]
	v_pk_add_f32 v[24:25], v[32:33], v[20:21]
	v_pk_add_f32 v[6:7], v[68:69], v[74:75]
	v_pk_add_f32 v[8:9], v[16:17], v[76:77]
	v_pk_add_f32 v[22:23], v[10:11], v[78:79]
	v_pk_add_f32 v[20:21], v[32:33], v[20:21] neg_lo:[0,1] neg_hi:[0,1]
	v_pk_add_f32 v[68:69], v[68:69], v[74:75] neg_lo:[0,1] neg_hi:[0,1]
	v_pk_add_f32 v[76:77], v[16:17], v[76:77] neg_lo:[0,1] neg_hi:[0,1]
	v_pk_add_f32 v[10:11], v[10:11], v[78:79] neg_lo:[0,1] neg_hi:[0,1]
	v_pk_add_f32 v[78:79], v[18:19], v[24:25]
	v_pk_add_f32 v[16:17], v[70:71], v[6:7]
	v_pk_add_f32 v[74:75], v[14:15], v[8:9]
	v_pk_add_f32 v[32:33], v[28:29], v[22:23]
	v_pk_add_f32 v[18:19], v[18:19], v[24:25] neg_lo:[0,1] neg_hi:[0,1]
	v_pk_add_f32 v[70:71], v[70:71], v[6:7] neg_lo:[0,1] neg_hi:[0,1]
	v_pk_add_f32 v[8:9], v[14:15], v[8:9] neg_lo:[0,1] neg_hi:[0,1]
	v_pk_add_f32 v[22:23], v[28:29], v[22:23] neg_lo:[0,1] neg_hi:[0,1]
	v_pk_add_f32 v[28:29], v[34:35], v[20:21] op_sel:[0,1] op_sel_hi:[1,0] neg_hi:[0,1]
	v_pk_add_f32 v[14:15], v[4:5], v[68:69] op_sel:[0,1] op_sel_hi:[1,0] neg_hi:[0,1]
	v_pk_add_f32 v[6:7], v[64:65], v[76:77] op_sel:[0,1] op_sel_hi:[1,0] neg_hi:[0,1]
	v_pk_add_f32 v[24:25], v[72:73], v[10:11] op_sel:[0,1] op_sel_hi:[1,0] neg_hi:[0,1]
	v_pk_add_f32 v[34:35], v[34:35], v[20:21] op_sel:[0,1] op_sel_hi:[1,0] neg_lo:[0,1]
	v_pk_add_f32 v[4:5], v[4:5], v[68:69] op_sel:[0,1] op_sel_hi:[1,0] neg_lo:[0,1]
	v_pk_add_f32 v[76:77], v[64:65], v[76:77] op_sel:[0,1] op_sel_hi:[1,0] neg_lo:[0,1]
	v_pk_add_f32 v[10:11], v[72:73], v[10:11] op_sel:[0,1] op_sel_hi:[1,0] neg_lo:[0,1]
	v_pk_mul_f32 v[72:73], v[16:17], v[38:39] op_sel:[0,1] op_sel_hi:[1,1]
	v_pk_mul_f32 v[64:65], v[74:75], v[2:3] op_sel:[0,1] op_sel_hi:[1,1]
	v_pk_fma_f32 v[16:17], v[16:17], v[38:39], v[72:73] op_sel:[0,0,1] op_sel_hi:[1,0,0] neg_lo:[0,0,1]
; #define LAS __attribute__((address_space(3)))
; __device__ __forceinline__ f32x2 cmul(f32x2 a, f32x2 b) { return (f32x2){a.x * b.x - a.y * b.y, a.x * b.y + a.y * b.x}; }
; __device__ __forceinline__ f32x2 tw32k(const LAS f32x2* TH, const LAS f32x2* TL, int n) { return cmul(TH[n >> 7], TL[n & 127]); }
; #define LDS_BARRIER() do { asm volatile("s_waitcnt lgkmcnt(0)" ::: "memory"); __builtin_amdgcn_s_barrier(); asm volatile("" ::: "memory"); } while (0)
; template <bool INV> __device__ __forceinline__ void bfly16(f32x2 (&x)[16], const LAS f32x2* TH, const LAS f32x2* TL, int tw) {
;     f32x2 W = tw32k(TH, TL, tw); if (INV) W.y = -W.y;
;     if (INV) { f32x2 p = W;
; #pragma unroll
;         for (int q = 1; q < 16; ++q) { x[q] = cmul(x[q], p); if (q < 15) p = cmul(p, W); } }
;     dft16<INV>(x);
;     if (!INV) { f32x2 p = W;
; #pragma unroll
;         for (int r = 1; r < 16; ++r) { x[4 * (r & 3) + (r >> 2)] = cmul(x[4 * (r & 3) + (r >> 2)], p); if (r < 15) p = cmul(p, W); } }
; }
; template <bool INV> __device__ __forceinline__ void bfly16_tab(f32x2 (&x)[16], const LAS f32x2* T, int tstride, int j) {
;     if (INV) {
; #pragma unroll
;         for (int q = 1; q < 16; ++q) { f32x2 p = T[q * tstride + j]; p.y = -p.y; x[q] = cmul(x[q], p); } }
;     dft16<INV>(x);
;     if (!INV) {
; #pragma unroll
;         for (int r = 1; r < 16; ++r) { const f32x2 p = T[r * tstride + j]; x[4 * (r & 3) + (r >> 2)] = cmul(x[4 * (r & 3) + (r >> 2)], p); } }
; }
; template <bool INV> __device__ __forceinline__ void pass16_s64(LAS f32x2* X, const LAS f32x2* TH, int base, int j) {
;     f32x2 x[16];
; #pragma unroll
;     for (int q = 0; q < 16; ++q) x[q] = X[base + q * 68];
;     bfly16_tab<INV>(x, TH - 2048, 64, j);
; #pragma unroll
;     for (int c = 0; c < 4; ++c)
; #pragma unroll
;         for (int d = 0; d < 4; ++d) X[base + (c + 4 * d) * 68] = x[4 * c + d];
; __device__ __forceinline__ void fft_fwd_head(LAS f32x2* X, const LAS f32x2* TH, const LAS f32x2* TL, int tid) {
;     ...
;     for (int i = 0; i < 2; ++i) { const int j = tid + NTHR * i; pass16<false>(X, TH, TL, j + ((j >> 6) << 2), 1088, 2 * j); }
;     LDS_BARRIER();
; #pragma unroll 1
;     for (int i = 0; i < 2; ++i) { const int b = tid + NTHR * i, j = b & 63, blk = b >> 6; pass16_s64<false>(X, TH, blk * 1088 + j, j); }
	v_pk_mul_f32 v[38:39], v[32:33], v[0:1] op_sel:[0,1] op_sel_hi:[1,1]
	v_pk_fma_f32 v[2:3], v[74:75], v[2:3], v[64:65] op_sel:[0,0,1] op_sel_hi:[1,0,0] neg_lo:[0,0,1]
	v_pk_mul_f32 v[74:75], v[28:29], v[40:41] op_sel:[0,1] op_sel_hi:[1,1]
	v_pk_fma_f32 v[38:39], v[32:33], v[0:1], v[38:39] op_sel:[0,0,1] op_sel_hi:[1,0,0] neg_lo:[0,0,1]
	v_pk_mul_f32 v[32:33], v[14:15], v[42:43] op_sel:[0,1] op_sel_hi:[1,1]
	v_pk_fma_f32 v[40:41], v[28:29], v[40:41], v[74:75] op_sel:[0,0,1] op_sel_hi:[1,0,0] neg_lo:[0,0,1]
	v_pk_mul_f32 v[74:75], v[6:7], v[44:45] op_sel:[0,1] op_sel_hi:[1,1]
	v_pk_fma_f32 v[42:43], v[14:15], v[42:43], v[32:33] op_sel:[0,0,1] op_sel_hi:[1,0,0] neg_lo:[0,0,1]
	v_pk_mul_f32 v[32:33], v[24:25], v[46:47] op_sel:[0,1] op_sel_hi:[1,1]
	v_pk_fma_f32 v[6:7], v[6:7], v[44:45], v[74:75] op_sel:[0,0,1] op_sel_hi:[1,0,0] neg_lo:[0,0,1]
	v_pk_mul_f32 v[44:45], v[18:19], v[48:49] op_sel:[0,1] op_sel_hi:[1,1]
	v_pk_fma_f32 v[24:25], v[24:25], v[46:47], v[32:33] op_sel:[0,0,1] op_sel_hi:[1,0,0] neg_lo:[0,0,1]
	v_pk_mul_f32 v[46:47], v[70:71], v[50:51] op_sel:[0,1] op_sel_hi:[1,1]
	v_pk_fma_f32 v[48:49], v[18:19], v[48:49], v[44:45] op_sel:[0,0,1] op_sel_hi:[1,0,0] neg_lo:[0,0,1]
	v_pk_mul_f32 v[18:19], v[8:9], v[52:53] op_sel:[0,1] op_sel_hi:[1,1]
	v_pk_fma_f32 v[50:51], v[70:71], v[50:51], v[46:47] op_sel:[0,0,1] op_sel_hi:[1,0,0] neg_lo:[0,0,1]
	v_pk_mul_f32 v[46:47], v[22:23], v[54:55] op_sel:[0,1] op_sel_hi:[1,1]
	v_pk_fma_f32 v[52:53], v[8:9], v[52:53], v[18:19] op_sel:[0,0,1] op_sel_hi:[1,0,0] neg_lo:[0,0,1]
	v_pk_mul_f32 v[18:19], v[34:35], v[56:57] op_sel:[0,1] op_sel_hi:[1,1]
	v_pk_fma_f32 v[46:47], v[22:23], v[54:55], v[46:47] op_sel:[0,0,1] op_sel_hi:[1,0,0] neg_lo:[0,0,1]
	v_pk_mul_f32 v[54:55], v[4:5], v[58:59] op_sel:[0,1] op_sel_hi:[1,1]
	v_pk_fma_f32 v[56:57], v[34:35], v[56:57], v[18:19] op_sel:[0,0,1] op_sel_hi:[1,0,0] neg_lo:[0,0,1]
	v_pk_mul_f32 v[18:19], v[76:77], v[60:61] op_sel:[0,1] op_sel_hi:[1,1]
	v_pk_fma_f32 v[54:55], v[4:5], v[58:59], v[54:55] op_sel:[0,0,1] op_sel_hi:[1,0,0] neg_lo:[0,0,1]
	v_pk_mul_f32 v[4:5], v[10:11], v[62:63] op_sel:[0,1] op_sel_hi:[1,1]
	v_pk_fma_f32 v[60:61], v[76:77], v[60:61], v[18:19] op_sel:[0,0,1] op_sel_hi:[1,0,0] neg_lo:[0,0,1]
	v_pk_fma_f32 v[4:5], v[10:11], v[62:63], v[4:5] op_sel:[0,0,1] op_sel_hi:[1,0,0] neg_lo:[0,0,1]
	ds_write2st64_b64 v176, v[78:79], v[16:17] offset0:0 offset1:17
	ds_write2st64_b64 v176, v[2:3], v[38:39] offset0:34 offset1:51
	ds_write2st64_b64 v176, v[40:41], v[42:43] offset0:68 offset1:85
	ds_write2st64_b64 v176, v[6:7], v[24:25] offset0:102 offset1:119
	ds_write2st64_b64 v176, v[48:49], v[50:51] offset0:136 offset1:153
	ds_write2st64_b64 v176, v[52:53], v[46:47] offset0:170 offset1:187
	ds_write2st64_b64 v176, v[56:57], v[54:55] offset0:204 offset1:221
	ds_write2st64_b64 v176, v[60:61], v[4:5] offset0:238 offset1:255
	s_cbranch_scc1 .LBB0_944
	s_waitcnt lgkmcnt(0)
	s_barrier
	s_mov_b32 s0, 0
	s_mov_b64 s[8:9], -1
	ds_read2st64_b64 v[208:211], v139 offset0:1 offset1:2
	ds_read2st64_b64 v[204:207], v139 offset0:3 offset1:4
	ds_read2st64_b64 v[200:203], v139 offset0:5 offset1:6
	ds_read2st64_b64 v[196:199], v139 offset0:7 offset1:8
	ds_read2st64_b64 v[192:195], v139 offset0:9 offset1:10
	ds_read2st64_b64 v[188:191], v139 offset0:11 offset1:12
	ds_read2st64_b64 v[184:187], v139 offset0:13 offset1:14
	ds_read_b64 v[232:233], v139 offset:7680
.LBB0_946:
	v_add_u32_e32 v37, s0, v140
	v_lshrrev_b32_e32 v138, 6, v37
	v_mad_u32_u24 v176, v138, s77, v142
	v_add_u32_e32 v218, 0x800, v176
	v_add_u32_e32 v234, 0x1000, v176
	v_add_u32_e32 v235, 0x1800, v176
	ds_read2_b64 v[0:3], v176 offset0:0 offset1:68
	ds_read2_b64 v[4:7], v234 offset0:32 offset1:100
	ds_read2_b64 v[8:11], v176 offset0:136 offset1:204
	ds_read2_b64 v[12:15], v234 offset0:168 offset1:236
	ds_read2_b64 v[16:19], v218 offset0:16 offset1:84
	ds_read2_b64 v[20:23], v235 offset0:48 offset1:116
	ds_read2_b64 v[24:27], v218 offset0:152 offset1:220
	ds_read2_b64 v[28:31], v235 offset0:184 offset1:252
	s_cmp_eq_u32 s0, 0
	s_movk_i32 s0, 0x200
	s_mov_b64 s[8:9], 0
	s_waitcnt lgkmcnt(6)
	v_pk_add_f32 v[32:33], v[0:1], v[4:5]
	v_pk_add_f32 v[34:35], v[2:3], v[6:7]
	s_waitcnt lgkmcnt(4)
	v_pk_add_f32 v[38:39], v[8:9], v[12:13]
	v_pk_add_f32 v[40:41], v[10:11], v[14:15]
	v_pk_add_f32 v[0:1], v[0:1], v[4:5] neg_lo:[0,1] neg_hi:[0,1]
	v_pk_add_f32 v[2:3], v[2:3], v[6:7] neg_lo:[0,1] neg_hi:[0,1]
	v_pk_add_f32 v[12:13], v[8:9], v[12:13] neg_lo:[0,1] neg_hi:[0,1]
	v_pk_add_f32 v[14:15], v[10:11], v[14:15] neg_lo:[0,1] neg_hi:[0,1]
	s_waitcnt lgkmcnt(2)
	v_pk_add_f32 v[10:11], v[16:17], v[20:21]
	v_pk_add_f32 v[8:9], v[18:19], v[22:23]
	s_waitcnt lgkmcnt(0)
; #define LAS __attribute__((address_space(3)))
; template <bool INV> __device__ __forceinline__ void dft16(f32x2 (&x)[16]) {
; #pragma unroll
;     for (int b = 0; b < 4; ++b) r4<INV>(x[b], x[4 + b], x[8 + b], x[12 + b]);
;     const float sg = INV ? -1.f : 1.f;
;     const f32x2 W1 = {0.92387953251f, -0.38268343236f * sg}, W2 = {0.70710678118f, -0.70710678118f * sg}, W3 = {0.38268343236f, -0.92387953251f * sg},
;                 W4 = {0.f, -1.f * sg}, W6 = {-0.70710678118f, -0.70710678118f * sg}, W9 = {-0.92387953251f, 0.38268343236f * sg};
;     x[5] = cmul(x[5], W1); x[9] = cmul(x[9], W2); x[13] = cmul(x[13], W3);
;     x[6] = cmul(x[6], W2); x[10] = cmul(x[10], W4); x[14] = cmul(x[14], W6);
;     x[7] = cmul(x[7], W3); x[11] = cmul(x[11], W6); x[15] = cmul(x[15], W9);
; #pragma unroll
;     for (int c = 0; c < 4; ++c) r4<INV>(x[4 * c], x[4 * c + 1], x[4 * c + 2], x[4 * c + 3]);
; }
; template <bool INV> __device__ __forceinline__ void bfly16(f32x2 (&x)[16], const LAS f32x2* TH, const LAS f32x2* TL, int tw) {
;     f32x2 W = tw32k(TH, TL, tw); if (INV) W.y = -W.y;
;     if (INV) { f32x2 p = W;
; #pragma unroll
;         for (int q = 1; q < 16; ++q) { x[q] = cmul(x[q], p); if (q < 15) p = cmul(p, W); } }
;     dft16<INV>(x);
;     if (!INV) { f32x2 p = W;
; #pragma unroll
;         for (int r = 1; r < 16; ++r) { x[4 * (r & 3) + (r >> 2)] = cmul(x[4 * (r & 3) + (r >> 2)], p); if (r < 15) p = cmul(p, W); } }
; }
; template <bool INV> __device__ __forceinline__ void bfly16_tab(f32x2 (&x)[16], const LAS f32x2* T, int tstride, int j) {
;     if (INV) {
; #pragma unroll
;         for (int q = 1; q < 16; ++q) { f32x2 p = T[q * tstride + j]; p.y = -p.y; x[q] = cmul(x[q], p); } }
;     dft16<INV>(x);
;     if (!INV) {
; #pragma unroll
;         for (int r = 1; r < 16; ++r) { const f32x2 p = T[r * tstride + j]; x[4 * (r & 3) + (r >> 2)] = cmul(x[4 * (r & 3) + (r >> 2)], p); } }
; }
; template <bool INV> __device__ __forceinline__ void pass16_s64(LAS f32x2* X, const LAS f32x2* TH, int base, int j) {
;     f32x2 x[16];
; #pragma unroll
;     for (int q = 0; q < 16; ++q) x[q] = X[base + q * 68];
;     bfly16_tab<INV>(x, TH - 2048, 64, j);
; #pragma unroll
;     for (int c = 0; c < 4; ++c)
; #pragma unroll
;         for (int d = 0; d < 4; ++d) X[base + (c + 4 * d) * 68] = x[4 * c + d];
	v_pk_add_f32 v[6:7], v[24:25], v[28:29]
	v_pk_add_f32 v[4:5], v[26:27], v[30:31]
	v_pk_add_f32 v[20:21], v[16:17], v[20:21] neg_lo:[0,1] neg_hi:[0,1]
	v_pk_add_f32 v[18:19], v[18:19], v[22:23] neg_lo:[0,1] neg_hi:[0,1]
	v_pk_add_f32 v[28:29], v[24:25], v[28:29] neg_lo:[0,1] neg_hi:[0,1]
	v_pk_add_f32 v[30:31], v[26:27], v[30:31] neg_lo:[0,1] neg_hi:[0,1]
	v_pk_add_f32 v[26:27], v[32:33], v[10:11]
	v_pk_add_f32 v[24:25], v[34:35], v[8:9]
	v_pk_add_f32 v[22:23], v[38:39], v[6:7]
	v_pk_add_f32 v[16:17], v[40:41], v[4:5]
	v_pk_add_f32 v[10:11], v[32:33], v[10:11] neg_lo:[0,1] neg_hi:[0,1]
	v_pk_add_f32 v[8:9], v[34:35], v[8:9] neg_lo:[0,1] neg_hi:[0,1]
	v_pk_add_f32 v[38:39], v[38:39], v[6:7] neg_lo:[0,1] neg_hi:[0,1]
	v_pk_add_f32 v[40:41], v[40:41], v[4:5] neg_lo:[0,1] neg_hi:[0,1]
	v_pk_add_f32 v[4:5], v[0:1], v[20:21] op_sel:[0,1] op_sel_hi:[1,0] neg_hi:[0,1]
	v_pk_add_f32 v[6:7], v[2:3], v[18:19] op_sel:[0,1] op_sel_hi:[1,0] neg_hi:[0,1]
	v_pk_add_f32 v[34:35], v[12:13], v[28:29] op_sel:[0,1] op_sel_hi:[1,0] neg_hi:[0,1]
	v_pk_add_f32 v[32:33], v[14:15], v[30:31] op_sel:[0,1] op_sel_hi:[1,0] neg_hi:[0,1]
	v_pk_add_f32 v[0:1], v[0:1], v[20:21] op_sel:[0,1] op_sel_hi:[1,0] neg_lo:[0,1]
	v_pk_add_f32 v[2:3], v[2:3], v[18:19] op_sel:[0,1] op_sel_hi:[1,0] neg_lo:[0,1]
	v_pk_add_f32 v[28:29], v[12:13], v[28:29] op_sel:[0,1] op_sel_hi:[1,0] neg_lo:[0,1]
	v_pk_add_f32 v[30:31], v[14:15], v[30:31] op_sel:[0,1] op_sel_hi:[1,0] neg_lo:[0,1]
	v_pk_mul_f32 v[14:15], v[6:7], s[70:71] op_sel_hi:[1,0]
	v_pk_mul_f32 v[12:13], v[8:9], s[72:73] op_sel_hi:[1,0]
	v_pk_mul_f32 v[18:19], v[2:3], s[64:65] op_sel_hi:[1,0]
	v_pk_mul_f32 v[20:21], v[34:35], s[72:73] op_sel_hi:[1,0]
	v_pk_mul_f32 v[42:43], v[28:29], s[72:73] op_sel_hi:[1,0]
	v_pk_mul_f32 v[44:45], v[32:33], s[64:65] op_sel_hi:[1,0]
	v_pk_mul_f32 v[46:47], v[40:41], s[72:73] op_sel_hi:[1,0]
	v_pk_mul_f32 v[48:49], v[30:31], s[82:83] op_sel_hi:[1,0]
	v_pk_fma_f32 v[14:15], v[6:7], s[44:45], v[14:15] op_sel:[0,0,1] op_sel_hi:[1,0,0] neg_lo:[0,0,1]
	v_pk_fma_f32 v[12:13], v[8:9], s[76:77], v[12:13] op_sel:[0,0,1] op_sel_hi:[1,0,0] neg_lo:[0,0,1]
	v_pk_fma_f32 v[18:19], v[2:3], s[82:83], v[18:19] op_sel:[0,0,1] op_sel_hi:[1,0,0] neg_lo:[0,0,1]
	v_pk_fma_f32 v[20:21], v[34:35], s[76:77], v[20:21] op_sel:[0,0,1] op_sel_hi:[1,0,0] neg_lo:[0,0,1]
	v_pk_fma_f32 v[42:43], v[28:29], s[72:73], v[42:43] op_sel:[0,0,1] op_sel_hi:[1,0,0] neg_lo:[0,0,1]
	v_pk_fma_f32 v[44:45], v[32:33], s[82:83], v[44:45] op_sel:[0,0,1] op_sel_hi:[1,0,0] neg_lo:[0,0,1]
	v_pk_fma_f32 v[46:47], v[40:41], s[72:73], v[46:47] op_sel:[0,0,1] op_sel_hi:[1,0,0] neg_lo:[0,0,1]
	v_pk_fma_f32 v[30:31], v[30:31], s[64:65], v[48:49] op_sel:[0,0,1] op_sel_hi:[1,0,0] neg_lo:[0,0,1]
	v_pk_add_f32 v[48:49], v[26:27], v[22:23]
	v_pk_add_f32 v[40:41], v[4:5], v[20:21]
	v_pk_add_f32 v[32:33], v[10:11], v[38:39] op_sel:[0,1] op_sel_hi:[1,0] neg_hi:[0,1]
	v_pk_add_f32 v[28:29], v[0:1], v[42:43]
	v_pk_add_f32 v[22:23], v[26:27], v[22:23] neg_lo:[0,1] neg_hi:[0,1]
	v_pk_add_f32 v[4:5], v[4:5], v[20:21] neg_lo:[0,1] neg_hi:[0,1]
	v_pk_add_f32 v[10:11], v[10:11], v[38:39] op_sel:[0,1] op_sel_hi:[1,0] neg_lo:[0,1]
	v_pk_add_f32 v[42:43], v[0:1], v[42:43] neg_lo:[0,1] neg_hi:[0,1]
	v_pk_add_f32 v[0:1], v[24:25], v[16:17]
	v_pk_add_f32 v[38:39], v[14:15], v[44:45]
	v_pk_add_f32 v[20:21], v[12:13], v[46:47]
	v_pk_add_f32 v[26:27], v[18:19], v[30:31]
	v_pk_add_f32 v[24:25], v[24:25], v[16:17] neg_lo:[0,1] neg_hi:[0,1]
	v_pk_add_f32 v[14:15], v[14:15], v[44:45] neg_lo:[0,1] neg_hi:[0,1]
	v_pk_add_f32 v[46:47], v[12:13], v[46:47] neg_lo:[0,1] neg_hi:[0,1]
	v_pk_add_f32 v[18:19], v[18:19], v[30:31] neg_lo:[0,1] neg_hi:[0,1]
	v_pk_add_f32 v[30:31], v[48:49], v[0:1]
	v_pk_add_f32 v[12:13], v[40:41], v[38:39]
	v_pk_add_f32 v[44:45], v[32:33], v[20:21]
	v_pk_add_f32 v[16:17], v[28:29], v[26:27]
	v_pk_add_f32 v[48:49], v[48:49], v[0:1] neg_lo:[0,1] neg_hi:[0,1]
	v_pk_add_f32 v[38:39], v[40:41], v[38:39] neg_lo:[0,1] neg_hi:[0,1]
	v_pk_add_f32 v[20:21], v[32:33], v[20:21] neg_lo:[0,1] neg_hi:[0,1]
	v_pk_add_f32 v[26:27], v[28:29], v[26:27] neg_lo:[0,1] neg_hi:[0,1]
	v_pk_add_f32 v[28:29], v[22:23], v[24:25] op_sel:[0,1] op_sel_hi:[1,0] neg_hi:[0,1]
	v_pk_add_f32 v[32:33], v[4:5], v[14:15] op_sel:[0,1] op_sel_hi:[1,0] neg_hi:[0,1]
	v_pk_add_f32 v[40:41], v[10:11], v[46:47] op_sel:[0,1] op_sel_hi:[1,0] neg_hi:[0,1]
	v_pk_add_f32 v[0:1], v[42:43], v[18:19] op_sel:[0,1] op_sel_hi:[1,0] neg_hi:[0,1]
	v_pk_add_f32 v[22:23], v[22:23], v[24:25] op_sel:[0,1] op_sel_hi:[1,0] neg_lo:[0,1]
	v_pk_add_f32 v[14:15], v[4:5], v[14:15] op_sel:[0,1] op_sel_hi:[1,0] neg_lo:[0,1]
	v_pk_add_f32 v[46:47], v[10:11], v[46:47] op_sel:[0,1] op_sel_hi:[1,0] neg_lo:[0,1]
	v_pk_add_f32 v[18:19], v[42:43], v[18:19] op_sel:[0,1] op_sel_hi:[1,0] neg_lo:[0,1]
	v_pk_mul_f32 v[42:43], v[12:13], v[208:209] op_sel:[0,1] op_sel_hi:[1,1]
	v_pk_mul_f32 v[10:11], v[44:45], v[210:211] op_sel:[0,1] op_sel_hi:[1,1]
	v_pk_fma_f32 v[12:13], v[12:13], v[208:209], v[42:43] op_sel:[0,0,1] op_sel_hi:[1,0,0] neg_lo:[0,0,1]
	v_pk_mul_f32 v[42:43], v[16:17], v[204:205] op_sel:[0,1] op_sel_hi:[1,1]
	v_pk_fma_f32 v[10:11], v[44:45], v[210:211], v[10:11] op_sel:[0,0,1] op_sel_hi:[1,0,0] neg_lo:[0,0,1]
	v_pk_mul_f32 v[44:45], v[28:29], v[206:207] op_sel:[0,1] op_sel_hi:[1,1]
	v_pk_fma_f32 v[42:43], v[16:17], v[204:205], v[42:43] op_sel:[0,0,1] op_sel_hi:[1,0,0] neg_lo:[0,0,1]
	v_pk_mul_f32 v[16:17], v[32:33], v[200:201] op_sel:[0,1] op_sel_hi:[1,1]
	v_pk_fma_f32 v[28:29], v[28:29], v[206:207], v[44:45] op_sel:[0,0,1] op_sel_hi:[1,0,0] neg_lo:[0,0,1]
	v_pk_mul_f32 v[44:45], v[40:41], v[202:203] op_sel:[0,1] op_sel_hi:[1,1]
; #define LAS __attribute__((address_space(3)))
; template <bool INV> __device__ __forceinline__ void pass16_s64(LAS f32x2* X, const LAS f32x2* TH, int base, int j) {
;     f32x2 x[16];
; #pragma unroll
;     for (int q = 0; q < 16; ++q) x[q] = X[base + q * 68];
;     bfly16_tab<INV>(x, TH - 2048, 64, j);
; #pragma unroll
;     for (int c = 0; c < 4; ++c)
; #pragma unroll
;         for (int d = 0; d < 4; ++d) X[base + (c + 4 * d) * 68] = x[4 * c + d];
; template <bool INV> __device__ __forceinline__ void pass16_s4(LAS f32x2* X, const LAS f32x2* TH, const LAS f32x2* TL, int tid) {
; #pragma unroll 1
;     for (int s = 0; s < 2; ++s) {
;         const int b = tid + NTHR * s, blk = b >> 2, jj = b & 3;
;         LAS f32x2* P = X + blk * 68 + jj;
;         f32x2 x[16];
; #pragma unroll
;         for (int q = 0; q < 16; ++q) x[q] = P[4 * q];
;         bfly16_tab<INV>(x, TH - 1024, 4, jj);
; #pragma unroll
;         for (int c = 0; c < 4; ++c)
; #pragma unroll
;             for (int d = 0; d < 4; ++d) P[4 * (c + 4 * d)] = x[4 * c + d];
;     }
; }
	v_pk_fma_f32 v[32:33], v[32:33], v[200:201], v[16:17] op_sel:[0,0,1] op_sel_hi:[1,0,0] neg_lo:[0,0,1]
	v_pk_mul_f32 v[16:17], v[0:1], v[196:197] op_sel:[0,1] op_sel_hi:[1,1]
	v_pk_fma_f32 v[40:41], v[40:41], v[202:203], v[44:45] op_sel:[0,0,1] op_sel_hi:[1,0,0] neg_lo:[0,0,1]
	v_pk_mul_f32 v[44:45], v[48:49], v[198:199] op_sel:[0,1] op_sel_hi:[1,1]
	v_pk_fma_f32 v[0:1], v[0:1], v[196:197], v[16:17] op_sel:[0,0,1] op_sel_hi:[1,0,0] neg_lo:[0,0,1]
	v_pk_mul_f32 v[16:17], v[38:39], v[192:193] op_sel:[0,1] op_sel_hi:[1,1]
	v_pk_fma_f32 v[48:49], v[48:49], v[198:199], v[44:45] op_sel:[0,0,1] op_sel_hi:[1,0,0] neg_lo:[0,0,1]
	v_pk_mul_f32 v[44:45], v[20:21], v[194:195] op_sel:[0,1] op_sel_hi:[1,1]
	v_pk_fma_f32 v[16:17], v[38:39], v[192:193], v[16:17] op_sel:[0,0,1] op_sel_hi:[1,0,0] neg_lo:[0,0,1]
	v_pk_mul_f32 v[38:39], v[26:27], v[188:189] op_sel:[0,1] op_sel_hi:[1,1]
	v_pk_fma_f32 v[44:45], v[20:21], v[194:195], v[44:45] op_sel:[0,0,1] op_sel_hi:[1,0,0] neg_lo:[0,0,1]
	v_pk_mul_f32 v[20:21], v[22:23], v[190:191] op_sel:[0,1] op_sel_hi:[1,1]
	v_pk_fma_f32 v[38:39], v[26:27], v[188:189], v[38:39] op_sel:[0,0,1] op_sel_hi:[1,0,0] neg_lo:[0,0,1]
	v_pk_mul_f32 v[26:27], v[14:15], v[184:185] op_sel:[0,1] op_sel_hi:[1,1]
	v_pk_fma_f32 v[20:21], v[22:23], v[190:191], v[20:21] op_sel:[0,0,1] op_sel_hi:[1,0,0] neg_lo:[0,0,1]
	v_pk_mul_f32 v[22:23], v[46:47], v[186:187] op_sel:[0,1] op_sel_hi:[1,1]
	v_pk_fma_f32 v[14:15], v[14:15], v[184:185], v[26:27] op_sel:[0,0,1] op_sel_hi:[1,0,0] neg_lo:[0,0,1]
	v_pk_mul_f32 v[26:27], v[18:19], v[232:233] op_sel:[0,1] op_sel_hi:[1,1]
	v_pk_fma_f32 v[22:23], v[46:47], v[186:187], v[22:23] op_sel:[0,0,1] op_sel_hi:[1,0,0] neg_lo:[0,0,1]
	v_pk_fma_f32 v[18:19], v[18:19], v[232:233], v[26:27] op_sel:[0,0,1] op_sel_hi:[1,0,0] neg_lo:[0,0,1]
	ds_write2_b64 v176, v[30:31], v[12:13] offset0:0 offset1:68
	ds_write2_b64 v176, v[10:11], v[42:43] offset0:136 offset1:204
	ds_write2_b64 v218, v[28:29], v[32:33] offset0:16 offset1:84
	ds_write2_b64 v218, v[40:41], v[0:1] offset0:152 offset1:220
	ds_write2_b64 v234, v[48:49], v[16:17] offset0:32 offset1:100
	ds_write2_b64 v234, v[44:45], v[38:39] offset0:168 offset1:236
	ds_write2_b64 v235, v[20:21], v[14:15] offset0:48 offset1:116
	ds_write2_b64 v235, v[22:23], v[18:19] offset0:184 offset1:252
	s_cbranch_scc1 .LBB0_946
	s_waitcnt lgkmcnt(0)
	s_barrier
	s_mov_b32 s0, 0
	s_mov_b64 s[8:9], -1
	ds_read2_b64 v[232:235], v141 offset0:4 offset1:8
	ds_read2_b64 v[208:211], v141 offset0:12 offset1:16
	ds_read2_b64 v[204:207], v141 offset0:20 offset1:24
	ds_read2_b64 v[200:203], v141 offset0:28 offset1:32
	ds_read2_b64 v[196:199], v141 offset0:36 offset1:40
	ds_read2_b64 v[192:195], v141 offset0:44 offset1:48
	ds_read2_b64 v[188:191], v141 offset0:52 offset1:56
	ds_read_b64 v[186:187], v141 offset:480
.LBB0_948:
	v_add_u32_e32 v37, s0, v140
	v_lshrrev_b32_e32 v138, 2, v37
	v_mad_u32_u24 v176, v138, s43, v144
	ds_read2_b64 v[0:3], v176 offset0:0 offset1:4
	ds_read2_b64 v[4:7], v176 offset0:32 offset1:36
	ds_read2_b64 v[8:11], v176 offset0:8 offset1:12
	ds_read2_b64 v[12:15], v176 offset0:40 offset1:44
	ds_read2_b64 v[16:19], v176 offset0:16 offset1:20
	ds_read2_b64 v[20:23], v176 offset0:48 offset1:52
	ds_read2_b64 v[24:27], v176 offset0:24 offset1:28
	ds_read2_b64 v[28:31], v176 offset0:56 offset1:60
	s_cmp_eq_u32 s0, 0
	s_movk_i32 s0, 0x200
	s_mov_b64 s[8:9], 0
	s_waitcnt lgkmcnt(6)
	v_pk_add_f32 v[32:33], v[0:1], v[4:5]
	v_pk_add_f32 v[34:35], v[2:3], v[6:7]
	s_waitcnt lgkmcnt(4)
	v_pk_add_f32 v[38:39], v[8:9], v[12:13]
	v_pk_add_f32 v[40:41], v[10:11], v[14:15]
	v_pk_add_f32 v[0:1], v[0:1], v[4:5] neg_lo:[0,1] neg_hi:[0,1]
	v_pk_add_f32 v[2:3], v[2:3], v[6:7] neg_lo:[0,1] neg_hi:[0,1]
	v_pk_add_f32 v[12:13], v[8:9], v[12:13] neg_lo:[0,1] neg_hi:[0,1]
	v_pk_add_f32 v[14:15], v[10:11], v[14:15] neg_lo:[0,1] neg_hi:[0,1]
	s_waitcnt lgkmcnt(2)
	v_pk_add_f32 v[10:11], v[16:17], v[20:21]
	v_pk_add_f32 v[8:9], v[18:19], v[22:23]
	s_waitcnt lgkmcnt(0)
	v_pk_add_f32 v[6:7], v[24:25], v[28:29]
	v_pk_add_f32 v[4:5], v[26:27], v[30:31]
	v_pk_add_f32 v[16:17], v[16:17], v[20:21] neg_lo:[0,1] neg_hi:[0,1]
	v_pk_add_f32 v[18:19], v[18:19], v[22:23] neg_lo:[0,1] neg_hi:[0,1]
	v_pk_add_f32 v[28:29], v[24:25], v[28:29] neg_lo:[0,1] neg_hi:[0,1]
	v_pk_add_f32 v[30:31], v[26:27], v[30:31] neg_lo:[0,1] neg_hi:[0,1]
	v_pk_add_f32 v[26:27], v[32:33], v[10:11]
	v_pk_add_f32 v[24:25], v[34:35], v[8:9]
	v_pk_add_f32 v[22:23], v[38:39], v[6:7]
	v_pk_add_f32 v[20:21], v[40:41], v[4:5]
	v_pk_add_f32 v[32:33], v[32:33], v[10:11] neg_lo:[0,1] neg_hi:[0,1]
	v_pk_add_f32 v[34:35], v[34:35], v[8:9] neg_lo:[0,1] neg_hi:[0,1]
	v_pk_add_f32 v[38:39], v[38:39], v[6:7] neg_lo:[0,1] neg_hi:[0,1]
	v_pk_add_f32 v[40:41], v[40:41], v[4:5] neg_lo:[0,1] neg_hi:[0,1]
	v_pk_add_f32 v[4:5], v[0:1], v[16:17] op_sel:[0,1] op_sel_hi:[1,0] neg_hi:[0,1]
	v_pk_add_f32 v[6:7], v[2:3], v[18:19] op_sel:[0,1] op_sel_hi:[1,0] neg_hi:[0,1]
	v_pk_add_f32 v[8:9], v[12:13], v[28:29] op_sel:[0,1] op_sel_hi:[1,0] neg_hi:[0,1]
	v_pk_add_f32 v[10:11], v[14:15], v[30:31] op_sel:[0,1] op_sel_hi:[1,0] neg_hi:[0,1]
	v_pk_add_f32 v[0:1], v[0:1], v[16:17] op_sel:[0,1] op_sel_hi:[1,0] neg_lo:[0,1]
	v_pk_add_f32 v[2:3], v[2:3], v[18:19] op_sel:[0,1] op_sel_hi:[1,0] neg_lo:[0,1]
	v_pk_add_f32 v[12:13], v[12:13], v[28:29] op_sel:[0,1] op_sel_hi:[1,0] neg_lo:[0,1]
	v_pk_add_f32 v[30:31], v[14:15], v[30:31] op_sel:[0,1] op_sel_hi:[1,0] neg_lo:[0,1]
	v_pk_mul_f32 v[14:15], v[6:7], s[70:71] op_sel_hi:[1,0]
	v_pk_mul_f32 v[28:29], v[34:35], s[72:73] op_sel_hi:[1,0]
	v_pk_mul_f32 v[18:19], v[2:3], s[64:65] op_sel_hi:[1,0]
	v_pk_mul_f32 v[16:17], v[8:9], s[72:73] op_sel_hi:[1,0]
; #define LAS __attribute__((address_space(3)))
; template <bool INV> __device__ __forceinline__ void dft16(f32x2 (&x)[16]) {
; #pragma unroll
;     for (int b = 0; b < 4; ++b) r4<INV>(x[b], x[4 + b], x[8 + b], x[12 + b]);
;     const float sg = INV ? -1.f : 1.f;
;     const f32x2 W1 = {0.92387953251f, -0.38268343236f * sg}, W2 = {0.70710678118f, -0.70710678118f * sg}, W3 = {0.38268343236f, -0.92387953251f * sg},
;                 W4 = {0.f, -1.f * sg}, W6 = {-0.70710678118f, -0.70710678118f * sg}, W9 = {-0.92387953251f, 0.38268343236f * sg};
;     x[5] = cmul(x[5], W1); x[9] = cmul(x[9], W2); x[13] = cmul(x[13], W3);
;     x[6] = cmul(x[6], W2); x[10] = cmul(x[10], W4); x[14] = cmul(x[14], W6);
;     x[7] = cmul(x[7], W3); x[11] = cmul(x[11], W6); x[15] = cmul(x[15], W9);
; #pragma unroll
;     for (int c = 0; c < 4; ++c) r4<INV>(x[4 * c], x[4 * c + 1], x[4 * c + 2], x[4 * c + 3]);
; }
; template <bool INV> __device__ __forceinline__ void bfly16(f32x2 (&x)[16], const LAS f32x2* TH, const LAS f32x2* TL, int tw) {
;     f32x2 W = tw32k(TH, TL, tw); if (INV) W.y = -W.y;
;     if (INV) { f32x2 p = W;
; #pragma unroll
;         for (int q = 1; q < 16; ++q) { x[q] = cmul(x[q], p); if (q < 15) p = cmul(p, W); } }
;     dft16<INV>(x);
;     if (!INV) { f32x2 p = W;
; #pragma unroll
;         for (int r = 1; r < 16; ++r) { x[4 * (r & 3) + (r >> 2)] = cmul(x[4 * (r & 3) + (r >> 2)], p); if (r < 15) p = cmul(p, W); } }
; }
; template <bool INV> __device__ __forceinline__ void bfly16_tab(f32x2 (&x)[16], const LAS f32x2* T, int tstride, int j) {
;     if (INV) {
; #pragma unroll
;         for (int q = 1; q < 16; ++q) { f32x2 p = T[q * tstride + j]; p.y = -p.y; x[q] = cmul(x[q], p); } }
;     dft16<INV>(x);
;     if (!INV) {
; #pragma unroll
;         for (int r = 1; r < 16; ++r) { const f32x2 p = T[r * tstride + j]; x[4 * (r & 3) + (r >> 2)] = cmul(x[4 * (r & 3) + (r >> 2)], p); } }
; }
; template <bool INV> __device__ __forceinline__ void pass16_s4(LAS f32x2* X, const LAS f32x2* TH, const LAS f32x2* TL, int tid) {
;     ...
;         for (int q = 0; q < 16; ++q) x[q] = P[4 * q];
;         bfly16_tab<INV>(x, TH - 1024, 4, jj);
; #pragma unroll
;         for (int c = 0; c < 4; ++c)
; #pragma unroll
;             for (int d = 0; d < 4; ++d) P[4 * (c + 4 * d)] = x[4 * c + d];
;     }
	v_pk_mul_f32 v[42:43], v[12:13], s[72:73] op_sel_hi:[1,0]
	v_pk_mul_f32 v[44:45], v[10:11], s[64:65] op_sel_hi:[1,0]
	v_pk_mul_f32 v[46:47], v[40:41], s[72:73] op_sel_hi:[1,0]
	v_pk_mul_f32 v[48:49], v[30:31], s[82:83] op_sel_hi:[1,0]
	v_pk_fma_f32 v[14:15], v[6:7], s[44:45], v[14:15] op_sel:[0,0,1] op_sel_hi:[1,0,0] neg_lo:[0,0,1]
	v_pk_fma_f32 v[28:29], v[34:35], s[76:77], v[28:29] op_sel:[0,0,1] op_sel_hi:[1,0,0] neg_lo:[0,0,1]
	v_pk_fma_f32 v[18:19], v[2:3], s[82:83], v[18:19] op_sel:[0,0,1] op_sel_hi:[1,0,0] neg_lo:[0,0,1]
	v_pk_fma_f32 v[16:17], v[8:9], s[76:77], v[16:17] op_sel:[0,0,1] op_sel_hi:[1,0,0] neg_lo:[0,0,1]
	v_pk_fma_f32 v[42:43], v[12:13], s[72:73], v[42:43] op_sel:[0,0,1] op_sel_hi:[1,0,0] neg_lo:[0,0,1]
	v_pk_fma_f32 v[10:11], v[10:11], s[82:83], v[44:45] op_sel:[0,0,1] op_sel_hi:[1,0,0] neg_lo:[0,0,1]
	v_pk_fma_f32 v[46:47], v[40:41], s[72:73], v[46:47] op_sel:[0,0,1] op_sel_hi:[1,0,0] neg_lo:[0,0,1]
	v_pk_fma_f32 v[48:49], v[30:31], s[64:65], v[48:49] op_sel:[0,0,1] op_sel_hi:[1,0,0] neg_lo:[0,0,1]
	v_pk_add_f32 v[30:31], v[26:27], v[22:23]
	v_pk_add_f32 v[40:41], v[4:5], v[16:17]
	v_pk_add_f32 v[44:45], v[32:33], v[38:39] op_sel:[0,1] op_sel_hi:[1,0] neg_hi:[0,1]
	v_pk_add_f32 v[12:13], v[0:1], v[42:43]
	v_pk_add_f32 v[26:27], v[26:27], v[22:23] neg_lo:[0,1] neg_hi:[0,1]
	v_pk_add_f32 v[16:17], v[4:5], v[16:17] neg_lo:[0,1] neg_hi:[0,1]
	v_pk_add_f32 v[32:33], v[32:33], v[38:39] op_sel:[0,1] op_sel_hi:[1,0] neg_lo:[0,1]
	v_pk_add_f32 v[42:43], v[0:1], v[42:43] neg_lo:[0,1] neg_hi:[0,1]
	v_pk_add_f32 v[0:1], v[24:25], v[20:21]
	v_pk_add_f32 v[38:39], v[14:15], v[10:11]
	v_pk_add_f32 v[4:5], v[28:29], v[46:47]
	v_pk_add_f32 v[22:23], v[18:19], v[48:49]
	v_pk_add_f32 v[24:25], v[24:25], v[20:21] neg_lo:[0,1] neg_hi:[0,1]
	v_pk_add_f32 v[10:11], v[14:15], v[10:11] neg_lo:[0,1] neg_hi:[0,1]
	v_pk_add_f32 v[28:29], v[28:29], v[46:47] neg_lo:[0,1] neg_hi:[0,1]
	v_pk_add_f32 v[48:49], v[18:19], v[48:49] neg_lo:[0,1] neg_hi:[0,1]
	v_pk_add_f32 v[18:19], v[30:31], v[0:1]
	v_pk_add_f32 v[46:47], v[40:41], v[38:39]
	v_pk_add_f32 v[14:15], v[44:45], v[4:5]
	v_pk_add_f32 v[20:21], v[12:13], v[22:23]
	v_pk_add_f32 v[0:1], v[30:31], v[0:1] neg_lo:[0,1] neg_hi:[0,1]
	v_pk_add_f32 v[38:39], v[40:41], v[38:39] neg_lo:[0,1] neg_hi:[0,1]
	v_pk_add_f32 v[4:5], v[44:45], v[4:5] neg_lo:[0,1] neg_hi:[0,1]
	v_pk_add_f32 v[12:13], v[12:13], v[22:23] neg_lo:[0,1] neg_hi:[0,1]
	v_pk_add_f32 v[22:23], v[26:27], v[24:25] op_sel:[0,1] op_sel_hi:[1,0] neg_hi:[0,1]
	v_pk_add_f32 v[44:45], v[16:17], v[10:11] op_sel:[0,1] op_sel_hi:[1,0] neg_hi:[0,1]
	v_pk_add_f32 v[40:41], v[32:33], v[28:29] op_sel:[0,1] op_sel_hi:[1,0] neg_hi:[0,1]
	v_pk_add_f32 v[30:31], v[42:43], v[48:49] op_sel:[0,1] op_sel_hi:[1,0] neg_hi:[0,1]
	v_pk_add_f32 v[24:25], v[26:27], v[24:25] op_sel:[0,1] op_sel_hi:[1,0] neg_lo:[0,1]
	v_pk_add_f32 v[10:11], v[16:17], v[10:11] op_sel:[0,1] op_sel_hi:[1,0] neg_lo:[0,1]
	v_pk_add_f32 v[28:29], v[32:33], v[28:29] op_sel:[0,1] op_sel_hi:[1,0] neg_lo:[0,1]
	v_pk_add_f32 v[42:43], v[42:43], v[48:49] op_sel:[0,1] op_sel_hi:[1,0] neg_lo:[0,1]
	v_pk_mul_f32 v[48:49], v[46:47], v[232:233] op_sel:[0,1] op_sel_hi:[1,1]
	v_pk_mul_f32 v[32:33], v[14:15], v[234:235] op_sel:[0,1] op_sel_hi:[1,1]
	v_pk_fma_f32 v[46:47], v[46:47], v[232:233], v[48:49] op_sel:[0,0,1] op_sel_hi:[1,0,0] neg_lo:[0,0,1]
	v_pk_mul_f32 v[48:49], v[20:21], v[208:209] op_sel:[0,1] op_sel_hi:[1,1]
	v_pk_fma_f32 v[14:15], v[14:15], v[234:235], v[32:33] op_sel:[0,0,1] op_sel_hi:[1,0,0] neg_lo:[0,0,1]
	v_pk_mul_f32 v[32:33], v[22:23], v[210:211] op_sel:[0,1] op_sel_hi:[1,1]
	v_pk_fma_f32 v[20:21], v[20:21], v[208:209], v[48:49] op_sel:[0,0,1] op_sel_hi:[1,0,0] neg_lo:[0,0,1]
	v_pk_mul_f32 v[48:49], v[44:45], v[204:205] op_sel:[0,1] op_sel_hi:[1,1]
	v_pk_fma_f32 v[22:23], v[22:23], v[210:211], v[32:33] op_sel:[0,0,1] op_sel_hi:[1,0,0] neg_lo:[0,0,1]
	v_pk_mul_f32 v[32:33], v[40:41], v[206:207] op_sel:[0,1] op_sel_hi:[1,1]
	v_pk_fma_f32 v[44:45], v[44:45], v[204:205], v[48:49] op_sel:[0,0,1] op_sel_hi:[1,0,0] neg_lo:[0,0,1]
	v_pk_mul_f32 v[48:49], v[30:31], v[200:201] op_sel:[0,1] op_sel_hi:[1,1]
	v_pk_fma_f32 v[40:41], v[40:41], v[206:207], v[32:33] op_sel:[0,0,1] op_sel_hi:[1,0,0] neg_lo:[0,0,1]
	v_pk_mul_f32 v[32:33], v[0:1], v[202:203] op_sel:[0,1] op_sel_hi:[1,1]
	v_pk_fma_f32 v[48:49], v[30:31], v[200:201], v[48:49] op_sel:[0,0,1] op_sel_hi:[1,0,0] neg_lo:[0,0,1]
	v_pk_mul_f32 v[30:31], v[38:39], v[196:197] op_sel:[0,1] op_sel_hi:[1,1]
	v_pk_fma_f32 v[32:33], v[0:1], v[202:203], v[32:33] op_sel:[0,0,1] op_sel_hi:[1,0,0] neg_lo:[0,0,1]
	v_pk_mul_f32 v[0:1], v[4:5], v[198:199] op_sel:[0,1] op_sel_hi:[1,1]
	v_pk_fma_f32 v[30:31], v[38:39], v[196:197], v[30:31] op_sel:[0,0,1] op_sel_hi:[1,0,0] neg_lo:[0,0,1]
	v_pk_mul_f32 v[38:39], v[12:13], v[192:193] op_sel:[0,1] op_sel_hi:[1,1]
	v_pk_fma_f32 v[0:1], v[4:5], v[198:199], v[0:1] op_sel:[0,0,1] op_sel_hi:[1,0,0] neg_lo:[0,0,1]
	v_pk_mul_f32 v[4:5], v[24:25], v[194:195] op_sel:[0,1] op_sel_hi:[1,1]
	v_pk_fma_f32 v[12:13], v[12:13], v[192:193], v[38:39] op_sel:[0,0,1] op_sel_hi:[1,0,0] neg_lo:[0,0,1]
	v_pk_mul_f32 v[38:39], v[10:11], v[188:189] op_sel:[0,1] op_sel_hi:[1,1]
	v_pk_fma_f32 v[4:5], v[24:25], v[194:195], v[4:5] op_sel:[0,0,1] op_sel_hi:[1,0,0] neg_lo:[0,0,1]
	v_pk_mul_f32 v[24:25], v[28:29], v[190:191] op_sel:[0,1] op_sel_hi:[1,1]
	v_pk_fma_f32 v[10:11], v[10:11], v[188:189], v[38:39] op_sel:[0,0,1] op_sel_hi:[1,0,0] neg_lo:[0,0,1]
	v_pk_mul_f32 v[38:39], v[42:43], v[186:187] op_sel:[0,1] op_sel_hi:[1,1]
	v_pk_fma_f32 v[24:25], v[28:29], v[190:191], v[24:25] op_sel:[0,0,1] op_sel_hi:[1,0,0] neg_lo:[0,0,1]
	v_pk_fma_f32 v[38:39], v[42:43], v[186:187], v[38:39] op_sel:[0,0,1] op_sel_hi:[1,0,0] neg_lo:[0,0,1]
	ds_write2_b64 v176, v[18:19], v[46:47] offset0:0 offset1:4
	ds_write2_b64 v176, v[14:15], v[20:21] offset0:8 offset1:12
	ds_write2_b64 v176, v[22:23], v[44:45] offset0:16 offset1:20
	ds_write2_b64 v176, v[40:41], v[48:49] offset0:24 offset1:28
	ds_write2_b64 v176, v[32:33], v[30:31] offset0:32 offset1:36
	ds_write2_b64 v176, v[0:1], v[12:13] offset0:40 offset1:44
	ds_write2_b64 v176, v[4:5], v[10:11] offset0:48 offset1:52
	ds_write2_b64 v176, v[24:25], v[38:39] offset0:56 offset1:60
	s_cbranch_scc1 .LBB0_948
	s_waitcnt lgkmcnt(0)
	s_barrier
	s_mov_b32 s0, 0
	v_mov_b32_e32 v0, v36
